# K-loop MFMA segment tails: s_setprio 0 and the m0/pointer SALU moved from in front of the post-MFMA barrier to just behind it
# speedup vs baseline: 1.0291x; 1.0096x over previous
; #define PG8_STAGE(bufoff, gbase, voff) do { _Pragma("unroll") for (int _i = 0; _i < 2; ++_i) \
;         __builtin_amdgcn_global_load_lds((const unsigned*)((const char*)(gbase) + (voff)[_i]), (LAS unsigned*)(lds + (bufoff) + ldsw + _i * 8192), 16, 0, 0); } while (0)
; #define PG8_LDA(dst, b, h) do { _Pragma("unroll") for (int m = 0; m < 4; ++m) _Pragma("unroll") for (int k = 0; k < 2; ++k) dst[m][k] = *(const LAS bf16x8*)(lds + PG8_SA(b, h) + aoff + m * 2048 + k * 1024); } while (0)
; #define PG8_LDB(dst, b, h) do { _Pragma("unroll") for (int n = 0; n < 2; ++n) _Pragma("unroll") for (int k = 0; k < 2; ++k) dst[n][k] = *(const LAS bf16x8*)(lds + PG8_SB(b, h) + boff + n * 2048 + k * 1024); } while (0)
; #define PG8_WAIT_V(n) asm volatile("s_waitcnt vmcnt(" #n ")" ::: "memory")
; #define PG8_WAIT_L(n) asm volatile("s_waitcnt lgkmcnt(" #n ")" ::: "memory")
; #define PG8_BAR __builtin_amdgcn_s_barrier()
; #define PG8_SCHED __builtin_amdgcn_sched_barrier(0)
; template <class Epi>
; __device__ __forceinline__ void gemm_phase(LAS unsigned char* lds, const bf16_t* A, int lda, const bf16_t* Bt, int ldb, int M, int N, int K, int asel, const Epi& E, const int fixed_round = -1) {
;     ...
;             PG8_LDB(B0, 0, 0); PG8_SCHED; PG8_LDA(At, 0, 0); PG8_STAGE(PG8_SA(1, 1), a1 + hstepA, voffA);
;             PG8_WAIT_L(8); PG8_BAR; PG8_WAIT_L(0); PG8_MMA(0, 0, At, B0); PG8_BAR; PG8_SCHED;
;             PG8_LDB(B1, 0, 1); PG8_STAGE(PG8_SB(0, 0), b2, voffB);
;             PG8_BAR; PG8_WAIT_L(0); PG8_MMA(0, 1, At, B1); PG8_BAR;
;             PG8_LDA(At, 0, 1); PG8_STAGE(PG8_SA(0, 0), a2, voffA);
;             PG8_BAR; PG8_WAIT_L(0); PG8_MMA(1, 0, At, B0); PG8_BAR; PG8_SCHED;
;             PG8_STAGE(PG8_SB(0, 1), b2 + hstepB, voffB);
;             PG8_WAIT_V(6); PG8_BAR; PG8_MMA(1, 1, At, B1); PG8_BAR;
.LBB0_199:
	ds_read_b128 v[148:151], v161
	ds_read_b128 v[152:155], v161 offset:1024
	ds_read_b128 v[156:159], v161 offset:2048
	ds_read_b128 v[166:169], v161 offset:3072
	s_add_i32 m0, s39, 0xc000
	ds_read_b128 v[170:173], v162
	ds_read_b128 v[174:177], v162 offset:1024
	ds_read_b128 v[178:181], v162 offset:2048
	ds_read_b128 v[182:185], v162 offset:3072
	ds_read_b128 v[186:189], v162 offset:4096
	ds_read_b128 v[190:193], v162 offset:5120
	ds_read_b128 v[196:199], v162 offset:6144
	ds_read_b128 v[202:205], v162 offset:7168
	global_load_lds_dwordx4 v140, s[28:29]
	s_add_i32 m0, s39, 0xe000
	s_nop 0
	global_load_lds_dwordx4 v142, s[28:29]
	s_waitcnt lgkmcnt(8)
	s_setprio 1
	s_barrier
	s_waitcnt lgkmcnt(0)
	v_mfma_f32_16x16x32_bf16 v[124:127], v[148:151], v[170:173], v[124:127]
	v_mfma_f32_16x16x32_bf16 v[120:123], v[156:159], v[170:173], v[120:123]
	v_mfma_f32_16x16x32_bf16 v[112:115], v[148:151], v[178:181], v[112:115]
	v_mfma_f32_16x16x32_bf16 v[108:111], v[156:159], v[178:181], v[108:111]
	v_mfma_f32_16x16x32_bf16 v[100:103], v[148:151], v[186:189], v[100:103]
	v_mfma_f32_16x16x32_bf16 v[92:95], v[156:159], v[186:189], v[92:95]
	v_mfma_f32_16x16x32_bf16 v[84:87], v[148:151], v[196:199], v[84:87]
	v_mfma_f32_16x16x32_bf16 v[76:79], v[156:159], v[196:199], v[76:79]
	v_mfma_f32_16x16x32_bf16 v[124:127], v[152:155], v[174:177], v[124:127]
	v_mfma_f32_16x16x32_bf16 v[120:123], v[166:169], v[174:177], v[120:123]
	v_mfma_f32_16x16x32_bf16 v[112:115], v[152:155], v[182:185], v[112:115]
	v_mfma_f32_16x16x32_bf16 v[108:111], v[166:169], v[182:185], v[108:111]
	v_mfma_f32_16x16x32_bf16 v[100:103], v[152:155], v[190:193], v[100:103]
	v_mfma_f32_16x16x32_bf16 v[92:95], v[166:169], v[190:193], v[92:95]
	v_mfma_f32_16x16x32_bf16 v[84:87], v[152:155], v[202:205], v[84:87]
	v_mfma_f32_16x16x32_bf16 v[76:79], v[166:169], v[202:205], v[76:79]
	s_barrier
	s_setprio 0
	s_add_u32 s30, s28, 0xfff80080
	s_addc_u32 s31, s29, -1
	s_cmp_eq_u32 s58, 28
	s_cselect_b32 s35, s4, s31
	s_cselect_b32 s34, s21, s30
	s_cselect_b32 s31, s19, s57
	s_cselect_b32 s30, s55, s56
	s_add_i32 s59, s46, s38
	s_add_u32 s98, s30, s6
	s_addc_u32 s99, s31, s7
	s_mov_b32 m0, s59
	ds_read_b128 v[206:209], v163
	ds_read_b128 v[210:213], v163 offset:1024
	ds_read_b128 v[214:217], v163 offset:2048
	ds_read_b128 v[218:221], v163 offset:3072
	global_load_lds_dwordx4 v130, s[30:31]
	s_add_i32 m0, s59, 0x2000
	s_nop 0
	global_load_lds_dwordx4 v134, s[30:31]
	s_setprio 1
	s_barrier
	s_waitcnt lgkmcnt(0)
	v_mfma_f32_16x16x32_bf16 v[116:119], v[206:209], v[170:173], v[116:119]
	v_mfma_f32_16x16x32_bf16 v[104:107], v[214:217], v[170:173], v[104:107]
	v_mfma_f32_16x16x32_bf16 v[96:99], v[206:209], v[178:181], v[96:99]
	v_mfma_f32_16x16x32_bf16 v[88:91], v[214:217], v[178:181], v[88:91]
	v_mfma_f32_16x16x32_bf16 v[80:83], v[206:209], v[186:189], v[80:83]
	v_mfma_f32_16x16x32_bf16 v[72:75], v[214:217], v[186:189], v[72:75]
	v_mfma_f32_16x16x32_bf16 v[68:71], v[206:209], v[196:199], v[68:71]
	v_mfma_f32_16x16x32_bf16 v[64:67], v[214:217], v[196:199], v[64:67]
	v_mfma_f32_16x16x32_bf16 v[116:119], v[210:213], v[174:177], v[116:119]
	v_mfma_f32_16x16x32_bf16 v[104:107], v[218:221], v[174:177], v[104:107]
	v_mfma_f32_16x16x32_bf16 v[96:99], v[210:213], v[182:185], v[96:99]
	v_mfma_f32_16x16x32_bf16 v[88:91], v[218:221], v[182:185], v[88:91]
	v_mfma_f32_16x16x32_bf16 v[80:83], v[210:213], v[190:193], v[80:83]
	v_mfma_f32_16x16x32_bf16 v[72:75], v[218:221], v[190:193], v[72:75]
	v_mfma_f32_16x16x32_bf16 v[68:71], v[210:213], v[202:205], v[68:71]
	v_mfma_f32_16x16x32_bf16 v[64:67], v[218:221], v[202:205], v[64:67]
	s_barrier
	s_setprio 0
	s_mov_b32 m0, s39
	s_add_u32 s100, s34, s6
	s_addc_u32 s101, s35, s7
	ds_read_b128 v[170:173], v162 offset:16384
	ds_read_b128 v[174:177], v162 offset:17408
	ds_read_b128 v[178:181], v162 offset:18432
	ds_read_b128 v[182:185], v162 offset:19456
	ds_read_b128 v[186:189], v162 offset:20480
	ds_read_b128 v[190:193], v162 offset:21504
	ds_read_b128 v[196:199], v162 offset:22528
	ds_read_b128 v[202:205], v162 offset:23552
	global_load_lds_dwordx4 v128, s[34:35]
	s_mov_b32 m0, s40
	s_nop 0
	global_load_lds_dwordx4 v132, s[34:35]
	s_setprio 1
	s_barrier
	s_waitcnt lgkmcnt(0)
	v_mfma_f32_16x16x32_bf16 v[60:63], v[148:151], v[170:173], v[60:63]
	v_mfma_f32_16x16x32_bf16 v[56:59], v[156:159], v[170:173], v[56:59]
	v_mfma_f32_16x16x32_bf16 v[52:55], v[148:151], v[178:181], v[52:55]
	v_mfma_f32_16x16x32_bf16 v[44:47], v[156:159], v[178:181], v[44:47]
	v_mfma_f32_16x16x32_bf16 v[36:39], v[148:151], v[186:189], v[36:39]
	v_mfma_f32_16x16x32_bf16 v[28:31], v[156:159], v[186:189], v[28:31]
	v_mfma_f32_16x16x32_bf16 v[20:23], v[148:151], v[196:199], v[20:23]
	v_mfma_f32_16x16x32_bf16 v[12:15], v[156:159], v[196:199], v[12:15]
	v_mfma_f32_16x16x32_bf16 v[60:63], v[152:155], v[174:177], v[60:63]
	v_mfma_f32_16x16x32_bf16 v[56:59], v[166:169], v[174:177], v[56:59]
	v_mfma_f32_16x16x32_bf16 v[52:55], v[152:155], v[182:185], v[52:55]
	v_mfma_f32_16x16x32_bf16 v[44:47], v[166:169], v[182:185], v[44:47]
	v_mfma_f32_16x16x32_bf16 v[36:39], v[152:155], v[190:193], v[36:39]
	v_mfma_f32_16x16x32_bf16 v[28:31], v[166:169], v[190:193], v[28:31]
	v_mfma_f32_16x16x32_bf16 v[20:23], v[152:155], v[202:205], v[20:23]
	v_mfma_f32_16x16x32_bf16 v[12:15], v[166:169], v[202:205], v[12:15]
	s_barrier
	s_setprio 0
	s_add_u32 s60, s30, 0x80000
	s_addc_u32 s61, s31, 0
	s_add_i32 s59, s47, s38
	s_mov_b32 m0, s59
	s_nop 0
	global_load_lds_dwordx4 v130, s[60:61]
	s_add_i32 m0, s59, 0x2000
	s_nop 0
	global_load_lds_dwordx4 v134, s[60:61]
	s_waitcnt vmcnt(6)
	s_setprio 1
	s_barrier
; #define PG8_STAGE(bufoff, gbase, voff) do { _Pragma("unroll") for (int _i = 0; _i < 2; ++_i) \
;         __builtin_amdgcn_global_load_lds((const unsigned*)((const char*)(gbase) + (voff)[_i]), (LAS unsigned*)(lds + (bufoff) + ldsw + _i * 8192), 16, 0, 0); } while (0)
; #define PG8_LDA(dst, b, h) do { _Pragma("unroll") for (int m = 0; m < 4; ++m) _Pragma("unroll") for (int k = 0; k < 2; ++k) dst[m][k] = *(const LAS bf16x8*)(lds + PG8_SA(b, h) + aoff + m * 2048 + k * 1024); } while (0)
; #define PG8_LDB(dst, b, h) do { _Pragma("unroll") for (int n = 0; n < 2; ++n) _Pragma("unroll") for (int k = 0; k < 2; ++k) dst[n][k] = *(const LAS bf16x8*)(lds + PG8_SB(b, h) + boff + n * 2048 + k * 1024); } while (0)
; #define PG8_WAIT_V(n) asm volatile("s_waitcnt vmcnt(" #n ")" ::: "memory")
; #define PG8_WAIT_L(n) asm volatile("s_waitcnt lgkmcnt(" #n ")" ::: "memory")
; #define PG8_BAR __builtin_amdgcn_s_barrier()
; #define PG8_SCHED __builtin_amdgcn_sched_barrier(0)
; template <class Epi>
; __device__ __forceinline__ void gemm_phase(LAS unsigned char* lds, const bf16_t* A, int lda, const bf16_t* Bt, int ldb, int M, int N, int K, int asel, const Epi& E, const int fixed_round = -1) {
;     ...
;             PG8_WAIT_V(6); PG8_BAR; PG8_MMA(1, 1, At, B1); PG8_BAR;
;             PG8_LDB(B0, 1, 0); PG8_SCHED; PG8_LDA(At, 1, 0); PG8_STAGE(PG8_SA(0, 1), a2 + hstepA, voffA);
;             PG8_WAIT_L(8); PG8_BAR; PG8_WAIT_L(0); PG8_MMA(0, 0, At, B0); PG8_BAR; PG8_SCHED;
;             PG8_LDB(B1, 1, 1); PG8_STAGE(PG8_SB(1, 0), b3, voffB);
;             PG8_BAR; PG8_WAIT_L(0); PG8_MMA(0, 1, At, B1); PG8_BAR;
	v_mfma_f32_16x16x32_bf16 v[48:51], v[206:209], v[170:173], v[48:51]
	v_mfma_f32_16x16x32_bf16 v[40:43], v[214:217], v[170:173], v[40:43]
	v_mfma_f32_16x16x32_bf16 v[32:35], v[206:209], v[178:181], v[32:35]
	v_mfma_f32_16x16x32_bf16 v[24:27], v[214:217], v[178:181], v[24:27]
	v_mfma_f32_16x16x32_bf16 v[16:19], v[206:209], v[186:189], v[16:19]
	v_mfma_f32_16x16x32_bf16 v[8:11], v[214:217], v[186:189], v[8:11]
	v_mfma_f32_16x16x32_bf16 v[4:7], v[206:209], v[196:199], v[4:7]
	v_mfma_f32_16x16x32_bf16 v[0:3], v[214:217], v[196:199], v[0:3]
	v_mfma_f32_16x16x32_bf16 v[48:51], v[210:213], v[174:177], v[48:51]
	v_mfma_f32_16x16x32_bf16 v[40:43], v[218:221], v[174:177], v[40:43]
	v_mfma_f32_16x16x32_bf16 v[32:35], v[210:213], v[182:185], v[32:35]
	v_mfma_f32_16x16x32_bf16 v[24:27], v[218:221], v[182:185], v[24:27]
	v_mfma_f32_16x16x32_bf16 v[16:19], v[210:213], v[190:193], v[16:19]
	v_mfma_f32_16x16x32_bf16 v[8:11], v[218:221], v[190:193], v[8:11]
	v_mfma_f32_16x16x32_bf16 v[4:7], v[210:213], v[202:205], v[4:7]
	v_mfma_f32_16x16x32_bf16 v[0:3], v[218:221], v[202:205], v[0:3]
	s_barrier
	s_setprio 0
	s_add_i32 s59, 0, 0x18000
	v_add_u32_e32 v136, s59, v160
	ds_read_b128 v[148:151], v136
	ds_read_b128 v[152:155], v136 offset:1024
	ds_read_b128 v[156:159], v136 offset:2048
	ds_read_b128 v[166:169], v136 offset:3072
	s_add_u32 s34, s34, 0x80000
	s_addc_u32 s35, s35, 0
	s_mov_b32 m0, s41
	ds_read_b128 v[170:173], v162 offset:32768
	ds_read_b128 v[174:177], v162 offset:33792
	ds_read_b128 v[178:181], v162 offset:34816
	ds_read_b128 v[182:185], v162 offset:35840
	ds_read_b128 v[186:189], v162 offset:36864
	ds_read_b128 v[190:193], v162 offset:37888
	ds_read_b128 v[196:199], v162 offset:38912
	ds_read_b128 v[202:205], v162 offset:39936
	global_load_lds_dwordx4 v128, s[34:35]
	s_mov_b32 m0, s42
	s_nop 0
	global_load_lds_dwordx4 v132, s[34:35]
	s_waitcnt lgkmcnt(8)
	s_setprio 1
	s_barrier
	s_waitcnt lgkmcnt(0)
	v_mfma_f32_16x16x32_bf16 v[124:127], v[148:151], v[170:173], v[124:127]
	v_mfma_f32_16x16x32_bf16 v[120:123], v[156:159], v[170:173], v[120:123]
	v_mfma_f32_16x16x32_bf16 v[112:115], v[148:151], v[178:181], v[112:115]
	v_mfma_f32_16x16x32_bf16 v[108:111], v[156:159], v[178:181], v[108:111]
	v_mfma_f32_16x16x32_bf16 v[100:103], v[148:151], v[186:189], v[100:103]
	v_mfma_f32_16x16x32_bf16 v[92:95], v[156:159], v[186:189], v[92:95]
	v_mfma_f32_16x16x32_bf16 v[84:87], v[148:151], v[196:199], v[84:87]
	v_mfma_f32_16x16x32_bf16 v[76:79], v[156:159], v[196:199], v[76:79]
	v_mfma_f32_16x16x32_bf16 v[124:127], v[152:155], v[174:177], v[124:127]
	v_mfma_f32_16x16x32_bf16 v[120:123], v[166:169], v[174:177], v[120:123]
	v_mfma_f32_16x16x32_bf16 v[112:115], v[152:155], v[182:185], v[112:115]
	v_mfma_f32_16x16x32_bf16 v[108:111], v[166:169], v[182:185], v[108:111]
	v_mfma_f32_16x16x32_bf16 v[100:103], v[152:155], v[190:193], v[100:103]
	v_mfma_f32_16x16x32_bf16 v[92:95], v[166:169], v[190:193], v[92:95]
	v_mfma_f32_16x16x32_bf16 v[84:87], v[152:155], v[202:205], v[84:87]
	v_mfma_f32_16x16x32_bf16 v[76:79], v[166:169], v[202:205], v[76:79]
	s_barrier
	s_setprio 0
	s_add_i32 s34, 0, 0x1c000
	s_add_i32 s35, s59, s38
	v_add_u32_e32 v136, s34, v160
	s_mov_b32 m0, s35
	ds_read_b128 v[206:209], v136
	ds_read_b128 v[210:213], v136 offset:1024
	ds_read_b128 v[214:217], v136 offset:2048
	ds_read_b128 v[218:221], v136 offset:3072
	global_load_lds_dwordx4 v130, s[98:99]
	s_add_i32 m0, s35, 0x2000
	s_nop 0
	global_load_lds_dwordx4 v134, s[98:99]
	s_setprio 1
	s_barrier
	s_waitcnt lgkmcnt(0)
	v_mfma_f32_16x16x32_bf16 v[116:119], v[206:209], v[170:173], v[116:119]
	v_mfma_f32_16x16x32_bf16 v[104:107], v[214:217], v[170:173], v[104:107]
	v_mfma_f32_16x16x32_bf16 v[96:99], v[206:209], v[178:181], v[96:99]
	v_mfma_f32_16x16x32_bf16 v[88:91], v[214:217], v[178:181], v[88:91]
	v_mfma_f32_16x16x32_bf16 v[80:83], v[206:209], v[186:189], v[80:83]
	v_mfma_f32_16x16x32_bf16 v[72:75], v[214:217], v[186:189], v[72:75]
	v_mfma_f32_16x16x32_bf16 v[68:71], v[206:209], v[196:199], v[68:71]
	v_mfma_f32_16x16x32_bf16 v[64:67], v[214:217], v[196:199], v[64:67]
	v_mfma_f32_16x16x32_bf16 v[116:119], v[210:213], v[174:177], v[116:119]
	v_mfma_f32_16x16x32_bf16 v[104:107], v[218:221], v[174:177], v[104:107]
	v_mfma_f32_16x16x32_bf16 v[96:99], v[210:213], v[182:185], v[96:99]
	v_mfma_f32_16x16x32_bf16 v[88:91], v[218:221], v[182:185], v[88:91]
	v_mfma_f32_16x16x32_bf16 v[80:83], v[210:213], v[190:193], v[80:83]
	v_mfma_f32_16x16x32_bf16 v[72:75], v[218:221], v[190:193], v[72:75]
	v_mfma_f32_16x16x32_bf16 v[68:71], v[210:213], v[202:205], v[68:71]
	v_mfma_f32_16x16x32_bf16 v[64:67], v[218:221], v[202:205], v[64:67]
	s_barrier
	s_setprio 0
	s_mov_b32 m0, s43
	ds_read_b128 v[170:173], v162 offset:49152
	ds_read_b128 v[174:177], v162 offset:50176
	ds_read_b128 v[178:181], v162 offset:51200
	ds_read_b128 v[182:185], v162 offset:52224
	ds_read_b128 v[186:189], v162 offset:53248
	ds_read_b128 v[190:193], v162 offset:54272
	ds_read_b128 v[196:199], v162 offset:55296
	ds_read_b128 v[202:205], v162 offset:56320
	global_load_lds_dwordx4 v128, s[100:101]
	s_mov_b32 m0, s44
	s_nop 0
	global_load_lds_dwordx4 v132, s[100:101]
	s_setprio 1
	s_barrier
; __device__ __forceinline__ unsigned cvt_pk_bf16(float lo, float hi) { const bf16x2_t r = __builtin_convertvector((f32x2){lo, hi}, bf16x2_t); return __builtin_bit_cast(unsigned, r); }
; #define PG8_STAGE(bufoff, gbase, voff) do { _Pragma("unroll") for (int _i = 0; _i < 2; ++_i) \
;         __builtin_amdgcn_global_load_lds((const unsigned*)((const char*)(gbase) + (voff)[_i]), (LAS unsigned*)(lds + (bufoff) + ldsw + _i * 8192), 16, 0, 0); } while (0)
; #define PG8_LDA(dst, b, h) do { _Pragma("unroll") for (int m = 0; m < 4; ++m) _Pragma("unroll") for (int k = 0; k < 2; ++k) dst[m][k] = *(const LAS bf16x8*)(lds + PG8_SA(b, h) + aoff + m * 2048 + k * 1024); } while (0)
; #define PG8_WAIT_V(n) asm volatile("s_waitcnt vmcnt(" #n ")" ::: "memory")
; #define PG8_WAIT_L(n) asm volatile("s_waitcnt lgkmcnt(" #n ")" ::: "memory")
; #define PG8_BAR __builtin_amdgcn_s_barrier()
; #define PG8_SCHED __builtin_amdgcn_sched_barrier(0)
; template <class Epi>
; __device__ __forceinline__ void gemm_phase(LAS unsigned char* lds, const bf16_t* A, int lda, const bf16_t* Bt, int ldb, int M, int N, int K, int asel, const Epi& E, const int fixed_round = -1) {
;     ...
;             PG8_BAR; PG8_WAIT_L(0); PG8_MMA(0, 1, At, B1); PG8_BAR;
;             PG8_LDA(At, 1, 1); PG8_STAGE(PG8_SA(1, 0), a3, voffA);
;             PG8_BAR; PG8_WAIT_L(0); PG8_MMA(1, 0, At, B0); PG8_BAR; PG8_SCHED;
;             PG8_STAGE(PG8_SB(1, 1), b3 + hstepB, voffB);
;             PG8_WAIT_V(6); PG8_BAR; PG8_MMA(1, 1, At, B1); PG8_BAR;
;     __device__ __forceinline__ void operator()(const AccT& acc, const Unit& u, int wr, int wc, int fr, int fq) const {
;     ...
;         if (pn < 8) {
;             bf16_t* base = pn < 4 ? Q : Kn; const int colt = (pn & 3) * BM; const float sc = pn < 4 ? 0.08838834764831845f : 1.0f;
; #pragma unroll
;             for (int ai = 0; ai < 2; ++ai)
; #pragma unroll
;                 for (int m = 0; m < 4; ++m) { bf16_t* rowp = base + (size_t)(row0 + ai * HALF + m * 16) * 1024 + colt + cl;
; #pragma unroll
;                     for (int bj = 0; bj < 2; ++bj) { const f32x4 v0 = acc[ai][bj][m][0] * sc, v1 = acc[ai][bj][m][1] * sc;
;                         u32x4 w; w.x = cvt_pk_bf16(v0[0], v0[1]); w.y = cvt_pk_bf16(v0[2], v0[3]); w.z = cvt_pk_bf16(v1[0], v1[1]); w.w = cvt_pk_bf16(v1[2], v1[3]);
;                         *(u32x4*)(rowp + bj * HALF) = w; } }
	s_waitcnt lgkmcnt(0)
	v_mfma_f32_16x16x32_bf16 v[60:63], v[148:151], v[170:173], v[60:63]
	v_mfma_f32_16x16x32_bf16 v[56:59], v[156:159], v[170:173], v[56:59]
	v_mfma_f32_16x16x32_bf16 v[52:55], v[148:151], v[178:181], v[52:55]
	v_mfma_f32_16x16x32_bf16 v[44:47], v[156:159], v[178:181], v[44:47]
	v_mfma_f32_16x16x32_bf16 v[36:39], v[148:151], v[186:189], v[36:39]
	v_mfma_f32_16x16x32_bf16 v[28:31], v[156:159], v[186:189], v[28:31]
	v_mfma_f32_16x16x32_bf16 v[20:23], v[148:151], v[196:199], v[20:23]
	v_mfma_f32_16x16x32_bf16 v[12:15], v[156:159], v[196:199], v[12:15]
	v_mfma_f32_16x16x32_bf16 v[60:63], v[152:155], v[174:177], v[60:63]
	v_mfma_f32_16x16x32_bf16 v[56:59], v[166:169], v[174:177], v[56:59]
	v_mfma_f32_16x16x32_bf16 v[52:55], v[152:155], v[182:185], v[52:55]
	v_mfma_f32_16x16x32_bf16 v[44:47], v[166:169], v[182:185], v[44:47]
	v_mfma_f32_16x16x32_bf16 v[36:39], v[152:155], v[190:193], v[36:39]
	v_mfma_f32_16x16x32_bf16 v[28:31], v[166:169], v[190:193], v[28:31]
	v_mfma_f32_16x16x32_bf16 v[20:23], v[152:155], v[202:205], v[20:23]
	v_mfma_f32_16x16x32_bf16 v[12:15], v[166:169], v[202:205], v[12:15]
	s_barrier
	s_setprio 0
	s_add_u32 s30, s30, 0x80080
	s_addc_u32 s31, s31, 0
	s_add_i32 s34, s34, s38
	s_mov_b32 m0, s34
	s_nop 0
	global_load_lds_dwordx4 v130, s[30:31]
	s_add_i32 m0, s34, 0x2000
	s_nop 0
	global_load_lds_dwordx4 v134, s[30:31]
	s_waitcnt vmcnt(6)
	s_setprio 1
	s_barrier
	v_mfma_f32_16x16x32_bf16 v[48:51], v[206:209], v[170:173], v[48:51]
	v_mfma_f32_16x16x32_bf16 v[40:43], v[214:217], v[170:173], v[40:43]
	v_mfma_f32_16x16x32_bf16 v[32:35], v[206:209], v[178:181], v[32:35]
	v_mfma_f32_16x16x32_bf16 v[24:27], v[214:217], v[178:181], v[24:27]
	v_mfma_f32_16x16x32_bf16 v[16:19], v[206:209], v[186:189], v[16:19]
	v_mfma_f32_16x16x32_bf16 v[8:11], v[214:217], v[186:189], v[8:11]
	v_mfma_f32_16x16x32_bf16 v[4:7], v[206:209], v[196:199], v[4:7]
	v_mfma_f32_16x16x32_bf16 v[0:3], v[214:217], v[196:199], v[0:3]
	v_mfma_f32_16x16x32_bf16 v[48:51], v[210:213], v[174:177], v[48:51]
	v_mfma_f32_16x16x32_bf16 v[40:43], v[218:221], v[174:177], v[40:43]
	v_mfma_f32_16x16x32_bf16 v[32:35], v[210:213], v[182:185], v[32:35]
	v_mfma_f32_16x16x32_bf16 v[24:27], v[218:221], v[182:185], v[24:27]
	v_mfma_f32_16x16x32_bf16 v[16:19], v[210:213], v[190:193], v[16:19]
	v_mfma_f32_16x16x32_bf16 v[8:11], v[218:221], v[190:193], v[8:11]
	v_mfma_f32_16x16x32_bf16 v[4:7], v[210:213], v[202:205], v[4:7]
	v_mfma_f32_16x16x32_bf16 v[0:3], v[218:221], v[202:205], v[0:3]
	s_setprio 0
	s_add_i32 s58, s58, 2
	s_add_u32 s28, s28, 0x100
	s_addc_u32 s29, s29, 0
	s_add_u32 s56, s56, 0x100
	s_addc_u32 s57, s57, 0
	s_cmp_gt_u32 s58, 29
	s_cbranch_scc0 .Lrot_1
	s_barrier
	s_lshl_b32 s19, s26, 8
	v_add_u32_e32 v154, s19, v139
	s_cmp_lt_i32 s27, 8
	v_or_b32_e32 v152, 16, v154
	v_or_b32_e32 v150, 32, v154
	v_or_b32_e32 v148, 48, v154
	s_cselect_b64 s[28:29], -1, 0
	s_cmp_gt_i32 s27, 7
	v_ashrrev_i32_e32 v155, 31, v154
	v_lshlrev_b32_e32 v136, 1, v138
	v_ashrrev_i32_e32 v153, 31, v152
	v_ashrrev_i32_e32 v151, 31, v150
	v_ashrrev_i32_e32 v149, 31, v148
	s_cbranch_scc1 .LBB0_203
	s_cmp_lt_i32 s27, 4
	s_cselect_b64 vcc, -1, 0
	s_and_b64 s[30:31], vcc, exec
	s_cselect_b32 s4, s89, s81
	s_cselect_b32 s21, s88, s91
	s_lshl_b32 s30, s27, 9
	s_and_b32 s30, s30, 0x600
	s_add_u32 s30, s21, s30
	v_cndmask_b32_e32 v156, 1.0, v164, vcc
	s_addc_u32 s31, s4, 0
	v_lshl_add_u64 v[170:171], s[30:31], 0, v[136:137]
	v_lshlrev_b64 v[158:159], 11, v[154:155]
	v_pk_mul_f32 v[168:169], v[156:157], v[126:127] op_sel_hi:[0,1]
	v_pk_mul_f32 v[166:167], v[156:157], v[124:125] op_sel_hi:[0,1]
	v_pk_mul_f32 v[172:173], v[156:157], v[122:123] op_sel_hi:[0,1]
	v_pk_mul_f32 v[174:175], v[156:157], v[120:121] op_sel_hi:[0,1]
	v_lshl_add_u64 v[158:159], v[170:171], 0, v[158:159]
	v_cvt_pk_bf16_f32 v166, v166, v167
	v_cvt_pk_bf16_f32 v167, v168, v169
	v_cvt_pk_bf16_f32 v168, v174, v175
	v_cvt_pk_bf16_f32 v169, v172, v173
	global_store_dwordx4 v[158:159], v[166:169], off
	v_pk_mul_f32 v[172:173], v[156:157], v[106:107] op_sel_hi:[0,1]
	v_pk_mul_f32 v[174:175], v[156:157], v[104:105] op_sel_hi:[0,1]
	v_pk_mul_f32 v[168:169], v[156:157], v[118:119] op_sel_hi:[0,1]
	v_pk_mul_f32 v[166:167], v[156:157], v[116:117] op_sel_hi:[0,1]
	v_cvt_pk_bf16_f32 v166, v166, v167
	v_cvt_pk_bf16_f32 v167, v168, v169
	v_cvt_pk_bf16_f32 v168, v174, v175
	v_cvt_pk_bf16_f32 v169, v172, v173
	global_store_dwordx4 v[158:159], v[166:169], off offset:256
	v_pk_mul_f32 v[174:175], v[156:157], v[110:111] op_sel_hi:[0,1]
	v_pk_mul_f32 v[176:177], v[156:157], v[108:109] op_sel_hi:[0,1]
	v_lshlrev_b64 v[166:167], 11, v[152:153]
	v_lshl_add_u64 v[172:173], v[170:171], 0, v[166:167]
	v_pk_mul_f32 v[168:169], v[156:157], v[114:115] op_sel_hi:[0,1]
	v_pk_mul_f32 v[166:167], v[156:157], v[112:113] op_sel_hi:[0,1]
	v_cvt_pk_bf16_f32 v166, v166, v167
	v_cvt_pk_bf16_f32 v167, v168, v169
	v_cvt_pk_bf16_f32 v168, v176, v177
	v_cvt_pk_bf16_f32 v169, v174, v175
	global_store_dwordx4 v[172:173], v[166:169], off
	v_pk_mul_f32 v[174:175], v[156:157], v[90:91] op_sel_hi:[0,1]
	v_pk_mul_f32 v[176:177], v[156:157], v[88:89] op_sel_hi:[0,1]
	v_pk_mul_f32 v[168:169], v[156:157], v[98:99] op_sel_hi:[0,1]
	v_pk_mul_f32 v[166:167], v[156:157], v[96:97] op_sel_hi:[0,1]
	v_cvt_pk_bf16_f32 v166, v166, v167
	v_cvt_pk_bf16_f32 v167, v168, v169
	v_cvt_pk_bf16_f32 v168, v176, v177
	v_cvt_pk_bf16_f32 v169, v174, v175
	global_store_dwordx4 v[172:173], v[166:169], off offset:256
	v_pk_mul_f32 v[174:175], v[156:157], v[94:95] op_sel_hi:[0,1]
	v_pk_mul_f32 v[176:177], v[156:157], v[92:93] op_sel_hi:[0,1]
	v_lshlrev_b64 v[166:167], 11, v[150:151]
; __device__ __forceinline__ unsigned cvt_pk_bf16(float lo, float hi) { const bf16x2_t r = __builtin_convertvector((f32x2){lo, hi}, bf16x2_t); return __builtin_bit_cast(unsigned, r); }
;     __device__ __forceinline__ void operator()(const AccT& acc, const Unit& u, int wr, int wc, int fr, int fq) const {
;     ...
;         if (pn < 8) {
;             bf16_t* base = pn < 4 ? Q : Kn; const int colt = (pn & 3) * BM; const float sc = pn < 4 ? 0.08838834764831845f : 1.0f;
; #pragma unroll
;             for (int ai = 0; ai < 2; ++ai)
; #pragma unroll
;                 for (int m = 0; m < 4; ++m) { bf16_t* rowp = base + (size_t)(row0 + ai * HALF + m * 16) * 1024 + colt + cl;
; #pragma unroll
;                     for (int bj = 0; bj < 2; ++bj) { const f32x4 v0 = acc[ai][bj][m][0] * sc, v1 = acc[ai][bj][m][1] * sc;
;                         u32x4 w; w.x = cvt_pk_bf16(v0[0], v0[1]); w.y = cvt_pk_bf16(v0[2], v0[3]); w.z = cvt_pk_bf16(v1[0], v1[1]); w.w = cvt_pk_bf16(v1[2], v1[3]);
;                         *(u32x4*)(rowp + bj * HALF) = w; } }
;         }
;         if (pn >= 16) {
	v_lshl_add_u64 v[172:173], v[170:171], 0, v[166:167]
	v_pk_mul_f32 v[168:169], v[156:157], v[102:103] op_sel_hi:[0,1]
	v_pk_mul_f32 v[166:167], v[156:157], v[100:101] op_sel_hi:[0,1]
	v_cvt_pk_bf16_f32 v166, v166, v167
	v_cvt_pk_bf16_f32 v167, v168, v169
	v_cvt_pk_bf16_f32 v168, v176, v177
	v_cvt_pk_bf16_f32 v169, v174, v175
	global_store_dwordx4 v[172:173], v[166:169], off
	v_pk_mul_f32 v[174:175], v[156:157], v[74:75] op_sel_hi:[0,1]
	v_pk_mul_f32 v[176:177], v[156:157], v[72:73] op_sel_hi:[0,1]
	v_pk_mul_f32 v[168:169], v[156:157], v[82:83] op_sel_hi:[0,1]
	v_pk_mul_f32 v[166:167], v[156:157], v[80:81] op_sel_hi:[0,1]
	v_cvt_pk_bf16_f32 v166, v166, v167
	v_cvt_pk_bf16_f32 v167, v168, v169
	v_cvt_pk_bf16_f32 v168, v176, v177
	v_cvt_pk_bf16_f32 v169, v174, v175
	global_store_dwordx4 v[172:173], v[166:169], off offset:256
	v_pk_mul_f32 v[172:173], v[156:157], v[78:79] op_sel_hi:[0,1]
	v_pk_mul_f32 v[174:175], v[156:157], v[76:77] op_sel_hi:[0,1]
	v_lshlrev_b64 v[166:167], 11, v[148:149]
	v_lshl_add_u64 v[170:171], v[170:171], 0, v[166:167]
	v_pk_mul_f32 v[168:169], v[156:157], v[86:87] op_sel_hi:[0,1]
	v_pk_mul_f32 v[166:167], v[156:157], v[84:85] op_sel_hi:[0,1]
	v_cvt_pk_bf16_f32 v166, v166, v167
	v_cvt_pk_bf16_f32 v167, v168, v169
	v_cvt_pk_bf16_f32 v168, v174, v175
	v_cvt_pk_bf16_f32 v169, v172, v173
	global_store_dwordx4 v[170:171], v[166:169], off
	v_pk_mul_f32 v[172:173], v[156:157], v[66:67] op_sel_hi:[0,1]
	v_pk_mul_f32 v[174:175], v[156:157], v[64:65] op_sel_hi:[0,1]
	v_pk_mul_f32 v[168:169], v[156:157], v[70:71] op_sel_hi:[0,1]
	v_pk_mul_f32 v[166:167], v[156:157], v[68:69] op_sel_hi:[0,1]
	v_cvt_pk_bf16_f32 v166, v166, v167
	v_cvt_pk_bf16_f32 v167, v168, v169
	v_cvt_pk_bf16_f32 v168, v174, v175
	v_cvt_pk_bf16_f32 v169, v172, v173
	global_store_dwordx4 v[170:171], v[166:169], off offset:256
	v_pk_mul_f32 v[172:173], v[156:157], v[58:59] op_sel_hi:[0,1]
	s_mov_b32 s4, 0x40000
	v_pk_mul_f32 v[168:169], v[156:157], v[62:63] op_sel_hi:[0,1]
	v_pk_mul_f32 v[166:167], v[156:157], v[60:61] op_sel_hi:[0,1]
	v_pk_mul_f32 v[174:175], v[156:157], v[56:57] op_sel_hi:[0,1]
	v_cvt_pk_bf16_f32 v166, v166, v167
	v_cvt_pk_bf16_f32 v167, v168, v169
	v_cvt_pk_bf16_f32 v169, v172, v173
	v_add_co_u32_e32 v172, vcc, s4, v158
	v_cvt_pk_bf16_f32 v168, v174, v175
	s_nop 0
	v_addc_co_u32_e32 v173, vcc, 0, v159, vcc
	s_mov_b64 s[30:31], 0x40000
	global_store_dwordx4 v[172:173], v[166:169], off
	v_pk_mul_f32 v[172:173], v[156:157], v[42:43] op_sel_hi:[0,1]
	v_pk_mul_f32 v[174:175], v[156:157], v[40:41] op_sel_hi:[0,1]
	v_pk_mul_f32 v[168:169], v[156:157], v[50:51] op_sel_hi:[0,1]
	v_pk_mul_f32 v[166:167], v[156:157], v[48:49] op_sel_hi:[0,1]
	v_lshl_add_u64 v[170:171], v[158:159], 0, s[30:31]
	v_cvt_pk_bf16_f32 v166, v166, v167
	v_cvt_pk_bf16_f32 v167, v168, v169
	v_cvt_pk_bf16_f32 v168, v174, v175
	v_cvt_pk_bf16_f32 v169, v172, v173
	global_store_dwordx4 v[170:171], v[166:169], off offset:256
	v_pk_mul_f32 v[172:173], v[156:157], v[46:47] op_sel_hi:[0,1]
	s_mov_b32 s4, 0x48000
	v_pk_mul_f32 v[168:169], v[156:157], v[54:55] op_sel_hi:[0,1]
	v_pk_mul_f32 v[166:167], v[156:157], v[52:53] op_sel_hi:[0,1]
	v_pk_mul_f32 v[174:175], v[156:157], v[44:45] op_sel_hi:[0,1]
	v_cvt_pk_bf16_f32 v166, v166, v167
	v_cvt_pk_bf16_f32 v167, v168, v169
	v_cvt_pk_bf16_f32 v169, v172, v173
	v_add_co_u32_e32 v172, vcc, s4, v158
	v_cvt_pk_bf16_f32 v168, v174, v175
	s_nop 0
	v_addc_co_u32_e32 v173, vcc, 0, v159, vcc
	s_mov_b64 s[30:31], 0x48000
	global_store_dwordx4 v[172:173], v[166:169], off
	v_pk_mul_f32 v[172:173], v[156:157], v[26:27] op_sel_hi:[0,1]
	v_pk_mul_f32 v[174:175], v[156:157], v[24:25] op_sel_hi:[0,1]
	v_pk_mul_f32 v[168:169], v[156:157], v[34:35] op_sel_hi:[0,1]
	v_pk_mul_f32 v[166:167], v[156:157], v[32:33] op_sel_hi:[0,1]
	v_lshl_add_u64 v[170:171], v[158:159], 0, s[30:31]
	v_cvt_pk_bf16_f32 v166, v166, v167
	v_cvt_pk_bf16_f32 v167, v168, v169
	v_cvt_pk_bf16_f32 v168, v174, v175
	v_cvt_pk_bf16_f32 v169, v172, v173
	global_store_dwordx4 v[170:171], v[166:169], off offset:256
	v_pk_mul_f32 v[172:173], v[156:157], v[30:31] op_sel_hi:[0,1]
	v_pk_mul_f32 v[174:175], v[156:157], v[28:29] op_sel_hi:[0,1]
	v_pk_mul_f32 v[168:169], v[156:157], v[38:39] op_sel_hi:[0,1]
	v_pk_mul_f32 v[166:167], v[156:157], v[36:37] op_sel_hi:[0,1]
	v_cvt_pk_bf16_f32 v166, v166, v167
	v_cvt_pk_bf16_f32 v167, v168, v169
	v_cvt_pk_bf16_f32 v169, v172, v173
	v_add_co_u32_e32 v172, vcc, s48, v158
	v_cvt_pk_bf16_f32 v168, v174, v175
	s_nop 0
	v_addc_co_u32_e32 v173, vcc, 0, v159, vcc
	global_store_dwordx4 v[172:173], v[166:169], off
	v_pk_mul_f32 v[172:173], v[156:157], v[10:11] op_sel_hi:[0,1]
	v_pk_mul_f32 v[174:175], v[156:157], v[8:9] op_sel_hi:[0,1]
	v_pk_mul_f32 v[168:169], v[156:157], v[18:19] op_sel_hi:[0,1]
	v_pk_mul_f32 v[166:167], v[156:157], v[16:17] op_sel_hi:[0,1]
	v_lshl_add_u64 v[170:171], v[158:159], 0, s[8:9]
	v_cvt_pk_bf16_f32 v166, v166, v167
	v_cvt_pk_bf16_f32 v167, v168, v169
	v_cvt_pk_bf16_f32 v168, v174, v175
	v_cvt_pk_bf16_f32 v169, v172, v173
	global_store_dwordx4 v[170:171], v[166:169], off offset:256
	v_lshl_add_u64 v[170:171], v[158:159], 0, s[10:11]
	v_pk_mul_f32 v[172:173], v[156:157], v[14:15] op_sel_hi:[0,1]
	v_pk_mul_f32 v[168:169], v[156:157], v[22:23] op_sel_hi:[0,1]
	v_pk_mul_f32 v[166:167], v[156:157], v[20:21] op_sel_hi:[0,1]
	v_pk_mul_f32 v[174:175], v[156:157], v[12:13] op_sel_hi:[0,1]
	v_add_co_u32_e32 v158, vcc, s49, v158
	v_cvt_pk_bf16_f32 v166, v166, v167
	v_cvt_pk_bf16_f32 v167, v168, v169
	v_cvt_pk_bf16_f32 v168, v174, v175
	v_cvt_pk_bf16_f32 v169, v172, v173
	v_addc_co_u32_e32 v159, vcc, 0, v159, vcc
	global_store_dwordx4 v[158:159], v[166:169], off
	v_pk_mul_f32 v[158:159], v[156:157], v[6:7] op_sel_hi:[0,1]
	v_pk_mul_f32 v[172:173], v[156:157], v[0:1] op_sel_hi:[0,1]
	v_pk_mul_f32 v[166:167], v[156:157], v[4:5] op_sel_hi:[0,1]
	v_pk_mul_f32 v[168:169], v[156:157], v[2:3] op_sel_hi:[0,1]
	v_cvt_pk_bf16_f32 v156, v166, v167
	v_cvt_pk_bf16_f32 v157, v158, v159
	v_cvt_pk_bf16_f32 v158, v172, v173
	v_cvt_pk_bf16_f32 v159, v168, v169
	global_store_dwordx4 v[170:171], v[156:159], off offset:256
	s_cmp_lt_i32 s27, 16
	s_cbranch_scc0 .LBB0_204

; #define PG8_STAGE(bufoff, gbase, voff) do { _Pragma("unroll") for (int _i = 0; _i < 2; ++_i) \
;         __builtin_amdgcn_global_load_lds((const unsigned*)((const char*)(gbase) + (voff)[_i]), (LAS unsigned*)(lds + (bufoff) + ldsw + _i * 8192), 16, 0, 0); } while (0)
; #define PG8_LDA(dst, b, h) do { _Pragma("unroll") for (int m = 0; m < 4; ++m) _Pragma("unroll") for (int k = 0; k < 2; ++k) dst[m][k] = *(const LAS bf16x8*)(lds + PG8_SA(b, h) + aoff + m * 2048 + k * 1024); } while (0)
; #define PG8_LDB(dst, b, h) do { _Pragma("unroll") for (int n = 0; n < 2; ++n) _Pragma("unroll") for (int k = 0; k < 2; ++k) dst[n][k] = *(const LAS bf16x8*)(lds + PG8_SB(b, h) + boff + n * 2048 + k * 1024); } while (0)
; #define PG8_WAIT_V(n) asm volatile("s_waitcnt vmcnt(" #n ")" ::: "memory")
; #define PG8_WAIT_L(n) asm volatile("s_waitcnt lgkmcnt(" #n ")" ::: "memory")
; #define PG8_BAR __builtin_amdgcn_s_barrier()
; #define PG8_SCHED __builtin_amdgcn_sched_barrier(0)
; template <class Epi>
; __device__ __forceinline__ void gemm_phase(LAS unsigned char* lds, const bf16_t* A, int lda, const bf16_t* Bt, int ldb, int M, int N, int K, int asel, const Epi& E, const int fixed_round = -1) {
;     ...
;             PG8_LDB(B0, 0, 0); PG8_SCHED; PG8_LDA(At, 0, 0); PG8_STAGE(PG8_SA(1, 1), a1 + hstepA, voffA);
;             PG8_WAIT_L(8); PG8_BAR; PG8_WAIT_L(0); PG8_MMA(0, 0, At, B0); PG8_BAR; PG8_SCHED;
;             PG8_LDB(B1, 0, 1); PG8_STAGE(PG8_SB(0, 0), b2, voffB);
;             PG8_BAR; PG8_WAIT_L(0); PG8_MMA(0, 1, At, B1); PG8_BAR;
;             PG8_LDA(At, 0, 1); PG8_STAGE(PG8_SA(0, 0), a2, voffA);
;             PG8_BAR; PG8_WAIT_L(0); PG8_MMA(1, 0, At, B0); PG8_BAR; PG8_SCHED;
;             PG8_STAGE(PG8_SB(0, 1), b2 + hstepB, voffB);
;             PG8_WAIT_V(6); PG8_BAR; PG8_MMA(1, 1, At, B1); PG8_BAR;
.LBB0_224:
	ds_read_b128 v[146:149], v143
	ds_read_b128 v[150:153], v143 offset:1024
	ds_read_b128 v[154:157], v143 offset:2048
	ds_read_b128 v[158:161], v143 offset:3072
	s_add_i32 m0, s7, 0xc000
	ds_read_b128 v[162:165], v144
	ds_read_b128 v[166:169], v144 offset:1024
	ds_read_b128 v[170:173], v144 offset:2048
	ds_read_b128 v[174:177], v144 offset:3072
	ds_read_b128 v[178:181], v144 offset:4096
	ds_read_b128 v[182:185], v144 offset:5120
	ds_read_b128 v[186:189], v144 offset:6144
	ds_read_b128 v[190:193], v144 offset:7168
	global_load_lds_dwordx4 v132, s[16:17]
	s_add_i32 m0, s7, 0xe000
	s_nop 0
	global_load_lds_dwordx4 v134, s[16:17]
	s_waitcnt lgkmcnt(8)
	s_setprio 1
	s_barrier
	s_waitcnt lgkmcnt(0)
	v_mfma_f32_16x16x32_bf16 v[124:127], v[162:165], v[146:149], v[124:127]
	v_mfma_f32_16x16x32_bf16 v[108:111], v[162:165], v[154:157], v[108:111]
	v_mfma_f32_16x16x32_bf16 v[120:123], v[170:173], v[146:149], v[120:123]
	v_mfma_f32_16x16x32_bf16 v[104:107], v[170:173], v[154:157], v[104:107]
	v_mfma_f32_16x16x32_bf16 v[116:119], v[178:181], v[146:149], v[116:119]
	v_mfma_f32_16x16x32_bf16 v[100:103], v[178:181], v[154:157], v[100:103]
	v_mfma_f32_16x16x32_bf16 v[112:115], v[186:189], v[146:149], v[112:115]
	v_mfma_f32_16x16x32_bf16 v[92:95], v[186:189], v[154:157], v[92:95]
	v_mfma_f32_16x16x32_bf16 v[124:127], v[166:169], v[150:153], v[124:127]
	v_mfma_f32_16x16x32_bf16 v[108:111], v[166:169], v[158:161], v[108:111]
	v_mfma_f32_16x16x32_bf16 v[120:123], v[174:177], v[150:153], v[120:123]
	v_mfma_f32_16x16x32_bf16 v[104:107], v[174:177], v[158:161], v[104:107]
	v_mfma_f32_16x16x32_bf16 v[116:119], v[182:185], v[150:153], v[116:119]
	v_mfma_f32_16x16x32_bf16 v[100:103], v[182:185], v[158:161], v[100:103]
	v_mfma_f32_16x16x32_bf16 v[112:115], v[190:193], v[150:153], v[112:115]
	v_mfma_f32_16x16x32_bf16 v[92:95], v[190:193], v[158:161], v[92:95]
	s_barrier
	s_setprio 0
	s_add_u32 s18, s16, 0xfff80080
	s_addc_u32 s19, s17, -1
	s_cmp_eq_u32 s41, 28
	s_cselect_b32 s21, s11, s19
	s_cselect_b32 s20, s37, s18
	s_cselect_b32 s19, s9, s40
	s_cselect_b32 s18, s38, s39
	s_add_i32 s42, s34, s25
	s_add_u32 s98, s18, s2
	s_addc_u32 s99, s19, s3
	s_mov_b32 m0, s42
	ds_read_b128 v[196:199], v145
	ds_read_b128 v[202:205], v145 offset:1024
	ds_read_b128 v[206:209], v145 offset:2048
	ds_read_b128 v[210:213], v145 offset:3072
	global_load_lds_dwordx4 v128, s[18:19]
	s_add_i32 m0, s42, 0x2000
	s_nop 0
	global_load_lds_dwordx4 v130, s[18:19]
	s_setprio 1
	s_barrier
	s_waitcnt lgkmcnt(0)
	v_mfma_f32_16x16x32_bf16 v[80:83], v[162:165], v[196:199], v[80:83]
	v_mfma_f32_16x16x32_bf16 v[48:51], v[162:165], v[206:209], v[48:51]
	v_mfma_f32_16x16x32_bf16 v[68:71], v[170:173], v[196:199], v[68:71]
	v_mfma_f32_16x16x32_bf16 v[40:43], v[170:173], v[206:209], v[40:43]
	v_mfma_f32_16x16x32_bf16 v[60:63], v[178:181], v[196:199], v[60:63]
	v_mfma_f32_16x16x32_bf16 v[36:39], v[178:181], v[206:209], v[36:39]
	v_mfma_f32_16x16x32_bf16 v[52:55], v[186:189], v[196:199], v[52:55]
	v_mfma_f32_16x16x32_bf16 v[28:31], v[186:189], v[206:209], v[28:31]
	v_mfma_f32_16x16x32_bf16 v[80:83], v[166:169], v[202:205], v[80:83]
	v_mfma_f32_16x16x32_bf16 v[48:51], v[166:169], v[210:213], v[48:51]
	v_mfma_f32_16x16x32_bf16 v[68:71], v[174:177], v[202:205], v[68:71]
	v_mfma_f32_16x16x32_bf16 v[40:43], v[174:177], v[210:213], v[40:43]
	v_mfma_f32_16x16x32_bf16 v[60:63], v[182:185], v[202:205], v[60:63]
	v_mfma_f32_16x16x32_bf16 v[36:39], v[182:185], v[210:213], v[36:39]
	v_mfma_f32_16x16x32_bf16 v[52:55], v[190:193], v[202:205], v[52:55]
	v_mfma_f32_16x16x32_bf16 v[28:31], v[190:193], v[210:213], v[28:31]
	s_barrier
	s_setprio 0
	s_mov_b32 m0, s7
	s_add_u32 s100, s20, s2
	s_addc_u32 s101, s21, s3
	ds_read_b128 v[162:165], v144 offset:16384
	ds_read_b128 v[166:169], v144 offset:17408
	ds_read_b128 v[170:173], v144 offset:18432
	ds_read_b128 v[174:177], v144 offset:19456
	ds_read_b128 v[178:181], v144 offset:20480
	ds_read_b128 v[182:185], v144 offset:21504
	ds_read_b128 v[186:189], v144 offset:22528
	ds_read_b128 v[190:193], v144 offset:23552
	global_load_lds_dwordx4 v128, s[20:21]
	s_mov_b32 m0, s26
	s_nop 0
	global_load_lds_dwordx4 v130, s[20:21]
	s_setprio 1
	s_barrier
	s_waitcnt lgkmcnt(0)
	v_mfma_f32_16x16x32_bf16 v[96:99], v[162:165], v[146:149], v[96:99]
	v_mfma_f32_16x16x32_bf16 v[72:75], v[162:165], v[154:157], v[72:75]
	v_mfma_f32_16x16x32_bf16 v[88:91], v[170:173], v[146:149], v[88:91]
	v_mfma_f32_16x16x32_bf16 v[64:67], v[170:173], v[154:157], v[64:67]
	v_mfma_f32_16x16x32_bf16 v[84:87], v[178:181], v[146:149], v[84:87]
	v_mfma_f32_16x16x32_bf16 v[56:59], v[178:181], v[154:157], v[56:59]
	v_mfma_f32_16x16x32_bf16 v[76:79], v[186:189], v[146:149], v[76:79]
	v_mfma_f32_16x16x32_bf16 v[44:47], v[186:189], v[154:157], v[44:47]
	v_mfma_f32_16x16x32_bf16 v[96:99], v[166:169], v[150:153], v[96:99]
	v_mfma_f32_16x16x32_bf16 v[72:75], v[166:169], v[158:161], v[72:75]
	v_mfma_f32_16x16x32_bf16 v[88:91], v[174:177], v[150:153], v[88:91]
	v_mfma_f32_16x16x32_bf16 v[64:67], v[174:177], v[158:161], v[64:67]
	v_mfma_f32_16x16x32_bf16 v[84:87], v[182:185], v[150:153], v[84:87]
	v_mfma_f32_16x16x32_bf16 v[56:59], v[182:185], v[158:161], v[56:59]
	v_mfma_f32_16x16x32_bf16 v[76:79], v[190:193], v[150:153], v[76:79]
	v_mfma_f32_16x16x32_bf16 v[44:47], v[190:193], v[158:161], v[44:47]
	s_barrier
	s_setprio 0
	s_add_u32 s42, s18, 0x80000
	s_addc_u32 s43, s19, 0
	s_add_i32 s44, s35, s25
	s_mov_b32 m0, s44
	s_nop 0
	global_load_lds_dwordx4 v128, s[42:43]
	s_add_i32 m0, s44, 0x2000
	s_nop 0
	global_load_lds_dwordx4 v130, s[42:43]
	s_waitcnt vmcnt(6)
	s_setprio 1
	s_barrier
; #define PG8_STAGE(bufoff, gbase, voff) do { _Pragma("unroll") for (int _i = 0; _i < 2; ++_i) \
;         __builtin_amdgcn_global_load_lds((const unsigned*)((const char*)(gbase) + (voff)[_i]), (LAS unsigned*)(lds + (bufoff) + ldsw + _i * 8192), 16, 0, 0); } while (0)
; #define PG8_LDA(dst, b, h) do { _Pragma("unroll") for (int m = 0; m < 4; ++m) _Pragma("unroll") for (int k = 0; k < 2; ++k) dst[m][k] = *(const LAS bf16x8*)(lds + PG8_SA(b, h) + aoff + m * 2048 + k * 1024); } while (0)
; #define PG8_LDB(dst, b, h) do { _Pragma("unroll") for (int n = 0; n < 2; ++n) _Pragma("unroll") for (int k = 0; k < 2; ++k) dst[n][k] = *(const LAS bf16x8*)(lds + PG8_SB(b, h) + boff + n * 2048 + k * 1024); } while (0)
; #define PG8_WAIT_V(n) asm volatile("s_waitcnt vmcnt(" #n ")" ::: "memory")
; #define PG8_WAIT_L(n) asm volatile("s_waitcnt lgkmcnt(" #n ")" ::: "memory")
; #define PG8_BAR __builtin_amdgcn_s_barrier()
; #define PG8_SCHED __builtin_amdgcn_sched_barrier(0)
; template <class Epi>
; __device__ __forceinline__ void gemm_phase(LAS unsigned char* lds, const bf16_t* A, int lda, const bf16_t* Bt, int ldb, int M, int N, int K, int asel, const Epi& E, const int fixed_round = -1) {
;     ...
;             PG8_WAIT_V(6); PG8_BAR; PG8_MMA(1, 1, At, B1); PG8_BAR;
;             PG8_LDB(B0, 1, 0); PG8_SCHED; PG8_LDA(At, 1, 0); PG8_STAGE(PG8_SA(0, 1), a2 + hstepA, voffA);
;             PG8_WAIT_L(8); PG8_BAR; PG8_WAIT_L(0); PG8_MMA(0, 0, At, B0); PG8_BAR; PG8_SCHED;
;             PG8_LDB(B1, 1, 1); PG8_STAGE(PG8_SB(1, 0), b3, voffB);
;             PG8_BAR; PG8_WAIT_L(0); PG8_MMA(0, 1, At, B1); PG8_BAR;
	v_mfma_f32_16x16x32_bf16 v[32:35], v[162:165], v[196:199], v[32:35]
	v_mfma_f32_16x16x32_bf16 v[12:15], v[162:165], v[206:209], v[12:15]
	v_mfma_f32_16x16x32_bf16 v[24:27], v[170:173], v[196:199], v[24:27]
	v_mfma_f32_16x16x32_bf16 v[8:11], v[170:173], v[206:209], v[8:11]
	v_mfma_f32_16x16x32_bf16 v[20:23], v[178:181], v[196:199], v[20:23]
	v_mfma_f32_16x16x32_bf16 v[4:7], v[178:181], v[206:209], v[4:7]
	v_mfma_f32_16x16x32_bf16 v[16:19], v[186:189], v[196:199], v[16:19]
	v_mfma_f32_16x16x32_bf16 v[0:3], v[186:189], v[206:209], v[0:3]
	v_mfma_f32_16x16x32_bf16 v[32:35], v[166:169], v[202:205], v[32:35]
	v_mfma_f32_16x16x32_bf16 v[12:15], v[166:169], v[210:213], v[12:15]
	v_mfma_f32_16x16x32_bf16 v[24:27], v[174:177], v[202:205], v[24:27]
	v_mfma_f32_16x16x32_bf16 v[8:11], v[174:177], v[210:213], v[8:11]
	v_mfma_f32_16x16x32_bf16 v[20:23], v[182:185], v[202:205], v[20:23]
	v_mfma_f32_16x16x32_bf16 v[4:7], v[182:185], v[210:213], v[4:7]
	v_mfma_f32_16x16x32_bf16 v[16:19], v[190:193], v[202:205], v[16:19]
	v_mfma_f32_16x16x32_bf16 v[0:3], v[190:193], v[210:213], v[0:3]
	s_barrier
	s_setprio 0
	s_add_i32 s42, 0, 0x18000
	v_add_u32_e32 v158, s42, v140
	ds_read_b128 v[146:149], v158
	ds_read_b128 v[150:153], v158 offset:1024
	ds_read_b128 v[154:157], v158 offset:2048
	ds_read_b128 v[158:161], v158 offset:3072
	s_add_u32 s20, s20, 0x80000
	s_addc_u32 s21, s21, 0
	s_mov_b32 m0, s27
	ds_read_b128 v[162:165], v144 offset:32768
	ds_read_b128 v[166:169], v144 offset:33792
	ds_read_b128 v[170:173], v144 offset:34816
	ds_read_b128 v[174:177], v144 offset:35840
	ds_read_b128 v[178:181], v144 offset:36864
	ds_read_b128 v[182:185], v144 offset:37888
	ds_read_b128 v[186:189], v144 offset:38912
	ds_read_b128 v[190:193], v144 offset:39936
	global_load_lds_dwordx4 v128, s[20:21]
	s_mov_b32 m0, s28
	s_nop 0
	global_load_lds_dwordx4 v130, s[20:21]
	s_waitcnt lgkmcnt(8)
	s_setprio 1
	s_barrier
	s_waitcnt lgkmcnt(0)
	v_mfma_f32_16x16x32_bf16 v[124:127], v[162:165], v[146:149], v[124:127]
	v_mfma_f32_16x16x32_bf16 v[108:111], v[162:165], v[154:157], v[108:111]
	v_mfma_f32_16x16x32_bf16 v[120:123], v[170:173], v[146:149], v[120:123]
	v_mfma_f32_16x16x32_bf16 v[104:107], v[170:173], v[154:157], v[104:107]
	v_mfma_f32_16x16x32_bf16 v[116:119], v[178:181], v[146:149], v[116:119]
	v_mfma_f32_16x16x32_bf16 v[100:103], v[178:181], v[154:157], v[100:103]
	v_mfma_f32_16x16x32_bf16 v[112:115], v[186:189], v[146:149], v[112:115]
	v_mfma_f32_16x16x32_bf16 v[92:95], v[186:189], v[154:157], v[92:95]
	v_mfma_f32_16x16x32_bf16 v[124:127], v[166:169], v[150:153], v[124:127]
	v_mfma_f32_16x16x32_bf16 v[108:111], v[166:169], v[158:161], v[108:111]
	v_mfma_f32_16x16x32_bf16 v[120:123], v[174:177], v[150:153], v[120:123]
	v_mfma_f32_16x16x32_bf16 v[104:107], v[174:177], v[158:161], v[104:107]
	v_mfma_f32_16x16x32_bf16 v[116:119], v[182:185], v[150:153], v[116:119]
	v_mfma_f32_16x16x32_bf16 v[100:103], v[182:185], v[158:161], v[100:103]
	v_mfma_f32_16x16x32_bf16 v[112:115], v[190:193], v[150:153], v[112:115]
	v_mfma_f32_16x16x32_bf16 v[92:95], v[190:193], v[158:161], v[92:95]
	s_barrier
	s_setprio 0
	s_add_i32 s20, 0, 0x1c000
	s_add_i32 s21, s42, s25
	v_add_u32_e32 v195, s20, v140
	s_mov_b32 m0, s21
	ds_read_b128 v[196:199], v195
	ds_read_b128 v[202:205], v195 offset:1024
	ds_read_b128 v[206:209], v195 offset:2048
	ds_read_b128 v[210:213], v195 offset:3072
	global_load_lds_dwordx4 v128, s[98:99]
	s_add_i32 m0, s21, 0x2000
	s_nop 0
	global_load_lds_dwordx4 v130, s[98:99]
	s_setprio 1
	s_barrier
	s_waitcnt lgkmcnt(0)
	v_mfma_f32_16x16x32_bf16 v[80:83], v[162:165], v[196:199], v[80:83]
	v_mfma_f32_16x16x32_bf16 v[48:51], v[162:165], v[206:209], v[48:51]
	v_mfma_f32_16x16x32_bf16 v[68:71], v[170:173], v[196:199], v[68:71]
	v_mfma_f32_16x16x32_bf16 v[40:43], v[170:173], v[206:209], v[40:43]
	v_mfma_f32_16x16x32_bf16 v[60:63], v[178:181], v[196:199], v[60:63]
	v_mfma_f32_16x16x32_bf16 v[36:39], v[178:181], v[206:209], v[36:39]
	v_mfma_f32_16x16x32_bf16 v[52:55], v[186:189], v[196:199], v[52:55]
	v_mfma_f32_16x16x32_bf16 v[28:31], v[186:189], v[206:209], v[28:31]
	v_mfma_f32_16x16x32_bf16 v[80:83], v[166:169], v[202:205], v[80:83]
	v_mfma_f32_16x16x32_bf16 v[48:51], v[166:169], v[210:213], v[48:51]
	v_mfma_f32_16x16x32_bf16 v[68:71], v[174:177], v[202:205], v[68:71]
	v_mfma_f32_16x16x32_bf16 v[40:43], v[174:177], v[210:213], v[40:43]
	v_mfma_f32_16x16x32_bf16 v[60:63], v[182:185], v[202:205], v[60:63]
	v_mfma_f32_16x16x32_bf16 v[36:39], v[182:185], v[210:213], v[36:39]
	v_mfma_f32_16x16x32_bf16 v[52:55], v[190:193], v[202:205], v[52:55]
	v_mfma_f32_16x16x32_bf16 v[28:31], v[190:193], v[210:213], v[28:31]
	s_barrier
	s_setprio 0
	s_mov_b32 m0, s30
	ds_read_b128 v[162:165], v144 offset:49152
	ds_read_b128 v[166:169], v144 offset:50176
	ds_read_b128 v[170:173], v144 offset:51200
	ds_read_b128 v[174:177], v144 offset:52224
	ds_read_b128 v[178:181], v144 offset:53248
	ds_read_b128 v[182:185], v144 offset:54272
	ds_read_b128 v[186:189], v144 offset:55296
	ds_read_b128 v[190:193], v144 offset:56320
	global_load_lds_dwordx4 v128, s[100:101]
	s_mov_b32 m0, s31
	s_nop 0
	global_load_lds_dwordx4 v130, s[100:101]
	s_setprio 1
	s_barrier
; #define PG8_STAGE(bufoff, gbase, voff) do { _Pragma("unroll") for (int _i = 0; _i < 2; ++_i) \
;         __builtin_amdgcn_global_load_lds((const unsigned*)((const char*)(gbase) + (voff)[_i]), (LAS unsigned*)(lds + (bufoff) + ldsw + _i * 8192), 16, 0, 0); } while (0)
; #define PG8_LDA(dst, b, h) do { _Pragma("unroll") for (int m = 0; m < 4; ++m) _Pragma("unroll") for (int k = 0; k < 2; ++k) dst[m][k] = *(const LAS bf16x8*)(lds + PG8_SA(b, h) + aoff + m * 2048 + k * 1024); } while (0)
; #define PG8_WAIT_V(n) asm volatile("s_waitcnt vmcnt(" #n ")" ::: "memory")
; #define PG8_WAIT_L(n) asm volatile("s_waitcnt lgkmcnt(" #n ")" ::: "memory")
; #define PG8_BAR __builtin_amdgcn_s_barrier()
; #define PG8_SCHED __builtin_amdgcn_sched_barrier(0)
; template <class Epi>
; __device__ __forceinline__ void gemm_phase(LAS unsigned char* lds, const bf16_t* A, int lda, const bf16_t* Bt, int ldb, int M, int N, int K, int asel, const Epi& E, const int fixed_round = -1) {
;     ...
;             PG8_BAR; PG8_WAIT_L(0); PG8_MMA(0, 1, At, B1); PG8_BAR;
;             PG8_LDA(At, 1, 1); PG8_STAGE(PG8_SA(1, 0), a3, voffA);
;             PG8_BAR; PG8_WAIT_L(0); PG8_MMA(1, 0, At, B0); PG8_BAR; PG8_SCHED;
;             PG8_STAGE(PG8_SB(1, 1), b3 + hstepB, voffB);
;             PG8_WAIT_V(6); PG8_BAR; PG8_MMA(1, 1, At, B1); PG8_BAR;
	s_waitcnt lgkmcnt(0)
	v_mfma_f32_16x16x32_bf16 v[96:99], v[162:165], v[146:149], v[96:99]
	v_mfma_f32_16x16x32_bf16 v[72:75], v[162:165], v[154:157], v[72:75]
	v_mfma_f32_16x16x32_bf16 v[88:91], v[170:173], v[146:149], v[88:91]
	v_mfma_f32_16x16x32_bf16 v[64:67], v[170:173], v[154:157], v[64:67]
	v_mfma_f32_16x16x32_bf16 v[84:87], v[178:181], v[146:149], v[84:87]
	v_mfma_f32_16x16x32_bf16 v[56:59], v[178:181], v[154:157], v[56:59]
	v_mfma_f32_16x16x32_bf16 v[76:79], v[186:189], v[146:149], v[76:79]
	v_mfma_f32_16x16x32_bf16 v[44:47], v[186:189], v[154:157], v[44:47]
	v_mfma_f32_16x16x32_bf16 v[96:99], v[166:169], v[150:153], v[96:99]
	v_mfma_f32_16x16x32_bf16 v[72:75], v[166:169], v[158:161], v[72:75]
	v_mfma_f32_16x16x32_bf16 v[88:91], v[174:177], v[150:153], v[88:91]
	v_mfma_f32_16x16x32_bf16 v[64:67], v[174:177], v[158:161], v[64:67]
	v_mfma_f32_16x16x32_bf16 v[84:87], v[182:185], v[150:153], v[84:87]
	v_mfma_f32_16x16x32_bf16 v[56:59], v[182:185], v[158:161], v[56:59]
	v_mfma_f32_16x16x32_bf16 v[76:79], v[190:193], v[150:153], v[76:79]
	v_mfma_f32_16x16x32_bf16 v[44:47], v[190:193], v[158:161], v[44:47]
	s_barrier
	s_setprio 0
	s_add_u32 s18, s18, 0x80080
	s_addc_u32 s19, s19, 0
	s_add_i32 s20, s20, s25
	s_mov_b32 m0, s20
	s_nop 0
	global_load_lds_dwordx4 v128, s[18:19]
	s_add_i32 m0, s20, 0x2000
	s_nop 0
	global_load_lds_dwordx4 v130, s[18:19]
	s_waitcnt vmcnt(6)
	s_setprio 1
	s_barrier
	v_mfma_f32_16x16x32_bf16 v[32:35], v[162:165], v[196:199], v[32:35]
	v_mfma_f32_16x16x32_bf16 v[12:15], v[162:165], v[206:209], v[12:15]
	v_mfma_f32_16x16x32_bf16 v[24:27], v[170:173], v[196:199], v[24:27]
	v_mfma_f32_16x16x32_bf16 v[8:11], v[170:173], v[206:209], v[8:11]
	v_mfma_f32_16x16x32_bf16 v[20:23], v[178:181], v[196:199], v[20:23]
	v_mfma_f32_16x16x32_bf16 v[4:7], v[178:181], v[206:209], v[4:7]
	v_mfma_f32_16x16x32_bf16 v[16:19], v[186:189], v[196:199], v[16:19]
	v_mfma_f32_16x16x32_bf16 v[0:3], v[186:189], v[206:209], v[0:3]
	v_mfma_f32_16x16x32_bf16 v[32:35], v[166:169], v[202:205], v[32:35]
	v_mfma_f32_16x16x32_bf16 v[12:15], v[166:169], v[210:213], v[12:15]
	v_mfma_f32_16x16x32_bf16 v[24:27], v[174:177], v[202:205], v[24:27]
	v_mfma_f32_16x16x32_bf16 v[8:11], v[174:177], v[210:213], v[8:11]
	v_mfma_f32_16x16x32_bf16 v[20:23], v[182:185], v[202:205], v[20:23]
	v_mfma_f32_16x16x32_bf16 v[4:7], v[182:185], v[210:213], v[4:7]
	v_mfma_f32_16x16x32_bf16 v[16:19], v[190:193], v[202:205], v[16:19]
	v_mfma_f32_16x16x32_bf16 v[0:3], v[190:193], v[210:213], v[0:3]
	s_setprio 0
	s_add_i32 s41, s41, 2
	s_add_u32 s16, s16, 0x100
	s_addc_u32 s17, s17, 0
	s_add_u32 s39, s39, 0x100
	s_addc_u32 s40, s40, 0
	s_cmp_gt_u32 s41, 29
	s_cbranch_scc0 .Lrot_2
	s_barrier
; __device__ __forceinline__ unsigned cvt_pk_bf16(float lo, float hi) { const bf16x2_t r = __builtin_convertvector((f32x2){lo, hi}, bf16x2_t); return __builtin_bit_cast(unsigned, r); }
; #define PG8_WAIT_V(n) asm volatile("s_waitcnt vmcnt(" #n ")" ::: "memory")
; #define PG8_BAR __builtin_amdgcn_s_barrier()
; template <class Epi>
; __device__ __forceinline__ void gemm_phase(LAS unsigned char* lds, const bf16_t* A, int lda, const bf16_t* Bt, int ldb, int M, int N, int K, int asel, const Epi& E, const int fixed_round = -1) {
;     ...
;         if (!has_next) break;
; #pragma unroll
;         for (int a = 0; a < 2; ++a)
; #pragma unroll
;             for (int b = 0; b < 2; ++b)
; #pragma unroll
;                 for (int m = 0; m < 4; ++m)
; #pragma unroll
;                     for (int n = 0; n < 2; ++n) acc[a][b][m][n] = (f32x4){0.f, 0.f, 0.f, 0.f};
;         cur = nxt; cA = nA; cB = nB; ++ui;
;     }
;     PG8_WAIT_V(0);
;     if (wr == 0) PG8_BAR;
;     PG8_BAR;
;     __device__ __forceinline__ void operator()(const AccT& acc, const Unit& u, int wr, int wc, int fr, int fq) const {
;         const int bb = u.pm >> 4, s0 = (u.pm & 15) * BM + wr * 64 + 4 * fq, feat0 = u.pn * BM + wc * 32 + fr;
; #pragma unroll
;         for (int bj = 0; bj < 2; ++bj)
; #pragma unroll
;             for (int n = 0; n < 2; ++n) { bf16_t* fp = VT + ((size_t)bb * 2048 + feat0 + bj * HALF + n * 16) * SEQ + s0;
; #pragma unroll
;                 for (int ai = 0; ai < 2; ++ai)
; #pragma unroll
;                     for (int m = 0; m < 4; ++m) { const f32x4 v = acc[ai][bj][m][n]; u32x2 w; w.x = cvt_pk_bf16(v[0], v[1]); w.y = cvt_pk_bf16(v[2], v[3]);
;                         *(u32x2*)(fp + ai * HALF + m * 16) = w; } }
;     }
	s_ashr_i32 s16, s6, 4
	v_lshl_or_b32 v148, s36, 8, v142
	s_lshl_b32 s6, s6, 8
	s_ashr_i32 s17, s16, 31
	v_ashrrev_i32_e32 v149, 31, v148
	s_and_b32 s6, s6, 0xf00
	s_lshl_b64 s[16:17], s[16:17], 24
	v_lshlrev_b64 v[148:149], 13, v[148:149]
	v_add_u32_e32 v146, s6, v141
	v_lshl_add_u64 v[148:149], v[148:149], 0, s[16:17]
	v_readlane_b32 s16, v254, 47
	v_ashrrev_i32_e32 v147, 31, v146
	v_readlane_b32 s17, v254, 48
	v_lshlrev_b64 v[146:147], 1, v[146:147]
	v_cvt_pk_bf16_f32 v76, v76, v77
	v_lshl_add_u64 v[150:151], s[16:17], 0, v[148:149]
	v_lshl_add_u64 v[150:151], v[150:151], 0, v[146:147]
	v_cvt_pk_bf16_f32 v77, v78, v79
	global_store_dwordx2 v[150:151], v[76:77], off offset:352
	v_or_b32_e32 v76, 0x20000, v148
	v_mov_b32_e32 v77, v149
	v_lshl_add_u64 v[76:77], s[16:17], 0, v[76:77]
	v_cvt_pk_bf16_f32 v124, v124, v125
	v_cvt_pk_bf16_f32 v125, v126, v127
	v_cvt_pk_bf16_f32 v120, v120, v121
	v_cvt_pk_bf16_f32 v121, v122, v123
	v_cvt_pk_bf16_f32 v116, v116, v117
	v_cvt_pk_bf16_f32 v117, v118, v119
	v_cvt_pk_bf16_f32 v112, v112, v113
	v_cvt_pk_bf16_f32 v113, v114, v115
	v_cvt_pk_bf16_f32 v96, v96, v97
	v_cvt_pk_bf16_f32 v97, v98, v99
	v_cvt_pk_bf16_f32 v88, v88, v89
	v_cvt_pk_bf16_f32 v89, v90, v91
	v_cvt_pk_bf16_f32 v84, v84, v85
	v_cvt_pk_bf16_f32 v85, v86, v87
	v_lshl_add_u64 v[76:77], v[76:77], 0, v[146:147]
	v_cvt_pk_bf16_f32 v78, v108, v109
	v_cvt_pk_bf16_f32 v79, v110, v111
	v_cvt_pk_bf16_f32 v44, v44, v45
	v_cvt_pk_bf16_f32 v45, v46, v47
	global_store_dwordx2 v[150:151], v[124:125], off
	global_store_dwordx2 v[150:151], v[120:121], off offset:32
	global_store_dwordx2 v[150:151], v[116:117], off offset:64
	global_store_dwordx2 v[150:151], v[112:113], off offset:96
	global_store_dwordx2 v[150:151], v[96:97], off offset:256
	global_store_dwordx2 v[150:151], v[88:89], off offset:288
	global_store_dwordx2 v[150:151], v[84:85], off offset:320
	global_store_dwordx2 v[76:77], v[78:79], off
	v_cvt_pk_bf16_f32 v78, v104, v105
	v_cvt_pk_bf16_f32 v79, v106, v107
	global_store_dwordx2 v[76:77], v[44:45], off offset:352
	v_or_b32_e32 v44, 0x100000, v148
	v_mov_b32_e32 v45, v149
	global_store_dwordx2 v[76:77], v[78:79], off offset:32
	v_cvt_pk_bf16_f32 v78, v100, v101
	v_cvt_pk_bf16_f32 v79, v102, v103
	v_lshl_add_u64 v[44:45], s[16:17], 0, v[44:45]
	global_store_dwordx2 v[76:77], v[78:79], off offset:64
	v_cvt_pk_bf16_f32 v78, v92, v93
	v_cvt_pk_bf16_f32 v79, v94, v95
	v_cvt_pk_bf16_f32 v72, v72, v73
	v_cvt_pk_bf16_f32 v73, v74, v75
	v_cvt_pk_bf16_f32 v64, v64, v65
	v_cvt_pk_bf16_f32 v65, v66, v67
	v_cvt_pk_bf16_f32 v56, v56, v57
	v_cvt_pk_bf16_f32 v57, v58, v59
	v_lshl_add_u64 v[44:45], v[44:45], 0, v[146:147]
	v_cvt_pk_bf16_f32 v46, v80, v81
	v_cvt_pk_bf16_f32 v47, v82, v83
	global_store_dwordx2 v[76:77], v[78:79], off offset:96
	global_store_dwordx2 v[76:77], v[72:73], off offset:256
	global_store_dwordx2 v[76:77], v[64:65], off offset:288
	global_store_dwordx2 v[76:77], v[56:57], off offset:320
	global_store_dwordx2 v[44:45], v[46:47], off
	v_cvt_pk_bf16_f32 v46, v68, v69
	v_cvt_pk_bf16_f32 v47, v70, v71
	v_cvt_pk_bf16_f32 v16, v16, v17
	v_cvt_pk_bf16_f32 v17, v18, v19
	v_or_b32_e32 v148, 0x120000, v148
	global_store_dwordx2 v[44:45], v[46:47], off offset:32
	v_cvt_pk_bf16_f32 v46, v60, v61
	v_cvt_pk_bf16_f32 v47, v62, v63
	global_store_dwordx2 v[44:45], v[16:17], off offset:352
	v_lshl_add_u64 v[16:17], s[16:17], 0, v[148:149]
	global_store_dwordx2 v[44:45], v[46:47], off offset:64
	v_cvt_pk_bf16_f32 v46, v52, v53
	v_cvt_pk_bf16_f32 v47, v54, v55
	v_cvt_pk_bf16_f32 v32, v32, v33
	v_cvt_pk_bf16_f32 v33, v34, v35
	v_cvt_pk_bf16_f32 v24, v24, v25
	v_cvt_pk_bf16_f32 v25, v26, v27
	v_cvt_pk_bf16_f32 v20, v20, v21
	v_cvt_pk_bf16_f32 v21, v22, v23
	v_lshl_add_u64 v[16:17], v[16:17], 0, v[146:147]
	v_cvt_pk_bf16_f32 v18, v48, v49
	v_cvt_pk_bf16_f32 v19, v50, v51
	global_store_dwordx2 v[44:45], v[46:47], off offset:96
	global_store_dwordx2 v[44:45], v[32:33], off offset:256
	global_store_dwordx2 v[44:45], v[24:25], off offset:288
	global_store_dwordx2 v[44:45], v[20:21], off offset:320
	global_store_dwordx2 v[16:17], v[18:19], off
	v_cvt_pk_bf16_f32 v18, v40, v41
	v_cvt_pk_bf16_f32 v19, v42, v43
	global_store_dwordx2 v[16:17], v[18:19], off offset:32
	v_cvt_pk_bf16_f32 v18, v36, v37
	v_cvt_pk_bf16_f32 v19, v38, v39
	global_store_dwordx2 v[16:17], v[18:19], off offset:64
	v_cvt_pk_bf16_f32 v18, v28, v29
	v_cvt_pk_bf16_f32 v19, v30, v31
	v_cvt_pk_bf16_f32 v12, v12, v13
	v_cvt_pk_bf16_f32 v13, v14, v15
	v_cvt_pk_bf16_f32 v8, v8, v9
	v_cvt_pk_bf16_f32 v9, v10, v11
	v_cvt_pk_bf16_f32 v4, v4, v5
	v_cvt_pk_bf16_f32 v5, v6, v7
	v_cvt_pk_bf16_f32 v0, v0, v1
	v_cvt_pk_bf16_f32 v1, v2, v3
	s_and_b64 vcc, exec, s[4:5]
	s_mov_b32 s36, s8
	s_mov_b32 s6, s10
	s_mov_b64 s[18:19], s[14:15]
	s_mov_b64 s[16:17], s[12:13]
	global_store_dwordx2 v[16:17], v[18:19], off offset:96
	global_store_dwordx2 v[16:17], v[12:13], off offset:256
	global_store_dwordx2 v[16:17], v[8:9], off offset:288
	global_store_dwordx2 v[16:17], v[4:5], off offset:320
	global_store_dwordx2 v[16:17], v[0:1], off offset:352
	s_cbranch_vccz .LBB0_217
	s_waitcnt vmcnt(0)
	s_cmpk_gt_u32 s22, 0xff
	s_cbranch_scc1 .LBB0_228
	s_barrier

; #define PG8_STAGE(bufoff, gbase, voff) do { _Pragma("unroll") for (int _i = 0; _i < 2; ++_i) \
;         __builtin_amdgcn_global_load_lds((const unsigned*)((const char*)(gbase) + (voff)[_i]), (LAS unsigned*)(lds + (bufoff) + ldsw + _i * 8192), 16, 0, 0); } while (0)
; #define PG8_LDA(dst, b, h) do { _Pragma("unroll") for (int m = 0; m < 4; ++m) _Pragma("unroll") for (int k = 0; k < 2; ++k) dst[m][k] = *(const LAS bf16x8*)(lds + PG8_SA(b, h) + aoff + m * 2048 + k * 1024); } while (0)
; #define PG8_LDB(dst, b, h) do { _Pragma("unroll") for (int n = 0; n < 2; ++n) _Pragma("unroll") for (int k = 0; k < 2; ++k) dst[n][k] = *(const LAS bf16x8*)(lds + PG8_SB(b, h) + boff + n * 2048 + k * 1024); } while (0)
; #define PG8_WAIT_V(n) asm volatile("s_waitcnt vmcnt(" #n ")" ::: "memory")
; #define PG8_WAIT_L(n) asm volatile("s_waitcnt lgkmcnt(" #n ")" ::: "memory")
; #define PG8_BAR __builtin_amdgcn_s_barrier()
; #define PG8_SCHED __builtin_amdgcn_sched_barrier(0)
; template <class Epi>
; __device__ __forceinline__ void gemm_phase(LAS unsigned char* lds, const bf16_t* A, int lda, const bf16_t* Bt, int ldb, int M, int N, int K, int asel, const Epi& E, const int fixed_round = -1) {
;     ...
;             PG8_LDB(B0, 0, 0); PG8_SCHED; PG8_LDA(At, 0, 0); PG8_STAGE(PG8_SA(1, 1), a1 + hstepA, voffA);
;             PG8_WAIT_L(8); PG8_BAR; PG8_WAIT_L(0); PG8_MMA(0, 0, At, B0); PG8_BAR; PG8_SCHED;
;             PG8_LDB(B1, 0, 1); PG8_STAGE(PG8_SB(0, 0), b2, voffB);
;             PG8_BAR; PG8_WAIT_L(0); PG8_MMA(0, 1, At, B1); PG8_BAR;
;             PG8_LDA(At, 0, 1); PG8_STAGE(PG8_SA(0, 0), a2, voffA);
;             PG8_BAR; PG8_WAIT_L(0); PG8_MMA(1, 0, At, B0); PG8_BAR; PG8_SCHED;
;             PG8_STAGE(PG8_SB(0, 1), b2 + hstepB, voffB);
;             PG8_WAIT_V(6); PG8_BAR; PG8_MMA(1, 1, At, B1); PG8_BAR;
.LBB0_245:
	ds_read_b128 v[148:151], v161
	ds_read_b128 v[152:155], v161 offset:1024
	ds_read_b128 v[156:159], v161 offset:2048
	ds_read_b128 v[166:169], v161 offset:3072
	s_add_i32 m0, s37, 0xc000
	ds_read_b128 v[170:173], v162
	ds_read_b128 v[174:177], v162 offset:1024
	ds_read_b128 v[178:181], v162 offset:2048
	ds_read_b128 v[182:185], v162 offset:3072
	ds_read_b128 v[186:189], v162 offset:4096
	ds_read_b128 v[190:193], v162 offset:5120
	ds_read_b128 v[196:199], v162 offset:6144
	ds_read_b128 v[202:205], v162 offset:7168
	global_load_lds_dwordx4 v140, s[26:27]
	s_add_i32 m0, s37, 0xe000
	s_nop 0
	global_load_lds_dwordx4 v142, s[26:27]
	s_waitcnt lgkmcnt(8)
	s_setprio 1
	s_barrier
	s_waitcnt lgkmcnt(0)
	v_mfma_f32_16x16x32_bf16 v[124:127], v[148:151], v[170:173], v[124:127]
	v_mfma_f32_16x16x32_bf16 v[120:123], v[156:159], v[170:173], v[120:123]
	v_mfma_f32_16x16x32_bf16 v[112:115], v[148:151], v[178:181], v[112:115]
	v_mfma_f32_16x16x32_bf16 v[108:111], v[156:159], v[178:181], v[108:111]
	v_mfma_f32_16x16x32_bf16 v[100:103], v[148:151], v[186:189], v[100:103]
	v_mfma_f32_16x16x32_bf16 v[92:95], v[156:159], v[186:189], v[92:95]
	v_mfma_f32_16x16x32_bf16 v[84:87], v[148:151], v[196:199], v[84:87]
	v_mfma_f32_16x16x32_bf16 v[76:79], v[156:159], v[196:199], v[76:79]
	v_mfma_f32_16x16x32_bf16 v[124:127], v[152:155], v[174:177], v[124:127]
	v_mfma_f32_16x16x32_bf16 v[120:123], v[166:169], v[174:177], v[120:123]
	v_mfma_f32_16x16x32_bf16 v[112:115], v[152:155], v[182:185], v[112:115]
	v_mfma_f32_16x16x32_bf16 v[108:111], v[166:169], v[182:185], v[108:111]
	v_mfma_f32_16x16x32_bf16 v[100:103], v[152:155], v[190:193], v[100:103]
	v_mfma_f32_16x16x32_bf16 v[92:95], v[166:169], v[190:193], v[92:95]
	v_mfma_f32_16x16x32_bf16 v[84:87], v[152:155], v[202:205], v[84:87]
	v_mfma_f32_16x16x32_bf16 v[76:79], v[166:169], v[202:205], v[76:79]
	s_barrier
	s_setprio 0
	s_add_u32 s28, s26, 0xfff80080
	s_addc_u32 s29, s27, -1
	s_cmp_eq_u32 s57, 28
	s_cselect_b32 s31, s2, s29
	s_cselect_b32 s30, s19, s28
	s_cselect_b32 s29, s17, s56
	s_cselect_b32 s28, s54, s55
	s_add_i32 s58, s44, s36
	s_add_u32 s98, s28, s4
	s_addc_u32 s99, s29, s5
	s_mov_b32 m0, s58
	ds_read_b128 v[206:209], v163
	ds_read_b128 v[210:213], v163 offset:1024
	ds_read_b128 v[214:217], v163 offset:2048
	ds_read_b128 v[218:221], v163 offset:3072
	global_load_lds_dwordx4 v130, s[28:29]
	s_add_i32 m0, s58, 0x2000
	s_nop 0
	global_load_lds_dwordx4 v134, s[28:29]
	s_setprio 1
	s_barrier
	s_waitcnt lgkmcnt(0)
	v_mfma_f32_16x16x32_bf16 v[116:119], v[206:209], v[170:173], v[116:119]
	v_mfma_f32_16x16x32_bf16 v[104:107], v[214:217], v[170:173], v[104:107]
	v_mfma_f32_16x16x32_bf16 v[96:99], v[206:209], v[178:181], v[96:99]
	v_mfma_f32_16x16x32_bf16 v[88:91], v[214:217], v[178:181], v[88:91]
	v_mfma_f32_16x16x32_bf16 v[80:83], v[206:209], v[186:189], v[80:83]
	v_mfma_f32_16x16x32_bf16 v[72:75], v[214:217], v[186:189], v[72:75]
	v_mfma_f32_16x16x32_bf16 v[68:71], v[206:209], v[196:199], v[68:71]
	v_mfma_f32_16x16x32_bf16 v[64:67], v[214:217], v[196:199], v[64:67]
	v_mfma_f32_16x16x32_bf16 v[116:119], v[210:213], v[174:177], v[116:119]
	v_mfma_f32_16x16x32_bf16 v[104:107], v[218:221], v[174:177], v[104:107]
	v_mfma_f32_16x16x32_bf16 v[96:99], v[210:213], v[182:185], v[96:99]
	v_mfma_f32_16x16x32_bf16 v[88:91], v[218:221], v[182:185], v[88:91]
	v_mfma_f32_16x16x32_bf16 v[80:83], v[210:213], v[190:193], v[80:83]
	v_mfma_f32_16x16x32_bf16 v[72:75], v[218:221], v[190:193], v[72:75]
	v_mfma_f32_16x16x32_bf16 v[68:71], v[210:213], v[202:205], v[68:71]
	v_mfma_f32_16x16x32_bf16 v[64:67], v[218:221], v[202:205], v[64:67]
	s_barrier
	s_setprio 0
	s_mov_b32 m0, s37
	s_add_u32 s100, s30, s4
	s_addc_u32 s101, s31, s5
	ds_read_b128 v[170:173], v162 offset:16384
	ds_read_b128 v[174:177], v162 offset:17408
	ds_read_b128 v[178:181], v162 offset:18432
	ds_read_b128 v[182:185], v162 offset:19456
	ds_read_b128 v[186:189], v162 offset:20480
	ds_read_b128 v[190:193], v162 offset:21504
	ds_read_b128 v[196:199], v162 offset:22528
	ds_read_b128 v[202:205], v162 offset:23552
	global_load_lds_dwordx4 v128, s[30:31]
	s_mov_b32 m0, s38
	s_nop 0
	global_load_lds_dwordx4 v132, s[30:31]
	s_setprio 1
	s_barrier
	s_waitcnt lgkmcnt(0)
	v_mfma_f32_16x16x32_bf16 v[60:63], v[148:151], v[170:173], v[60:63]
	v_mfma_f32_16x16x32_bf16 v[56:59], v[156:159], v[170:173], v[56:59]
	v_mfma_f32_16x16x32_bf16 v[52:55], v[148:151], v[178:181], v[52:55]
	v_mfma_f32_16x16x32_bf16 v[44:47], v[156:159], v[178:181], v[44:47]
	v_mfma_f32_16x16x32_bf16 v[36:39], v[148:151], v[186:189], v[36:39]
	v_mfma_f32_16x16x32_bf16 v[28:31], v[156:159], v[186:189], v[28:31]
	v_mfma_f32_16x16x32_bf16 v[20:23], v[148:151], v[196:199], v[20:23]
	v_mfma_f32_16x16x32_bf16 v[12:15], v[156:159], v[196:199], v[12:15]
	v_mfma_f32_16x16x32_bf16 v[60:63], v[152:155], v[174:177], v[60:63]
	v_mfma_f32_16x16x32_bf16 v[56:59], v[166:169], v[174:177], v[56:59]
	v_mfma_f32_16x16x32_bf16 v[52:55], v[152:155], v[182:185], v[52:55]
	v_mfma_f32_16x16x32_bf16 v[44:47], v[166:169], v[182:185], v[44:47]
	v_mfma_f32_16x16x32_bf16 v[36:39], v[152:155], v[190:193], v[36:39]
	v_mfma_f32_16x16x32_bf16 v[28:31], v[166:169], v[190:193], v[28:31]
	v_mfma_f32_16x16x32_bf16 v[20:23], v[152:155], v[202:205], v[20:23]
	v_mfma_f32_16x16x32_bf16 v[12:15], v[166:169], v[202:205], v[12:15]
	s_barrier
	s_setprio 0
	s_add_u32 s58, s28, 0x80000
	s_addc_u32 s59, s29, 0
	s_add_i32 s60, s45, s36
	s_mov_b32 m0, s60
	s_nop 0
	global_load_lds_dwordx4 v130, s[58:59]
	s_add_i32 m0, s60, 0x2000
	s_nop 0
	global_load_lds_dwordx4 v134, s[58:59]
	s_waitcnt vmcnt(6)
	s_setprio 1
	s_barrier
; #define PG8_STAGE(bufoff, gbase, voff) do { _Pragma("unroll") for (int _i = 0; _i < 2; ++_i) \
;         __builtin_amdgcn_global_load_lds((const unsigned*)((const char*)(gbase) + (voff)[_i]), (LAS unsigned*)(lds + (bufoff) + ldsw + _i * 8192), 16, 0, 0); } while (0)
; #define PG8_LDA(dst, b, h) do { _Pragma("unroll") for (int m = 0; m < 4; ++m) _Pragma("unroll") for (int k = 0; k < 2; ++k) dst[m][k] = *(const LAS bf16x8*)(lds + PG8_SA(b, h) + aoff + m * 2048 + k * 1024); } while (0)
; #define PG8_LDB(dst, b, h) do { _Pragma("unroll") for (int n = 0; n < 2; ++n) _Pragma("unroll") for (int k = 0; k < 2; ++k) dst[n][k] = *(const LAS bf16x8*)(lds + PG8_SB(b, h) + boff + n * 2048 + k * 1024); } while (0)
; #define PG8_WAIT_V(n) asm volatile("s_waitcnt vmcnt(" #n ")" ::: "memory")
; #define PG8_WAIT_L(n) asm volatile("s_waitcnt lgkmcnt(" #n ")" ::: "memory")
; #define PG8_BAR __builtin_amdgcn_s_barrier()
; #define PG8_SCHED __builtin_amdgcn_sched_barrier(0)
; template <class Epi>
; __device__ __forceinline__ void gemm_phase(LAS unsigned char* lds, const bf16_t* A, int lda, const bf16_t* Bt, int ldb, int M, int N, int K, int asel, const Epi& E, const int fixed_round = -1) {
;     ...
;             PG8_WAIT_V(6); PG8_BAR; PG8_MMA(1, 1, At, B1); PG8_BAR;
;             PG8_LDB(B0, 1, 0); PG8_SCHED; PG8_LDA(At, 1, 0); PG8_STAGE(PG8_SA(0, 1), a2 + hstepA, voffA);
;             PG8_WAIT_L(8); PG8_BAR; PG8_WAIT_L(0); PG8_MMA(0, 0, At, B0); PG8_BAR; PG8_SCHED;
;             PG8_LDB(B1, 1, 1); PG8_STAGE(PG8_SB(1, 0), b3, voffB);
;             PG8_BAR; PG8_WAIT_L(0); PG8_MMA(0, 1, At, B1); PG8_BAR;
	v_mfma_f32_16x16x32_bf16 v[48:51], v[206:209], v[170:173], v[48:51]
	v_mfma_f32_16x16x32_bf16 v[40:43], v[214:217], v[170:173], v[40:43]
	v_mfma_f32_16x16x32_bf16 v[32:35], v[206:209], v[178:181], v[32:35]
	v_mfma_f32_16x16x32_bf16 v[24:27], v[214:217], v[178:181], v[24:27]
	v_mfma_f32_16x16x32_bf16 v[16:19], v[206:209], v[186:189], v[16:19]
	v_mfma_f32_16x16x32_bf16 v[8:11], v[214:217], v[186:189], v[8:11]
	v_mfma_f32_16x16x32_bf16 v[4:7], v[206:209], v[196:199], v[4:7]
	v_mfma_f32_16x16x32_bf16 v[0:3], v[214:217], v[196:199], v[0:3]
	v_mfma_f32_16x16x32_bf16 v[48:51], v[210:213], v[174:177], v[48:51]
	v_mfma_f32_16x16x32_bf16 v[40:43], v[218:221], v[174:177], v[40:43]
	v_mfma_f32_16x16x32_bf16 v[32:35], v[210:213], v[182:185], v[32:35]
	v_mfma_f32_16x16x32_bf16 v[24:27], v[218:221], v[182:185], v[24:27]
	v_mfma_f32_16x16x32_bf16 v[16:19], v[210:213], v[190:193], v[16:19]
	v_mfma_f32_16x16x32_bf16 v[8:11], v[218:221], v[190:193], v[8:11]
	v_mfma_f32_16x16x32_bf16 v[4:7], v[210:213], v[202:205], v[4:7]
	v_mfma_f32_16x16x32_bf16 v[0:3], v[218:221], v[202:205], v[0:3]
	s_barrier
	s_setprio 0
	s_add_i32 s58, 0, 0x18000
	v_add_u32_e32 v136, s58, v160
	ds_read_b128 v[148:151], v136
	ds_read_b128 v[152:155], v136 offset:1024
	ds_read_b128 v[156:159], v136 offset:2048
	ds_read_b128 v[166:169], v136 offset:3072
	s_add_u32 s30, s30, 0x80000
	s_addc_u32 s31, s31, 0
	s_mov_b32 m0, s39
	ds_read_b128 v[170:173], v162 offset:32768
	ds_read_b128 v[174:177], v162 offset:33792
	ds_read_b128 v[178:181], v162 offset:34816
	ds_read_b128 v[182:185], v162 offset:35840
	ds_read_b128 v[186:189], v162 offset:36864
	ds_read_b128 v[190:193], v162 offset:37888
	ds_read_b128 v[196:199], v162 offset:38912
	ds_read_b128 v[202:205], v162 offset:39936
	global_load_lds_dwordx4 v128, s[30:31]
	s_mov_b32 m0, s40
	s_nop 0
	global_load_lds_dwordx4 v132, s[30:31]
	s_waitcnt lgkmcnt(8)
	s_setprio 1
	s_barrier
	s_waitcnt lgkmcnt(0)
	v_mfma_f32_16x16x32_bf16 v[124:127], v[148:151], v[170:173], v[124:127]
	v_mfma_f32_16x16x32_bf16 v[120:123], v[156:159], v[170:173], v[120:123]
	v_mfma_f32_16x16x32_bf16 v[112:115], v[148:151], v[178:181], v[112:115]
	v_mfma_f32_16x16x32_bf16 v[108:111], v[156:159], v[178:181], v[108:111]
	v_mfma_f32_16x16x32_bf16 v[100:103], v[148:151], v[186:189], v[100:103]
	v_mfma_f32_16x16x32_bf16 v[92:95], v[156:159], v[186:189], v[92:95]
	v_mfma_f32_16x16x32_bf16 v[84:87], v[148:151], v[196:199], v[84:87]
	v_mfma_f32_16x16x32_bf16 v[76:79], v[156:159], v[196:199], v[76:79]
	v_mfma_f32_16x16x32_bf16 v[124:127], v[152:155], v[174:177], v[124:127]
	v_mfma_f32_16x16x32_bf16 v[120:123], v[166:169], v[174:177], v[120:123]
	v_mfma_f32_16x16x32_bf16 v[112:115], v[152:155], v[182:185], v[112:115]
	v_mfma_f32_16x16x32_bf16 v[108:111], v[166:169], v[182:185], v[108:111]
	v_mfma_f32_16x16x32_bf16 v[100:103], v[152:155], v[190:193], v[100:103]
	v_mfma_f32_16x16x32_bf16 v[92:95], v[166:169], v[190:193], v[92:95]
	v_mfma_f32_16x16x32_bf16 v[84:87], v[152:155], v[202:205], v[84:87]
	v_mfma_f32_16x16x32_bf16 v[76:79], v[166:169], v[202:205], v[76:79]
	s_barrier
	s_setprio 0
	s_add_i32 s30, 0, 0x1c000
	s_add_i32 s31, s58, s36
	v_add_u32_e32 v136, s30, v160
	s_mov_b32 m0, s31
	ds_read_b128 v[206:209], v136
	ds_read_b128 v[210:213], v136 offset:1024
	ds_read_b128 v[214:217], v136 offset:2048
	ds_read_b128 v[218:221], v136 offset:3072
	global_load_lds_dwordx4 v130, s[98:99]
	s_add_i32 m0, s31, 0x2000
	s_nop 0
	global_load_lds_dwordx4 v134, s[98:99]
	s_setprio 1
	s_barrier
	s_waitcnt lgkmcnt(0)
	v_mfma_f32_16x16x32_bf16 v[116:119], v[206:209], v[170:173], v[116:119]
	v_mfma_f32_16x16x32_bf16 v[104:107], v[214:217], v[170:173], v[104:107]
	v_mfma_f32_16x16x32_bf16 v[96:99], v[206:209], v[178:181], v[96:99]
	v_mfma_f32_16x16x32_bf16 v[88:91], v[214:217], v[178:181], v[88:91]
	v_mfma_f32_16x16x32_bf16 v[80:83], v[206:209], v[186:189], v[80:83]
	v_mfma_f32_16x16x32_bf16 v[72:75], v[214:217], v[186:189], v[72:75]
	v_mfma_f32_16x16x32_bf16 v[68:71], v[206:209], v[196:199], v[68:71]
	v_mfma_f32_16x16x32_bf16 v[64:67], v[214:217], v[196:199], v[64:67]
	v_mfma_f32_16x16x32_bf16 v[116:119], v[210:213], v[174:177], v[116:119]
	v_mfma_f32_16x16x32_bf16 v[104:107], v[218:221], v[174:177], v[104:107]
	v_mfma_f32_16x16x32_bf16 v[96:99], v[210:213], v[182:185], v[96:99]
	v_mfma_f32_16x16x32_bf16 v[88:91], v[218:221], v[182:185], v[88:91]
	v_mfma_f32_16x16x32_bf16 v[80:83], v[210:213], v[190:193], v[80:83]
	v_mfma_f32_16x16x32_bf16 v[72:75], v[218:221], v[190:193], v[72:75]
	v_mfma_f32_16x16x32_bf16 v[68:71], v[210:213], v[202:205], v[68:71]
	v_mfma_f32_16x16x32_bf16 v[64:67], v[218:221], v[202:205], v[64:67]
	s_barrier
	s_setprio 0
	s_mov_b32 m0, s41
	ds_read_b128 v[170:173], v162 offset:49152
	ds_read_b128 v[174:177], v162 offset:50176
	ds_read_b128 v[178:181], v162 offset:51200
	ds_read_b128 v[182:185], v162 offset:52224
	ds_read_b128 v[186:189], v162 offset:53248
	ds_read_b128 v[190:193], v162 offset:54272
	ds_read_b128 v[196:199], v162 offset:55296
	ds_read_b128 v[202:205], v162 offset:56320
	global_load_lds_dwordx4 v128, s[100:101]
	s_mov_b32 m0, s42
	s_nop 0
	global_load_lds_dwordx4 v132, s[100:101]
	s_setprio 1
	s_barrier
; __device__ __forceinline__ unsigned cvt_pk_bf16(float lo, float hi) { const bf16x2_t r = __builtin_convertvector((f32x2){lo, hi}, bf16x2_t); return __builtin_bit_cast(unsigned, r); }
; #define PG8_STAGE(bufoff, gbase, voff) do { _Pragma("unroll") for (int _i = 0; _i < 2; ++_i) \
;         __builtin_amdgcn_global_load_lds((const unsigned*)((const char*)(gbase) + (voff)[_i]), (LAS unsigned*)(lds + (bufoff) + ldsw + _i * 8192), 16, 0, 0); } while (0)
; #define PG8_LDA(dst, b, h) do { _Pragma("unroll") for (int m = 0; m < 4; ++m) _Pragma("unroll") for (int k = 0; k < 2; ++k) dst[m][k] = *(const LAS bf16x8*)(lds + PG8_SA(b, h) + aoff + m * 2048 + k * 1024); } while (0)
; #define PG8_WAIT_V(n) asm volatile("s_waitcnt vmcnt(" #n ")" ::: "memory")
; #define PG8_WAIT_L(n) asm volatile("s_waitcnt lgkmcnt(" #n ")" ::: "memory")
; #define PG8_BAR __builtin_amdgcn_s_barrier()
; #define PG8_SCHED __builtin_amdgcn_sched_barrier(0)
; template <class Epi>
; __device__ __forceinline__ void gemm_phase(LAS unsigned char* lds, const bf16_t* A, int lda, const bf16_t* Bt, int ldb, int M, int N, int K, int asel, const Epi& E, const int fixed_round = -1) {
;     ...
;             PG8_BAR; PG8_WAIT_L(0); PG8_MMA(0, 1, At, B1); PG8_BAR;
;             PG8_LDA(At, 1, 1); PG8_STAGE(PG8_SA(1, 0), a3, voffA);
;             PG8_BAR; PG8_WAIT_L(0); PG8_MMA(1, 0, At, B0); PG8_BAR; PG8_SCHED;
;             PG8_STAGE(PG8_SB(1, 1), b3 + hstepB, voffB);
;             PG8_WAIT_V(6); PG8_BAR; PG8_MMA(1, 1, At, B1); PG8_BAR;
;     __device__ __forceinline__ void operator()(const AccT& acc, const Unit& u, int wr, int wc, int fr, int fq) const {
;     ...
;         if (pn < 8) {
;             bf16_t* base = pn < 4 ? Q : Kn; const int colt = (pn & 3) * BM; const float sc = pn < 4 ? 0.08838834764831845f : 1.0f;
; #pragma unroll
;             for (int ai = 0; ai < 2; ++ai)
; #pragma unroll
;                 for (int m = 0; m < 4; ++m) { bf16_t* rowp = base + (size_t)(row0 + ai * HALF + m * 16) * 1024 + colt + cl;
; #pragma unroll
;                     for (int bj = 0; bj < 2; ++bj) { const f32x4 v0 = acc[ai][bj][m][0] * sc, v1 = acc[ai][bj][m][1] * sc;
;                         u32x4 w; w.x = cvt_pk_bf16(v0[0], v0[1]); w.y = cvt_pk_bf16(v0[2], v0[3]); w.z = cvt_pk_bf16(v1[0], v1[1]); w.w = cvt_pk_bf16(v1[2], v1[3]);
;                         *(u32x4*)(rowp + bj * HALF) = w; } }
	s_waitcnt lgkmcnt(0)
	v_mfma_f32_16x16x32_bf16 v[60:63], v[148:151], v[170:173], v[60:63]
	v_mfma_f32_16x16x32_bf16 v[56:59], v[156:159], v[170:173], v[56:59]
	v_mfma_f32_16x16x32_bf16 v[52:55], v[148:151], v[178:181], v[52:55]
	v_mfma_f32_16x16x32_bf16 v[44:47], v[156:159], v[178:181], v[44:47]
	v_mfma_f32_16x16x32_bf16 v[36:39], v[148:151], v[186:189], v[36:39]
	v_mfma_f32_16x16x32_bf16 v[28:31], v[156:159], v[186:189], v[28:31]
	v_mfma_f32_16x16x32_bf16 v[20:23], v[148:151], v[196:199], v[20:23]
	v_mfma_f32_16x16x32_bf16 v[12:15], v[156:159], v[196:199], v[12:15]
	v_mfma_f32_16x16x32_bf16 v[60:63], v[152:155], v[174:177], v[60:63]
	v_mfma_f32_16x16x32_bf16 v[56:59], v[166:169], v[174:177], v[56:59]
	v_mfma_f32_16x16x32_bf16 v[52:55], v[152:155], v[182:185], v[52:55]
	v_mfma_f32_16x16x32_bf16 v[44:47], v[166:169], v[182:185], v[44:47]
	v_mfma_f32_16x16x32_bf16 v[36:39], v[152:155], v[190:193], v[36:39]
	v_mfma_f32_16x16x32_bf16 v[28:31], v[166:169], v[190:193], v[28:31]
	v_mfma_f32_16x16x32_bf16 v[20:23], v[152:155], v[202:205], v[20:23]
	v_mfma_f32_16x16x32_bf16 v[12:15], v[166:169], v[202:205], v[12:15]
	s_barrier
	s_setprio 0
	s_add_u32 s28, s28, 0x80080
	s_addc_u32 s29, s29, 0
	s_add_i32 s30, s30, s36
	s_mov_b32 m0, s30
	s_nop 0
	global_load_lds_dwordx4 v130, s[28:29]
	s_add_i32 m0, s30, 0x2000
	s_nop 0
	global_load_lds_dwordx4 v134, s[28:29]
	s_waitcnt vmcnt(6)
	s_setprio 1
	s_barrier
	v_mfma_f32_16x16x32_bf16 v[48:51], v[206:209], v[170:173], v[48:51]
	v_mfma_f32_16x16x32_bf16 v[40:43], v[214:217], v[170:173], v[40:43]
	v_mfma_f32_16x16x32_bf16 v[32:35], v[206:209], v[178:181], v[32:35]
	v_mfma_f32_16x16x32_bf16 v[24:27], v[214:217], v[178:181], v[24:27]
	v_mfma_f32_16x16x32_bf16 v[16:19], v[206:209], v[186:189], v[16:19]
	v_mfma_f32_16x16x32_bf16 v[8:11], v[214:217], v[186:189], v[8:11]
	v_mfma_f32_16x16x32_bf16 v[4:7], v[206:209], v[196:199], v[4:7]
	v_mfma_f32_16x16x32_bf16 v[0:3], v[214:217], v[196:199], v[0:3]
	v_mfma_f32_16x16x32_bf16 v[48:51], v[210:213], v[174:177], v[48:51]
	v_mfma_f32_16x16x32_bf16 v[40:43], v[218:221], v[174:177], v[40:43]
	v_mfma_f32_16x16x32_bf16 v[32:35], v[210:213], v[182:185], v[32:35]
	v_mfma_f32_16x16x32_bf16 v[24:27], v[218:221], v[182:185], v[24:27]
	v_mfma_f32_16x16x32_bf16 v[16:19], v[210:213], v[190:193], v[16:19]
	v_mfma_f32_16x16x32_bf16 v[8:11], v[218:221], v[190:193], v[8:11]
	v_mfma_f32_16x16x32_bf16 v[4:7], v[210:213], v[202:205], v[4:7]
	v_mfma_f32_16x16x32_bf16 v[0:3], v[218:221], v[202:205], v[0:3]
	s_setprio 0
	s_add_i32 s57, s57, 2
	s_add_u32 s26, s26, 0x100
	s_addc_u32 s27, s27, 0
	s_add_u32 s55, s55, 0x100
	s_addc_u32 s56, s56, 0
	s_cmp_gt_u32 s57, 29
	s_cbranch_scc0 .Lrot_3
	s_barrier
	s_lshl_b32 s17, s24, 8
	v_add_u32_e32 v154, s17, v139
	s_cmp_lt_i32 s25, -8
	v_or_b32_e32 v152, 16, v154
	v_or_b32_e32 v150, 32, v154
	v_or_b32_e32 v148, 48, v154
	s_cselect_b64 s[26:27], -1, 0
	s_cmp_gt_i32 s25, -9
	v_ashrrev_i32_e32 v155, 31, v154
	v_lshlrev_b32_e32 v136, 1, v138
	v_ashrrev_i32_e32 v153, 31, v152
	v_ashrrev_i32_e32 v151, 31, v150
	v_ashrrev_i32_e32 v149, 31, v148
	s_cbranch_scc1 .LBB0_248
	s_cmp_lt_u32 s25, -12
	s_cselect_b64 vcc, -1, 0
	s_and_b64 s[28:29], vcc, exec
	s_cselect_b32 s2, s89, s81
	s_cselect_b32 s19, s88, s91
	s_lshl_b32 s28, s25, 9
	s_and_b32 s28, s28, 0x600
	s_add_u32 s28, s19, s28
	v_cndmask_b32_e32 v156, 1.0, v164, vcc
	s_addc_u32 s29, s2, 0
	v_lshl_add_u64 v[170:171], s[28:29], 0, v[136:137]
	v_lshlrev_b64 v[158:159], 11, v[154:155]
	v_pk_mul_f32 v[168:169], v[156:157], v[126:127] op_sel_hi:[0,1]
	v_pk_mul_f32 v[166:167], v[156:157], v[124:125] op_sel_hi:[0,1]
	v_pk_mul_f32 v[172:173], v[156:157], v[122:123] op_sel_hi:[0,1]
	v_pk_mul_f32 v[174:175], v[156:157], v[120:121] op_sel_hi:[0,1]
	v_lshl_add_u64 v[158:159], v[170:171], 0, v[158:159]
	v_cvt_pk_bf16_f32 v166, v166, v167
	v_cvt_pk_bf16_f32 v167, v168, v169
	v_cvt_pk_bf16_f32 v168, v174, v175
	v_cvt_pk_bf16_f32 v169, v172, v173
	global_store_dwordx4 v[158:159], v[166:169], off
	v_pk_mul_f32 v[172:173], v[156:157], v[106:107] op_sel_hi:[0,1]
	v_pk_mul_f32 v[174:175], v[156:157], v[104:105] op_sel_hi:[0,1]
	v_pk_mul_f32 v[168:169], v[156:157], v[118:119] op_sel_hi:[0,1]
	v_pk_mul_f32 v[166:167], v[156:157], v[116:117] op_sel_hi:[0,1]
	v_cvt_pk_bf16_f32 v166, v166, v167
	v_cvt_pk_bf16_f32 v167, v168, v169
	v_cvt_pk_bf16_f32 v168, v174, v175
	v_cvt_pk_bf16_f32 v169, v172, v173
	global_store_dwordx4 v[158:159], v[166:169], off offset:256
	v_pk_mul_f32 v[174:175], v[156:157], v[110:111] op_sel_hi:[0,1]
	v_pk_mul_f32 v[176:177], v[156:157], v[108:109] op_sel_hi:[0,1]
	v_lshlrev_b64 v[166:167], 11, v[152:153]
	v_lshl_add_u64 v[172:173], v[170:171], 0, v[166:167]
	v_pk_mul_f32 v[168:169], v[156:157], v[114:115] op_sel_hi:[0,1]
	v_pk_mul_f32 v[166:167], v[156:157], v[112:113] op_sel_hi:[0,1]
	v_cvt_pk_bf16_f32 v166, v166, v167
	v_cvt_pk_bf16_f32 v167, v168, v169
	v_cvt_pk_bf16_f32 v168, v176, v177
	v_cvt_pk_bf16_f32 v169, v174, v175
	global_store_dwordx4 v[172:173], v[166:169], off
	v_pk_mul_f32 v[174:175], v[156:157], v[90:91] op_sel_hi:[0,1]
	v_pk_mul_f32 v[176:177], v[156:157], v[88:89] op_sel_hi:[0,1]
	v_pk_mul_f32 v[168:169], v[156:157], v[98:99] op_sel_hi:[0,1]
	v_pk_mul_f32 v[166:167], v[156:157], v[96:97] op_sel_hi:[0,1]
	v_cvt_pk_bf16_f32 v166, v166, v167
	v_cvt_pk_bf16_f32 v167, v168, v169
	v_cvt_pk_bf16_f32 v168, v176, v177
	v_cvt_pk_bf16_f32 v169, v174, v175
	global_store_dwordx4 v[172:173], v[166:169], off offset:256
	v_pk_mul_f32 v[174:175], v[156:157], v[94:95] op_sel_hi:[0,1]
	v_pk_mul_f32 v[176:177], v[156:157], v[92:93] op_sel_hi:[0,1]
	v_lshlrev_b64 v[166:167], 11, v[150:151]
; __device__ __forceinline__ unsigned cvt_pk_bf16(float lo, float hi) { const bf16x2_t r = __builtin_convertvector((f32x2){lo, hi}, bf16x2_t); return __builtin_bit_cast(unsigned, r); }
;     __device__ __forceinline__ void operator()(const AccT& acc, const Unit& u, int wr, int wc, int fr, int fq) const {
;     ...
;         if (pn < 8) {
;             bf16_t* base = pn < 4 ? Q : Kn; const int colt = (pn & 3) * BM; const float sc = pn < 4 ? 0.08838834764831845f : 1.0f;
; #pragma unroll
;             for (int ai = 0; ai < 2; ++ai)
; #pragma unroll
;                 for (int m = 0; m < 4; ++m) { bf16_t* rowp = base + (size_t)(row0 + ai * HALF + m * 16) * 1024 + colt + cl;
; #pragma unroll
;                     for (int bj = 0; bj < 2; ++bj) { const f32x4 v0 = acc[ai][bj][m][0] * sc, v1 = acc[ai][bj][m][1] * sc;
;                         u32x4 w; w.x = cvt_pk_bf16(v0[0], v0[1]); w.y = cvt_pk_bf16(v0[2], v0[3]); w.z = cvt_pk_bf16(v1[0], v1[1]); w.w = cvt_pk_bf16(v1[2], v1[3]);
;                         *(u32x4*)(rowp + bj * HALF) = w; } }
	v_lshl_add_u64 v[172:173], v[170:171], 0, v[166:167]
	v_pk_mul_f32 v[168:169], v[156:157], v[102:103] op_sel_hi:[0,1]
	v_pk_mul_f32 v[166:167], v[156:157], v[100:101] op_sel_hi:[0,1]
	v_cvt_pk_bf16_f32 v166, v166, v167
	v_cvt_pk_bf16_f32 v167, v168, v169
	v_cvt_pk_bf16_f32 v168, v176, v177
	v_cvt_pk_bf16_f32 v169, v174, v175
	global_store_dwordx4 v[172:173], v[166:169], off
	v_pk_mul_f32 v[174:175], v[156:157], v[74:75] op_sel_hi:[0,1]
	v_pk_mul_f32 v[176:177], v[156:157], v[72:73] op_sel_hi:[0,1]
	v_pk_mul_f32 v[168:169], v[156:157], v[82:83] op_sel_hi:[0,1]
	v_pk_mul_f32 v[166:167], v[156:157], v[80:81] op_sel_hi:[0,1]
	v_cvt_pk_bf16_f32 v166, v166, v167
	v_cvt_pk_bf16_f32 v167, v168, v169
	v_cvt_pk_bf16_f32 v168, v176, v177
	v_cvt_pk_bf16_f32 v169, v174, v175
	global_store_dwordx4 v[172:173], v[166:169], off offset:256
	v_pk_mul_f32 v[172:173], v[156:157], v[78:79] op_sel_hi:[0,1]
	v_pk_mul_f32 v[174:175], v[156:157], v[76:77] op_sel_hi:[0,1]
	v_lshlrev_b64 v[166:167], 11, v[148:149]
	v_lshl_add_u64 v[170:171], v[170:171], 0, v[166:167]
	v_pk_mul_f32 v[168:169], v[156:157], v[86:87] op_sel_hi:[0,1]
	v_pk_mul_f32 v[166:167], v[156:157], v[84:85] op_sel_hi:[0,1]
	v_cvt_pk_bf16_f32 v166, v166, v167
	v_cvt_pk_bf16_f32 v167, v168, v169
	v_cvt_pk_bf16_f32 v168, v174, v175
	v_cvt_pk_bf16_f32 v169, v172, v173
	global_store_dwordx4 v[170:171], v[166:169], off
	v_pk_mul_f32 v[172:173], v[156:157], v[66:67] op_sel_hi:[0,1]
	v_pk_mul_f32 v[174:175], v[156:157], v[64:65] op_sel_hi:[0,1]
	v_pk_mul_f32 v[168:169], v[156:157], v[70:71] op_sel_hi:[0,1]
	v_pk_mul_f32 v[166:167], v[156:157], v[68:69] op_sel_hi:[0,1]
	v_cvt_pk_bf16_f32 v166, v166, v167
	v_cvt_pk_bf16_f32 v167, v168, v169
	v_cvt_pk_bf16_f32 v168, v174, v175
	v_cvt_pk_bf16_f32 v169, v172, v173
	global_store_dwordx4 v[170:171], v[166:169], off offset:256
	v_pk_mul_f32 v[172:173], v[156:157], v[58:59] op_sel_hi:[0,1]
	s_mov_b32 s2, 0x40000
	v_pk_mul_f32 v[168:169], v[156:157], v[62:63] op_sel_hi:[0,1]
	v_pk_mul_f32 v[166:167], v[156:157], v[60:61] op_sel_hi:[0,1]
	v_pk_mul_f32 v[174:175], v[156:157], v[56:57] op_sel_hi:[0,1]
	v_cvt_pk_bf16_f32 v166, v166, v167
	v_cvt_pk_bf16_f32 v167, v168, v169
	v_cvt_pk_bf16_f32 v169, v172, v173
	v_add_co_u32_e32 v172, vcc, s2, v158
	v_cvt_pk_bf16_f32 v168, v174, v175
	s_nop 0
	v_addc_co_u32_e32 v173, vcc, 0, v159, vcc
	s_mov_b64 s[28:29], 0x40000
	global_store_dwordx4 v[172:173], v[166:169], off
	v_pk_mul_f32 v[172:173], v[156:157], v[42:43] op_sel_hi:[0,1]
	v_pk_mul_f32 v[174:175], v[156:157], v[40:41] op_sel_hi:[0,1]
	v_pk_mul_f32 v[168:169], v[156:157], v[50:51] op_sel_hi:[0,1]
	v_pk_mul_f32 v[166:167], v[156:157], v[48:49] op_sel_hi:[0,1]
	v_lshl_add_u64 v[170:171], v[158:159], 0, s[28:29]
	v_cvt_pk_bf16_f32 v166, v166, v167
	v_cvt_pk_bf16_f32 v167, v168, v169
	v_cvt_pk_bf16_f32 v168, v174, v175
	v_cvt_pk_bf16_f32 v169, v172, v173
	global_store_dwordx4 v[170:171], v[166:169], off offset:256
	v_pk_mul_f32 v[172:173], v[156:157], v[46:47] op_sel_hi:[0,1]
	v_pk_mul_f32 v[174:175], v[156:157], v[44:45] op_sel_hi:[0,1]
	v_pk_mul_f32 v[168:169], v[156:157], v[54:55] op_sel_hi:[0,1]
	v_pk_mul_f32 v[166:167], v[156:157], v[52:53] op_sel_hi:[0,1]
	v_cvt_pk_bf16_f32 v166, v166, v167
	v_cvt_pk_bf16_f32 v167, v168, v169
	v_cvt_pk_bf16_f32 v169, v172, v173
	v_add_co_u32_e32 v172, vcc, s46, v158
	v_cvt_pk_bf16_f32 v168, v174, v175
	s_nop 0
	v_addc_co_u32_e32 v173, vcc, 0, v159, vcc
	s_mov_b64 s[28:29], 0x48000
	global_store_dwordx4 v[172:173], v[166:169], off
	v_pk_mul_f32 v[172:173], v[156:157], v[26:27] op_sel_hi:[0,1]
	v_pk_mul_f32 v[174:175], v[156:157], v[24:25] op_sel_hi:[0,1]
	v_pk_mul_f32 v[168:169], v[156:157], v[34:35] op_sel_hi:[0,1]
	v_pk_mul_f32 v[166:167], v[156:157], v[32:33] op_sel_hi:[0,1]
	v_lshl_add_u64 v[170:171], v[158:159], 0, s[28:29]
	v_cvt_pk_bf16_f32 v166, v166, v167
	v_cvt_pk_bf16_f32 v167, v168, v169
	v_cvt_pk_bf16_f32 v168, v174, v175
	v_cvt_pk_bf16_f32 v169, v172, v173
	global_store_dwordx4 v[170:171], v[166:169], off offset:256
	v_pk_mul_f32 v[172:173], v[156:157], v[30:31] op_sel_hi:[0,1]
	v_pk_mul_f32 v[174:175], v[156:157], v[28:29] op_sel_hi:[0,1]
	v_pk_mul_f32 v[168:169], v[156:157], v[38:39] op_sel_hi:[0,1]
	v_pk_mul_f32 v[166:167], v[156:157], v[36:37] op_sel_hi:[0,1]
	v_cvt_pk_bf16_f32 v166, v166, v167
	v_cvt_pk_bf16_f32 v167, v168, v169
	v_cvt_pk_bf16_f32 v169, v172, v173
	v_add_co_u32_e32 v172, vcc, s47, v158
	v_cvt_pk_bf16_f32 v168, v174, v175
	s_nop 0
	v_addc_co_u32_e32 v173, vcc, 0, v159, vcc
	global_store_dwordx4 v[172:173], v[166:169], off
	v_pk_mul_f32 v[172:173], v[156:157], v[10:11] op_sel_hi:[0,1]
	v_pk_mul_f32 v[174:175], v[156:157], v[8:9] op_sel_hi:[0,1]
	v_pk_mul_f32 v[168:169], v[156:157], v[18:19] op_sel_hi:[0,1]
	v_pk_mul_f32 v[166:167], v[156:157], v[16:17] op_sel_hi:[0,1]
	v_lshl_add_u64 v[170:171], v[158:159], 0, s[6:7]
	v_cvt_pk_bf16_f32 v166, v166, v167
	v_cvt_pk_bf16_f32 v167, v168, v169
	v_cvt_pk_bf16_f32 v168, v174, v175
	v_cvt_pk_bf16_f32 v169, v172, v173
	global_store_dwordx4 v[170:171], v[166:169], off offset:256
	v_lshl_add_u64 v[170:171], v[158:159], 0, s[8:9]
	v_pk_mul_f32 v[172:173], v[156:157], v[14:15] op_sel_hi:[0,1]
	v_pk_mul_f32 v[168:169], v[156:157], v[22:23] op_sel_hi:[0,1]
	v_pk_mul_f32 v[166:167], v[156:157], v[20:21] op_sel_hi:[0,1]
	v_pk_mul_f32 v[174:175], v[156:157], v[12:13] op_sel_hi:[0,1]
	v_add_co_u32_e32 v158, vcc, s48, v158
	v_cvt_pk_bf16_f32 v166, v166, v167
	v_cvt_pk_bf16_f32 v167, v168, v169
	v_cvt_pk_bf16_f32 v168, v174, v175
	v_cvt_pk_bf16_f32 v169, v172, v173
	v_addc_co_u32_e32 v159, vcc, 0, v159, vcc
	global_store_dwordx4 v[158:159], v[166:169], off
	v_pk_mul_f32 v[158:159], v[156:157], v[6:7] op_sel_hi:[0,1]
	v_pk_mul_f32 v[172:173], v[156:157], v[0:1] op_sel_hi:[0,1]
	v_pk_mul_f32 v[166:167], v[156:157], v[4:5] op_sel_hi:[0,1]
	v_pk_mul_f32 v[168:169], v[156:157], v[2:3] op_sel_hi:[0,1]
	v_cvt_pk_bf16_f32 v156, v166, v167
	v_cvt_pk_bf16_f32 v157, v158, v159
	v_cvt_pk_bf16_f32 v158, v172, v173
	v_cvt_pk_bf16_f32 v159, v168, v169
	global_store_dwordx4 v[170:171], v[156:159], off offset:256

; #define PG8_STAGE(bufoff, gbase, voff) do { _Pragma("unroll") for (int _i = 0; _i < 2; ++_i) \
;         __builtin_amdgcn_global_load_lds((const unsigned*)((const char*)(gbase) + (voff)[_i]), (LAS unsigned*)(lds + (bufoff) + ldsw + _i * 8192), 16, 0, 0); } while (0)
; #define PG8_LDA(dst, b, h) do { _Pragma("unroll") for (int m = 0; m < 4; ++m) _Pragma("unroll") for (int k = 0; k < 2; ++k) dst[m][k] = *(const LAS bf16x8*)(lds + PG8_SA(b, h) + aoff + m * 2048 + k * 1024); } while (0)
; #define PG8_LDB(dst, b, h) do { _Pragma("unroll") for (int n = 0; n < 2; ++n) _Pragma("unroll") for (int k = 0; k < 2; ++k) dst[n][k] = *(const LAS bf16x8*)(lds + PG8_SB(b, h) + boff + n * 2048 + k * 1024); } while (0)
; #define PG8_WAIT_V(n) asm volatile("s_waitcnt vmcnt(" #n ")" ::: "memory")
; #define PG8_WAIT_L(n) asm volatile("s_waitcnt lgkmcnt(" #n ")" ::: "memory")
; #define PG8_BAR __builtin_amdgcn_s_barrier()
; #define PG8_SCHED __builtin_amdgcn_sched_barrier(0)
; template <class Epi>
; __device__ __forceinline__ void gemm_phase(LAS unsigned char* lds, const bf16_t* A, int lda, const bf16_t* Bt, int ldb, int M, int N, int K, int asel, const Epi& E, const int fixed_round = -1) {
;     ...
;             PG8_LDB(B0, 0, 0); PG8_SCHED; PG8_LDA(At, 0, 0); PG8_STAGE(PG8_SA(1, 1), a1 + hstepA, voffA);
;             PG8_WAIT_L(8); PG8_BAR; PG8_WAIT_L(0); PG8_MMA(0, 0, At, B0); PG8_BAR; PG8_SCHED;
;             PG8_LDB(B1, 0, 1); PG8_STAGE(PG8_SB(0, 0), b2, voffB);
;             PG8_BAR; PG8_WAIT_L(0); PG8_MMA(0, 1, At, B1); PG8_BAR;
;             PG8_LDA(At, 0, 1); PG8_STAGE(PG8_SA(0, 0), a2, voffA);
;             PG8_BAR; PG8_WAIT_L(0); PG8_MMA(1, 0, At, B0); PG8_BAR; PG8_SCHED;
;             PG8_STAGE(PG8_SB(0, 1), b2 + hstepB, voffB);
;             PG8_WAIT_V(6); PG8_BAR; PG8_MMA(1, 1, At, B1); PG8_BAR;
.LBB0_440:
	s_add_i32 s34, s34, 2
	s_add_u32 s16, s12, s14
	ds_read_b128 v[150:153], v141
	ds_read_b128 v[154:157], v141 offset:1024
	ds_read_b128 v[160:163], v141 offset:2048
	ds_read_b128 v[168:171], v141 offset:3072
	s_addc_u32 s17, s13, s15
	s_add_u32 s16, s16, 0x14500100
	s_addc_u32 s17, s17, 0
	s_add_u32 s46, s26, s14
	s_addc_u32 s47, s27, s15
	s_cmpk_eq_i32 s14, 0xf00
	s_cselect_b32 s19, s1, s17
	s_cselect_b32 s18, s0, s16
	s_cselect_b32 s17, s3, s47
	s_cselect_b32 s16, s2, s46
	s_mov_b32 m0, s36
	v_lshl_add_u64 v[146:147], v[136:137], 0, s[14:15]
	ds_read_b128 v[172:175], v142
	ds_read_b128 v[176:179], v142 offset:1024
	ds_read_b128 v[180:183], v142 offset:2048
	ds_read_b128 v[184:187], v142 offset:3072
	ds_read_b128 v[188:191], v142 offset:4096
	ds_read_b128 v[196:199], v142 offset:5120
	ds_read_b128 v[202:205], v142 offset:6144
	ds_read_b128 v[206:209], v142 offset:7168
	global_load_lds_dwordx4 v[146:147], off
	v_lshl_add_u64 v[146:147], v[138:139], 0, s[14:15]
	s_mov_b32 m0, s37
	s_nop 0
	global_load_lds_dwordx4 v[146:147], off
	s_waitcnt lgkmcnt(8)
	s_setprio 1
	s_barrier
	s_waitcnt lgkmcnt(0)
	v_mfma_f32_16x16x32_bf16 v[124:127], v[150:153], v[172:175], v[124:127]
	v_mfma_f32_16x16x32_bf16 v[120:123], v[160:163], v[172:175], v[120:123]
	v_mfma_f32_16x16x32_bf16 v[116:119], v[150:153], v[180:183], v[116:119]
	v_mfma_f32_16x16x32_bf16 v[112:115], v[160:163], v[180:183], v[112:115]
	v_mfma_f32_16x16x32_bf16 v[100:103], v[150:153], v[188:191], v[100:103]
	v_mfma_f32_16x16x32_bf16 v[92:95], v[160:163], v[188:191], v[92:95]
	v_mfma_f32_16x16x32_bf16 v[84:87], v[150:153], v[202:205], v[84:87]
	v_mfma_f32_16x16x32_bf16 v[76:79], v[160:163], v[202:205], v[76:79]
	v_mfma_f32_16x16x32_bf16 v[124:127], v[154:157], v[176:179], v[124:127]
	v_mfma_f32_16x16x32_bf16 v[120:123], v[168:171], v[176:179], v[120:123]
	v_mfma_f32_16x16x32_bf16 v[116:119], v[154:157], v[184:187], v[116:119]
	v_mfma_f32_16x16x32_bf16 v[112:115], v[168:171], v[184:187], v[112:115]
	v_mfma_f32_16x16x32_bf16 v[100:103], v[154:157], v[196:199], v[100:103]
	v_mfma_f32_16x16x32_bf16 v[92:95], v[168:171], v[196:199], v[92:95]
	v_mfma_f32_16x16x32_bf16 v[84:87], v[154:157], v[206:209], v[84:87]
	v_mfma_f32_16x16x32_bf16 v[76:79], v[168:171], v[206:209], v[76:79]
	s_barrier
	s_setprio 0
	s_mov_b32 m0, s38
	s_add_u32 s98, s16, s10
	s_addc_u32 s99, s17, s11
	ds_read_b128 v[210:213], v143
	ds_read_b128 v[214:217], v143 offset:1024
	ds_read_b128 v[218:221], v143 offset:2048
	ds_read_b128 v[222:225], v143 offset:3072
	global_load_lds_dwordx4 v130, s[16:17]
	s_mov_b32 m0, s39
	s_nop 0
	global_load_lds_dwordx4 v134, s[16:17]
	s_setprio 1
	s_barrier
	s_waitcnt lgkmcnt(0)
	v_mfma_f32_16x16x32_bf16 v[108:111], v[210:213], v[172:175], v[108:111]
	v_mfma_f32_16x16x32_bf16 v[104:107], v[218:221], v[172:175], v[104:107]
	v_mfma_f32_16x16x32_bf16 v[96:99], v[210:213], v[180:183], v[96:99]
	v_mfma_f32_16x16x32_bf16 v[88:91], v[218:221], v[180:183], v[88:91]
	v_mfma_f32_16x16x32_bf16 v[80:83], v[210:213], v[188:191], v[80:83]
	v_mfma_f32_16x16x32_bf16 v[72:75], v[218:221], v[188:191], v[72:75]
	v_mfma_f32_16x16x32_bf16 v[68:71], v[210:213], v[202:205], v[68:71]
	v_mfma_f32_16x16x32_bf16 v[64:67], v[218:221], v[202:205], v[64:67]
	v_mfma_f32_16x16x32_bf16 v[108:111], v[214:217], v[176:179], v[108:111]
	v_mfma_f32_16x16x32_bf16 v[104:107], v[222:225], v[176:179], v[104:107]
	v_mfma_f32_16x16x32_bf16 v[96:99], v[214:217], v[184:187], v[96:99]
	v_mfma_f32_16x16x32_bf16 v[88:91], v[222:225], v[184:187], v[88:91]
	v_mfma_f32_16x16x32_bf16 v[80:83], v[214:217], v[196:199], v[80:83]
	v_mfma_f32_16x16x32_bf16 v[72:75], v[222:225], v[196:199], v[72:75]
	v_mfma_f32_16x16x32_bf16 v[68:71], v[214:217], v[206:209], v[68:71]
	v_mfma_f32_16x16x32_bf16 v[64:67], v[222:225], v[206:209], v[64:67]
	s_barrier
	s_setprio 0
	s_mov_b32 m0, s25
	s_add_u32 s100, s18, s10
	s_addc_u32 s101, s19, s11
	ds_read_b128 v[172:175], v142 offset:16384
	ds_read_b128 v[176:179], v142 offset:17408
	ds_read_b128 v[180:183], v142 offset:18432
	ds_read_b128 v[184:187], v142 offset:19456
	ds_read_b128 v[188:191], v142 offset:20480
	ds_read_b128 v[196:199], v142 offset:21504
	ds_read_b128 v[202:205], v142 offset:22528
	ds_read_b128 v[206:209], v142 offset:23552
	global_load_lds_dwordx4 v128, s[18:19]
	s_mov_b32 m0, s28
	s_nop 0
	global_load_lds_dwordx4 v132, s[18:19]
	s_setprio 1
	s_barrier
	s_waitcnt lgkmcnt(0)
	v_mfma_f32_16x16x32_bf16 v[60:63], v[150:153], v[172:175], v[60:63]
	v_mfma_f32_16x16x32_bf16 v[56:59], v[160:163], v[172:175], v[56:59]
	v_mfma_f32_16x16x32_bf16 v[52:55], v[150:153], v[180:183], v[52:55]
	v_mfma_f32_16x16x32_bf16 v[44:47], v[160:163], v[180:183], v[44:47]
	v_mfma_f32_16x16x32_bf16 v[36:39], v[150:153], v[188:191], v[36:39]
	v_mfma_f32_16x16x32_bf16 v[28:31], v[160:163], v[188:191], v[28:31]
	v_mfma_f32_16x16x32_bf16 v[20:23], v[150:153], v[202:205], v[20:23]
	v_mfma_f32_16x16x32_bf16 v[12:15], v[160:163], v[202:205], v[12:15]
	v_mfma_f32_16x16x32_bf16 v[60:63], v[154:157], v[176:179], v[60:63]
	v_mfma_f32_16x16x32_bf16 v[56:59], v[168:171], v[176:179], v[56:59]
	v_mfma_f32_16x16x32_bf16 v[52:55], v[154:157], v[184:187], v[52:55]
	v_mfma_f32_16x16x32_bf16 v[44:47], v[168:171], v[184:187], v[44:47]
	v_mfma_f32_16x16x32_bf16 v[36:39], v[154:157], v[196:199], v[36:39]
	v_mfma_f32_16x16x32_bf16 v[28:31], v[168:171], v[196:199], v[28:31]
	v_mfma_f32_16x16x32_bf16 v[20:23], v[154:157], v[206:209], v[20:23]
	v_mfma_f32_16x16x32_bf16 v[12:15], v[168:171], v[206:209], v[12:15]
	s_barrier
	s_setprio 0
	s_add_u32 s46, s16, 0x80000
	s_addc_u32 s47, s17, 0
	s_mov_b32 m0, s40
	s_nop 0
	global_load_lds_dwordx4 v130, s[46:47]
	s_mov_b32 m0, s41
	s_nop 0
	global_load_lds_dwordx4 v134, s[46:47]
	s_waitcnt vmcnt(6)
	s_setprio 1
	s_barrier
; #define PG8_STAGE(bufoff, gbase, voff) do { _Pragma("unroll") for (int _i = 0; _i < 2; ++_i) \
;         __builtin_amdgcn_global_load_lds((const unsigned*)((const char*)(gbase) + (voff)[_i]), (LAS unsigned*)(lds + (bufoff) + ldsw + _i * 8192), 16, 0, 0); } while (0)
; #define PG8_LDA(dst, b, h) do { _Pragma("unroll") for (int m = 0; m < 4; ++m) _Pragma("unroll") for (int k = 0; k < 2; ++k) dst[m][k] = *(const LAS bf16x8*)(lds + PG8_SA(b, h) + aoff + m * 2048 + k * 1024); } while (0)
; #define PG8_LDB(dst, b, h) do { _Pragma("unroll") for (int n = 0; n < 2; ++n) _Pragma("unroll") for (int k = 0; k < 2; ++k) dst[n][k] = *(const LAS bf16x8*)(lds + PG8_SB(b, h) + boff + n * 2048 + k * 1024); } while (0)
; #define PG8_WAIT_V(n) asm volatile("s_waitcnt vmcnt(" #n ")" ::: "memory")
; #define PG8_WAIT_L(n) asm volatile("s_waitcnt lgkmcnt(" #n ")" ::: "memory")
; #define PG8_BAR __builtin_amdgcn_s_barrier()
; #define PG8_SCHED __builtin_amdgcn_sched_barrier(0)
; template <class Epi>
; __device__ __forceinline__ void gemm_phase(LAS unsigned char* lds, const bf16_t* A, int lda, const bf16_t* Bt, int ldb, int M, int N, int K, int asel, const Epi& E, const int fixed_round = -1) {
;     ...
;             PG8_WAIT_V(6); PG8_BAR; PG8_MMA(1, 1, At, B1); PG8_BAR;
;             PG8_LDB(B0, 1, 0); PG8_SCHED; PG8_LDA(At, 1, 0); PG8_STAGE(PG8_SA(0, 1), a2 + hstepA, voffA);
;             PG8_WAIT_L(8); PG8_BAR; PG8_WAIT_L(0); PG8_MMA(0, 0, At, B0); PG8_BAR; PG8_SCHED;
;             PG8_LDB(B1, 1, 1); PG8_STAGE(PG8_SB(1, 0), b3, voffB);
;             PG8_BAR; PG8_WAIT_L(0); PG8_MMA(0, 1, At, B1); PG8_BAR;
;             PG8_LDA(At, 1, 1); PG8_STAGE(PG8_SA(1, 0), a3, voffA);
;             PG8_BAR; PG8_WAIT_L(0); PG8_MMA(1, 0, At, B0); PG8_BAR; PG8_SCHED;
;             PG8_STAGE(PG8_SB(1, 1), b3 + hstepB, voffB);
;             PG8_WAIT_V(6); PG8_BAR; PG8_MMA(1, 1, At, B1); PG8_BAR;
	v_mfma_f32_16x16x32_bf16 v[48:51], v[210:213], v[172:175], v[48:51]
	v_mfma_f32_16x16x32_bf16 v[40:43], v[218:221], v[172:175], v[40:43]
	v_mfma_f32_16x16x32_bf16 v[32:35], v[210:213], v[180:183], v[32:35]
	v_mfma_f32_16x16x32_bf16 v[24:27], v[218:221], v[180:183], v[24:27]
	v_mfma_f32_16x16x32_bf16 v[16:19], v[210:213], v[188:191], v[16:19]
	v_mfma_f32_16x16x32_bf16 v[8:11], v[218:221], v[188:191], v[8:11]
	v_mfma_f32_16x16x32_bf16 v[4:7], v[210:213], v[202:205], v[4:7]
	v_mfma_f32_16x16x32_bf16 v[0:3], v[218:221], v[202:205], v[0:3]
	v_mfma_f32_16x16x32_bf16 v[48:51], v[214:217], v[176:179], v[48:51]
	v_mfma_f32_16x16x32_bf16 v[40:43], v[222:225], v[176:179], v[40:43]
	v_mfma_f32_16x16x32_bf16 v[32:35], v[214:217], v[184:187], v[32:35]
	v_mfma_f32_16x16x32_bf16 v[24:27], v[222:225], v[184:187], v[24:27]
	v_mfma_f32_16x16x32_bf16 v[16:19], v[214:217], v[196:199], v[16:19]
	v_mfma_f32_16x16x32_bf16 v[8:11], v[222:225], v[196:199], v[8:11]
	v_mfma_f32_16x16x32_bf16 v[4:7], v[214:217], v[206:209], v[4:7]
	v_mfma_f32_16x16x32_bf16 v[0:3], v[222:225], v[206:209], v[0:3]
	s_barrier
	s_setprio 0
	ds_read_b128 v[150:153], v144
	ds_read_b128 v[154:157], v144 offset:1024
	ds_read_b128 v[160:163], v144 offset:2048
	ds_read_b128 v[168:171], v144 offset:3072
	s_add_u32 s18, s18, 0x80000
	s_addc_u32 s19, s19, 0
	s_mov_b32 m0, s29
	ds_read_b128 v[172:175], v142 offset:32768
	ds_read_b128 v[176:179], v142 offset:33792
	ds_read_b128 v[180:183], v142 offset:34816
	ds_read_b128 v[184:187], v142 offset:35840
	ds_read_b128 v[188:191], v142 offset:36864
	ds_read_b128 v[196:199], v142 offset:37888
	ds_read_b128 v[202:205], v142 offset:38912
	ds_read_b128 v[206:209], v142 offset:39936
	global_load_lds_dwordx4 v128, s[18:19]
	s_mov_b32 m0, s30
	s_nop 0
	global_load_lds_dwordx4 v132, s[18:19]
	s_waitcnt lgkmcnt(8)
	s_setprio 1
	s_barrier
	s_waitcnt lgkmcnt(0)
	v_mfma_f32_16x16x32_bf16 v[124:127], v[150:153], v[172:175], v[124:127]
	v_mfma_f32_16x16x32_bf16 v[120:123], v[160:163], v[172:175], v[120:123]
	v_mfma_f32_16x16x32_bf16 v[116:119], v[150:153], v[180:183], v[116:119]
	v_mfma_f32_16x16x32_bf16 v[112:115], v[160:163], v[180:183], v[112:115]
	v_mfma_f32_16x16x32_bf16 v[100:103], v[150:153], v[188:191], v[100:103]
	v_mfma_f32_16x16x32_bf16 v[92:95], v[160:163], v[188:191], v[92:95]
	v_mfma_f32_16x16x32_bf16 v[84:87], v[150:153], v[202:205], v[84:87]
	v_mfma_f32_16x16x32_bf16 v[76:79], v[160:163], v[202:205], v[76:79]
	v_mfma_f32_16x16x32_bf16 v[124:127], v[154:157], v[176:179], v[124:127]
	v_mfma_f32_16x16x32_bf16 v[120:123], v[168:171], v[176:179], v[120:123]
	v_mfma_f32_16x16x32_bf16 v[116:119], v[154:157], v[184:187], v[116:119]
	v_mfma_f32_16x16x32_bf16 v[112:115], v[168:171], v[184:187], v[112:115]
	v_mfma_f32_16x16x32_bf16 v[100:103], v[154:157], v[196:199], v[100:103]
	v_mfma_f32_16x16x32_bf16 v[92:95], v[168:171], v[196:199], v[92:95]
	v_mfma_f32_16x16x32_bf16 v[84:87], v[154:157], v[206:209], v[84:87]
	v_mfma_f32_16x16x32_bf16 v[76:79], v[168:171], v[206:209], v[76:79]
	s_barrier
	s_setprio 0
	s_mov_b32 m0, s42
	ds_read_b128 v[210:213], v145
	ds_read_b128 v[214:217], v145 offset:1024
	ds_read_b128 v[218:221], v145 offset:2048
	ds_read_b128 v[222:225], v145 offset:3072
	global_load_lds_dwordx4 v130, s[98:99]
	s_mov_b32 m0, s43
	s_nop 0
	global_load_lds_dwordx4 v134, s[98:99]
	s_setprio 1
	s_barrier
	s_waitcnt lgkmcnt(0)
	v_mfma_f32_16x16x32_bf16 v[108:111], v[210:213], v[172:175], v[108:111]
	v_mfma_f32_16x16x32_bf16 v[104:107], v[218:221], v[172:175], v[104:107]
	v_mfma_f32_16x16x32_bf16 v[96:99], v[210:213], v[180:183], v[96:99]
	v_mfma_f32_16x16x32_bf16 v[88:91], v[218:221], v[180:183], v[88:91]
	v_mfma_f32_16x16x32_bf16 v[80:83], v[210:213], v[188:191], v[80:83]
	v_mfma_f32_16x16x32_bf16 v[72:75], v[218:221], v[188:191], v[72:75]
	v_mfma_f32_16x16x32_bf16 v[68:71], v[210:213], v[202:205], v[68:71]
	v_mfma_f32_16x16x32_bf16 v[64:67], v[218:221], v[202:205], v[64:67]
	v_mfma_f32_16x16x32_bf16 v[108:111], v[214:217], v[176:179], v[108:111]
	v_mfma_f32_16x16x32_bf16 v[104:107], v[222:225], v[176:179], v[104:107]
	v_mfma_f32_16x16x32_bf16 v[96:99], v[214:217], v[184:187], v[96:99]
	v_mfma_f32_16x16x32_bf16 v[88:91], v[222:225], v[184:187], v[88:91]
	v_mfma_f32_16x16x32_bf16 v[80:83], v[214:217], v[196:199], v[80:83]
	v_mfma_f32_16x16x32_bf16 v[72:75], v[222:225], v[196:199], v[72:75]
	v_mfma_f32_16x16x32_bf16 v[68:71], v[214:217], v[206:209], v[68:71]
	v_mfma_f32_16x16x32_bf16 v[64:67], v[222:225], v[206:209], v[64:67]
	s_barrier
	s_setprio 0
	s_mov_b32 m0, s31
	ds_read_b128 v[172:175], v142 offset:49152
	ds_read_b128 v[176:179], v142 offset:50176
	ds_read_b128 v[180:183], v142 offset:51200
	ds_read_b128 v[184:187], v142 offset:52224
	ds_read_b128 v[188:191], v142 offset:53248
	ds_read_b128 v[196:199], v142 offset:54272
	ds_read_b128 v[202:205], v142 offset:55296
	ds_read_b128 v[206:209], v142 offset:56320
	global_load_lds_dwordx4 v128, s[100:101]
	s_mov_b32 m0, s33
	s_nop 0
	global_load_lds_dwordx4 v132, s[100:101]
	s_setprio 1
	s_barrier
	s_waitcnt lgkmcnt(0)
	v_mfma_f32_16x16x32_bf16 v[60:63], v[150:153], v[172:175], v[60:63]
	v_mfma_f32_16x16x32_bf16 v[56:59], v[160:163], v[172:175], v[56:59]
	v_mfma_f32_16x16x32_bf16 v[52:55], v[150:153], v[180:183], v[52:55]
	v_mfma_f32_16x16x32_bf16 v[44:47], v[160:163], v[180:183], v[44:47]
	v_mfma_f32_16x16x32_bf16 v[36:39], v[150:153], v[188:191], v[36:39]
	v_mfma_f32_16x16x32_bf16 v[28:31], v[160:163], v[188:191], v[28:31]
	v_mfma_f32_16x16x32_bf16 v[20:23], v[150:153], v[202:205], v[20:23]
	v_mfma_f32_16x16x32_bf16 v[12:15], v[160:163], v[202:205], v[12:15]
	v_mfma_f32_16x16x32_bf16 v[60:63], v[154:157], v[176:179], v[60:63]
	v_mfma_f32_16x16x32_bf16 v[56:59], v[168:171], v[176:179], v[56:59]
	v_mfma_f32_16x16x32_bf16 v[52:55], v[154:157], v[184:187], v[52:55]
	v_mfma_f32_16x16x32_bf16 v[44:47], v[168:171], v[184:187], v[44:47]
	v_mfma_f32_16x16x32_bf16 v[36:39], v[154:157], v[196:199], v[36:39]
	v_mfma_f32_16x16x32_bf16 v[28:31], v[168:171], v[196:199], v[28:31]
	v_mfma_f32_16x16x32_bf16 v[20:23], v[154:157], v[206:209], v[20:23]
	v_mfma_f32_16x16x32_bf16 v[12:15], v[168:171], v[206:209], v[12:15]
	s_barrier
; #define LAS __attribute__((address_space(3)))
; #define PG8_STAGE(bufoff, gbase, voff) do { _Pragma("unroll") for (int _i = 0; _i < 2; ++_i) \
;         __builtin_amdgcn_global_load_lds((const unsigned*)((const char*)(gbase) + (voff)[_i]), (LAS unsigned*)(lds + (bufoff) + ldsw + _i * 8192), 16, 0, 0); } while (0)
; #define PG8_LDA(dst, b, h) do { _Pragma("unroll") for (int m = 0; m < 4; ++m) _Pragma("unroll") for (int k = 0; k < 2; ++k) dst[m][k] = *(const LAS bf16x8*)(lds + PG8_SA(b, h) + aoff + m * 2048 + k * 1024); } while (0)
; #define PG8_LDB(dst, b, h) do { _Pragma("unroll") for (int n = 0; n < 2; ++n) _Pragma("unroll") for (int k = 0; k < 2; ++k) dst[n][k] = *(const LAS bf16x8*)(lds + PG8_SB(b, h) + boff + n * 2048 + k * 1024); } while (0)
; #define PG8_WAIT_V(n) asm volatile("s_waitcnt vmcnt(" #n ")" ::: "memory")
; #define PG8_WAIT_L(n) asm volatile("s_waitcnt lgkmcnt(" #n ")" ::: "memory")
; template <class Epi>
; __device__ __forceinline__ void gemm_phase(LAS unsigned char* lds, const bf16_t* A, int lda, const bf16_t* Bt, int ldb, int M, int N, int K, int asel, const Epi& E, const int fixed_round = -1) {
;     ...
;             PG8_WAIT_V(6); PG8_BAR; PG8_MMA(1, 1, At, B1); PG8_BAR;
;             PG8_LDB(B0, 1, 0); PG8_SCHED; PG8_LDA(At, 1, 0); PG8_STAGE(PG8_SA(0, 1), a2 + hstepA, voffA);
;             PG8_WAIT_L(8); PG8_BAR; PG8_WAIT_L(0); PG8_MMA(0, 0, At, B0); PG8_BAR; PG8_SCHED;
;             PG8_LDB(B1, 1, 1); PG8_STAGE(PG8_SB(1, 0), b3, voffB);
;             PG8_BAR; PG8_WAIT_L(0); PG8_MMA(0, 1, At, B1); PG8_BAR;
;             PG8_LDA(At, 1, 1); PG8_STAGE(PG8_SA(1, 0), a3, voffA);
;             PG8_BAR; PG8_WAIT_L(0); PG8_MMA(1, 0, At, B0); PG8_BAR; PG8_SCHED;
;             PG8_STAGE(PG8_SB(1, 1), b3 + hstepB, voffB);
;             PG8_WAIT_V(6); PG8_BAR; PG8_MMA(1, 1, At, B1); PG8_BAR;
;             if constexpr (Epi::HEADSCALE) {
;                 if (t & 2) {
;                     const LAS float* rt = (const LAS float*)(lds + L_RT) + (t >> 2);
; #pragma unroll
;                     for (int ai = 0; ai < 2; ++ai)
; #pragma unroll
;                         for (int m = 0; m < 4; ++m) { const float f = rt[(ai * HALF + wr * 64 + m * 16 + fr) * 8];
; #pragma unroll
;                             for (int bj = 0; bj < 2; ++bj)
; #pragma unroll
;                                 for (int n = 0; n < 2; ++n) acc[ai][bj][m][n] *= f; }
;                 }
	s_setprio 0
	s_add_u32 s16, s16, 0x80080
	s_addc_u32 s17, s17, 0
	s_mov_b32 m0, s44
	s_nop 0
	global_load_lds_dwordx4 v130, s[16:17]
	s_mov_b32 m0, s45
	s_nop 0
	global_load_lds_dwordx4 v134, s[16:17]
	s_waitcnt vmcnt(6)
	s_setprio 1
	s_barrier
	v_mfma_f32_16x16x32_bf16 v[48:51], v[210:213], v[172:175], v[48:51]
	v_mfma_f32_16x16x32_bf16 v[40:43], v[218:221], v[172:175], v[40:43]
	v_mfma_f32_16x16x32_bf16 v[32:35], v[210:213], v[180:183], v[32:35]
	v_mfma_f32_16x16x32_bf16 v[24:27], v[218:221], v[180:183], v[24:27]
	v_mfma_f32_16x16x32_bf16 v[16:19], v[210:213], v[188:191], v[16:19]
	v_mfma_f32_16x16x32_bf16 v[8:11], v[218:221], v[188:191], v[8:11]
	v_mfma_f32_16x16x32_bf16 v[4:7], v[210:213], v[202:205], v[4:7]
	v_mfma_f32_16x16x32_bf16 v[0:3], v[218:221], v[202:205], v[0:3]
	v_mfma_f32_16x16x32_bf16 v[48:51], v[214:217], v[176:179], v[48:51]
	v_mfma_f32_16x16x32_bf16 v[40:43], v[222:225], v[176:179], v[40:43]
	v_mfma_f32_16x16x32_bf16 v[32:35], v[214:217], v[184:187], v[32:35]
	v_mfma_f32_16x16x32_bf16 v[24:27], v[222:225], v[184:187], v[24:27]
	v_mfma_f32_16x16x32_bf16 v[16:19], v[214:217], v[196:199], v[16:19]
	v_mfma_f32_16x16x32_bf16 v[8:11], v[222:225], v[196:199], v[8:11]
	v_mfma_f32_16x16x32_bf16 v[4:7], v[214:217], v[206:209], v[4:7]
	v_mfma_f32_16x16x32_bf16 v[0:3], v[222:225], v[206:209], v[0:3]
	s_setprio 0
	s_bitcmp0_b32 s34, 1
	s_barrier
	s_cbranch_scc1 .LBB0_439
	s_and_b32 s16, s34, -4
	v_add_u32_e32 v148, s16, v140
	ds_read2st64_b32 v[146:147], v148 offset1:2
	ds_read2st64_b32 v[150:151], v148 offset0:4 offset1:6
	s_waitcnt lgkmcnt(0)
	v_pk_mul_f32 v[126:127], v[126:127], v[146:147] op_sel_hi:[1,0]
	v_pk_mul_f32 v[124:125], v[124:125], v[146:147] op_sel_hi:[1,0]
	v_pk_mul_f32 v[122:123], v[122:123], v[146:147] op_sel_hi:[1,0]
	v_pk_mul_f32 v[120:121], v[120:121], v[146:147] op_sel_hi:[1,0]
	v_pk_mul_f32 v[110:111], v[110:111], v[146:147] op_sel_hi:[1,0]
	v_pk_mul_f32 v[108:109], v[108:109], v[146:147] op_sel_hi:[1,0]
	v_pk_mul_f32 v[106:107], v[106:107], v[146:147] op_sel_hi:[1,0]
	v_pk_mul_f32 v[104:105], v[104:105], v[146:147] op_sel_hi:[1,0]
	v_mov_b32_e32 v146, v147
	v_pk_mul_f32 v[118:119], v[118:119], v[146:147] op_sel_hi:[1,0]
	v_pk_mul_f32 v[116:117], v[116:117], v[146:147] op_sel_hi:[1,0]
	v_pk_mul_f32 v[114:115], v[114:115], v[146:147] op_sel_hi:[1,0]
	v_pk_mul_f32 v[112:113], v[112:113], v[146:147] op_sel_hi:[1,0]
	v_pk_mul_f32 v[98:99], v[98:99], v[146:147] op_sel_hi:[1,0]
	v_pk_mul_f32 v[96:97], v[96:97], v[146:147] op_sel_hi:[1,0]
	v_pk_mul_f32 v[90:91], v[90:91], v[146:147] op_sel_hi:[1,0]
	v_pk_mul_f32 v[88:89], v[88:89], v[146:147] op_sel_hi:[1,0]
	v_pk_mul_f32 v[102:103], v[102:103], v[150:151] op_sel_hi:[1,0]
	v_pk_mul_f32 v[100:101], v[100:101], v[150:151] op_sel_hi:[1,0]
	v_pk_mul_f32 v[94:95], v[94:95], v[150:151] op_sel_hi:[1,0]
	v_pk_mul_f32 v[92:93], v[92:93], v[150:151] op_sel_hi:[1,0]
	v_pk_mul_f32 v[82:83], v[82:83], v[150:151] op_sel_hi:[1,0]
	v_pk_mul_f32 v[80:81], v[80:81], v[150:151] op_sel_hi:[1,0]
	v_pk_mul_f32 v[74:75], v[74:75], v[150:151] op_sel_hi:[1,0]
	v_pk_mul_f32 v[72:73], v[72:73], v[150:151] op_sel_hi:[1,0]
	v_mov_b32_e32 v146, v151
	ds_read2st64_b32 v[150:151], v148 offset0:16 offset1:18
	v_pk_mul_f32 v[86:87], v[86:87], v[146:147] op_sel_hi:[1,0]
	v_pk_mul_f32 v[84:85], v[84:85], v[146:147] op_sel_hi:[1,0]
	v_pk_mul_f32 v[78:79], v[78:79], v[146:147] op_sel_hi:[1,0]
	v_pk_mul_f32 v[76:77], v[76:77], v[146:147] op_sel_hi:[1,0]
	v_pk_mul_f32 v[70:71], v[70:71], v[146:147] op_sel_hi:[1,0]
	v_pk_mul_f32 v[68:69], v[68:69], v[146:147] op_sel_hi:[1,0]
	v_pk_mul_f32 v[66:67], v[66:67], v[146:147] op_sel_hi:[1,0]
	v_pk_mul_f32 v[64:65], v[64:65], v[146:147] op_sel_hi:[1,0]
	s_waitcnt lgkmcnt(0)
	v_pk_mul_f32 v[62:63], v[62:63], v[150:151] op_sel_hi:[1,0]
	v_pk_mul_f32 v[60:61], v[60:61], v[150:151] op_sel_hi:[1,0]
	v_pk_mul_f32 v[58:59], v[58:59], v[150:151] op_sel_hi:[1,0]
	v_pk_mul_f32 v[56:57], v[56:57], v[150:151] op_sel_hi:[1,0]
	v_pk_mul_f32 v[50:51], v[50:51], v[150:151] op_sel_hi:[1,0]
	v_pk_mul_f32 v[48:49], v[48:49], v[150:151] op_sel_hi:[1,0]
	v_pk_mul_f32 v[42:43], v[42:43], v[150:151] op_sel_hi:[1,0]
	v_pk_mul_f32 v[40:41], v[40:41], v[150:151] op_sel_hi:[1,0]
	v_mov_b32_e32 v146, v151
	ds_read2st64_b32 v[150:151], v148 offset0:20 offset1:22
	v_pk_mul_f32 v[54:55], v[54:55], v[146:147] op_sel_hi:[1,0]
	v_pk_mul_f32 v[52:53], v[52:53], v[146:147] op_sel_hi:[1,0]
	v_pk_mul_f32 v[46:47], v[46:47], v[146:147] op_sel_hi:[1,0]
	v_pk_mul_f32 v[44:45], v[44:45], v[146:147] op_sel_hi:[1,0]
	v_pk_mul_f32 v[34:35], v[34:35], v[146:147] op_sel_hi:[1,0]
	v_pk_mul_f32 v[32:33], v[32:33], v[146:147] op_sel_hi:[1,0]
	v_pk_mul_f32 v[26:27], v[26:27], v[146:147] op_sel_hi:[1,0]
	v_pk_mul_f32 v[24:25], v[24:25], v[146:147] op_sel_hi:[1,0]
	s_waitcnt lgkmcnt(0)
	v_mov_b32_e32 v146, v151
	v_pk_mul_f32 v[38:39], v[38:39], v[150:151] op_sel_hi:[1,0]
	v_pk_mul_f32 v[36:37], v[36:37], v[150:151] op_sel_hi:[1,0]
	v_pk_mul_f32 v[30:31], v[30:31], v[150:151] op_sel_hi:[1,0]
	v_pk_mul_f32 v[28:29], v[28:29], v[150:151] op_sel_hi:[1,0]
	v_pk_mul_f32 v[18:19], v[18:19], v[150:151] op_sel_hi:[1,0]
	v_pk_mul_f32 v[16:17], v[16:17], v[150:151] op_sel_hi:[1,0]
	v_pk_mul_f32 v[10:11], v[10:11], v[150:151] op_sel_hi:[1,0]
	v_pk_mul_f32 v[8:9], v[8:9], v[150:151] op_sel_hi:[1,0]
	v_pk_mul_f32 v[22:23], v[22:23], v[146:147] op_sel_hi:[1,0]
	v_pk_mul_f32 v[20:21], v[20:21], v[146:147] op_sel_hi:[1,0]
	v_pk_mul_f32 v[14:15], v[14:15], v[146:147] op_sel_hi:[1,0]
	v_pk_mul_f32 v[12:13], v[12:13], v[146:147] op_sel_hi:[1,0]
	v_pk_mul_f32 v[6:7], v[6:7], v[146:147] op_sel_hi:[1,0]
	v_pk_mul_f32 v[4:5], v[4:5], v[146:147] op_sel_hi:[1,0]
	v_pk_mul_f32 v[2:3], v[2:3], v[146:147] op_sel_hi:[1,0]
	v_pk_mul_f32 v[0:1], v[0:1], v[146:147] op_sel_hi:[1,0]
	s_branch .LBB0_439

; #define PG8_STAGE(bufoff, gbase, voff) do { _Pragma("unroll") for (int _i = 0; _i < 2; ++_i) \
;         __builtin_amdgcn_global_load_lds((const unsigned*)((const char*)(gbase) + (voff)[_i]), (LAS unsigned*)(lds + (bufoff) + ldsw + _i * 8192), 16, 0, 0); } while (0)
; #define PG8_LDA(dst, b, h) do { _Pragma("unroll") for (int m = 0; m < 4; ++m) _Pragma("unroll") for (int k = 0; k < 2; ++k) dst[m][k] = *(const LAS bf16x8*)(lds + PG8_SA(b, h) + aoff + m * 2048 + k * 1024); } while (0)
; #define PG8_LDB(dst, b, h) do { _Pragma("unroll") for (int n = 0; n < 2; ++n) _Pragma("unroll") for (int k = 0; k < 2; ++k) dst[n][k] = *(const LAS bf16x8*)(lds + PG8_SB(b, h) + boff + n * 2048 + k * 1024); } while (0)
; #define PG8_WAIT_V(n) asm volatile("s_waitcnt vmcnt(" #n ")" ::: "memory")
; #define PG8_WAIT_L(n) asm volatile("s_waitcnt lgkmcnt(" #n ")" ::: "memory")
; #define PG8_BAR __builtin_amdgcn_s_barrier()
; #define PG8_SCHED __builtin_amdgcn_sched_barrier(0)
; template <class Epi>
; __device__ __forceinline__ void gemm_phase(LAS unsigned char* lds, const bf16_t* A, int lda, const bf16_t* Bt, int ldb, int M, int N, int K, int asel, const Epi& E, const int fixed_round = -1) {
;     ...
;             const bool last = (t == nt - 2);
;             const char* a1 = cA + (size_t)(t + 1) * kstep;
;             const char* a2 = last ? nA : cA + (size_t)(t + 2) * kstep; const char* b2 = last ? nB : cB + (size_t)(t + 2) * kstep;
;             const char* a3 = a2 + kstep; const char* b3 = b2 + kstep;
;             PG8_LDB(B0, 0, 0); PG8_SCHED; PG8_LDA(At, 0, 0); PG8_STAGE(PG8_SA(1, 1), a1 + hstepA, voffA);
;             PG8_WAIT_L(8); PG8_BAR; PG8_WAIT_L(0); PG8_MMA(0, 0, At, B0); PG8_BAR; PG8_SCHED;
;             PG8_LDB(B1, 0, 1); PG8_STAGE(PG8_SB(0, 0), b2, voffB);
;             PG8_BAR; PG8_WAIT_L(0); PG8_MMA(0, 1, At, B1); PG8_BAR;
;             PG8_LDA(At, 0, 1); PG8_STAGE(PG8_SA(0, 0), a2, voffA);
;             PG8_BAR; PG8_WAIT_L(0); PG8_MMA(1, 0, At, B0); PG8_BAR; PG8_SCHED;
;             PG8_STAGE(PG8_SB(0, 1), b2 + hstepB, voffB);
;             PG8_WAIT_V(6); PG8_BAR; PG8_MMA(1, 1, At, B1); PG8_BAR;
.LBB0_487:
	s_add_i32 s35, s35, 2
	s_add_u32 s18, s6, s14
	ds_read_b128 v[150:153], v141
	ds_read_b128 v[154:157], v141 offset:1024
	ds_read_b128 v[160:163], v141 offset:2048
	ds_read_b128 v[168:171], v141 offset:3072
	s_addc_u32 s19, s7, s15
	s_add_u32 s18, s18, 0x14500100
	s_addc_u32 s19, s19, 0
	s_add_u32 s59, s26, s14
	s_addc_u32 s60, s27, s15
	s_cmpk_eq_i32 s14, 0xf00
	s_cselect_b32 s21, s1, s19
	s_cselect_b32 s20, s0, s18
	s_cselect_b32 s19, s3, s60
	s_cselect_b32 s18, s2, s59
	s_mov_b32 m0, s49
	v_lshl_add_u64 v[146:147], v[136:137], 0, s[14:15]
	ds_read_b128 v[172:175], v142
	ds_read_b128 v[176:179], v142 offset:1024
	ds_read_b128 v[180:183], v142 offset:2048
	ds_read_b128 v[184:187], v142 offset:3072
	ds_read_b128 v[188:191], v142 offset:4096
	ds_read_b128 v[192:195], v142 offset:5120
	ds_read_b128 v[196:199], v142 offset:6144
	ds_read_b128 v[202:205], v142 offset:7168
	global_load_lds_dwordx4 v[146:147], off
	v_lshl_add_u64 v[146:147], v[138:139], 0, s[14:15]
	s_mov_b32 m0, s50
	s_nop 0
	global_load_lds_dwordx4 v[146:147], off
	s_waitcnt lgkmcnt(8)
	s_setprio 1
	s_barrier
	s_waitcnt lgkmcnt(0)
	v_mfma_f32_16x16x32_bf16 v[124:127], v[150:153], v[172:175], v[124:127]
	v_mfma_f32_16x16x32_bf16 v[120:123], v[160:163], v[172:175], v[120:123]
	v_mfma_f32_16x16x32_bf16 v[116:119], v[150:153], v[180:183], v[116:119]
	v_mfma_f32_16x16x32_bf16 v[112:115], v[160:163], v[180:183], v[112:115]
	v_mfma_f32_16x16x32_bf16 v[100:103], v[150:153], v[188:191], v[100:103]
	v_mfma_f32_16x16x32_bf16 v[92:95], v[160:163], v[188:191], v[92:95]
	v_mfma_f32_16x16x32_bf16 v[84:87], v[150:153], v[196:199], v[84:87]
	v_mfma_f32_16x16x32_bf16 v[76:79], v[160:163], v[196:199], v[76:79]
	v_mfma_f32_16x16x32_bf16 v[124:127], v[154:157], v[176:179], v[124:127]
	v_mfma_f32_16x16x32_bf16 v[120:123], v[168:171], v[176:179], v[120:123]
	v_mfma_f32_16x16x32_bf16 v[116:119], v[154:157], v[184:187], v[116:119]
	v_mfma_f32_16x16x32_bf16 v[112:115], v[168:171], v[184:187], v[112:115]
	v_mfma_f32_16x16x32_bf16 v[100:103], v[154:157], v[192:195], v[100:103]
	v_mfma_f32_16x16x32_bf16 v[92:95], v[168:171], v[192:195], v[92:95]
	v_mfma_f32_16x16x32_bf16 v[84:87], v[154:157], v[202:205], v[84:87]
	v_mfma_f32_16x16x32_bf16 v[76:79], v[168:171], v[202:205], v[76:79]
	s_barrier
	s_setprio 0
	s_mov_b32 m0, s51
	s_add_u32 s98, s18, s4
	s_addc_u32 s99, s19, s5
	ds_read_b128 v[206:209], v143
	ds_read_b128 v[210:213], v143 offset:1024
	ds_read_b128 v[214:217], v143 offset:2048
	ds_read_b128 v[218:221], v143 offset:3072
	global_load_lds_dwordx4 v130, s[18:19]
	s_mov_b32 m0, s52
	s_nop 0
	global_load_lds_dwordx4 v134, s[18:19]
	s_setprio 1
	s_barrier
	s_waitcnt lgkmcnt(0)
	v_mfma_f32_16x16x32_bf16 v[108:111], v[206:209], v[172:175], v[108:111]
	v_mfma_f32_16x16x32_bf16 v[104:107], v[214:217], v[172:175], v[104:107]
	v_mfma_f32_16x16x32_bf16 v[96:99], v[206:209], v[180:183], v[96:99]
	v_mfma_f32_16x16x32_bf16 v[88:91], v[214:217], v[180:183], v[88:91]
	v_mfma_f32_16x16x32_bf16 v[80:83], v[206:209], v[188:191], v[80:83]
	v_mfma_f32_16x16x32_bf16 v[72:75], v[214:217], v[188:191], v[72:75]
	v_mfma_f32_16x16x32_bf16 v[68:71], v[206:209], v[196:199], v[68:71]
	v_mfma_f32_16x16x32_bf16 v[64:67], v[214:217], v[196:199], v[64:67]
	v_mfma_f32_16x16x32_bf16 v[108:111], v[210:213], v[176:179], v[108:111]
	v_mfma_f32_16x16x32_bf16 v[104:107], v[218:221], v[176:179], v[104:107]
	v_mfma_f32_16x16x32_bf16 v[96:99], v[210:213], v[184:187], v[96:99]
	v_mfma_f32_16x16x32_bf16 v[88:91], v[218:221], v[184:187], v[88:91]
	v_mfma_f32_16x16x32_bf16 v[80:83], v[210:213], v[192:195], v[80:83]
	v_mfma_f32_16x16x32_bf16 v[72:75], v[218:221], v[192:195], v[72:75]
	v_mfma_f32_16x16x32_bf16 v[68:71], v[210:213], v[202:205], v[68:71]
	v_mfma_f32_16x16x32_bf16 v[64:67], v[218:221], v[202:205], v[64:67]
	s_barrier
	s_setprio 0
	s_mov_b32 m0, s43
	s_add_u32 s100, s20, s4
	s_addc_u32 s101, s21, s5
	ds_read_b128 v[172:175], v142 offset:16384
	ds_read_b128 v[176:179], v142 offset:17408
	ds_read_b128 v[180:183], v142 offset:18432
	ds_read_b128 v[184:187], v142 offset:19456
	ds_read_b128 v[188:191], v142 offset:20480
	ds_read_b128 v[192:195], v142 offset:21504
	ds_read_b128 v[196:199], v142 offset:22528
	ds_read_b128 v[202:205], v142 offset:23552
	global_load_lds_dwordx4 v128, s[20:21]
	s_mov_b32 m0, s44
	s_nop 0
	global_load_lds_dwordx4 v132, s[20:21]
	s_setprio 1
	s_barrier
	s_waitcnt lgkmcnt(0)
	v_mfma_f32_16x16x32_bf16 v[60:63], v[150:153], v[172:175], v[60:63]
	v_mfma_f32_16x16x32_bf16 v[56:59], v[160:163], v[172:175], v[56:59]
	v_mfma_f32_16x16x32_bf16 v[52:55], v[150:153], v[180:183], v[52:55]
	v_mfma_f32_16x16x32_bf16 v[44:47], v[160:163], v[180:183], v[44:47]
	v_mfma_f32_16x16x32_bf16 v[36:39], v[150:153], v[188:191], v[36:39]
	v_mfma_f32_16x16x32_bf16 v[28:31], v[160:163], v[188:191], v[28:31]
	v_mfma_f32_16x16x32_bf16 v[20:23], v[150:153], v[196:199], v[20:23]
	v_mfma_f32_16x16x32_bf16 v[12:15], v[160:163], v[196:199], v[12:15]
	v_mfma_f32_16x16x32_bf16 v[60:63], v[154:157], v[176:179], v[60:63]
	v_mfma_f32_16x16x32_bf16 v[56:59], v[168:171], v[176:179], v[56:59]
	v_mfma_f32_16x16x32_bf16 v[52:55], v[154:157], v[184:187], v[52:55]
	v_mfma_f32_16x16x32_bf16 v[44:47], v[168:171], v[184:187], v[44:47]
	v_mfma_f32_16x16x32_bf16 v[36:39], v[154:157], v[192:195], v[36:39]
	v_mfma_f32_16x16x32_bf16 v[28:31], v[168:171], v[192:195], v[28:31]
	v_mfma_f32_16x16x32_bf16 v[20:23], v[154:157], v[202:205], v[20:23]
	v_mfma_f32_16x16x32_bf16 v[12:15], v[168:171], v[202:205], v[12:15]
	s_barrier
	s_setprio 0
	s_add_u32 s60, s18, 0x80000
	s_addc_u32 s61, s19, 0
	s_mov_b32 m0, s53
	s_nop 0
	global_load_lds_dwordx4 v130, s[60:61]
	s_mov_b32 m0, s54
	s_nop 0
	global_load_lds_dwordx4 v134, s[60:61]
	s_waitcnt vmcnt(6)
	s_setprio 1
	s_barrier
; #define PG8_STAGE(bufoff, gbase, voff) do { _Pragma("unroll") for (int _i = 0; _i < 2; ++_i) \
;         __builtin_amdgcn_global_load_lds((const unsigned*)((const char*)(gbase) + (voff)[_i]), (LAS unsigned*)(lds + (bufoff) + ldsw + _i * 8192), 16, 0, 0); } while (0)
; #define PG8_LDA(dst, b, h) do { _Pragma("unroll") for (int m = 0; m < 4; ++m) _Pragma("unroll") for (int k = 0; k < 2; ++k) dst[m][k] = *(const LAS bf16x8*)(lds + PG8_SA(b, h) + aoff + m * 2048 + k * 1024); } while (0)
; #define PG8_LDB(dst, b, h) do { _Pragma("unroll") for (int n = 0; n < 2; ++n) _Pragma("unroll") for (int k = 0; k < 2; ++k) dst[n][k] = *(const LAS bf16x8*)(lds + PG8_SB(b, h) + boff + n * 2048 + k * 1024); } while (0)
; #define PG8_WAIT_V(n) asm volatile("s_waitcnt vmcnt(" #n ")" ::: "memory")
; #define PG8_WAIT_L(n) asm volatile("s_waitcnt lgkmcnt(" #n ")" ::: "memory")
; #define PG8_BAR __builtin_amdgcn_s_barrier()
; #define PG8_SCHED __builtin_amdgcn_sched_barrier(0)
; template <class Epi>
; __device__ __forceinline__ void gemm_phase(LAS unsigned char* lds, const bf16_t* A, int lda, const bf16_t* Bt, int ldb, int M, int N, int K, int asel, const Epi& E, const int fixed_round = -1) {
;     ...
;             PG8_WAIT_V(6); PG8_BAR; PG8_MMA(1, 1, At, B1); PG8_BAR;
;             PG8_LDB(B0, 1, 0); PG8_SCHED; PG8_LDA(At, 1, 0); PG8_STAGE(PG8_SA(0, 1), a2 + hstepA, voffA);
;             PG8_WAIT_L(8); PG8_BAR; PG8_WAIT_L(0); PG8_MMA(0, 0, At, B0); PG8_BAR; PG8_SCHED;
;             PG8_LDB(B1, 1, 1); PG8_STAGE(PG8_SB(1, 0), b3, voffB);
;             PG8_BAR; PG8_WAIT_L(0); PG8_MMA(0, 1, At, B1); PG8_BAR;
;             PG8_LDA(At, 1, 1); PG8_STAGE(PG8_SA(1, 0), a3, voffA);
;             PG8_BAR; PG8_WAIT_L(0); PG8_MMA(1, 0, At, B0); PG8_BAR; PG8_SCHED;
	v_mfma_f32_16x16x32_bf16 v[48:51], v[206:209], v[172:175], v[48:51]
	v_mfma_f32_16x16x32_bf16 v[40:43], v[214:217], v[172:175], v[40:43]
	v_mfma_f32_16x16x32_bf16 v[32:35], v[206:209], v[180:183], v[32:35]
	v_mfma_f32_16x16x32_bf16 v[24:27], v[214:217], v[180:183], v[24:27]
	v_mfma_f32_16x16x32_bf16 v[16:19], v[206:209], v[188:191], v[16:19]
	v_mfma_f32_16x16x32_bf16 v[8:11], v[214:217], v[188:191], v[8:11]
	v_mfma_f32_16x16x32_bf16 v[4:7], v[206:209], v[196:199], v[4:7]
	v_mfma_f32_16x16x32_bf16 v[0:3], v[214:217], v[196:199], v[0:3]
	v_mfma_f32_16x16x32_bf16 v[48:51], v[210:213], v[176:179], v[48:51]
	v_mfma_f32_16x16x32_bf16 v[40:43], v[218:221], v[176:179], v[40:43]
	v_mfma_f32_16x16x32_bf16 v[32:35], v[210:213], v[184:187], v[32:35]
	v_mfma_f32_16x16x32_bf16 v[24:27], v[218:221], v[184:187], v[24:27]
	v_mfma_f32_16x16x32_bf16 v[16:19], v[210:213], v[192:195], v[16:19]
	v_mfma_f32_16x16x32_bf16 v[8:11], v[218:221], v[192:195], v[8:11]
	v_mfma_f32_16x16x32_bf16 v[4:7], v[210:213], v[202:205], v[4:7]
	v_mfma_f32_16x16x32_bf16 v[0:3], v[218:221], v[202:205], v[0:3]
	s_barrier
	s_setprio 0
	ds_read_b128 v[150:153], v144
	ds_read_b128 v[154:157], v144 offset:1024
	ds_read_b128 v[160:163], v144 offset:2048
	ds_read_b128 v[168:171], v144 offset:3072
	s_add_u32 s20, s20, 0x80000
	s_addc_u32 s21, s21, 0
	s_mov_b32 m0, s45
	ds_read_b128 v[172:175], v142 offset:32768
	ds_read_b128 v[176:179], v142 offset:33792
	ds_read_b128 v[180:183], v142 offset:34816
	ds_read_b128 v[184:187], v142 offset:35840
	ds_read_b128 v[188:191], v142 offset:36864
	ds_read_b128 v[192:195], v142 offset:37888
	ds_read_b128 v[196:199], v142 offset:38912
	ds_read_b128 v[202:205], v142 offset:39936
	global_load_lds_dwordx4 v128, s[20:21]
	s_mov_b32 m0, s46
	s_nop 0
	global_load_lds_dwordx4 v132, s[20:21]
	s_waitcnt lgkmcnt(8)
	s_setprio 1
	s_barrier
	s_waitcnt lgkmcnt(0)
	v_mfma_f32_16x16x32_bf16 v[124:127], v[150:153], v[172:175], v[124:127]
	v_mfma_f32_16x16x32_bf16 v[120:123], v[160:163], v[172:175], v[120:123]
	v_mfma_f32_16x16x32_bf16 v[116:119], v[150:153], v[180:183], v[116:119]
	v_mfma_f32_16x16x32_bf16 v[112:115], v[160:163], v[180:183], v[112:115]
	v_mfma_f32_16x16x32_bf16 v[100:103], v[150:153], v[188:191], v[100:103]
	v_mfma_f32_16x16x32_bf16 v[92:95], v[160:163], v[188:191], v[92:95]
	v_mfma_f32_16x16x32_bf16 v[84:87], v[150:153], v[196:199], v[84:87]
	v_mfma_f32_16x16x32_bf16 v[76:79], v[160:163], v[196:199], v[76:79]
	v_mfma_f32_16x16x32_bf16 v[124:127], v[154:157], v[176:179], v[124:127]
	v_mfma_f32_16x16x32_bf16 v[120:123], v[168:171], v[176:179], v[120:123]
	v_mfma_f32_16x16x32_bf16 v[116:119], v[154:157], v[184:187], v[116:119]
	v_mfma_f32_16x16x32_bf16 v[112:115], v[168:171], v[184:187], v[112:115]
	v_mfma_f32_16x16x32_bf16 v[100:103], v[154:157], v[192:195], v[100:103]
	v_mfma_f32_16x16x32_bf16 v[92:95], v[168:171], v[192:195], v[92:95]
	v_mfma_f32_16x16x32_bf16 v[84:87], v[154:157], v[202:205], v[84:87]
	v_mfma_f32_16x16x32_bf16 v[76:79], v[168:171], v[202:205], v[76:79]
	s_barrier
	s_setprio 0
	s_mov_b32 m0, s55
	ds_read_b128 v[206:209], v145
	ds_read_b128 v[210:213], v145 offset:1024
	ds_read_b128 v[214:217], v145 offset:2048
	ds_read_b128 v[218:221], v145 offset:3072
	global_load_lds_dwordx4 v130, s[98:99]
	s_mov_b32 m0, s56
	s_nop 0
	global_load_lds_dwordx4 v134, s[98:99]
	s_setprio 1
	s_barrier
	s_waitcnt lgkmcnt(0)
	v_mfma_f32_16x16x32_bf16 v[108:111], v[206:209], v[172:175], v[108:111]
	v_mfma_f32_16x16x32_bf16 v[104:107], v[214:217], v[172:175], v[104:107]
	v_mfma_f32_16x16x32_bf16 v[96:99], v[206:209], v[180:183], v[96:99]
	v_mfma_f32_16x16x32_bf16 v[88:91], v[214:217], v[180:183], v[88:91]
	v_mfma_f32_16x16x32_bf16 v[80:83], v[206:209], v[188:191], v[80:83]
	v_mfma_f32_16x16x32_bf16 v[72:75], v[214:217], v[188:191], v[72:75]
	v_mfma_f32_16x16x32_bf16 v[68:71], v[206:209], v[196:199], v[68:71]
	v_mfma_f32_16x16x32_bf16 v[64:67], v[214:217], v[196:199], v[64:67]
	v_mfma_f32_16x16x32_bf16 v[108:111], v[210:213], v[176:179], v[108:111]
	v_mfma_f32_16x16x32_bf16 v[104:107], v[218:221], v[176:179], v[104:107]
	v_mfma_f32_16x16x32_bf16 v[96:99], v[210:213], v[184:187], v[96:99]
	v_mfma_f32_16x16x32_bf16 v[88:91], v[218:221], v[184:187], v[88:91]
	v_mfma_f32_16x16x32_bf16 v[80:83], v[210:213], v[192:195], v[80:83]
	v_mfma_f32_16x16x32_bf16 v[72:75], v[218:221], v[192:195], v[72:75]
	v_mfma_f32_16x16x32_bf16 v[68:71], v[210:213], v[202:205], v[68:71]
	v_mfma_f32_16x16x32_bf16 v[64:67], v[218:221], v[202:205], v[64:67]
	s_barrier
	s_setprio 0
	s_mov_b32 m0, s47
	ds_read_b128 v[172:175], v142 offset:49152
	ds_read_b128 v[176:179], v142 offset:50176
	ds_read_b128 v[180:183], v142 offset:51200
	ds_read_b128 v[184:187], v142 offset:52224
	ds_read_b128 v[188:191], v142 offset:53248
	ds_read_b128 v[192:195], v142 offset:54272
	ds_read_b128 v[196:199], v142 offset:55296
	ds_read_b128 v[202:205], v142 offset:56320
	global_load_lds_dwordx4 v128, s[100:101]
	s_mov_b32 m0, s48
	s_nop 0
	global_load_lds_dwordx4 v132, s[100:101]
	s_setprio 1
	s_barrier
	s_waitcnt lgkmcnt(0)
	v_mfma_f32_16x16x32_bf16 v[60:63], v[150:153], v[172:175], v[60:63]
	v_mfma_f32_16x16x32_bf16 v[56:59], v[160:163], v[172:175], v[56:59]
	v_mfma_f32_16x16x32_bf16 v[52:55], v[150:153], v[180:183], v[52:55]
	v_mfma_f32_16x16x32_bf16 v[44:47], v[160:163], v[180:183], v[44:47]
	v_mfma_f32_16x16x32_bf16 v[36:39], v[150:153], v[188:191], v[36:39]
	v_mfma_f32_16x16x32_bf16 v[28:31], v[160:163], v[188:191], v[28:31]
	v_mfma_f32_16x16x32_bf16 v[20:23], v[150:153], v[196:199], v[20:23]
	v_mfma_f32_16x16x32_bf16 v[12:15], v[160:163], v[196:199], v[12:15]
	v_mfma_f32_16x16x32_bf16 v[60:63], v[154:157], v[176:179], v[60:63]
	v_mfma_f32_16x16x32_bf16 v[56:59], v[168:171], v[176:179], v[56:59]
	v_mfma_f32_16x16x32_bf16 v[52:55], v[154:157], v[184:187], v[52:55]
	v_mfma_f32_16x16x32_bf16 v[44:47], v[168:171], v[184:187], v[44:47]
	v_mfma_f32_16x16x32_bf16 v[36:39], v[154:157], v[192:195], v[36:39]
	v_mfma_f32_16x16x32_bf16 v[28:31], v[168:171], v[192:195], v[28:31]
	v_mfma_f32_16x16x32_bf16 v[20:23], v[154:157], v[202:205], v[20:23]
	v_mfma_f32_16x16x32_bf16 v[12:15], v[168:171], v[202:205], v[12:15]
	s_barrier
; #define LAS __attribute__((address_space(3)))
; #define PG8_STAGE(bufoff, gbase, voff) do { _Pragma("unroll") for (int _i = 0; _i < 2; ++_i) \
;         __builtin_amdgcn_global_load_lds((const unsigned*)((const char*)(gbase) + (voff)[_i]), (LAS unsigned*)(lds + (bufoff) + ldsw + _i * 8192), 16, 0, 0); } while (0)
; #define PG8_WAIT_V(n) asm volatile("s_waitcnt vmcnt(" #n ")" ::: "memory")
; #define PG8_WAIT_L(n) asm volatile("s_waitcnt lgkmcnt(" #n ")" ::: "memory")
; #define PG8_BAR __builtin_amdgcn_s_barrier()
; #define PG8_SCHED __builtin_amdgcn_sched_barrier(0)
; template <class Epi>
; __device__ __forceinline__ void gemm_phase(LAS unsigned char* lds, const bf16_t* A, int lda, const bf16_t* Bt, int ldb, int M, int N, int K, int asel, const Epi& E, const int fixed_round = -1) {
;     ...
;             PG8_BAR; PG8_WAIT_L(0); PG8_MMA(1, 0, At, B0); PG8_BAR; PG8_SCHED;
;             PG8_STAGE(PG8_SB(1, 1), b3 + hstepB, voffB);
;             PG8_WAIT_V(6); PG8_BAR; PG8_MMA(1, 1, At, B1); PG8_BAR;
;             if constexpr (Epi::HEADSCALE) {
;                 if (t & 2) {
;                     const LAS float* rt = (const LAS float*)(lds + L_RT) + (t >> 2);
; #pragma unroll
;                     for (int ai = 0; ai < 2; ++ai)
; #pragma unroll
;                         for (int m = 0; m < 4; ++m) { const float f = rt[(ai * HALF + wr * 64 + m * 16 + fr) * 8];
; #pragma unroll
;                             for (int bj = 0; bj < 2; ++bj)
; #pragma unroll
;                                 for (int n = 0; n < 2; ++n) acc[ai][bj][m][n] *= f; }
;                 }
	s_setprio 0
	s_add_u32 s18, s18, 0x80080
	s_addc_u32 s19, s19, 0
	s_mov_b32 m0, s57
	s_nop 0
	global_load_lds_dwordx4 v130, s[18:19]
	s_mov_b32 m0, s58
	s_nop 0
	global_load_lds_dwordx4 v134, s[18:19]
	s_waitcnt vmcnt(6)
	s_setprio 1
	s_barrier
	v_mfma_f32_16x16x32_bf16 v[48:51], v[206:209], v[172:175], v[48:51]
	v_mfma_f32_16x16x32_bf16 v[40:43], v[214:217], v[172:175], v[40:43]
	v_mfma_f32_16x16x32_bf16 v[32:35], v[206:209], v[180:183], v[32:35]
	v_mfma_f32_16x16x32_bf16 v[24:27], v[214:217], v[180:183], v[24:27]
	v_mfma_f32_16x16x32_bf16 v[16:19], v[206:209], v[188:191], v[16:19]
	v_mfma_f32_16x16x32_bf16 v[8:11], v[214:217], v[188:191], v[8:11]
	v_mfma_f32_16x16x32_bf16 v[4:7], v[206:209], v[196:199], v[4:7]
	v_mfma_f32_16x16x32_bf16 v[0:3], v[214:217], v[196:199], v[0:3]
	v_mfma_f32_16x16x32_bf16 v[48:51], v[210:213], v[176:179], v[48:51]
	v_mfma_f32_16x16x32_bf16 v[40:43], v[218:221], v[176:179], v[40:43]
	v_mfma_f32_16x16x32_bf16 v[32:35], v[210:213], v[184:187], v[32:35]
	v_mfma_f32_16x16x32_bf16 v[24:27], v[218:221], v[184:187], v[24:27]
	v_mfma_f32_16x16x32_bf16 v[16:19], v[210:213], v[192:195], v[16:19]
	v_mfma_f32_16x16x32_bf16 v[8:11], v[218:221], v[192:195], v[8:11]
	v_mfma_f32_16x16x32_bf16 v[4:7], v[210:213], v[202:205], v[4:7]
	v_mfma_f32_16x16x32_bf16 v[0:3], v[218:221], v[202:205], v[0:3]
	s_setprio 0
	s_bitcmp0_b32 s35, 1
	s_barrier
	s_cbranch_scc1 .LBB0_486
	s_and_b32 s18, s35, -4
	v_add_u32_e32 v148, s18, v140
	ds_read2st64_b32 v[146:147], v148 offset1:2
	ds_read2st64_b32 v[150:151], v148 offset0:4 offset1:6
	s_waitcnt lgkmcnt(0)
	v_pk_mul_f32 v[126:127], v[126:127], v[146:147] op_sel_hi:[1,0]
	v_pk_mul_f32 v[124:125], v[124:125], v[146:147] op_sel_hi:[1,0]
	v_pk_mul_f32 v[122:123], v[122:123], v[146:147] op_sel_hi:[1,0]
	v_pk_mul_f32 v[120:121], v[120:121], v[146:147] op_sel_hi:[1,0]
	v_pk_mul_f32 v[110:111], v[110:111], v[146:147] op_sel_hi:[1,0]
	v_pk_mul_f32 v[108:109], v[108:109], v[146:147] op_sel_hi:[1,0]
	v_pk_mul_f32 v[106:107], v[106:107], v[146:147] op_sel_hi:[1,0]
	v_pk_mul_f32 v[104:105], v[104:105], v[146:147] op_sel_hi:[1,0]
	v_mov_b32_e32 v146, v147
	v_pk_mul_f32 v[118:119], v[118:119], v[146:147] op_sel_hi:[1,0]
	v_pk_mul_f32 v[116:117], v[116:117], v[146:147] op_sel_hi:[1,0]
	v_pk_mul_f32 v[114:115], v[114:115], v[146:147] op_sel_hi:[1,0]
	v_pk_mul_f32 v[112:113], v[112:113], v[146:147] op_sel_hi:[1,0]
	v_pk_mul_f32 v[98:99], v[98:99], v[146:147] op_sel_hi:[1,0]
	v_pk_mul_f32 v[96:97], v[96:97], v[146:147] op_sel_hi:[1,0]
	v_pk_mul_f32 v[90:91], v[90:91], v[146:147] op_sel_hi:[1,0]
	v_pk_mul_f32 v[88:89], v[88:89], v[146:147] op_sel_hi:[1,0]
	v_pk_mul_f32 v[102:103], v[102:103], v[150:151] op_sel_hi:[1,0]
	v_pk_mul_f32 v[100:101], v[100:101], v[150:151] op_sel_hi:[1,0]
	v_pk_mul_f32 v[94:95], v[94:95], v[150:151] op_sel_hi:[1,0]
	v_pk_mul_f32 v[92:93], v[92:93], v[150:151] op_sel_hi:[1,0]
	v_pk_mul_f32 v[82:83], v[82:83], v[150:151] op_sel_hi:[1,0]
	v_pk_mul_f32 v[80:81], v[80:81], v[150:151] op_sel_hi:[1,0]
	v_pk_mul_f32 v[74:75], v[74:75], v[150:151] op_sel_hi:[1,0]
	v_pk_mul_f32 v[72:73], v[72:73], v[150:151] op_sel_hi:[1,0]
	v_mov_b32_e32 v146, v151
	ds_read2st64_b32 v[150:151], v148 offset0:16 offset1:18
	v_pk_mul_f32 v[86:87], v[86:87], v[146:147] op_sel_hi:[1,0]
	v_pk_mul_f32 v[84:85], v[84:85], v[146:147] op_sel_hi:[1,0]
	v_pk_mul_f32 v[78:79], v[78:79], v[146:147] op_sel_hi:[1,0]
	v_pk_mul_f32 v[76:77], v[76:77], v[146:147] op_sel_hi:[1,0]
	v_pk_mul_f32 v[70:71], v[70:71], v[146:147] op_sel_hi:[1,0]
	v_pk_mul_f32 v[68:69], v[68:69], v[146:147] op_sel_hi:[1,0]
	v_pk_mul_f32 v[66:67], v[66:67], v[146:147] op_sel_hi:[1,0]
	v_pk_mul_f32 v[64:65], v[64:65], v[146:147] op_sel_hi:[1,0]
	s_waitcnt lgkmcnt(0)
	v_pk_mul_f32 v[62:63], v[62:63], v[150:151] op_sel_hi:[1,0]
	v_pk_mul_f32 v[60:61], v[60:61], v[150:151] op_sel_hi:[1,0]
	v_pk_mul_f32 v[58:59], v[58:59], v[150:151] op_sel_hi:[1,0]
	v_pk_mul_f32 v[56:57], v[56:57], v[150:151] op_sel_hi:[1,0]
	v_pk_mul_f32 v[50:51], v[50:51], v[150:151] op_sel_hi:[1,0]
	v_pk_mul_f32 v[48:49], v[48:49], v[150:151] op_sel_hi:[1,0]
	v_pk_mul_f32 v[42:43], v[42:43], v[150:151] op_sel_hi:[1,0]
	v_pk_mul_f32 v[40:41], v[40:41], v[150:151] op_sel_hi:[1,0]
	v_mov_b32_e32 v146, v151
	ds_read2st64_b32 v[150:151], v148 offset0:20 offset1:22
	v_pk_mul_f32 v[54:55], v[54:55], v[146:147] op_sel_hi:[1,0]
	v_pk_mul_f32 v[52:53], v[52:53], v[146:147] op_sel_hi:[1,0]
	v_pk_mul_f32 v[46:47], v[46:47], v[146:147] op_sel_hi:[1,0]
	v_pk_mul_f32 v[44:45], v[44:45], v[146:147] op_sel_hi:[1,0]
	v_pk_mul_f32 v[34:35], v[34:35], v[146:147] op_sel_hi:[1,0]
	v_pk_mul_f32 v[32:33], v[32:33], v[146:147] op_sel_hi:[1,0]
	v_pk_mul_f32 v[26:27], v[26:27], v[146:147] op_sel_hi:[1,0]
	v_pk_mul_f32 v[24:25], v[24:25], v[146:147] op_sel_hi:[1,0]
	s_waitcnt lgkmcnt(0)
	v_mov_b32_e32 v146, v151
	v_pk_mul_f32 v[38:39], v[38:39], v[150:151] op_sel_hi:[1,0]
	v_pk_mul_f32 v[36:37], v[36:37], v[150:151] op_sel_hi:[1,0]
	v_pk_mul_f32 v[30:31], v[30:31], v[150:151] op_sel_hi:[1,0]
	v_pk_mul_f32 v[28:29], v[28:29], v[150:151] op_sel_hi:[1,0]
	v_pk_mul_f32 v[18:19], v[18:19], v[150:151] op_sel_hi:[1,0]
	v_pk_mul_f32 v[16:17], v[16:17], v[150:151] op_sel_hi:[1,0]
	v_pk_mul_f32 v[10:11], v[10:11], v[150:151] op_sel_hi:[1,0]
	v_pk_mul_f32 v[8:9], v[8:9], v[150:151] op_sel_hi:[1,0]
	v_pk_mul_f32 v[22:23], v[22:23], v[146:147] op_sel_hi:[1,0]
	v_pk_mul_f32 v[20:21], v[20:21], v[146:147] op_sel_hi:[1,0]
	v_pk_mul_f32 v[14:15], v[14:15], v[146:147] op_sel_hi:[1,0]
	v_pk_mul_f32 v[12:13], v[12:13], v[146:147] op_sel_hi:[1,0]
	v_pk_mul_f32 v[6:7], v[6:7], v[146:147] op_sel_hi:[1,0]
	v_pk_mul_f32 v[4:5], v[4:5], v[146:147] op_sel_hi:[1,0]
	v_pk_mul_f32 v[2:3], v[2:3], v[146:147] op_sel_hi:[1,0]
	v_pk_mul_f32 v[0:1], v[0:1], v[146:147] op_sel_hi:[1,0]
	s_branch .LBB0_486

; #define PG8_STAGE(bufoff, gbase, voff) do { _Pragma("unroll") for (int _i = 0; _i < 2; ++_i) \
;         __builtin_amdgcn_global_load_lds((const unsigned*)((const char*)(gbase) + (voff)[_i]), (LAS unsigned*)(lds + (bufoff) + ldsw + _i * 8192), 16, 0, 0); } while (0)
; #define PG8_LDA(dst, b, h) do { _Pragma("unroll") for (int m = 0; m < 4; ++m) _Pragma("unroll") for (int k = 0; k < 2; ++k) dst[m][k] = *(const LAS bf16x8*)(lds + PG8_SA(b, h) + aoff + m * 2048 + k * 1024); } while (0)
; #define PG8_LDB(dst, b, h) do { _Pragma("unroll") for (int n = 0; n < 2; ++n) _Pragma("unroll") for (int k = 0; k < 2; ++k) dst[n][k] = *(const LAS bf16x8*)(lds + PG8_SB(b, h) + boff + n * 2048 + k * 1024); } while (0)
; #define PG8_WAIT_V(n) asm volatile("s_waitcnt vmcnt(" #n ")" ::: "memory")
; #define PG8_WAIT_L(n) asm volatile("s_waitcnt lgkmcnt(" #n ")" ::: "memory")
; #define PG8_BAR __builtin_amdgcn_s_barrier()
; #define PG8_SCHED __builtin_amdgcn_sched_barrier(0)
; template <class Epi>
; __device__ __forceinline__ void gemm_phase(LAS unsigned char* lds, const bf16_t* A, int lda, const bf16_t* Bt, int ldb, int M, int N, int K, int asel, const Epi& E, const int fixed_round = -1) {
;     ...
;             const bool last = (t == nt - 2);
;             const char* a1 = cA + (size_t)(t + 1) * kstep;
;             const char* a2 = last ? nA : cA + (size_t)(t + 2) * kstep; const char* b2 = last ? nB : cB + (size_t)(t + 2) * kstep;
;             const char* a3 = a2 + kstep; const char* b3 = b2 + kstep;
;             PG8_LDB(B0, 0, 0); PG8_SCHED; PG8_LDA(At, 0, 0); PG8_STAGE(PG8_SA(1, 1), a1 + hstepA, voffA);
;             PG8_WAIT_L(8); PG8_BAR; PG8_WAIT_L(0); PG8_MMA(0, 0, At, B0); PG8_BAR; PG8_SCHED;
;             PG8_LDB(B1, 0, 1); PG8_STAGE(PG8_SB(0, 0), b2, voffB);
;             PG8_BAR; PG8_WAIT_L(0); PG8_MMA(0, 1, At, B1); PG8_BAR;
;             PG8_LDA(At, 0, 1); PG8_STAGE(PG8_SA(0, 0), a2, voffA);
;             PG8_BAR; PG8_WAIT_L(0); PG8_MMA(1, 0, At, B0); PG8_BAR; PG8_SCHED;
;             PG8_STAGE(PG8_SB(0, 1), b2 + hstepB, voffB);
;             PG8_WAIT_V(6); PG8_BAR; PG8_MMA(1, 1, At, B1); PG8_BAR;
.LBB0_591:
	ds_read_b128 v[152:155], v149
	ds_read_b128 v[156:159], v149 offset:1024
	ds_read_b128 v[160:163], v149 offset:2048
	ds_read_b128 v[164:167], v149 offset:3072
	s_add_i32 m0, s27, 0xc000
	ds_read_b128 v[168:171], v150
	ds_read_b128 v[172:175], v150 offset:1024
	ds_read_b128 v[176:179], v150 offset:2048
	ds_read_b128 v[180:183], v150 offset:3072
	ds_read_b128 v[184:187], v150 offset:4096
	ds_read_b128 v[188:191], v150 offset:5120
	ds_read_b128 v[192:195], v150 offset:6144
	ds_read_b128 v[196:199], v150 offset:7168
	global_load_lds_dwordx4 v136, s[30:31]
	s_add_i32 m0, s27, 0xe000
	s_nop 0
	global_load_lds_dwordx4 v138, s[30:31]
	s_waitcnt lgkmcnt(8)
	s_setprio 1
	s_barrier
	s_waitcnt lgkmcnt(0)
	v_mfma_f32_16x16x32_bf16 v[124:127], v[152:155], v[168:171], v[124:127]
	v_mfma_f32_16x16x32_bf16 v[120:123], v[160:163], v[168:171], v[120:123]
	v_mfma_f32_16x16x32_bf16 v[108:111], v[152:155], v[176:179], v[108:111]
	v_mfma_f32_16x16x32_bf16 v[104:107], v[160:163], v[176:179], v[104:107]
	v_mfma_f32_16x16x32_bf16 v[92:95], v[152:155], v[184:187], v[92:95]
	v_mfma_f32_16x16x32_bf16 v[88:91], v[160:163], v[184:187], v[88:91]
	v_mfma_f32_16x16x32_bf16 v[76:79], v[152:155], v[192:195], v[76:79]
	v_mfma_f32_16x16x32_bf16 v[72:75], v[160:163], v[192:195], v[72:75]
	v_mfma_f32_16x16x32_bf16 v[124:127], v[156:159], v[172:175], v[124:127]
	v_mfma_f32_16x16x32_bf16 v[120:123], v[164:167], v[172:175], v[120:123]
	v_mfma_f32_16x16x32_bf16 v[108:111], v[156:159], v[180:183], v[108:111]
	v_mfma_f32_16x16x32_bf16 v[104:107], v[164:167], v[180:183], v[104:107]
	v_mfma_f32_16x16x32_bf16 v[92:95], v[156:159], v[188:191], v[92:95]
	v_mfma_f32_16x16x32_bf16 v[88:91], v[164:167], v[188:191], v[88:91]
	v_mfma_f32_16x16x32_bf16 v[76:79], v[156:159], v[196:199], v[76:79]
	v_mfma_f32_16x16x32_bf16 v[72:75], v[164:167], v[196:199], v[72:75]
	s_barrier
	s_setprio 0
	s_add_u32 s28, s30, 0xfff80080
	s_addc_u32 s29, s31, -1
	s_cmp_eq_u32 s56, 28
	s_cselect_b32 s37, s7, s29
	s_cselect_b32 s36, s52, s28
	s_cselect_b32 s35, s5, s55
	s_cselect_b32 s34, s53, s54
	s_add_i32 s28, s81, s42
	s_add_u32 s98, s34, s2
	s_addc_u32 s99, s35, s3
	s_mov_b32 m0, s28
	ds_read_b128 v[202:205], v151
	ds_read_b128 v[206:209], v151 offset:1024
	ds_read_b128 v[210:213], v151 offset:2048
	ds_read_b128 v[214:217], v151 offset:3072
	global_load_lds_dwordx4 v130, s[34:35]
	s_add_i32 m0, s28, 0x2000
	s_nop 0
	global_load_lds_dwordx4 v134, s[34:35]
	s_setprio 1
	s_barrier
	s_waitcnt lgkmcnt(0)
	v_mfma_f32_16x16x32_bf16 v[116:119], v[202:205], v[168:171], v[116:119]
	v_mfma_f32_16x16x32_bf16 v[112:115], v[210:213], v[168:171], v[112:115]
	v_mfma_f32_16x16x32_bf16 v[100:103], v[202:205], v[176:179], v[100:103]
	v_mfma_f32_16x16x32_bf16 v[96:99], v[210:213], v[176:179], v[96:99]
	v_mfma_f32_16x16x32_bf16 v[84:87], v[202:205], v[184:187], v[84:87]
	v_mfma_f32_16x16x32_bf16 v[80:83], v[210:213], v[184:187], v[80:83]
	v_mfma_f32_16x16x32_bf16 v[68:71], v[202:205], v[192:195], v[68:71]
	v_mfma_f32_16x16x32_bf16 v[64:67], v[210:213], v[192:195], v[64:67]
	v_mfma_f32_16x16x32_bf16 v[116:119], v[206:209], v[172:175], v[116:119]
	v_mfma_f32_16x16x32_bf16 v[112:115], v[214:217], v[172:175], v[112:115]
	v_mfma_f32_16x16x32_bf16 v[100:103], v[206:209], v[180:183], v[100:103]
	v_mfma_f32_16x16x32_bf16 v[96:99], v[214:217], v[180:183], v[96:99]
	v_mfma_f32_16x16x32_bf16 v[84:87], v[206:209], v[188:191], v[84:87]
	v_mfma_f32_16x16x32_bf16 v[80:83], v[214:217], v[188:191], v[80:83]
	v_mfma_f32_16x16x32_bf16 v[68:71], v[206:209], v[196:199], v[68:71]
	v_mfma_f32_16x16x32_bf16 v[64:67], v[214:217], v[196:199], v[64:67]
	s_barrier
	s_setprio 0
	s_mov_b32 m0, s27
	s_add_u32 s100, s36, s2
	s_addc_u32 s101, s37, s3
	ds_read_b128 v[168:171], v150 offset:16384
	ds_read_b128 v[172:175], v150 offset:17408
	ds_read_b128 v[176:179], v150 offset:18432
	ds_read_b128 v[180:183], v150 offset:19456
	ds_read_b128 v[184:187], v150 offset:20480
	ds_read_b128 v[188:191], v150 offset:21504
	ds_read_b128 v[192:195], v150 offset:22528
	ds_read_b128 v[196:199], v150 offset:23552
	global_load_lds_dwordx4 v128, s[36:37]
	s_mov_b32 m0, s43
	s_nop 0
	global_load_lds_dwordx4 v132, s[36:37]
	s_setprio 1
	s_barrier
	s_waitcnt lgkmcnt(0)
	v_mfma_f32_16x16x32_bf16 v[60:63], v[152:155], v[168:171], v[60:63]
	v_mfma_f32_16x16x32_bf16 v[56:59], v[160:163], v[168:171], v[56:59]
	v_mfma_f32_16x16x32_bf16 v[44:47], v[152:155], v[176:179], v[44:47]
	v_mfma_f32_16x16x32_bf16 v[40:43], v[160:163], v[176:179], v[40:43]
	v_mfma_f32_16x16x32_bf16 v[28:31], v[152:155], v[184:187], v[28:31]
	v_mfma_f32_16x16x32_bf16 v[24:27], v[160:163], v[184:187], v[24:27]
	v_mfma_f32_16x16x32_bf16 v[12:15], v[152:155], v[192:195], v[12:15]
	v_mfma_f32_16x16x32_bf16 v[8:11], v[160:163], v[192:195], v[8:11]
	v_mfma_f32_16x16x32_bf16 v[60:63], v[156:159], v[172:175], v[60:63]
	v_mfma_f32_16x16x32_bf16 v[56:59], v[164:167], v[172:175], v[56:59]
	v_mfma_f32_16x16x32_bf16 v[44:47], v[156:159], v[180:183], v[44:47]
	v_mfma_f32_16x16x32_bf16 v[40:43], v[164:167], v[180:183], v[40:43]
	v_mfma_f32_16x16x32_bf16 v[28:31], v[156:159], v[188:191], v[28:31]
	v_mfma_f32_16x16x32_bf16 v[24:27], v[164:167], v[188:191], v[24:27]
	v_mfma_f32_16x16x32_bf16 v[12:15], v[156:159], v[196:199], v[12:15]
	v_mfma_f32_16x16x32_bf16 v[8:11], v[164:167], v[196:199], v[8:11]
	s_barrier
	s_setprio 0
	s_add_u32 s28, s34, 0x80000
	s_addc_u32 s29, s35, 0
	s_add_i32 s57, s82, s42
	s_mov_b32 m0, s57
	s_nop 0
	global_load_lds_dwordx4 v130, s[28:29]
	s_add_i32 m0, s57, 0x2000
	s_nop 0
	global_load_lds_dwordx4 v134, s[28:29]
	s_waitcnt vmcnt(6)
	s_setprio 1
	s_barrier
; #define PG8_STAGE(bufoff, gbase, voff) do { _Pragma("unroll") for (int _i = 0; _i < 2; ++_i) \
;         __builtin_amdgcn_global_load_lds((const unsigned*)((const char*)(gbase) + (voff)[_i]), (LAS unsigned*)(lds + (bufoff) + ldsw + _i * 8192), 16, 0, 0); } while (0)
; #define PG8_LDA(dst, b, h) do { _Pragma("unroll") for (int m = 0; m < 4; ++m) _Pragma("unroll") for (int k = 0; k < 2; ++k) dst[m][k] = *(const LAS bf16x8*)(lds + PG8_SA(b, h) + aoff + m * 2048 + k * 1024); } while (0)
; #define PG8_LDB(dst, b, h) do { _Pragma("unroll") for (int n = 0; n < 2; ++n) _Pragma("unroll") for (int k = 0; k < 2; ++k) dst[n][k] = *(const LAS bf16x8*)(lds + PG8_SB(b, h) + boff + n * 2048 + k * 1024); } while (0)
; #define PG8_WAIT_V(n) asm volatile("s_waitcnt vmcnt(" #n ")" ::: "memory")
; #define PG8_WAIT_L(n) asm volatile("s_waitcnt lgkmcnt(" #n ")" ::: "memory")
; #define PG8_BAR __builtin_amdgcn_s_barrier()
; #define PG8_SCHED __builtin_amdgcn_sched_barrier(0)
; template <class Epi>
; __device__ __forceinline__ void gemm_phase(LAS unsigned char* lds, const bf16_t* A, int lda, const bf16_t* Bt, int ldb, int M, int N, int K, int asel, const Epi& E, const int fixed_round = -1) {
;     ...
;             PG8_WAIT_V(6); PG8_BAR; PG8_MMA(1, 1, At, B1); PG8_BAR;
;             PG8_LDB(B0, 1, 0); PG8_SCHED; PG8_LDA(At, 1, 0); PG8_STAGE(PG8_SA(0, 1), a2 + hstepA, voffA);
;             PG8_WAIT_L(8); PG8_BAR; PG8_WAIT_L(0); PG8_MMA(0, 0, At, B0); PG8_BAR; PG8_SCHED;
;             PG8_LDB(B1, 1, 1); PG8_STAGE(PG8_SB(1, 0), b3, voffB);
;             PG8_BAR; PG8_WAIT_L(0); PG8_MMA(0, 1, At, B1); PG8_BAR;
;             PG8_LDA(At, 1, 1); PG8_STAGE(PG8_SA(1, 0), a3, voffA);
	v_mfma_f32_16x16x32_bf16 v[52:55], v[202:205], v[168:171], v[52:55]
	v_mfma_f32_16x16x32_bf16 v[48:51], v[210:213], v[168:171], v[48:51]
	v_mfma_f32_16x16x32_bf16 v[36:39], v[202:205], v[176:179], v[36:39]
	v_mfma_f32_16x16x32_bf16 v[32:35], v[210:213], v[176:179], v[32:35]
	v_mfma_f32_16x16x32_bf16 v[20:23], v[202:205], v[184:187], v[20:23]
	v_mfma_f32_16x16x32_bf16 v[16:19], v[210:213], v[184:187], v[16:19]
	v_mfma_f32_16x16x32_bf16 v[4:7], v[202:205], v[192:195], v[4:7]
	v_mfma_f32_16x16x32_bf16 v[0:3], v[210:213], v[192:195], v[0:3]
	v_mfma_f32_16x16x32_bf16 v[52:55], v[206:209], v[172:175], v[52:55]
	v_mfma_f32_16x16x32_bf16 v[48:51], v[214:217], v[172:175], v[48:51]
	v_mfma_f32_16x16x32_bf16 v[36:39], v[206:209], v[180:183], v[36:39]
	v_mfma_f32_16x16x32_bf16 v[32:35], v[214:217], v[180:183], v[32:35]
	v_mfma_f32_16x16x32_bf16 v[20:23], v[206:209], v[188:191], v[20:23]
	v_mfma_f32_16x16x32_bf16 v[16:19], v[214:217], v[188:191], v[16:19]
	v_mfma_f32_16x16x32_bf16 v[4:7], v[206:209], v[196:199], v[4:7]
	v_mfma_f32_16x16x32_bf16 v[0:3], v[214:217], v[196:199], v[0:3]
	s_barrier
	s_setprio 0
	v_add_u32_e32 v164, s83, v147
	ds_read_b128 v[152:155], v164
	ds_read_b128 v[156:159], v164 offset:1024
	ds_read_b128 v[160:163], v164 offset:2048
	ds_read_b128 v[164:167], v164 offset:3072
	s_add_u32 s28, s36, 0x80000
	s_addc_u32 s29, s37, 0
	s_mov_b32 m0, s44
	ds_read_b128 v[168:171], v150 offset:32768
	ds_read_b128 v[172:175], v150 offset:33792
	ds_read_b128 v[176:179], v150 offset:34816
	ds_read_b128 v[180:183], v150 offset:35840
	ds_read_b128 v[184:187], v150 offset:36864
	ds_read_b128 v[188:191], v150 offset:37888
	ds_read_b128 v[192:195], v150 offset:38912
	ds_read_b128 v[196:199], v150 offset:39936
	global_load_lds_dwordx4 v128, s[28:29]
	s_mov_b32 m0, s45
	s_nop 0
	global_load_lds_dwordx4 v132, s[28:29]
	s_waitcnt lgkmcnt(8)
	s_setprio 1
	s_barrier
	s_waitcnt lgkmcnt(0)
	v_mfma_f32_16x16x32_bf16 v[124:127], v[152:155], v[168:171], v[124:127]
	v_mfma_f32_16x16x32_bf16 v[120:123], v[160:163], v[168:171], v[120:123]
	v_mfma_f32_16x16x32_bf16 v[108:111], v[152:155], v[176:179], v[108:111]
	v_mfma_f32_16x16x32_bf16 v[104:107], v[160:163], v[176:179], v[104:107]
	v_mfma_f32_16x16x32_bf16 v[92:95], v[152:155], v[184:187], v[92:95]
	v_mfma_f32_16x16x32_bf16 v[88:91], v[160:163], v[184:187], v[88:91]
	v_mfma_f32_16x16x32_bf16 v[76:79], v[152:155], v[192:195], v[76:79]
	v_mfma_f32_16x16x32_bf16 v[72:75], v[160:163], v[192:195], v[72:75]
	v_mfma_f32_16x16x32_bf16 v[124:127], v[156:159], v[172:175], v[124:127]
	v_mfma_f32_16x16x32_bf16 v[120:123], v[164:167], v[172:175], v[120:123]
	v_mfma_f32_16x16x32_bf16 v[108:111], v[156:159], v[180:183], v[108:111]
	v_mfma_f32_16x16x32_bf16 v[104:107], v[164:167], v[180:183], v[104:107]
	v_mfma_f32_16x16x32_bf16 v[92:95], v[156:159], v[188:191], v[92:95]
	v_mfma_f32_16x16x32_bf16 v[88:91], v[164:167], v[188:191], v[88:91]
	v_mfma_f32_16x16x32_bf16 v[76:79], v[156:159], v[196:199], v[76:79]
	v_mfma_f32_16x16x32_bf16 v[72:75], v[164:167], v[196:199], v[72:75]
	s_barrier
	s_setprio 0
	s_add_i32 s28, s83, s42
	v_add_u32_e32 v214, s84, v147
	s_mov_b32 m0, s28
	ds_read_b128 v[202:205], v214
	ds_read_b128 v[206:209], v214 offset:1024
	ds_read_b128 v[210:213], v214 offset:2048
	ds_read_b128 v[214:217], v214 offset:3072
	global_load_lds_dwordx4 v130, s[98:99]
	s_add_i32 m0, s28, 0x2000
	s_nop 0
	global_load_lds_dwordx4 v134, s[98:99]
	s_setprio 1
	s_barrier
	s_waitcnt lgkmcnt(0)
	v_mfma_f32_16x16x32_bf16 v[116:119], v[202:205], v[168:171], v[116:119]
	v_mfma_f32_16x16x32_bf16 v[112:115], v[210:213], v[168:171], v[112:115]
	v_mfma_f32_16x16x32_bf16 v[100:103], v[202:205], v[176:179], v[100:103]
	v_mfma_f32_16x16x32_bf16 v[96:99], v[210:213], v[176:179], v[96:99]
	v_mfma_f32_16x16x32_bf16 v[84:87], v[202:205], v[184:187], v[84:87]
	v_mfma_f32_16x16x32_bf16 v[80:83], v[210:213], v[184:187], v[80:83]
	v_mfma_f32_16x16x32_bf16 v[68:71], v[202:205], v[192:195], v[68:71]
	v_mfma_f32_16x16x32_bf16 v[64:67], v[210:213], v[192:195], v[64:67]
	v_mfma_f32_16x16x32_bf16 v[116:119], v[206:209], v[172:175], v[116:119]
	v_mfma_f32_16x16x32_bf16 v[112:115], v[214:217], v[172:175], v[112:115]
	v_mfma_f32_16x16x32_bf16 v[100:103], v[206:209], v[180:183], v[100:103]
	v_mfma_f32_16x16x32_bf16 v[96:99], v[214:217], v[180:183], v[96:99]
	v_mfma_f32_16x16x32_bf16 v[84:87], v[206:209], v[188:191], v[84:87]
	v_mfma_f32_16x16x32_bf16 v[80:83], v[214:217], v[188:191], v[80:83]
	v_mfma_f32_16x16x32_bf16 v[68:71], v[206:209], v[196:199], v[68:71]
	v_mfma_f32_16x16x32_bf16 v[64:67], v[214:217], v[196:199], v[64:67]
	s_barrier
	s_setprio 0
	s_mov_b32 m0, s47
	ds_read_b128 v[168:171], v150 offset:49152
	ds_read_b128 v[172:175], v150 offset:50176
	ds_read_b128 v[176:179], v150 offset:51200
	ds_read_b128 v[180:183], v150 offset:52224
	ds_read_b128 v[184:187], v150 offset:53248
	ds_read_b128 v[188:191], v150 offset:54272
	ds_read_b128 v[192:195], v150 offset:55296
	ds_read_b128 v[196:199], v150 offset:56320
	global_load_lds_dwordx4 v128, s[100:101]
	s_mov_b32 m0, s48
	s_nop 0
	global_load_lds_dwordx4 v132, s[100:101]
	s_setprio 1
	s_barrier
; __device__ __forceinline__ unsigned cvt_pk_bf16(float lo, float hi) { const bf16x2_t r = __builtin_convertvector((f32x2){lo, hi}, bf16x2_t); return __builtin_bit_cast(unsigned, r); }
; #define PG8_STAGE(bufoff, gbase, voff) do { _Pragma("unroll") for (int _i = 0; _i < 2; ++_i) \
;         __builtin_amdgcn_global_load_lds((const unsigned*)((const char*)(gbase) + (voff)[_i]), (LAS unsigned*)(lds + (bufoff) + ldsw + _i * 8192), 16, 0, 0); } while (0)
; #define PG8_WAIT_V(n) asm volatile("s_waitcnt vmcnt(" #n ")" ::: "memory")
; #define PG8_WAIT_L(n) asm volatile("s_waitcnt lgkmcnt(" #n ")" ::: "memory")
; #define PG8_BAR __builtin_amdgcn_s_barrier()
; #define PG8_SCHED __builtin_amdgcn_sched_barrier(0)
; template <class Epi>
; __device__ __forceinline__ void gemm_phase(LAS unsigned char* lds, const bf16_t* A, int lda, const bf16_t* Bt, int ldb, int M, int N, int K, int asel, const Epi& E, const int fixed_round = -1) {
;     ...
;             PG8_BAR; PG8_WAIT_L(0); PG8_MMA(1, 0, At, B0); PG8_BAR; PG8_SCHED;
;             PG8_STAGE(PG8_SB(1, 1), b3 + hstepB, voffB);
;             PG8_WAIT_V(6); PG8_BAR; PG8_MMA(1, 1, At, B1); PG8_BAR;
;     __device__ __forceinline__ void operator()(const AccT& acc, const Unit& u, int wr, int wc, int fr, int fq) const {
;         const int row0 = u.pm * BM + wr * 64 + fr, col0 = u.pn * BM + wc * 32 + 8 * fq;
; #pragma unroll
;         for (int ai = 0; ai < 2; ++ai)
; #pragma unroll
;             for (int m = 0; m < 4; ++m) { bf16_t* rowp = O + (size_t)(row0 + ai * HALF + m * 16) * DFF + col0;
; #pragma unroll
;                 for (int bj = 0; bj < 2; ++bj) { f32x4 v0 = acc[ai][bj][m][0], v1 = acc[ai][bj][m][1];
; #pragma unroll
;                     for (int j = 0; j < 4; ++j) { float a = fmaxf(v0[j], 0.f), b = fmaxf(v1[j], 0.f); v0[j] = a * a; v1[j] = b * b; }
;                     u32x4 w; w.x = cvt_pk_bf16(v0[0], v0[1]); w.y = cvt_pk_bf16(v0[2], v0[3]); w.z = cvt_pk_bf16(v1[0], v1[1]); w.w = cvt_pk_bf16(v1[2], v1[3]);
;                     *(u32x4*)(rowp + bj * HALF) = w; } }
;     }
	s_waitcnt lgkmcnt(0)
	v_mfma_f32_16x16x32_bf16 v[60:63], v[152:155], v[168:171], v[60:63]
	v_mfma_f32_16x16x32_bf16 v[56:59], v[160:163], v[168:171], v[56:59]
	v_mfma_f32_16x16x32_bf16 v[44:47], v[152:155], v[176:179], v[44:47]
	v_mfma_f32_16x16x32_bf16 v[40:43], v[160:163], v[176:179], v[40:43]
	v_mfma_f32_16x16x32_bf16 v[28:31], v[152:155], v[184:187], v[28:31]
	v_mfma_f32_16x16x32_bf16 v[24:27], v[160:163], v[184:187], v[24:27]
	v_mfma_f32_16x16x32_bf16 v[12:15], v[152:155], v[192:195], v[12:15]
	v_mfma_f32_16x16x32_bf16 v[8:11], v[160:163], v[192:195], v[8:11]
	v_mfma_f32_16x16x32_bf16 v[60:63], v[156:159], v[172:175], v[60:63]
	v_mfma_f32_16x16x32_bf16 v[56:59], v[164:167], v[172:175], v[56:59]
	v_mfma_f32_16x16x32_bf16 v[44:47], v[156:159], v[180:183], v[44:47]
	v_mfma_f32_16x16x32_bf16 v[40:43], v[164:167], v[180:183], v[40:43]
	v_mfma_f32_16x16x32_bf16 v[28:31], v[156:159], v[188:191], v[28:31]
	v_mfma_f32_16x16x32_bf16 v[24:27], v[164:167], v[188:191], v[24:27]
	v_mfma_f32_16x16x32_bf16 v[12:15], v[156:159], v[196:199], v[12:15]
	v_mfma_f32_16x16x32_bf16 v[8:11], v[164:167], v[196:199], v[8:11]
	s_barrier
	s_setprio 0
	s_add_u32 s28, s34, 0x80080
	s_addc_u32 s29, s35, 0
	s_add_i32 s34, s84, s42
	s_mov_b32 m0, s34
	s_nop 0
	global_load_lds_dwordx4 v130, s[28:29]
	s_add_i32 m0, s34, 0x2000
	s_nop 0
	global_load_lds_dwordx4 v134, s[28:29]
	s_waitcnt vmcnt(6)
	s_setprio 1
	s_barrier
	v_mfma_f32_16x16x32_bf16 v[52:55], v[202:205], v[168:171], v[52:55]
	v_mfma_f32_16x16x32_bf16 v[48:51], v[210:213], v[168:171], v[48:51]
	v_mfma_f32_16x16x32_bf16 v[36:39], v[202:205], v[176:179], v[36:39]
	v_mfma_f32_16x16x32_bf16 v[32:35], v[210:213], v[176:179], v[32:35]
	v_mfma_f32_16x16x32_bf16 v[20:23], v[202:205], v[184:187], v[20:23]
	v_mfma_f32_16x16x32_bf16 v[16:19], v[210:213], v[184:187], v[16:19]
	v_mfma_f32_16x16x32_bf16 v[4:7], v[202:205], v[192:195], v[4:7]
	v_mfma_f32_16x16x32_bf16 v[0:3], v[210:213], v[192:195], v[0:3]
	v_mfma_f32_16x16x32_bf16 v[52:55], v[206:209], v[172:175], v[52:55]
	v_mfma_f32_16x16x32_bf16 v[48:51], v[214:217], v[172:175], v[48:51]
	v_mfma_f32_16x16x32_bf16 v[36:39], v[206:209], v[180:183], v[36:39]
	v_mfma_f32_16x16x32_bf16 v[32:35], v[214:217], v[180:183], v[32:35]
	v_mfma_f32_16x16x32_bf16 v[20:23], v[206:209], v[188:191], v[20:23]
	v_mfma_f32_16x16x32_bf16 v[16:19], v[214:217], v[188:191], v[16:19]
	v_mfma_f32_16x16x32_bf16 v[4:7], v[206:209], v[196:199], v[4:7]
	v_mfma_f32_16x16x32_bf16 v[0:3], v[214:217], v[196:199], v[0:3]
	s_setprio 0
	s_add_i32 s56, s56, 2
	s_add_u32 s30, s30, 0x100
	s_addc_u32 s31, s31, 0
	s_add_u32 s54, s54, 0x100
	s_addc_u32 s55, s55, 0
	s_cmp_gt_u32 s56, 29
	s_cbranch_scc0 .Lrot_4
	s_barrier
	v_lshl_add_u32 v152, s26, 8, v146
	v_lshl_or_b32 v144, s51, 8, v148
	v_ashrrev_i32_e32 v153, 31, v152
	v_ashrrev_i32_e32 v145, 31, v144
	v_lshlrev_b64 v[154:155], 14, v[152:153]
	v_lshl_add_u64 v[154:155], s[88:89], 0, v[154:155]
	v_lshlrev_b64 v[156:157], 1, v[144:145]
	v_max_f32_e32 v120, 0, v120
	v_max_f32_e32 v121, 0, v121
	v_lshl_add_u64 v[144:145], v[154:155], 0, v[156:157]
	v_pk_mul_f32 v[154:155], v[120:121], v[120:121]
	v_max_f32_e32 v121, v122, v122
	v_max_f32_e32 v120, v126, v126
	v_max_f32_e32 v122, 0, v121
	v_max_f32_e32 v121, v127, v127
	v_max_f32_e32 v124, 0, v124
	v_max_f32_e32 v125, 0, v125
	v_max_f32_e32 v120, 0, v120
	v_max_f32_e32 v121, 0, v121
	v_max_f32_e32 v123, 0, v123
	v_pk_mul_f32 v[124:125], v[124:125], v[124:125]
	v_pk_mul_f32 v[126:127], v[120:121], v[120:121]
	v_pk_mul_f32 v[158:159], v[122:123], v[122:123]
	v_cvt_pk_bf16_f32 v120, v124, v125
	v_cvt_pk_bf16_f32 v121, v126, v127
	v_cvt_pk_bf16_f32 v122, v154, v155
	v_cvt_pk_bf16_f32 v123, v158, v159
	v_max_f32_e32 v112, 0, v112
	v_max_f32_e32 v113, 0, v113
	global_store_dwordx4 v[144:145], v[120:123], off
	s_nop 1
	v_pk_mul_f32 v[120:121], v[112:113], v[112:113]
	v_max_f32_e32 v113, v114, v114
	v_max_f32_e32 v112, v118, v118
	v_max_f32_e32 v114, 0, v113
	v_max_f32_e32 v113, v119, v119
	v_max_f32_e32 v116, 0, v116
	v_max_f32_e32 v117, 0, v117
	v_max_f32_e32 v112, 0, v112
	v_max_f32_e32 v113, 0, v113
	v_max_f32_e32 v115, 0, v115
	v_pk_mul_f32 v[116:117], v[116:117], v[116:117]
	v_pk_mul_f32 v[118:119], v[112:113], v[112:113]
	v_pk_mul_f32 v[122:123], v[114:115], v[114:115]
	v_cvt_pk_bf16_f32 v112, v116, v117
	v_cvt_pk_bf16_f32 v113, v118, v119
	v_cvt_pk_bf16_f32 v114, v120, v121
	v_cvt_pk_bf16_f32 v115, v122, v123
	v_max_f32_e32 v104, 0, v104
	v_max_f32_e32 v105, 0, v105
	global_store_dwordx4 v[144:145], v[112:115], off offset:256
	s_nop 1
	v_or_b32_e32 v112, 16, v152
	v_pk_mul_f32 v[114:115], v[104:105], v[104:105]
	v_max_f32_e32 v105, v106, v106
	v_ashrrev_i32_e32 v113, 31, v112
	v_max_f32_e32 v104, v110, v110
	v_max_f32_e32 v106, 0, v105
	v_max_f32_e32 v105, v111, v111
	v_lshlrev_b64 v[112:113], 14, v[112:113]
	v_max_f32_e32 v108, 0, v108
	v_max_f32_e32 v109, 0, v109
	v_max_f32_e32 v104, 0, v104
	v_max_f32_e32 v105, 0, v105
	v_max_f32_e32 v107, 0, v107
	v_lshl_add_u64 v[112:113], s[88:89], 0, v[112:113]
	v_pk_mul_f32 v[108:109], v[108:109], v[108:109]
	v_pk_mul_f32 v[110:111], v[104:105], v[104:105]
	v_pk_mul_f32 v[116:117], v[106:107], v[106:107]
	v_lshl_add_u64 v[112:113], v[112:113], 0, v[156:157]
	v_cvt_pk_bf16_f32 v104, v108, v109
	v_cvt_pk_bf16_f32 v105, v110, v111
	v_cvt_pk_bf16_f32 v106, v114, v115
	v_cvt_pk_bf16_f32 v107, v116, v117
	v_max_f32_e32 v96, 0, v96
	v_max_f32_e32 v97, 0, v97
	global_store_dwordx4 v[112:113], v[104:107], off
	s_nop 1
	v_pk_mul_f32 v[104:105], v[96:97], v[96:97]
	v_max_f32_e32 v97, v98, v98
	v_max_f32_e32 v96, v102, v102
	v_max_f32_e32 v98, 0, v97
	v_max_f32_e32 v97, v103, v103
; __device__ __forceinline__ unsigned cvt_pk_bf16(float lo, float hi) { const bf16x2_t r = __builtin_convertvector((f32x2){lo, hi}, bf16x2_t); return __builtin_bit_cast(unsigned, r); }
;     __device__ __forceinline__ void operator()(const AccT& acc, const Unit& u, int wr, int wc, int fr, int fq) const {
;     ...
;             for (int m = 0; m < 4; ++m) { bf16_t* rowp = O + (size_t)(row0 + ai * HALF + m * 16) * DFF + col0;
; #pragma unroll
;                 for (int bj = 0; bj < 2; ++bj) { f32x4 v0 = acc[ai][bj][m][0], v1 = acc[ai][bj][m][1];
; #pragma unroll
;                     for (int j = 0; j < 4; ++j) { float a = fmaxf(v0[j], 0.f), b = fmaxf(v1[j], 0.f); v0[j] = a * a; v1[j] = b * b; }
;                     u32x4 w; w.x = cvt_pk_bf16(v0[0], v0[1]); w.y = cvt_pk_bf16(v0[2], v0[3]); w.z = cvt_pk_bf16(v1[0], v1[1]); w.w = cvt_pk_bf16(v1[2], v1[3]);
;                     *(u32x4*)(rowp + bj * HALF) = w; } }
	v_max_f32_e32 v100, 0, v100
	v_max_f32_e32 v101, 0, v101
	v_max_f32_e32 v96, 0, v96
	v_max_f32_e32 v97, 0, v97
	v_max_f32_e32 v99, 0, v99
	v_pk_mul_f32 v[100:101], v[100:101], v[100:101]
	v_pk_mul_f32 v[102:103], v[96:97], v[96:97]
	v_pk_mul_f32 v[106:107], v[98:99], v[98:99]
	v_cvt_pk_bf16_f32 v96, v100, v101
	v_cvt_pk_bf16_f32 v97, v102, v103
	v_cvt_pk_bf16_f32 v98, v104, v105
	v_cvt_pk_bf16_f32 v99, v106, v107
	v_max_f32_e32 v88, 0, v88
	v_max_f32_e32 v89, 0, v89
	global_store_dwordx4 v[112:113], v[96:99], off offset:256
	s_nop 1
	v_or_b32_e32 v96, 32, v152
	v_pk_mul_f32 v[98:99], v[88:89], v[88:89]
	v_max_f32_e32 v89, v90, v90
	v_ashrrev_i32_e32 v97, 31, v96
	v_max_f32_e32 v88, v94, v94
	v_max_f32_e32 v90, 0, v89
	v_max_f32_e32 v89, v95, v95
	v_lshlrev_b64 v[96:97], 14, v[96:97]
	v_max_f32_e32 v92, 0, v92
	v_max_f32_e32 v93, 0, v93
	v_max_f32_e32 v88, 0, v88
	v_max_f32_e32 v89, 0, v89
	v_max_f32_e32 v91, 0, v91
	v_lshl_add_u64 v[96:97], s[88:89], 0, v[96:97]
	v_pk_mul_f32 v[92:93], v[92:93], v[92:93]
	v_pk_mul_f32 v[94:95], v[88:89], v[88:89]
	v_pk_mul_f32 v[100:101], v[90:91], v[90:91]
	v_lshl_add_u64 v[96:97], v[96:97], 0, v[156:157]
	v_cvt_pk_bf16_f32 v88, v92, v93
	v_cvt_pk_bf16_f32 v89, v94, v95
	v_cvt_pk_bf16_f32 v90, v98, v99
	v_cvt_pk_bf16_f32 v91, v100, v101
	v_max_f32_e32 v80, 0, v80
	v_max_f32_e32 v81, 0, v81
	global_store_dwordx4 v[96:97], v[88:91], off
	s_nop 1
	v_pk_mul_f32 v[88:89], v[80:81], v[80:81]
	v_max_f32_e32 v81, v82, v82
	v_max_f32_e32 v80, v86, v86
	v_max_f32_e32 v82, 0, v81
	v_max_f32_e32 v81, v87, v87
	v_max_f32_e32 v84, 0, v84
	v_max_f32_e32 v85, 0, v85
	v_max_f32_e32 v80, 0, v80
	v_max_f32_e32 v81, 0, v81
	v_max_f32_e32 v83, 0, v83
	v_pk_mul_f32 v[84:85], v[84:85], v[84:85]
	v_pk_mul_f32 v[86:87], v[80:81], v[80:81]
	v_pk_mul_f32 v[90:91], v[82:83], v[82:83]
	v_cvt_pk_bf16_f32 v80, v84, v85
	v_cvt_pk_bf16_f32 v81, v86, v87
	v_cvt_pk_bf16_f32 v82, v88, v89
	v_cvt_pk_bf16_f32 v83, v90, v91
	v_max_f32_e32 v72, 0, v72
	v_max_f32_e32 v73, 0, v73
	global_store_dwordx4 v[96:97], v[80:83], off offset:256
	s_nop 1
	v_or_b32_e32 v80, 48, v152
	v_pk_mul_f32 v[82:83], v[72:73], v[72:73]
	v_max_f32_e32 v73, v74, v74
	v_ashrrev_i32_e32 v81, 31, v80
	v_max_f32_e32 v72, v78, v78
	v_max_f32_e32 v74, 0, v73
	v_max_f32_e32 v73, v79, v79
	v_lshlrev_b64 v[80:81], 14, v[80:81]
	v_max_f32_e32 v76, 0, v76
	v_max_f32_e32 v77, 0, v77
	v_max_f32_e32 v72, 0, v72
	v_max_f32_e32 v73, 0, v73
	v_max_f32_e32 v75, 0, v75
	v_lshl_add_u64 v[80:81], s[88:89], 0, v[80:81]
	v_pk_mul_f32 v[76:77], v[76:77], v[76:77]
	v_pk_mul_f32 v[78:79], v[72:73], v[72:73]
	v_pk_mul_f32 v[84:85], v[74:75], v[74:75]
	v_lshl_add_u64 v[80:81], v[80:81], 0, v[156:157]
	v_cvt_pk_bf16_f32 v72, v76, v77
	v_cvt_pk_bf16_f32 v73, v78, v79
	v_cvt_pk_bf16_f32 v74, v82, v83
	v_cvt_pk_bf16_f32 v75, v84, v85
	v_max_f32_e32 v64, 0, v64
	v_max_f32_e32 v65, 0, v65
	global_store_dwordx4 v[80:81], v[72:75], off
	s_nop 1
	v_pk_mul_f32 v[72:73], v[64:65], v[64:65]
	v_max_f32_e32 v65, v66, v66
	v_max_f32_e32 v64, v70, v70
	v_max_f32_e32 v66, 0, v65
	v_max_f32_e32 v65, v71, v71
	v_max_f32_e32 v68, 0, v68
	v_max_f32_e32 v69, 0, v69
	v_max_f32_e32 v64, 0, v64
	v_max_f32_e32 v65, 0, v65
	v_max_f32_e32 v67, 0, v67
	v_pk_mul_f32 v[68:69], v[68:69], v[68:69]
	v_pk_mul_f32 v[70:71], v[64:65], v[64:65]
	v_pk_mul_f32 v[74:75], v[66:67], v[66:67]
	v_cvt_pk_bf16_f32 v64, v68, v69
	v_cvt_pk_bf16_f32 v65, v70, v71
	v_cvt_pk_bf16_f32 v66, v72, v73
	v_cvt_pk_bf16_f32 v67, v74, v75
	v_max_f32_e32 v56, 0, v56
	v_max_f32_e32 v57, 0, v57
	global_store_dwordx4 v[80:81], v[64:67], off offset:256
	s_nop 1
	v_pk_mul_f32 v[66:67], v[56:57], v[56:57]
	v_max_f32_e32 v57, v58, v58
	v_max_f32_e32 v60, 0, v60
	v_max_f32_e32 v61, 0, v61
	v_max_f32_e32 v56, v62, v62
	v_max_f32_e32 v58, 0, v57
	v_max_f32_e32 v57, v63, v63
	v_pk_mul_f32 v[60:61], v[60:61], v[60:61]
	v_max_f32_e32 v56, 0, v56
	v_max_f32_e32 v57, 0, v57
	v_max_f32_e32 v59, 0, v59
	s_mov_b32 s5, 0x200000
	v_pk_mul_f32 v[62:63], v[56:57], v[56:57]
	v_pk_mul_f32 v[68:69], v[58:59], v[58:59]
	v_cvt_pk_bf16_f32 v56, v60, v61
	v_add_co_u32_e32 v60, vcc, s5, v144
	v_cvt_pk_bf16_f32 v57, v62, v63
	v_cvt_pk_bf16_f32 v58, v66, v67
	v_cvt_pk_bf16_f32 v59, v68, v69
	v_addc_co_u32_e32 v61, vcc, 0, v145, vcc
	v_max_f32_e32 v48, 0, v48
	v_max_f32_e32 v49, 0, v49
	global_store_dwordx4 v[60:61], v[56:59], off
	s_nop 1
	v_pk_mul_f32 v[56:57], v[48:49], v[48:49]
	v_max_f32_e32 v49, v50, v50
	v_max_f32_e32 v48, v54, v54
	v_max_f32_e32 v50, 0, v49
	v_max_f32_e32 v49, v55, v55
	v_max_f32_e32 v52, 0, v52
	v_max_f32_e32 v53, 0, v53
	v_max_f32_e32 v48, 0, v48
	v_max_f32_e32 v49, 0, v49
	v_max_f32_e32 v51, 0, v51
	s_mov_b64 s[28:29], 0x200000
	v_pk_mul_f32 v[52:53], v[52:53], v[52:53]
	v_pk_mul_f32 v[54:55], v[48:49], v[48:49]
	v_pk_mul_f32 v[58:59], v[50:51], v[50:51]
	v_lshl_add_u64 v[64:65], v[144:145], 0, s[28:29]
; __device__ __forceinline__ unsigned cvt_pk_bf16(float lo, float hi) { const bf16x2_t r = __builtin_convertvector((f32x2){lo, hi}, bf16x2_t); return __builtin_bit_cast(unsigned, r); }
; #define PG8_WAIT_V(n) asm volatile("s_waitcnt vmcnt(" #n ")" ::: "memory")
; #define PG8_BAR __builtin_amdgcn_s_barrier()
; template <class Epi>
; __device__ __forceinline__ void gemm_phase(LAS unsigned char* lds, const bf16_t* A, int lda, const bf16_t* Bt, int ldb, int M, int N, int K, int asel, const Epi& E, const int fixed_round = -1) {
;     ...
;         if (!has_next) break;
; #pragma unroll
;         for (int a = 0; a < 2; ++a)
; #pragma unroll
;             for (int b = 0; b < 2; ++b)
; #pragma unroll
;                 for (int m = 0; m < 4; ++m)
; #pragma unroll
;                     for (int n = 0; n < 2; ++n) acc[a][b][m][n] = (f32x4){0.f, 0.f, 0.f, 0.f};
;         cur = nxt; cA = nA; cB = nB; ++ui;
;     }
;     PG8_WAIT_V(0);
;     if (wr == 0) PG8_BAR;
;     PG8_BAR;
;     __device__ __forceinline__ void operator()(const AccT& acc, const Unit& u, int wr, int wc, int fr, int fq) const {
;     ...
;             for (int m = 0; m < 4; ++m) { bf16_t* rowp = O + (size_t)(row0 + ai * HALF + m * 16) * DFF + col0;
; #pragma unroll
;                 for (int bj = 0; bj < 2; ++bj) { f32x4 v0 = acc[ai][bj][m][0], v1 = acc[ai][bj][m][1];
; #pragma unroll
;                     for (int j = 0; j < 4; ++j) { float a = fmaxf(v0[j], 0.f), b = fmaxf(v1[j], 0.f); v0[j] = a * a; v1[j] = b * b; }
;                     u32x4 w; w.x = cvt_pk_bf16(v0[0], v0[1]); w.y = cvt_pk_bf16(v0[2], v0[3]); w.z = cvt_pk_bf16(v1[0], v1[1]); w.w = cvt_pk_bf16(v1[2], v1[3]);
;                     *(u32x4*)(rowp + bj * HALF) = w; } }
	v_cvt_pk_bf16_f32 v48, v52, v53
	v_cvt_pk_bf16_f32 v49, v54, v55
	v_cvt_pk_bf16_f32 v50, v56, v57
	v_cvt_pk_bf16_f32 v51, v58, v59
	v_max_f32_e32 v40, 0, v40
	v_max_f32_e32 v41, 0, v41
	global_store_dwordx4 v[64:65], v[48:51], off offset:256
	s_nop 1
	v_pk_mul_f32 v[50:51], v[40:41], v[40:41]
	v_max_f32_e32 v41, v42, v42
	v_max_f32_e32 v44, 0, v44
	v_max_f32_e32 v45, 0, v45
	v_max_f32_e32 v40, v46, v46
	v_max_f32_e32 v42, 0, v41
	v_max_f32_e32 v41, v47, v47
	v_pk_mul_f32 v[44:45], v[44:45], v[44:45]
	v_max_f32_e32 v40, 0, v40
	v_max_f32_e32 v41, 0, v41
	v_max_f32_e32 v43, 0, v43
	s_mov_b32 s5, 0x240000
	v_pk_mul_f32 v[46:47], v[40:41], v[40:41]
	v_pk_mul_f32 v[52:53], v[42:43], v[42:43]
	v_cvt_pk_bf16_f32 v40, v44, v45
	v_add_co_u32_e32 v44, vcc, s5, v144
	v_cvt_pk_bf16_f32 v41, v46, v47
	v_cvt_pk_bf16_f32 v42, v50, v51
	v_cvt_pk_bf16_f32 v43, v52, v53
	v_addc_co_u32_e32 v45, vcc, 0, v145, vcc
	v_max_f32_e32 v32, 0, v32
	v_max_f32_e32 v33, 0, v33
	global_store_dwordx4 v[44:45], v[40:43], off
	s_nop 1
	v_pk_mul_f32 v[40:41], v[32:33], v[32:33]
	v_max_f32_e32 v33, v34, v34
	v_max_f32_e32 v32, v38, v38
	v_max_f32_e32 v34, 0, v33
	v_max_f32_e32 v33, v39, v39
	v_max_f32_e32 v36, 0, v36
	v_max_f32_e32 v37, 0, v37
	v_max_f32_e32 v32, 0, v32
	v_max_f32_e32 v33, 0, v33
	v_max_f32_e32 v35, 0, v35
	s_mov_b64 s[28:29], 0x240000
	v_pk_mul_f32 v[36:37], v[36:37], v[36:37]
	v_pk_mul_f32 v[38:39], v[32:33], v[32:33]
	v_pk_mul_f32 v[42:43], v[34:35], v[34:35]
	v_lshl_add_u64 v[48:49], v[144:145], 0, s[28:29]
	v_cvt_pk_bf16_f32 v32, v36, v37
	v_cvt_pk_bf16_f32 v33, v38, v39
	v_cvt_pk_bf16_f32 v34, v40, v41
	v_cvt_pk_bf16_f32 v35, v42, v43
	v_max_f32_e32 v24, 0, v24
	v_max_f32_e32 v25, 0, v25
	global_store_dwordx4 v[48:49], v[32:35], off offset:256
	s_nop 1
	v_pk_mul_f32 v[34:35], v[24:25], v[24:25]
	v_max_f32_e32 v25, v26, v26
	v_max_f32_e32 v28, 0, v28
	v_max_f32_e32 v29, 0, v29
	v_max_f32_e32 v24, v30, v30
	v_max_f32_e32 v26, 0, v25
	v_max_f32_e32 v25, v31, v31
	v_pk_mul_f32 v[28:29], v[28:29], v[28:29]
	v_max_f32_e32 v24, 0, v24
	v_max_f32_e32 v25, 0, v25
	v_max_f32_e32 v27, 0, v27
	s_mov_b32 s5, 0x280000
	v_pk_mul_f32 v[30:31], v[24:25], v[24:25]
	v_pk_mul_f32 v[36:37], v[26:27], v[26:27]
	v_cvt_pk_bf16_f32 v24, v28, v29
	v_add_co_u32_e32 v28, vcc, s5, v144
	v_cvt_pk_bf16_f32 v25, v30, v31
	v_cvt_pk_bf16_f32 v26, v34, v35
	v_cvt_pk_bf16_f32 v27, v36, v37
	v_addc_co_u32_e32 v29, vcc, 0, v145, vcc
	v_max_f32_e32 v16, 0, v16
	v_max_f32_e32 v17, 0, v17
	global_store_dwordx4 v[28:29], v[24:27], off
	s_nop 1
	v_pk_mul_f32 v[24:25], v[16:17], v[16:17]
	v_max_f32_e32 v17, v18, v18
	v_max_f32_e32 v16, v22, v22
	v_max_f32_e32 v18, 0, v17
	v_max_f32_e32 v17, v23, v23
	v_max_f32_e32 v20, 0, v20
	v_max_f32_e32 v21, 0, v21
	v_max_f32_e32 v16, 0, v16
	v_max_f32_e32 v17, 0, v17
	v_max_f32_e32 v19, 0, v19
	s_mov_b64 s[28:29], 0x280000
	v_pk_mul_f32 v[20:21], v[20:21], v[20:21]
	v_pk_mul_f32 v[22:23], v[16:17], v[16:17]
	v_pk_mul_f32 v[26:27], v[18:19], v[18:19]
	v_lshl_add_u64 v[32:33], v[144:145], 0, s[28:29]
	v_cvt_pk_bf16_f32 v16, v20, v21
	v_cvt_pk_bf16_f32 v17, v22, v23
	v_cvt_pk_bf16_f32 v18, v24, v25
	v_cvt_pk_bf16_f32 v19, v26, v27
	v_max_f32_e32 v8, 0, v8
	v_max_f32_e32 v9, 0, v9
	global_store_dwordx4 v[32:33], v[16:19], off offset:256
	s_nop 1
	v_pk_mul_f32 v[18:19], v[8:9], v[8:9]
	v_max_f32_e32 v9, v10, v10
	v_max_f32_e32 v12, 0, v12
	v_max_f32_e32 v13, 0, v13
	v_max_f32_e32 v8, v14, v14
	v_max_f32_e32 v10, 0, v9
	v_max_f32_e32 v9, v15, v15
	v_pk_mul_f32 v[12:13], v[12:13], v[12:13]
	v_max_f32_e32 v8, 0, v8
	v_max_f32_e32 v9, 0, v9
	v_max_f32_e32 v11, 0, v11
	v_pk_mul_f32 v[14:15], v[8:9], v[8:9]
	v_pk_mul_f32 v[20:21], v[10:11], v[10:11]
	v_cvt_pk_bf16_f32 v8, v12, v13
	v_add_co_u32_e32 v12, vcc, s50, v144
	v_cvt_pk_bf16_f32 v9, v14, v15
	v_cvt_pk_bf16_f32 v10, v18, v19
	v_cvt_pk_bf16_f32 v11, v20, v21
	v_addc_co_u32_e32 v13, vcc, 0, v145, vcc
	v_max_f32_e32 v0, 0, v0
	v_max_f32_e32 v1, 0, v1
	global_store_dwordx4 v[12:13], v[8:11], off
	s_nop 1
	v_pk_mul_f32 v[8:9], v[0:1], v[0:1]
	v_max_f32_e32 v1, v2, v2
	v_max_f32_e32 v0, v6, v6
	v_max_f32_e32 v2, 0, v1
	v_max_f32_e32 v1, v7, v7
	v_max_f32_e32 v4, 0, v4
	v_max_f32_e32 v5, 0, v5
	v_max_f32_e32 v0, 0, v0
	v_max_f32_e32 v1, 0, v1
	v_max_f32_e32 v3, 0, v3
	s_mov_b64 s[28:29], 0x2c0000
	v_pk_mul_f32 v[4:5], v[4:5], v[4:5]
	v_pk_mul_f32 v[6:7], v[0:1], v[0:1]
	v_pk_mul_f32 v[10:11], v[2:3], v[2:3]
	v_lshl_add_u64 v[16:17], v[144:145], 0, s[28:29]
	v_cvt_pk_bf16_f32 v0, v4, v5
	v_cvt_pk_bf16_f32 v1, v6, v7
	v_cvt_pk_bf16_f32 v2, v8, v9
	v_cvt_pk_bf16_f32 v3, v10, v11
	s_and_b64 vcc, exec, s[0:1]
	s_mov_b32 s51, s4
	s_mov_b32 s26, s6
	s_mov_b64 s[34:35], s[20:21]
	s_mov_b64 s[30:31], s[18:19]
	global_store_dwordx4 v[16:17], v[0:3], off offset:256
	s_cbranch_vccz .LBB0_584
	s_waitcnt vmcnt(0)
	s_cmpk_gt_u32 s33, 0xff
	s_cbranch_scc1 .LBB0_595
	s_barrier

; #define PG8_STAGE(bufoff, gbase, voff) do { _Pragma("unroll") for (int _i = 0; _i < 2; ++_i) \
;         __builtin_amdgcn_global_load_lds((const unsigned*)((const char*)(gbase) + (voff)[_i]), (LAS unsigned*)(lds + (bufoff) + ldsw + _i * 8192), 16, 0, 0); } while (0)
; #define PG8_LDA(dst, b, h) do { _Pragma("unroll") for (int m = 0; m < 4; ++m) _Pragma("unroll") for (int k = 0; k < 2; ++k) dst[m][k] = *(const LAS bf16x8*)(lds + PG8_SA(b, h) + aoff + m * 2048 + k * 1024); } while (0)
; #define PG8_LDB(dst, b, h) do { _Pragma("unroll") for (int n = 0; n < 2; ++n) _Pragma("unroll") for (int k = 0; k < 2; ++k) dst[n][k] = *(const LAS bf16x8*)(lds + PG8_SB(b, h) + boff + n * 2048 + k * 1024); } while (0)
; #define PG8_WAIT_V(n) asm volatile("s_waitcnt vmcnt(" #n ")" ::: "memory")
; #define PG8_WAIT_L(n) asm volatile("s_waitcnt lgkmcnt(" #n ")" ::: "memory")
; #define PG8_BAR __builtin_amdgcn_s_barrier()
; #define PG8_SCHED __builtin_amdgcn_sched_barrier(0)
; template <class Epi>
; __device__ __forceinline__ void gemm_phase(LAS unsigned char* lds, const bf16_t* A, int lda, const bf16_t* Bt, int ldb, int M, int N, int K, int asel, const Epi& E, const int fixed_round = -1) {
;     ...
;             const bool last = (t == nt - 2);
;             const char* a1 = cA + (size_t)(t + 1) * kstep;
;             const char* a2 = last ? nA : cA + (size_t)(t + 2) * kstep; const char* b2 = last ? nB : cB + (size_t)(t + 2) * kstep;
;             const char* a3 = a2 + kstep; const char* b3 = b2 + kstep;
;             PG8_LDB(B0, 0, 0); PG8_SCHED; PG8_LDA(At, 0, 0); PG8_STAGE(PG8_SA(1, 1), a1 + hstepA, voffA);
;             PG8_WAIT_L(8); PG8_BAR; PG8_WAIT_L(0); PG8_MMA(0, 0, At, B0); PG8_BAR; PG8_SCHED;
;             PG8_LDB(B1, 0, 1); PG8_STAGE(PG8_SB(0, 0), b2, voffB);
;             PG8_BAR; PG8_WAIT_L(0); PG8_MMA(0, 1, At, B1); PG8_BAR;
;             PG8_LDA(At, 0, 1); PG8_STAGE(PG8_SA(0, 0), a2, voffA);
;             PG8_BAR; PG8_WAIT_L(0); PG8_MMA(1, 0, At, B0); PG8_BAR; PG8_SCHED;
;             PG8_STAGE(PG8_SB(0, 1), b2 + hstepB, voffB);
;             PG8_WAIT_V(6); PG8_BAR; PG8_MMA(1, 1, At, B1); PG8_BAR;
.LBB0_651:
	ds_read_b128 v[146:149], v140
	ds_read_b128 v[150:153], v140 offset:1024
	ds_read_b128 v[160:163], v140 offset:2048
	ds_read_b128 v[166:169], v140 offset:3072
	s_mov_b32 m0, s49
	v_lshl_add_u64 v[156:157], v[136:137], 0, s[20:21]
	ds_read_b128 v[170:173], v141
	ds_read_b128 v[174:177], v141 offset:1024
	ds_read_b128 v[178:181], v141 offset:2048
	ds_read_b128 v[182:185], v141 offset:3072
	ds_read_b128 v[186:189], v141 offset:4096
	ds_read_b128 v[190:193], v141 offset:5120
	ds_read_b128 v[194:197], v141 offset:6144
	ds_read_b128 v[202:205], v141 offset:7168
	global_load_lds_dwordx4 v[156:157], off
	v_lshl_add_u64 v[156:157], v[138:139], 0, s[20:21]
	s_mov_b32 m0, s50
	s_nop 0
	global_load_lds_dwordx4 v[156:157], off
	s_waitcnt lgkmcnt(8)
	s_setprio 1
	s_barrier
	s_waitcnt lgkmcnt(0)
	v_mfma_f32_16x16x32_bf16 v[124:127], v[146:149], v[170:173], v[124:127]
	v_mfma_f32_16x16x32_bf16 v[120:123], v[160:163], v[170:173], v[120:123]
	v_mfma_f32_16x16x32_bf16 v[112:115], v[146:149], v[178:181], v[112:115]
	v_mfma_f32_16x16x32_bf16 v[104:107], v[160:163], v[178:181], v[104:107]
	v_mfma_f32_16x16x32_bf16 v[96:99], v[146:149], v[186:189], v[96:99]
	v_mfma_f32_16x16x32_bf16 v[88:91], v[160:163], v[186:189], v[88:91]
	v_mfma_f32_16x16x32_bf16 v[80:83], v[146:149], v[194:197], v[80:83]
	v_mfma_f32_16x16x32_bf16 v[72:75], v[160:163], v[194:197], v[72:75]
	v_mfma_f32_16x16x32_bf16 v[124:127], v[150:153], v[174:177], v[124:127]
	v_mfma_f32_16x16x32_bf16 v[120:123], v[166:169], v[174:177], v[120:123]
	v_mfma_f32_16x16x32_bf16 v[112:115], v[150:153], v[182:185], v[112:115]
	v_mfma_f32_16x16x32_bf16 v[104:107], v[166:169], v[182:185], v[104:107]
	v_mfma_f32_16x16x32_bf16 v[96:99], v[150:153], v[190:193], v[96:99]
	v_mfma_f32_16x16x32_bf16 v[88:91], v[166:169], v[190:193], v[88:91]
	v_mfma_f32_16x16x32_bf16 v[80:83], v[150:153], v[202:205], v[80:83]
	v_mfma_f32_16x16x32_bf16 v[72:75], v[166:169], v[202:205], v[72:75]
	s_barrier
	s_setprio 0
	s_add_u32 s28, s20, 0xe7900080
	s_addc_u32 s29, s21, -1
	s_cmpk_lg_i32 s48, 0x7c
	s_cselect_b32 s28, s28, 0
	s_cselect_b32 s29, s29, 0
	s_add_u32 s36, s86, s28
	s_addc_u32 s37, s87, s29
	s_add_u32 s34, s2, s28
	s_addc_u32 s35, s3, s29
	s_mov_b32 m0, s51
	s_add_u32 s98, s34, s0
	s_addc_u32 s99, s35, s1
	ds_read_b128 v[206:209], v142
	ds_read_b128 v[210:213], v142 offset:1024
	ds_read_b128 v[214:217], v142 offset:2048
	ds_read_b128 v[218:221], v142 offset:3072
	global_load_lds_dwordx4 v130, s[34:35]
	s_mov_b32 m0, s52
	s_nop 0
	global_load_lds_dwordx4 v134, s[34:35]
	s_setprio 1
	s_barrier
	s_waitcnt lgkmcnt(0)
	v_mfma_f32_16x16x32_bf16 v[116:119], v[206:209], v[170:173], v[116:119]
	v_mfma_f32_16x16x32_bf16 v[108:111], v[214:217], v[170:173], v[108:111]
	v_mfma_f32_16x16x32_bf16 v[100:103], v[206:209], v[178:181], v[100:103]
	v_mfma_f32_16x16x32_bf16 v[92:95], v[214:217], v[178:181], v[92:95]
	v_mfma_f32_16x16x32_bf16 v[84:87], v[206:209], v[186:189], v[84:87]
	v_mfma_f32_16x16x32_bf16 v[76:79], v[214:217], v[186:189], v[76:79]
	v_mfma_f32_16x16x32_bf16 v[68:71], v[206:209], v[194:197], v[68:71]
	v_mfma_f32_16x16x32_bf16 v[64:67], v[214:217], v[194:197], v[64:67]
	v_mfma_f32_16x16x32_bf16 v[116:119], v[210:213], v[174:177], v[116:119]
	v_mfma_f32_16x16x32_bf16 v[108:111], v[218:221], v[174:177], v[108:111]
	v_mfma_f32_16x16x32_bf16 v[100:103], v[210:213], v[182:185], v[100:103]
	v_mfma_f32_16x16x32_bf16 v[92:95], v[218:221], v[182:185], v[92:95]
	v_mfma_f32_16x16x32_bf16 v[84:87], v[210:213], v[190:193], v[84:87]
	v_mfma_f32_16x16x32_bf16 v[76:79], v[218:221], v[190:193], v[76:79]
	v_mfma_f32_16x16x32_bf16 v[68:71], v[210:213], v[202:205], v[68:71]
	v_mfma_f32_16x16x32_bf16 v[64:67], v[218:221], v[202:205], v[64:67]
	s_barrier
	s_setprio 0
	s_mov_b32 m0, s42
	s_add_u32 s100, s36, s0
	s_addc_u32 s101, s37, s1
	ds_read_b128 v[170:173], v141 offset:16384
	ds_read_b128 v[174:177], v141 offset:17408
	ds_read_b128 v[178:181], v141 offset:18432
	ds_read_b128 v[182:185], v141 offset:19456
	ds_read_b128 v[186:189], v141 offset:20480
	ds_read_b128 v[190:193], v141 offset:21504
	ds_read_b128 v[194:197], v141 offset:22528
	ds_read_b128 v[202:205], v141 offset:23552
	global_load_lds_dwordx4 v128, s[36:37]
	s_mov_b32 m0, s43
	s_nop 0
	global_load_lds_dwordx4 v132, s[36:37]
	s_setprio 1
	s_barrier
	s_waitcnt lgkmcnt(0)
	v_mfma_f32_16x16x32_bf16 v[60:63], v[146:149], v[170:173], v[60:63]
	v_mfma_f32_16x16x32_bf16 v[56:59], v[160:163], v[170:173], v[56:59]
	v_mfma_f32_16x16x32_bf16 v[48:51], v[146:149], v[178:181], v[48:51]
	v_mfma_f32_16x16x32_bf16 v[40:43], v[160:163], v[178:181], v[40:43]
	v_mfma_f32_16x16x32_bf16 v[32:35], v[146:149], v[186:189], v[32:35]
	v_mfma_f32_16x16x32_bf16 v[24:27], v[160:163], v[186:189], v[24:27]
	v_mfma_f32_16x16x32_bf16 v[16:19], v[146:149], v[194:197], v[16:19]
	v_mfma_f32_16x16x32_bf16 v[8:11], v[160:163], v[194:197], v[8:11]
	v_mfma_f32_16x16x32_bf16 v[60:63], v[150:153], v[174:177], v[60:63]
	v_mfma_f32_16x16x32_bf16 v[56:59], v[166:169], v[174:177], v[56:59]
	v_mfma_f32_16x16x32_bf16 v[48:51], v[150:153], v[182:185], v[48:51]
	v_mfma_f32_16x16x32_bf16 v[40:43], v[166:169], v[182:185], v[40:43]
	v_mfma_f32_16x16x32_bf16 v[32:35], v[150:153], v[190:193], v[32:35]
	v_mfma_f32_16x16x32_bf16 v[24:27], v[166:169], v[190:193], v[24:27]
	v_mfma_f32_16x16x32_bf16 v[16:19], v[150:153], v[202:205], v[16:19]
	v_mfma_f32_16x16x32_bf16 v[8:11], v[166:169], v[202:205], v[8:11]
	s_barrier
	s_setprio 0
	s_add_u32 s28, s34, 0x200000
	s_addc_u32 s29, s35, 0
	s_mov_b32 m0, s53
	s_nop 0
	global_load_lds_dwordx4 v130, s[28:29]
	s_mov_b32 m0, s54
	s_nop 0
	global_load_lds_dwordx4 v134, s[28:29]
	s_waitcnt vmcnt(6)
	s_setprio 1
	s_barrier
; #define PG8_STAGE(bufoff, gbase, voff) do { _Pragma("unroll") for (int _i = 0; _i < 2; ++_i) \
;         __builtin_amdgcn_global_load_lds((const unsigned*)((const char*)(gbase) + (voff)[_i]), (LAS unsigned*)(lds + (bufoff) + ldsw + _i * 8192), 16, 0, 0); } while (0)
; #define PG8_LDA(dst, b, h) do { _Pragma("unroll") for (int m = 0; m < 4; ++m) _Pragma("unroll") for (int k = 0; k < 2; ++k) dst[m][k] = *(const LAS bf16x8*)(lds + PG8_SA(b, h) + aoff + m * 2048 + k * 1024); } while (0)
; #define PG8_LDB(dst, b, h) do { _Pragma("unroll") for (int n = 0; n < 2; ++n) _Pragma("unroll") for (int k = 0; k < 2; ++k) dst[n][k] = *(const LAS bf16x8*)(lds + PG8_SB(b, h) + boff + n * 2048 + k * 1024); } while (0)
; #define PG8_WAIT_V(n) asm volatile("s_waitcnt vmcnt(" #n ")" ::: "memory")
; #define PG8_WAIT_L(n) asm volatile("s_waitcnt lgkmcnt(" #n ")" ::: "memory")
; #define PG8_BAR __builtin_amdgcn_s_barrier()
; #define PG8_SCHED __builtin_amdgcn_sched_barrier(0)
; template <class Epi>
; __device__ __forceinline__ void gemm_phase(LAS unsigned char* lds, const bf16_t* A, int lda, const bf16_t* Bt, int ldb, int M, int N, int K, int asel, const Epi& E, const int fixed_round = -1) {
;     ...
;             PG8_WAIT_V(6); PG8_BAR; PG8_MMA(1, 1, At, B1); PG8_BAR;
;             PG8_LDB(B0, 1, 0); PG8_SCHED; PG8_LDA(At, 1, 0); PG8_STAGE(PG8_SA(0, 1), a2 + hstepA, voffA);
;             PG8_WAIT_L(8); PG8_BAR; PG8_WAIT_L(0); PG8_MMA(0, 0, At, B0); PG8_BAR; PG8_SCHED;
	v_mfma_f32_16x16x32_bf16 v[52:55], v[206:209], v[170:173], v[52:55]
	v_mfma_f32_16x16x32_bf16 v[44:47], v[214:217], v[170:173], v[44:47]
	v_mfma_f32_16x16x32_bf16 v[36:39], v[206:209], v[178:181], v[36:39]
	v_mfma_f32_16x16x32_bf16 v[28:31], v[214:217], v[178:181], v[28:31]
	v_mfma_f32_16x16x32_bf16 v[20:23], v[206:209], v[186:189], v[20:23]
	v_mfma_f32_16x16x32_bf16 v[12:15], v[214:217], v[186:189], v[12:15]
	v_mfma_f32_16x16x32_bf16 v[4:7], v[206:209], v[194:197], v[4:7]
	v_mfma_f32_16x16x32_bf16 v[0:3], v[214:217], v[194:197], v[0:3]
	v_mfma_f32_16x16x32_bf16 v[52:55], v[210:213], v[174:177], v[52:55]
	v_mfma_f32_16x16x32_bf16 v[44:47], v[218:221], v[174:177], v[44:47]
	v_mfma_f32_16x16x32_bf16 v[36:39], v[210:213], v[182:185], v[36:39]
	v_mfma_f32_16x16x32_bf16 v[28:31], v[218:221], v[182:185], v[28:31]
	v_mfma_f32_16x16x32_bf16 v[20:23], v[210:213], v[190:193], v[20:23]
	v_mfma_f32_16x16x32_bf16 v[12:15], v[218:221], v[190:193], v[12:15]
	v_mfma_f32_16x16x32_bf16 v[4:7], v[210:213], v[202:205], v[4:7]
	v_mfma_f32_16x16x32_bf16 v[0:3], v[218:221], v[202:205], v[0:3]
	s_barrier
	s_setprio 0
	ds_read_b128 v[146:149], v143
	ds_read_b128 v[150:153], v143 offset:1024
	ds_read_b128 v[160:163], v143 offset:2048
	ds_read_b128 v[166:169], v143 offset:3072
	s_add_u32 s28, s36, 0x200000
	s_addc_u32 s29, s37, 0
	s_mov_b32 m0, s44
	ds_read_b128 v[170:173], v141 offset:32768
	ds_read_b128 v[174:177], v141 offset:33792
	ds_read_b128 v[178:181], v141 offset:34816
	ds_read_b128 v[182:185], v141 offset:35840
	ds_read_b128 v[186:189], v141 offset:36864
	ds_read_b128 v[190:193], v141 offset:37888
	ds_read_b128 v[194:197], v141 offset:38912
	ds_read_b128 v[202:205], v141 offset:39936
	global_load_lds_dwordx4 v128, s[28:29]
	s_mov_b32 m0, s45
	s_nop 0
	global_load_lds_dwordx4 v132, s[28:29]
	s_waitcnt lgkmcnt(8)
	s_setprio 1
	s_barrier
	s_waitcnt lgkmcnt(0)
	v_mfma_f32_16x16x32_bf16 v[124:127], v[146:149], v[170:173], v[124:127]
	v_mfma_f32_16x16x32_bf16 v[120:123], v[160:163], v[170:173], v[120:123]
	v_mfma_f32_16x16x32_bf16 v[112:115], v[146:149], v[178:181], v[112:115]
	v_mfma_f32_16x16x32_bf16 v[104:107], v[160:163], v[178:181], v[104:107]
	v_mfma_f32_16x16x32_bf16 v[96:99], v[146:149], v[186:189], v[96:99]
	v_mfma_f32_16x16x32_bf16 v[88:91], v[160:163], v[186:189], v[88:91]
	v_mfma_f32_16x16x32_bf16 v[80:83], v[146:149], v[194:197], v[80:83]
	v_mfma_f32_16x16x32_bf16 v[72:75], v[160:163], v[194:197], v[72:75]
	v_mfma_f32_16x16x32_bf16 v[124:127], v[150:153], v[174:177], v[124:127]
	v_mfma_f32_16x16x32_bf16 v[120:123], v[166:169], v[174:177], v[120:123]
	v_mfma_f32_16x16x32_bf16 v[112:115], v[150:153], v[182:185], v[112:115]
	v_mfma_f32_16x16x32_bf16 v[104:107], v[166:169], v[182:185], v[104:107]
	v_mfma_f32_16x16x32_bf16 v[96:99], v[150:153], v[190:193], v[96:99]
	v_mfma_f32_16x16x32_bf16 v[88:91], v[166:169], v[190:193], v[88:91]
	v_mfma_f32_16x16x32_bf16 v[80:83], v[150:153], v[202:205], v[80:83]
	v_mfma_f32_16x16x32_bf16 v[72:75], v[166:169], v[202:205], v[72:75]
	s_barrier
	s_setprio 0
	s_mov_b32 m0, s55
	ds_read_b128 v[206:209], v144
	ds_read_b128 v[210:213], v144 offset:1024
	ds_read_b128 v[214:217], v144 offset:2048
	ds_read_b128 v[218:221], v144 offset:3072
	global_load_lds_dwordx4 v130, s[98:99]
	s_mov_b32 m0, s56
	s_nop 0
	global_load_lds_dwordx4 v134, s[98:99]
	s_setprio 1
	s_barrier
; #define PG8_STAGE(bufoff, gbase, voff) do { _Pragma("unroll") for (int _i = 0; _i < 2; ++_i) \
;         __builtin_amdgcn_global_load_lds((const unsigned*)((const char*)(gbase) + (voff)[_i]), (LAS unsigned*)(lds + (bufoff) + ldsw + _i * 8192), 16, 0, 0); } while (0)
; #define PG8_LDA(dst, b, h) do { _Pragma("unroll") for (int m = 0; m < 4; ++m) _Pragma("unroll") for (int k = 0; k < 2; ++k) dst[m][k] = *(const LAS bf16x8*)(lds + PG8_SA(b, h) + aoff + m * 2048 + k * 1024); } while (0)
; #define PG8_LDB(dst, b, h) do { _Pragma("unroll") for (int n = 0; n < 2; ++n) _Pragma("unroll") for (int k = 0; k < 2; ++k) dst[n][k] = *(const LAS bf16x8*)(lds + PG8_SB(b, h) + boff + n * 2048 + k * 1024); } while (0)
; #define PG8_WAIT_V(n) asm volatile("s_waitcnt vmcnt(" #n ")" ::: "memory")
; #define PG8_WAIT_L(n) asm volatile("s_waitcnt lgkmcnt(" #n ")" ::: "memory")
; #define PG8_BAR __builtin_amdgcn_s_barrier()
; #define PG8_SCHED __builtin_amdgcn_sched_barrier(0)
; template <class Epi>
; __device__ __forceinline__ void gemm_phase(LAS unsigned char* lds, const bf16_t* A, int lda, const bf16_t* Bt, int ldb, int M, int N, int K, int asel, const Epi& E, const int fixed_round = -1) {
;     ...
;             PG8_WAIT_L(8); PG8_BAR; PG8_WAIT_L(0); PG8_MMA(0, 0, At, B0); PG8_BAR; PG8_SCHED;
;             PG8_LDB(B1, 1, 1); PG8_STAGE(PG8_SB(1, 0), b3, voffB);
;             PG8_BAR; PG8_WAIT_L(0); PG8_MMA(0, 1, At, B1); PG8_BAR;
;             PG8_LDA(At, 1, 1); PG8_STAGE(PG8_SA(1, 0), a3, voffA);
;             PG8_BAR; PG8_WAIT_L(0); PG8_MMA(1, 0, At, B0); PG8_BAR; PG8_SCHED;
;             PG8_STAGE(PG8_SB(1, 1), b3 + hstepB, voffB);
;             PG8_WAIT_V(6); PG8_BAR; PG8_MMA(1, 1, At, B1); PG8_BAR;
;     ...
;     PG8_WAIT_V(0);
;     if (wr == 0) PG8_BAR;
;     PG8_BAR;
	s_waitcnt lgkmcnt(0)
	v_mfma_f32_16x16x32_bf16 v[116:119], v[206:209], v[170:173], v[116:119]
	v_mfma_f32_16x16x32_bf16 v[108:111], v[214:217], v[170:173], v[108:111]
	v_mfma_f32_16x16x32_bf16 v[100:103], v[206:209], v[178:181], v[100:103]
	v_mfma_f32_16x16x32_bf16 v[92:95], v[214:217], v[178:181], v[92:95]
	v_mfma_f32_16x16x32_bf16 v[84:87], v[206:209], v[186:189], v[84:87]
	v_mfma_f32_16x16x32_bf16 v[76:79], v[214:217], v[186:189], v[76:79]
	v_mfma_f32_16x16x32_bf16 v[68:71], v[206:209], v[194:197], v[68:71]
	v_mfma_f32_16x16x32_bf16 v[64:67], v[214:217], v[194:197], v[64:67]
	v_mfma_f32_16x16x32_bf16 v[116:119], v[210:213], v[174:177], v[116:119]
	v_mfma_f32_16x16x32_bf16 v[108:111], v[218:221], v[174:177], v[108:111]
	v_mfma_f32_16x16x32_bf16 v[100:103], v[210:213], v[182:185], v[100:103]
	v_mfma_f32_16x16x32_bf16 v[92:95], v[218:221], v[182:185], v[92:95]
	v_mfma_f32_16x16x32_bf16 v[84:87], v[210:213], v[190:193], v[84:87]
	v_mfma_f32_16x16x32_bf16 v[76:79], v[218:221], v[190:193], v[76:79]
	v_mfma_f32_16x16x32_bf16 v[68:71], v[210:213], v[202:205], v[68:71]
	v_mfma_f32_16x16x32_bf16 v[64:67], v[218:221], v[202:205], v[64:67]
	s_barrier
	s_setprio 0
	s_mov_b32 m0, s46
	ds_read_b128 v[170:173], v141 offset:49152
	ds_read_b128 v[174:177], v141 offset:50176
	ds_read_b128 v[178:181], v141 offset:51200
	ds_read_b128 v[182:185], v141 offset:52224
	ds_read_b128 v[186:189], v141 offset:53248
	ds_read_b128 v[190:193], v141 offset:54272
	ds_read_b128 v[194:197], v141 offset:55296
	ds_read_b128 v[202:205], v141 offset:56320
	global_load_lds_dwordx4 v128, s[100:101]
	s_mov_b32 m0, s47
	s_nop 0
	global_load_lds_dwordx4 v132, s[100:101]
	s_setprio 1
	s_barrier
	s_waitcnt lgkmcnt(0)
	v_mfma_f32_16x16x32_bf16 v[60:63], v[146:149], v[170:173], v[60:63]
	v_mfma_f32_16x16x32_bf16 v[56:59], v[160:163], v[170:173], v[56:59]
	v_mfma_f32_16x16x32_bf16 v[48:51], v[146:149], v[178:181], v[48:51]
	v_mfma_f32_16x16x32_bf16 v[40:43], v[160:163], v[178:181], v[40:43]
	v_mfma_f32_16x16x32_bf16 v[32:35], v[146:149], v[186:189], v[32:35]
	v_mfma_f32_16x16x32_bf16 v[24:27], v[160:163], v[186:189], v[24:27]
	v_mfma_f32_16x16x32_bf16 v[16:19], v[146:149], v[194:197], v[16:19]
	v_mfma_f32_16x16x32_bf16 v[8:11], v[160:163], v[194:197], v[8:11]
	v_mfma_f32_16x16x32_bf16 v[60:63], v[150:153], v[174:177], v[60:63]
	v_mfma_f32_16x16x32_bf16 v[56:59], v[166:169], v[174:177], v[56:59]
	v_mfma_f32_16x16x32_bf16 v[48:51], v[150:153], v[182:185], v[48:51]
	v_mfma_f32_16x16x32_bf16 v[40:43], v[166:169], v[182:185], v[40:43]
	v_mfma_f32_16x16x32_bf16 v[32:35], v[150:153], v[190:193], v[32:35]
	v_mfma_f32_16x16x32_bf16 v[24:27], v[166:169], v[190:193], v[24:27]
	v_mfma_f32_16x16x32_bf16 v[16:19], v[150:153], v[202:205], v[16:19]
	v_mfma_f32_16x16x32_bf16 v[8:11], v[166:169], v[202:205], v[8:11]
	s_barrier
	s_setprio 0
	s_add_u32 s28, s34, 0x200080
	s_addc_u32 s29, s35, 0
	s_mov_b32 m0, s57
	s_nop 0
	global_load_lds_dwordx4 v130, s[28:29]
	s_mov_b32 m0, s58
	s_nop 0
	global_load_lds_dwordx4 v134, s[28:29]
	s_waitcnt vmcnt(6)
	s_setprio 1
	s_barrier
	v_mfma_f32_16x16x32_bf16 v[52:55], v[206:209], v[170:173], v[52:55]
	v_mfma_f32_16x16x32_bf16 v[44:47], v[214:217], v[170:173], v[44:47]
	v_mfma_f32_16x16x32_bf16 v[36:39], v[206:209], v[178:181], v[36:39]
	v_mfma_f32_16x16x32_bf16 v[28:31], v[214:217], v[178:181], v[28:31]
	v_mfma_f32_16x16x32_bf16 v[20:23], v[206:209], v[186:189], v[20:23]
	v_mfma_f32_16x16x32_bf16 v[12:15], v[214:217], v[186:189], v[12:15]
	v_mfma_f32_16x16x32_bf16 v[4:7], v[206:209], v[194:197], v[4:7]
	v_mfma_f32_16x16x32_bf16 v[0:3], v[214:217], v[194:197], v[0:3]
	v_mfma_f32_16x16x32_bf16 v[52:55], v[210:213], v[174:177], v[52:55]
	v_mfma_f32_16x16x32_bf16 v[44:47], v[218:221], v[174:177], v[44:47]
	v_mfma_f32_16x16x32_bf16 v[36:39], v[210:213], v[182:185], v[36:39]
	v_mfma_f32_16x16x32_bf16 v[28:31], v[218:221], v[182:185], v[28:31]
	v_mfma_f32_16x16x32_bf16 v[20:23], v[210:213], v[190:193], v[20:23]
	v_mfma_f32_16x16x32_bf16 v[12:15], v[218:221], v[190:193], v[12:15]
	v_mfma_f32_16x16x32_bf16 v[4:7], v[210:213], v[202:205], v[4:7]
	v_mfma_f32_16x16x32_bf16 v[0:3], v[218:221], v[202:205], v[0:3]
	s_setprio 0
	s_add_i32 s48, s48, 2
	s_add_u32 s20, s20, 0x100
	s_addc_u32 s21, s21, 0
	s_cmpk_lt_u32 s48, 0x7e
	s_cbranch_scc1 .Lrot_5
	s_barrier
	s_waitcnt vmcnt(0)
	v_writelane_b32 v255, s8, 26
	s_cmpk_gt_u32 s41, 0xff
	s_nop 0
	v_writelane_b32 v255, s9, 27
	s_cbranch_scc1 .LBB0_654
	s_barrier

; #define PG8_STAGE(bufoff, gbase, voff) do { _Pragma("unroll") for (int _i = 0; _i < 2; ++_i) \
;         __builtin_amdgcn_global_load_lds((const unsigned*)((const char*)(gbase) + (voff)[_i]), (LAS unsigned*)(lds + (bufoff) + ldsw + _i * 8192), 16, 0, 0); } while (0)
; #define PG8_LDA(dst, b, h) do { _Pragma("unroll") for (int m = 0; m < 4; ++m) _Pragma("unroll") for (int k = 0; k < 2; ++k) dst[m][k] = *(const LAS bf16x8*)(lds + PG8_SA(b, h) + aoff + m * 2048 + k * 1024); } while (0)
; #define PG8_LDB(dst, b, h) do { _Pragma("unroll") for (int n = 0; n < 2; ++n) _Pragma("unroll") for (int k = 0; k < 2; ++k) dst[n][k] = *(const LAS bf16x8*)(lds + PG8_SB(b, h) + boff + n * 2048 + k * 1024); } while (0)
; #define PG8_WAIT_V(n) asm volatile("s_waitcnt vmcnt(" #n ")" ::: "memory")
; #define PG8_WAIT_L(n) asm volatile("s_waitcnt lgkmcnt(" #n ")" ::: "memory")
; #define PG8_BAR __builtin_amdgcn_s_barrier()
; #define PG8_SCHED __builtin_amdgcn_sched_barrier(0)
; template <class Epi>
; __device__ __forceinline__ void gemm_phase(LAS unsigned char* lds, const bf16_t* A, int lda, const bf16_t* Bt, int ldb, int M, int N, int K, int asel, const Epi& E, const int fixed_round = -1) {
;     ...
;             const bool last = (t == nt - 2);
;             const char* a1 = cA + (size_t)(t + 1) * kstep;
;             const char* a2 = last ? nA : cA + (size_t)(t + 2) * kstep; const char* b2 = last ? nB : cB + (size_t)(t + 2) * kstep;
;             const char* a3 = a2 + kstep; const char* b3 = b2 + kstep;
;             PG8_LDB(B0, 0, 0); PG8_SCHED; PG8_LDA(At, 0, 0); PG8_STAGE(PG8_SA(1, 1), a1 + hstepA, voffA);
;             PG8_WAIT_L(8); PG8_BAR; PG8_WAIT_L(0); PG8_MMA(0, 0, At, B0); PG8_BAR; PG8_SCHED;
;             PG8_LDB(B1, 0, 1); PG8_STAGE(PG8_SB(0, 0), b2, voffB);
;             PG8_BAR; PG8_WAIT_L(0); PG8_MMA(0, 1, At, B1); PG8_BAR;
;             PG8_LDA(At, 0, 1); PG8_STAGE(PG8_SA(0, 0), a2, voffA);
;             PG8_BAR; PG8_WAIT_L(0); PG8_MMA(1, 0, At, B0); PG8_BAR; PG8_SCHED;
;             PG8_STAGE(PG8_SB(0, 1), b2 + hstepB, voffB);
;             PG8_WAIT_V(6); PG8_BAR; PG8_MMA(1, 1, At, B1); PG8_BAR;
.LBB0_690:
	ds_read_b128 v[146:149], v138
	ds_read_b128 v[150:153], v138 offset:1024
	ds_read_b128 v[160:163], v138 offset:2048
	ds_read_b128 v[166:169], v138 offset:3072
	s_mov_b32 m0, s59
	v_lshl_add_u64 v[156:157], v[134:135], 0, s[4:5]
	ds_read_b128 v[170:173], v139
	ds_read_b128 v[174:177], v139 offset:1024
	ds_read_b128 v[178:181], v139 offset:2048
	ds_read_b128 v[182:185], v139 offset:3072
	ds_read_b128 v[186:189], v139 offset:4096
	ds_read_b128 v[190:193], v139 offset:5120
	ds_read_b128 v[194:197], v139 offset:6144
	ds_read_b128 v[202:205], v139 offset:7168
	global_load_lds_dwordx4 v[156:157], off
	v_lshl_add_u64 v[156:157], v[136:137], 0, s[4:5]
	s_mov_b32 m0, s60
	s_nop 0
	global_load_lds_dwordx4 v[156:157], off
	s_waitcnt lgkmcnt(8)
	s_setprio 1
	s_barrier
	s_waitcnt lgkmcnt(0)
	v_mfma_f32_16x16x32_bf16 v[124:127], v[146:149], v[170:173], v[124:127]
	v_mfma_f32_16x16x32_bf16 v[120:123], v[160:163], v[170:173], v[120:123]
	v_mfma_f32_16x16x32_bf16 v[112:115], v[146:149], v[178:181], v[112:115]
	v_mfma_f32_16x16x32_bf16 v[104:107], v[160:163], v[178:181], v[104:107]
	v_mfma_f32_16x16x32_bf16 v[96:99], v[146:149], v[186:189], v[96:99]
	v_mfma_f32_16x16x32_bf16 v[88:91], v[160:163], v[186:189], v[88:91]
	v_mfma_f32_16x16x32_bf16 v[80:83], v[146:149], v[194:197], v[80:83]
	v_mfma_f32_16x16x32_bf16 v[72:75], v[160:163], v[194:197], v[72:75]
	v_mfma_f32_16x16x32_bf16 v[124:127], v[150:153], v[174:177], v[124:127]
	v_mfma_f32_16x16x32_bf16 v[120:123], v[166:169], v[174:177], v[120:123]
	v_mfma_f32_16x16x32_bf16 v[112:115], v[150:153], v[182:185], v[112:115]
	v_mfma_f32_16x16x32_bf16 v[104:107], v[166:169], v[182:185], v[104:107]
	v_mfma_f32_16x16x32_bf16 v[96:99], v[150:153], v[190:193], v[96:99]
	v_mfma_f32_16x16x32_bf16 v[88:91], v[166:169], v[190:193], v[88:91]
	v_mfma_f32_16x16x32_bf16 v[80:83], v[150:153], v[202:205], v[80:83]
	v_mfma_f32_16x16x32_bf16 v[72:75], v[166:169], v[202:205], v[72:75]
	s_barrier
	s_setprio 0
	s_add_u32 s6, s4, 0xe7900080
	s_addc_u32 s7, s5, -1
	s_cmpk_lg_i32 s58, 0x7c
	s_cselect_b32 s6, s6, 0
	s_cselect_b32 s7, s7, 0
	s_add_u32 s40, s8, s6
	s_addc_u32 s41, s9, s7
	s_add_u32 s6, s2, s6
	s_addc_u32 s7, s3, s7
	s_mov_b32 m0, s61
	s_add_u32 s98, s6, s0
	s_addc_u32 s99, s7, s1
	ds_read_b128 v[206:209], v140
	ds_read_b128 v[210:213], v140 offset:1024
	ds_read_b128 v[214:217], v140 offset:2048
	ds_read_b128 v[218:221], v140 offset:3072
	global_load_lds_dwordx4 v144, s[6:7]
	s_mov_b32 m0, s62
	s_nop 0
	global_load_lds_dwordx4 v132, s[6:7]
	s_setprio 1
	s_barrier
	s_waitcnt lgkmcnt(0)
	v_mfma_f32_16x16x32_bf16 v[116:119], v[206:209], v[170:173], v[116:119]
	v_mfma_f32_16x16x32_bf16 v[108:111], v[214:217], v[170:173], v[108:111]
	v_mfma_f32_16x16x32_bf16 v[100:103], v[206:209], v[178:181], v[100:103]
	v_mfma_f32_16x16x32_bf16 v[92:95], v[214:217], v[178:181], v[92:95]
	v_mfma_f32_16x16x32_bf16 v[84:87], v[206:209], v[186:189], v[84:87]
	v_mfma_f32_16x16x32_bf16 v[76:79], v[214:217], v[186:189], v[76:79]
	v_mfma_f32_16x16x32_bf16 v[68:71], v[206:209], v[194:197], v[68:71]
	v_mfma_f32_16x16x32_bf16 v[64:67], v[214:217], v[194:197], v[64:67]
	v_mfma_f32_16x16x32_bf16 v[116:119], v[210:213], v[174:177], v[116:119]
	v_mfma_f32_16x16x32_bf16 v[108:111], v[218:221], v[174:177], v[108:111]
	v_mfma_f32_16x16x32_bf16 v[100:103], v[210:213], v[182:185], v[100:103]
	v_mfma_f32_16x16x32_bf16 v[92:95], v[218:221], v[182:185], v[92:95]
	v_mfma_f32_16x16x32_bf16 v[84:87], v[210:213], v[190:193], v[84:87]
	v_mfma_f32_16x16x32_bf16 v[76:79], v[218:221], v[190:193], v[76:79]
	v_mfma_f32_16x16x32_bf16 v[68:71], v[210:213], v[202:205], v[68:71]
	v_mfma_f32_16x16x32_bf16 v[64:67], v[218:221], v[202:205], v[64:67]
	s_barrier
	s_setprio 0
	s_mov_b32 m0, s52
	s_add_u32 s100, s40, s0
	s_addc_u32 s101, s41, s1
	ds_read_b128 v[170:173], v139 offset:16384
	ds_read_b128 v[174:177], v139 offset:17408
	ds_read_b128 v[178:181], v139 offset:18432
	ds_read_b128 v[182:185], v139 offset:19456
	ds_read_b128 v[186:189], v139 offset:20480
	ds_read_b128 v[190:193], v139 offset:21504
	ds_read_b128 v[194:197], v139 offset:22528
	ds_read_b128 v[202:205], v139 offset:23552
	global_load_lds_dwordx4 v128, s[40:41]
	s_mov_b32 m0, s53
	s_nop 0
	global_load_lds_dwordx4 v130, s[40:41]
	s_setprio 1
	s_barrier
	s_waitcnt lgkmcnt(0)
	v_mfma_f32_16x16x32_bf16 v[60:63], v[146:149], v[170:173], v[60:63]
	v_mfma_f32_16x16x32_bf16 v[56:59], v[160:163], v[170:173], v[56:59]
	v_mfma_f32_16x16x32_bf16 v[48:51], v[146:149], v[178:181], v[48:51]
	v_mfma_f32_16x16x32_bf16 v[40:43], v[160:163], v[178:181], v[40:43]
	v_mfma_f32_16x16x32_bf16 v[32:35], v[146:149], v[186:189], v[32:35]
	v_mfma_f32_16x16x32_bf16 v[24:27], v[160:163], v[186:189], v[24:27]
	v_mfma_f32_16x16x32_bf16 v[16:19], v[146:149], v[194:197], v[16:19]
	v_mfma_f32_16x16x32_bf16 v[8:11], v[160:163], v[194:197], v[8:11]
	v_mfma_f32_16x16x32_bf16 v[60:63], v[150:153], v[174:177], v[60:63]
	v_mfma_f32_16x16x32_bf16 v[56:59], v[166:169], v[174:177], v[56:59]
	v_mfma_f32_16x16x32_bf16 v[48:51], v[150:153], v[182:185], v[48:51]
	v_mfma_f32_16x16x32_bf16 v[40:43], v[166:169], v[182:185], v[40:43]
	v_mfma_f32_16x16x32_bf16 v[32:35], v[150:153], v[190:193], v[32:35]
	v_mfma_f32_16x16x32_bf16 v[24:27], v[166:169], v[190:193], v[24:27]
	v_mfma_f32_16x16x32_bf16 v[16:19], v[150:153], v[202:205], v[16:19]
	v_mfma_f32_16x16x32_bf16 v[8:11], v[166:169], v[202:205], v[8:11]
	s_barrier
	s_setprio 0
	s_add_u32 s28, s6, 0x200000
	s_addc_u32 s29, s7, 0
	s_mov_b32 m0, s63
	s_nop 0
	global_load_lds_dwordx4 v144, s[28:29]
	s_mov_b32 m0, s64
	s_nop 0
	global_load_lds_dwordx4 v132, s[28:29]
	s_waitcnt vmcnt(6)
	s_setprio 1
	s_barrier
; #define PG8_STAGE(bufoff, gbase, voff) do { _Pragma("unroll") for (int _i = 0; _i < 2; ++_i) \
;         __builtin_amdgcn_global_load_lds((const unsigned*)((const char*)(gbase) + (voff)[_i]), (LAS unsigned*)(lds + (bufoff) + ldsw + _i * 8192), 16, 0, 0); } while (0)
; #define PG8_LDA(dst, b, h) do { _Pragma("unroll") for (int m = 0; m < 4; ++m) _Pragma("unroll") for (int k = 0; k < 2; ++k) dst[m][k] = *(const LAS bf16x8*)(lds + PG8_SA(b, h) + aoff + m * 2048 + k * 1024); } while (0)
; #define PG8_LDB(dst, b, h) do { _Pragma("unroll") for (int n = 0; n < 2; ++n) _Pragma("unroll") for (int k = 0; k < 2; ++k) dst[n][k] = *(const LAS bf16x8*)(lds + PG8_SB(b, h) + boff + n * 2048 + k * 1024); } while (0)
; #define PG8_WAIT_V(n) asm volatile("s_waitcnt vmcnt(" #n ")" ::: "memory")
; #define PG8_WAIT_L(n) asm volatile("s_waitcnt lgkmcnt(" #n ")" ::: "memory")
; #define PG8_BAR __builtin_amdgcn_s_barrier()
; #define PG8_SCHED __builtin_amdgcn_sched_barrier(0)
; template <class Epi>
; __device__ __forceinline__ void gemm_phase(LAS unsigned char* lds, const bf16_t* A, int lda, const bf16_t* Bt, int ldb, int M, int N, int K, int asel, const Epi& E, const int fixed_round = -1) {
;     ...
;             PG8_WAIT_V(6); PG8_BAR; PG8_MMA(1, 1, At, B1); PG8_BAR;
;             PG8_LDB(B0, 1, 0); PG8_SCHED; PG8_LDA(At, 1, 0); PG8_STAGE(PG8_SA(0, 1), a2 + hstepA, voffA);
;             PG8_WAIT_L(8); PG8_BAR; PG8_WAIT_L(0); PG8_MMA(0, 0, At, B0); PG8_BAR; PG8_SCHED;
	v_mfma_f32_16x16x32_bf16 v[52:55], v[206:209], v[170:173], v[52:55]
	v_mfma_f32_16x16x32_bf16 v[44:47], v[214:217], v[170:173], v[44:47]
	v_mfma_f32_16x16x32_bf16 v[36:39], v[206:209], v[178:181], v[36:39]
	v_mfma_f32_16x16x32_bf16 v[28:31], v[214:217], v[178:181], v[28:31]
	v_mfma_f32_16x16x32_bf16 v[20:23], v[206:209], v[186:189], v[20:23]
	v_mfma_f32_16x16x32_bf16 v[12:15], v[214:217], v[186:189], v[12:15]
	v_mfma_f32_16x16x32_bf16 v[4:7], v[206:209], v[194:197], v[4:7]
	v_mfma_f32_16x16x32_bf16 v[0:3], v[214:217], v[194:197], v[0:3]
	v_mfma_f32_16x16x32_bf16 v[52:55], v[210:213], v[174:177], v[52:55]
	v_mfma_f32_16x16x32_bf16 v[44:47], v[218:221], v[174:177], v[44:47]
	v_mfma_f32_16x16x32_bf16 v[36:39], v[210:213], v[182:185], v[36:39]
	v_mfma_f32_16x16x32_bf16 v[28:31], v[218:221], v[182:185], v[28:31]
	v_mfma_f32_16x16x32_bf16 v[20:23], v[210:213], v[190:193], v[20:23]
	v_mfma_f32_16x16x32_bf16 v[12:15], v[218:221], v[190:193], v[12:15]
	v_mfma_f32_16x16x32_bf16 v[4:7], v[210:213], v[202:205], v[4:7]
	v_mfma_f32_16x16x32_bf16 v[0:3], v[218:221], v[202:205], v[0:3]
	s_barrier
	s_setprio 0
	ds_read_b128 v[146:149], v141
	ds_read_b128 v[150:153], v141 offset:1024
	ds_read_b128 v[160:163], v141 offset:2048
	ds_read_b128 v[166:169], v141 offset:3072
	s_add_u32 s28, s40, 0x200000
	s_addc_u32 s29, s41, 0
	s_mov_b32 m0, s54
	ds_read_b128 v[170:173], v139 offset:32768
	ds_read_b128 v[174:177], v139 offset:33792
	ds_read_b128 v[178:181], v139 offset:34816
	ds_read_b128 v[182:185], v139 offset:35840
	ds_read_b128 v[186:189], v139 offset:36864
	ds_read_b128 v[190:193], v139 offset:37888
	ds_read_b128 v[194:197], v139 offset:38912
	ds_read_b128 v[202:205], v139 offset:39936
	global_load_lds_dwordx4 v128, s[28:29]
	s_mov_b32 m0, s55
	s_nop 0
	global_load_lds_dwordx4 v130, s[28:29]
	s_waitcnt lgkmcnt(8)
	s_setprio 1
	s_barrier
	s_waitcnt lgkmcnt(0)
	v_mfma_f32_16x16x32_bf16 v[124:127], v[146:149], v[170:173], v[124:127]
	v_mfma_f32_16x16x32_bf16 v[120:123], v[160:163], v[170:173], v[120:123]
	v_mfma_f32_16x16x32_bf16 v[112:115], v[146:149], v[178:181], v[112:115]
	v_mfma_f32_16x16x32_bf16 v[104:107], v[160:163], v[178:181], v[104:107]
	v_mfma_f32_16x16x32_bf16 v[96:99], v[146:149], v[186:189], v[96:99]
	v_mfma_f32_16x16x32_bf16 v[88:91], v[160:163], v[186:189], v[88:91]
	v_mfma_f32_16x16x32_bf16 v[80:83], v[146:149], v[194:197], v[80:83]
	v_mfma_f32_16x16x32_bf16 v[72:75], v[160:163], v[194:197], v[72:75]
	v_mfma_f32_16x16x32_bf16 v[124:127], v[150:153], v[174:177], v[124:127]
	v_mfma_f32_16x16x32_bf16 v[120:123], v[166:169], v[174:177], v[120:123]
	v_mfma_f32_16x16x32_bf16 v[112:115], v[150:153], v[182:185], v[112:115]
	v_mfma_f32_16x16x32_bf16 v[104:107], v[166:169], v[182:185], v[104:107]
	v_mfma_f32_16x16x32_bf16 v[96:99], v[150:153], v[190:193], v[96:99]
	v_mfma_f32_16x16x32_bf16 v[88:91], v[166:169], v[190:193], v[88:91]
	v_mfma_f32_16x16x32_bf16 v[80:83], v[150:153], v[202:205], v[80:83]
	v_mfma_f32_16x16x32_bf16 v[72:75], v[166:169], v[202:205], v[72:75]
	s_barrier
	s_setprio 0
	s_mov_b32 m0, s65
	ds_read_b128 v[206:209], v142
	ds_read_b128 v[210:213], v142 offset:1024
	ds_read_b128 v[214:217], v142 offset:2048
	ds_read_b128 v[218:221], v142 offset:3072
	global_load_lds_dwordx4 v144, s[98:99]
	s_mov_b32 m0, s66
	s_nop 0
	global_load_lds_dwordx4 v132, s[98:99]
	s_setprio 1
	s_barrier
; #define PG8_STAGE(bufoff, gbase, voff) do { _Pragma("unroll") for (int _i = 0; _i < 2; ++_i) \
;         __builtin_amdgcn_global_load_lds((const unsigned*)((const char*)(gbase) + (voff)[_i]), (LAS unsigned*)(lds + (bufoff) + ldsw + _i * 8192), 16, 0, 0); } while (0)
; #define PG8_LDA(dst, b, h) do { _Pragma("unroll") for (int m = 0; m < 4; ++m) _Pragma("unroll") for (int k = 0; k < 2; ++k) dst[m][k] = *(const LAS bf16x8*)(lds + PG8_SA(b, h) + aoff + m * 2048 + k * 1024); } while (0)
; #define PG8_LDB(dst, b, h) do { _Pragma("unroll") for (int n = 0; n < 2; ++n) _Pragma("unroll") for (int k = 0; k < 2; ++k) dst[n][k] = *(const LAS bf16x8*)(lds + PG8_SB(b, h) + boff + n * 2048 + k * 1024); } while (0)
; #define PG8_WAIT_V(n) asm volatile("s_waitcnt vmcnt(" #n ")" ::: "memory")
; #define PG8_WAIT_L(n) asm volatile("s_waitcnt lgkmcnt(" #n ")" ::: "memory")
; #define PG8_BAR __builtin_amdgcn_s_barrier()
; #define PG8_SCHED __builtin_amdgcn_sched_barrier(0)
; template <class Epi>
; __device__ __forceinline__ void gemm_phase(LAS unsigned char* lds, const bf16_t* A, int lda, const bf16_t* Bt, int ldb, int M, int N, int K, int asel, const Epi& E, const int fixed_round = -1) {
;     ...
;             PG8_WAIT_L(8); PG8_BAR; PG8_WAIT_L(0); PG8_MMA(0, 0, At, B0); PG8_BAR; PG8_SCHED;
;             PG8_LDB(B1, 1, 1); PG8_STAGE(PG8_SB(1, 0), b3, voffB);
;             PG8_BAR; PG8_WAIT_L(0); PG8_MMA(0, 1, At, B1); PG8_BAR;
;             PG8_LDA(At, 1, 1); PG8_STAGE(PG8_SA(1, 0), a3, voffA);
;             PG8_BAR; PG8_WAIT_L(0); PG8_MMA(1, 0, At, B0); PG8_BAR; PG8_SCHED;
;             PG8_STAGE(PG8_SB(1, 1), b3 + hstepB, voffB);
;             PG8_WAIT_V(6); PG8_BAR; PG8_MMA(1, 1, At, B1); PG8_BAR;
;     ...
;     PG8_WAIT_V(0);
;     if (wr == 0) PG8_BAR;
;     PG8_BAR;
	s_waitcnt lgkmcnt(0)
	v_mfma_f32_16x16x32_bf16 v[116:119], v[206:209], v[170:173], v[116:119]
	v_mfma_f32_16x16x32_bf16 v[108:111], v[214:217], v[170:173], v[108:111]
	v_mfma_f32_16x16x32_bf16 v[100:103], v[206:209], v[178:181], v[100:103]
	v_mfma_f32_16x16x32_bf16 v[92:95], v[214:217], v[178:181], v[92:95]
	v_mfma_f32_16x16x32_bf16 v[84:87], v[206:209], v[186:189], v[84:87]
	v_mfma_f32_16x16x32_bf16 v[76:79], v[214:217], v[186:189], v[76:79]
	v_mfma_f32_16x16x32_bf16 v[68:71], v[206:209], v[194:197], v[68:71]
	v_mfma_f32_16x16x32_bf16 v[64:67], v[214:217], v[194:197], v[64:67]
	v_mfma_f32_16x16x32_bf16 v[116:119], v[210:213], v[174:177], v[116:119]
	v_mfma_f32_16x16x32_bf16 v[108:111], v[218:221], v[174:177], v[108:111]
	v_mfma_f32_16x16x32_bf16 v[100:103], v[210:213], v[182:185], v[100:103]
	v_mfma_f32_16x16x32_bf16 v[92:95], v[218:221], v[182:185], v[92:95]
	v_mfma_f32_16x16x32_bf16 v[84:87], v[210:213], v[190:193], v[84:87]
	v_mfma_f32_16x16x32_bf16 v[76:79], v[218:221], v[190:193], v[76:79]
	v_mfma_f32_16x16x32_bf16 v[68:71], v[210:213], v[202:205], v[68:71]
	v_mfma_f32_16x16x32_bf16 v[64:67], v[218:221], v[202:205], v[64:67]
	s_barrier
	s_setprio 0
	s_mov_b32 m0, s56
	ds_read_b128 v[170:173], v139 offset:49152
	ds_read_b128 v[174:177], v139 offset:50176
	ds_read_b128 v[178:181], v139 offset:51200
	ds_read_b128 v[182:185], v139 offset:52224
	ds_read_b128 v[186:189], v139 offset:53248
	ds_read_b128 v[190:193], v139 offset:54272
	ds_read_b128 v[194:197], v139 offset:55296
	ds_read_b128 v[202:205], v139 offset:56320
	global_load_lds_dwordx4 v128, s[100:101]
	s_mov_b32 m0, s57
	s_nop 0
	global_load_lds_dwordx4 v130, s[100:101]
	s_setprio 1
	s_barrier
	s_waitcnt lgkmcnt(0)
	v_mfma_f32_16x16x32_bf16 v[60:63], v[146:149], v[170:173], v[60:63]
	v_mfma_f32_16x16x32_bf16 v[56:59], v[160:163], v[170:173], v[56:59]
	v_mfma_f32_16x16x32_bf16 v[48:51], v[146:149], v[178:181], v[48:51]
	v_mfma_f32_16x16x32_bf16 v[40:43], v[160:163], v[178:181], v[40:43]
	v_mfma_f32_16x16x32_bf16 v[32:35], v[146:149], v[186:189], v[32:35]
	v_mfma_f32_16x16x32_bf16 v[24:27], v[160:163], v[186:189], v[24:27]
	v_mfma_f32_16x16x32_bf16 v[16:19], v[146:149], v[194:197], v[16:19]
	v_mfma_f32_16x16x32_bf16 v[8:11], v[160:163], v[194:197], v[8:11]
	v_mfma_f32_16x16x32_bf16 v[60:63], v[150:153], v[174:177], v[60:63]
	v_mfma_f32_16x16x32_bf16 v[56:59], v[166:169], v[174:177], v[56:59]
	v_mfma_f32_16x16x32_bf16 v[48:51], v[150:153], v[182:185], v[48:51]
	v_mfma_f32_16x16x32_bf16 v[40:43], v[166:169], v[182:185], v[40:43]
	v_mfma_f32_16x16x32_bf16 v[32:35], v[150:153], v[190:193], v[32:35]
	v_mfma_f32_16x16x32_bf16 v[24:27], v[166:169], v[190:193], v[24:27]
	v_mfma_f32_16x16x32_bf16 v[16:19], v[150:153], v[202:205], v[16:19]
	v_mfma_f32_16x16x32_bf16 v[8:11], v[166:169], v[202:205], v[8:11]
	s_barrier
	s_setprio 0
	s_add_u32 s6, s6, 0x200080
	s_addc_u32 s7, s7, 0
	s_mov_b32 m0, s67
	s_nop 0
	global_load_lds_dwordx4 v144, s[6:7]
	s_mov_b32 m0, s68
	s_nop 0
	global_load_lds_dwordx4 v132, s[6:7]
	s_waitcnt vmcnt(6)
	s_setprio 1
	s_barrier
	v_mfma_f32_16x16x32_bf16 v[52:55], v[206:209], v[170:173], v[52:55]
	v_mfma_f32_16x16x32_bf16 v[44:47], v[214:217], v[170:173], v[44:47]
	v_mfma_f32_16x16x32_bf16 v[36:39], v[206:209], v[178:181], v[36:39]
	v_mfma_f32_16x16x32_bf16 v[28:31], v[214:217], v[178:181], v[28:31]
	v_mfma_f32_16x16x32_bf16 v[20:23], v[206:209], v[186:189], v[20:23]
	v_mfma_f32_16x16x32_bf16 v[12:15], v[214:217], v[186:189], v[12:15]
	v_mfma_f32_16x16x32_bf16 v[4:7], v[206:209], v[194:197], v[4:7]
	v_mfma_f32_16x16x32_bf16 v[0:3], v[214:217], v[194:197], v[0:3]
	v_mfma_f32_16x16x32_bf16 v[52:55], v[210:213], v[174:177], v[52:55]
	v_mfma_f32_16x16x32_bf16 v[44:47], v[218:221], v[174:177], v[44:47]
	v_mfma_f32_16x16x32_bf16 v[36:39], v[210:213], v[182:185], v[36:39]
	v_mfma_f32_16x16x32_bf16 v[28:31], v[218:221], v[182:185], v[28:31]
	v_mfma_f32_16x16x32_bf16 v[20:23], v[210:213], v[190:193], v[20:23]
	v_mfma_f32_16x16x32_bf16 v[12:15], v[218:221], v[190:193], v[12:15]
	v_mfma_f32_16x16x32_bf16 v[4:7], v[210:213], v[202:205], v[4:7]
	v_mfma_f32_16x16x32_bf16 v[0:3], v[218:221], v[202:205], v[0:3]
	s_setprio 0
	s_add_i32 s58, s58, 2
	s_add_u32 s4, s4, 0x100
	s_addc_u32 s5, s5, 0
	s_cmpk_lt_u32 s58, 0x7e
	s_cbranch_scc1 .Lrot_6
	s_barrier
	s_waitcnt vmcnt(0)
	s_cmpk_gt_u32 s51, 0xff
	s_cbranch_scc1 .LBB0_693
	s_barrier

; #define PG8_STAGE(bufoff, gbase, voff) do { _Pragma("unroll") for (int _i = 0; _i < 2; ++_i) \
;         __builtin_amdgcn_global_load_lds((const unsigned*)((const char*)(gbase) + (voff)[_i]), (LAS unsigned*)(lds + (bufoff) + ldsw + _i * 8192), 16, 0, 0); } while (0)
; #define PG8_LDA(dst, b, h) do { _Pragma("unroll") for (int m = 0; m < 4; ++m) _Pragma("unroll") for (int k = 0; k < 2; ++k) dst[m][k] = *(const LAS bf16x8*)(lds + PG8_SA(b, h) + aoff + m * 2048 + k * 1024); } while (0)
; #define PG8_LDB(dst, b, h) do { _Pragma("unroll") for (int n = 0; n < 2; ++n) _Pragma("unroll") for (int k = 0; k < 2; ++k) dst[n][k] = *(const LAS bf16x8*)(lds + PG8_SB(b, h) + boff + n * 2048 + k * 1024); } while (0)
; #define PG8_WAIT_V(n) asm volatile("s_waitcnt vmcnt(" #n ")" ::: "memory")
; #define PG8_WAIT_L(n) asm volatile("s_waitcnt lgkmcnt(" #n ")" ::: "memory")
; #define PG8_BAR __builtin_amdgcn_s_barrier()
; #define PG8_SCHED __builtin_amdgcn_sched_barrier(0)
; template <class Epi>
; __device__ __forceinline__ void gemm_phase(LAS unsigned char* lds, const bf16_t* A, int lda, const bf16_t* Bt, int ldb, int M, int N, int K, int asel, const Epi& E, const int fixed_round = -1) {
;     ...
;             const bool last = (t == nt - 2);
;             const char* a1 = cA + (size_t)(t + 1) * kstep;
;             const char* a2 = last ? nA : cA + (size_t)(t + 2) * kstep; const char* b2 = last ? nB : cB + (size_t)(t + 2) * kstep;
;             const char* a3 = a2 + kstep; const char* b3 = b2 + kstep;
;             PG8_LDB(B0, 0, 0); PG8_SCHED; PG8_LDA(At, 0, 0); PG8_STAGE(PG8_SA(1, 1), a1 + hstepA, voffA);
;             PG8_WAIT_L(8); PG8_BAR; PG8_WAIT_L(0); PG8_MMA(0, 0, At, B0); PG8_BAR; PG8_SCHED;
;             PG8_LDB(B1, 0, 1); PG8_STAGE(PG8_SB(0, 0), b2, voffB);
;             PG8_BAR; PG8_WAIT_L(0); PG8_MMA(0, 1, At, B1); PG8_BAR;
;             PG8_LDA(At, 0, 1); PG8_STAGE(PG8_SA(0, 0), a2, voffA);
;             PG8_BAR; PG8_WAIT_L(0); PG8_MMA(1, 0, At, B0); PG8_BAR; PG8_SCHED;
;             PG8_STAGE(PG8_SB(0, 1), b2 + hstepB, voffB);
;             PG8_WAIT_V(6); PG8_BAR; PG8_MMA(1, 1, At, B1); PG8_BAR;
.LBB0_799:
	ds_read_b128 v[146:149], v155
	ds_read_b128 v[158:161], v155 offset:1024
	ds_read_b128 v[162:165], v155 offset:2048
	ds_read_b128 v[166:169], v155 offset:3072
	s_add_i32 m0, s49, 0xc000
	ds_read_b128 v[170:173], v156
	ds_read_b128 v[174:177], v156 offset:1024
	ds_read_b128 v[178:181], v156 offset:2048
	ds_read_b128 v[182:185], v156 offset:3072
	ds_read_b128 v[186:189], v156 offset:4096
	ds_read_b128 v[190:193], v156 offset:5120
	ds_read_b128 v[194:197], v156 offset:6144
	ds_read_b128 v[202:205], v156 offset:7168
	global_load_lds_dwordx4 v138, s[50:51]
	s_add_i32 m0, s49, 0xe000
	s_nop 0
	global_load_lds_dwordx4 v140, s[50:51]
	s_waitcnt lgkmcnt(8)
	s_setprio 1
	s_barrier
	s_waitcnt lgkmcnt(0)
	v_mfma_f32_16x16x32_bf16 v[124:127], v[146:149], v[170:173], v[124:127]
	v_mfma_f32_16x16x32_bf16 v[120:123], v[162:165], v[170:173], v[120:123]
	v_mfma_f32_16x16x32_bf16 v[108:111], v[146:149], v[178:181], v[108:111]
	v_mfma_f32_16x16x32_bf16 v[104:107], v[162:165], v[178:181], v[104:107]
	v_mfma_f32_16x16x32_bf16 v[92:95], v[146:149], v[186:189], v[92:95]
	v_mfma_f32_16x16x32_bf16 v[88:91], v[162:165], v[186:189], v[88:91]
	v_mfma_f32_16x16x32_bf16 v[76:79], v[146:149], v[194:197], v[76:79]
	v_mfma_f32_16x16x32_bf16 v[72:75], v[162:165], v[194:197], v[72:75]
	v_mfma_f32_16x16x32_bf16 v[124:127], v[158:161], v[174:177], v[124:127]
	v_mfma_f32_16x16x32_bf16 v[120:123], v[166:169], v[174:177], v[120:123]
	v_mfma_f32_16x16x32_bf16 v[108:111], v[158:161], v[182:185], v[108:111]
	v_mfma_f32_16x16x32_bf16 v[104:107], v[166:169], v[182:185], v[104:107]
	v_mfma_f32_16x16x32_bf16 v[92:95], v[158:161], v[190:193], v[92:95]
	v_mfma_f32_16x16x32_bf16 v[88:91], v[166:169], v[190:193], v[88:91]
	v_mfma_f32_16x16x32_bf16 v[76:79], v[158:161], v[202:205], v[76:79]
	v_mfma_f32_16x16x32_bf16 v[72:75], v[166:169], v[202:205], v[72:75]
	s_barrier
	s_setprio 0
	s_add_u32 s28, s50, 0xfff80080
	s_addc_u32 s29, s51, -1
	s_cmp_eq_u32 s68, 28
	s_cselect_b32 s55, s5, s29
	s_cselect_b32 s54, s41, s28
	s_cselect_b32 s53, s7, s67
	s_cselect_b32 s52, s65, s66
	s_add_i32 s28, s81, s58
	s_add_u32 s98, s52, s2
	s_addc_u32 s99, s53, s3
	s_mov_b32 m0, s28
	ds_read_b128 v[206:209], v157
	ds_read_b128 v[210:213], v157 offset:1024
	ds_read_b128 v[214:217], v157 offset:2048
	ds_read_b128 v[218:221], v157 offset:3072
	global_load_lds_dwordx4 v130, s[52:53]
	s_add_i32 m0, s28, 0x2000
	s_nop 0
	global_load_lds_dwordx4 v134, s[52:53]
	s_setprio 1
	s_barrier
	s_waitcnt lgkmcnt(0)
	v_mfma_f32_16x16x32_bf16 v[116:119], v[206:209], v[170:173], v[116:119]
	v_mfma_f32_16x16x32_bf16 v[112:115], v[214:217], v[170:173], v[112:115]
	v_mfma_f32_16x16x32_bf16 v[100:103], v[206:209], v[178:181], v[100:103]
	v_mfma_f32_16x16x32_bf16 v[96:99], v[214:217], v[178:181], v[96:99]
	v_mfma_f32_16x16x32_bf16 v[84:87], v[206:209], v[186:189], v[84:87]
	v_mfma_f32_16x16x32_bf16 v[80:83], v[214:217], v[186:189], v[80:83]
	v_mfma_f32_16x16x32_bf16 v[68:71], v[206:209], v[194:197], v[68:71]
	v_mfma_f32_16x16x32_bf16 v[64:67], v[214:217], v[194:197], v[64:67]
	v_mfma_f32_16x16x32_bf16 v[116:119], v[210:213], v[174:177], v[116:119]
	v_mfma_f32_16x16x32_bf16 v[112:115], v[218:221], v[174:177], v[112:115]
	v_mfma_f32_16x16x32_bf16 v[100:103], v[210:213], v[182:185], v[100:103]
	v_mfma_f32_16x16x32_bf16 v[96:99], v[218:221], v[182:185], v[96:99]
	v_mfma_f32_16x16x32_bf16 v[84:87], v[210:213], v[190:193], v[84:87]
	v_mfma_f32_16x16x32_bf16 v[80:83], v[218:221], v[190:193], v[80:83]
	v_mfma_f32_16x16x32_bf16 v[68:71], v[210:213], v[202:205], v[68:71]
	v_mfma_f32_16x16x32_bf16 v[64:67], v[218:221], v[202:205], v[64:67]
	s_barrier
	s_setprio 0
	s_mov_b32 m0, s49
	s_add_u32 s100, s54, s2
	s_addc_u32 s101, s55, s3
	ds_read_b128 v[170:173], v156 offset:16384
	ds_read_b128 v[174:177], v156 offset:17408
	ds_read_b128 v[178:181], v156 offset:18432
	ds_read_b128 v[182:185], v156 offset:19456
	ds_read_b128 v[186:189], v156 offset:20480
	ds_read_b128 v[190:193], v156 offset:21504
	ds_read_b128 v[194:197], v156 offset:22528
	ds_read_b128 v[202:205], v156 offset:23552
	global_load_lds_dwordx4 v128, s[54:55]
	s_mov_b32 m0, s59
	s_nop 0
	global_load_lds_dwordx4 v132, s[54:55]
	s_setprio 1
	s_barrier
	s_waitcnt lgkmcnt(0)
	v_mfma_f32_16x16x32_bf16 v[60:63], v[146:149], v[170:173], v[60:63]
	v_mfma_f32_16x16x32_bf16 v[56:59], v[162:165], v[170:173], v[56:59]
	v_mfma_f32_16x16x32_bf16 v[44:47], v[146:149], v[178:181], v[44:47]
	v_mfma_f32_16x16x32_bf16 v[40:43], v[162:165], v[178:181], v[40:43]
	v_mfma_f32_16x16x32_bf16 v[28:31], v[146:149], v[186:189], v[28:31]
	v_mfma_f32_16x16x32_bf16 v[24:27], v[162:165], v[186:189], v[24:27]
	v_mfma_f32_16x16x32_bf16 v[12:15], v[146:149], v[194:197], v[12:15]
	v_mfma_f32_16x16x32_bf16 v[8:11], v[162:165], v[194:197], v[8:11]
	v_mfma_f32_16x16x32_bf16 v[60:63], v[158:161], v[174:177], v[60:63]
	v_mfma_f32_16x16x32_bf16 v[56:59], v[166:169], v[174:177], v[56:59]
	v_mfma_f32_16x16x32_bf16 v[44:47], v[158:161], v[182:185], v[44:47]
	v_mfma_f32_16x16x32_bf16 v[40:43], v[166:169], v[182:185], v[40:43]
	v_mfma_f32_16x16x32_bf16 v[28:31], v[158:161], v[190:193], v[28:31]
	v_mfma_f32_16x16x32_bf16 v[24:27], v[166:169], v[190:193], v[24:27]
	v_mfma_f32_16x16x32_bf16 v[12:15], v[158:161], v[202:205], v[12:15]
	v_mfma_f32_16x16x32_bf16 v[8:11], v[166:169], v[202:205], v[8:11]
	s_barrier
	s_setprio 0
	s_add_u32 s28, s52, 0x80000
	s_addc_u32 s29, s53, 0
	s_add_i32 s69, s82, s58
	s_mov_b32 m0, s69
	s_nop 0
	global_load_lds_dwordx4 v130, s[28:29]
	s_add_i32 m0, s69, 0x2000
	s_nop 0
	global_load_lds_dwordx4 v134, s[28:29]
	s_waitcnt vmcnt(6)
	s_setprio 1
	s_barrier
; #define PG8_STAGE(bufoff, gbase, voff) do { _Pragma("unroll") for (int _i = 0; _i < 2; ++_i) \
;         __builtin_amdgcn_global_load_lds((const unsigned*)((const char*)(gbase) + (voff)[_i]), (LAS unsigned*)(lds + (bufoff) + ldsw + _i * 8192), 16, 0, 0); } while (0)
; #define PG8_LDA(dst, b, h) do { _Pragma("unroll") for (int m = 0; m < 4; ++m) _Pragma("unroll") for (int k = 0; k < 2; ++k) dst[m][k] = *(const LAS bf16x8*)(lds + PG8_SA(b, h) + aoff + m * 2048 + k * 1024); } while (0)
; #define PG8_LDB(dst, b, h) do { _Pragma("unroll") for (int n = 0; n < 2; ++n) _Pragma("unroll") for (int k = 0; k < 2; ++k) dst[n][k] = *(const LAS bf16x8*)(lds + PG8_SB(b, h) + boff + n * 2048 + k * 1024); } while (0)
; #define PG8_WAIT_V(n) asm volatile("s_waitcnt vmcnt(" #n ")" ::: "memory")
; #define PG8_WAIT_L(n) asm volatile("s_waitcnt lgkmcnt(" #n ")" ::: "memory")
; #define PG8_BAR __builtin_amdgcn_s_barrier()
; #define PG8_SCHED __builtin_amdgcn_sched_barrier(0)
; template <class Epi>
; __device__ __forceinline__ void gemm_phase(LAS unsigned char* lds, const bf16_t* A, int lda, const bf16_t* Bt, int ldb, int M, int N, int K, int asel, const Epi& E, const int fixed_round = -1) {
;     ...
;             PG8_WAIT_V(6); PG8_BAR; PG8_MMA(1, 1, At, B1); PG8_BAR;
;             PG8_LDB(B0, 1, 0); PG8_SCHED; PG8_LDA(At, 1, 0); PG8_STAGE(PG8_SA(0, 1), a2 + hstepA, voffA);
;             PG8_WAIT_L(8); PG8_BAR; PG8_WAIT_L(0); PG8_MMA(0, 0, At, B0); PG8_BAR; PG8_SCHED;
;             PG8_LDB(B1, 1, 1); PG8_STAGE(PG8_SB(1, 0), b3, voffB);
;             PG8_BAR; PG8_WAIT_L(0); PG8_MMA(0, 1, At, B1); PG8_BAR;
;             PG8_LDA(At, 1, 1); PG8_STAGE(PG8_SA(1, 0), a3, voffA);
	v_mfma_f32_16x16x32_bf16 v[52:55], v[206:209], v[170:173], v[52:55]
	v_mfma_f32_16x16x32_bf16 v[48:51], v[214:217], v[170:173], v[48:51]
	v_mfma_f32_16x16x32_bf16 v[36:39], v[206:209], v[178:181], v[36:39]
	v_mfma_f32_16x16x32_bf16 v[32:35], v[214:217], v[178:181], v[32:35]
	v_mfma_f32_16x16x32_bf16 v[20:23], v[206:209], v[186:189], v[20:23]
	v_mfma_f32_16x16x32_bf16 v[16:19], v[214:217], v[186:189], v[16:19]
	v_mfma_f32_16x16x32_bf16 v[4:7], v[206:209], v[194:197], v[4:7]
	v_mfma_f32_16x16x32_bf16 v[0:3], v[214:217], v[194:197], v[0:3]
	v_mfma_f32_16x16x32_bf16 v[52:55], v[210:213], v[174:177], v[52:55]
	v_mfma_f32_16x16x32_bf16 v[48:51], v[218:221], v[174:177], v[48:51]
	v_mfma_f32_16x16x32_bf16 v[36:39], v[210:213], v[182:185], v[36:39]
	v_mfma_f32_16x16x32_bf16 v[32:35], v[218:221], v[182:185], v[32:35]
	v_mfma_f32_16x16x32_bf16 v[20:23], v[210:213], v[190:193], v[20:23]
	v_mfma_f32_16x16x32_bf16 v[16:19], v[218:221], v[190:193], v[16:19]
	v_mfma_f32_16x16x32_bf16 v[4:7], v[210:213], v[202:205], v[4:7]
	v_mfma_f32_16x16x32_bf16 v[0:3], v[218:221], v[202:205], v[0:3]
	s_barrier
	s_setprio 0
	v_add_u32_e32 v136, s83, v153
	ds_read_b128 v[146:149], v136
	ds_read_b128 v[158:161], v136 offset:1024
	ds_read_b128 v[162:165], v136 offset:2048
	ds_read_b128 v[166:169], v136 offset:3072
	s_add_u32 s28, s54, 0x80000
	s_addc_u32 s29, s55, 0
	s_mov_b32 m0, s60
	ds_read_b128 v[170:173], v156 offset:32768
	ds_read_b128 v[174:177], v156 offset:33792
	ds_read_b128 v[178:181], v156 offset:34816
	ds_read_b128 v[182:185], v156 offset:35840
	ds_read_b128 v[186:189], v156 offset:36864
	ds_read_b128 v[190:193], v156 offset:37888
	ds_read_b128 v[194:197], v156 offset:38912
	ds_read_b128 v[202:205], v156 offset:39936
	global_load_lds_dwordx4 v128, s[28:29]
	s_mov_b32 m0, s61
	s_nop 0
	global_load_lds_dwordx4 v132, s[28:29]
	s_waitcnt lgkmcnt(8)
	s_setprio 1
	s_barrier
	s_waitcnt lgkmcnt(0)
	v_mfma_f32_16x16x32_bf16 v[124:127], v[146:149], v[170:173], v[124:127]
	v_mfma_f32_16x16x32_bf16 v[120:123], v[162:165], v[170:173], v[120:123]
	v_mfma_f32_16x16x32_bf16 v[108:111], v[146:149], v[178:181], v[108:111]
	v_mfma_f32_16x16x32_bf16 v[104:107], v[162:165], v[178:181], v[104:107]
	v_mfma_f32_16x16x32_bf16 v[92:95], v[146:149], v[186:189], v[92:95]
	v_mfma_f32_16x16x32_bf16 v[88:91], v[162:165], v[186:189], v[88:91]
	v_mfma_f32_16x16x32_bf16 v[76:79], v[146:149], v[194:197], v[76:79]
	v_mfma_f32_16x16x32_bf16 v[72:75], v[162:165], v[194:197], v[72:75]
	v_mfma_f32_16x16x32_bf16 v[124:127], v[158:161], v[174:177], v[124:127]
	v_mfma_f32_16x16x32_bf16 v[120:123], v[166:169], v[174:177], v[120:123]
	v_mfma_f32_16x16x32_bf16 v[108:111], v[158:161], v[182:185], v[108:111]
	v_mfma_f32_16x16x32_bf16 v[104:107], v[166:169], v[182:185], v[104:107]
	v_mfma_f32_16x16x32_bf16 v[92:95], v[158:161], v[190:193], v[92:95]
	v_mfma_f32_16x16x32_bf16 v[88:91], v[166:169], v[190:193], v[88:91]
	v_mfma_f32_16x16x32_bf16 v[76:79], v[158:161], v[202:205], v[76:79]
	v_mfma_f32_16x16x32_bf16 v[72:75], v[166:169], v[202:205], v[72:75]
	s_barrier
	s_setprio 0
	s_add_i32 s28, s83, s58
	v_add_u32_e32 v136, s84, v153
	s_mov_b32 m0, s28
	ds_read_b128 v[206:209], v136
	ds_read_b128 v[210:213], v136 offset:1024
	ds_read_b128 v[214:217], v136 offset:2048
	ds_read_b128 v[218:221], v136 offset:3072
	global_load_lds_dwordx4 v130, s[98:99]
	s_add_i32 m0, s28, 0x2000
	s_nop 0
	global_load_lds_dwordx4 v134, s[98:99]
	s_setprio 1
	s_barrier
	s_waitcnt lgkmcnt(0)
	v_mfma_f32_16x16x32_bf16 v[116:119], v[206:209], v[170:173], v[116:119]
	v_mfma_f32_16x16x32_bf16 v[112:115], v[214:217], v[170:173], v[112:115]
	v_mfma_f32_16x16x32_bf16 v[100:103], v[206:209], v[178:181], v[100:103]
	v_mfma_f32_16x16x32_bf16 v[96:99], v[214:217], v[178:181], v[96:99]
	v_mfma_f32_16x16x32_bf16 v[84:87], v[206:209], v[186:189], v[84:87]
	v_mfma_f32_16x16x32_bf16 v[80:83], v[214:217], v[186:189], v[80:83]
	v_mfma_f32_16x16x32_bf16 v[68:71], v[206:209], v[194:197], v[68:71]
	v_mfma_f32_16x16x32_bf16 v[64:67], v[214:217], v[194:197], v[64:67]
	v_mfma_f32_16x16x32_bf16 v[116:119], v[210:213], v[174:177], v[116:119]
	v_mfma_f32_16x16x32_bf16 v[112:115], v[218:221], v[174:177], v[112:115]
	v_mfma_f32_16x16x32_bf16 v[100:103], v[210:213], v[182:185], v[100:103]
	v_mfma_f32_16x16x32_bf16 v[96:99], v[218:221], v[182:185], v[96:99]
	v_mfma_f32_16x16x32_bf16 v[84:87], v[210:213], v[190:193], v[84:87]
	v_mfma_f32_16x16x32_bf16 v[80:83], v[218:221], v[190:193], v[80:83]
	v_mfma_f32_16x16x32_bf16 v[68:71], v[210:213], v[202:205], v[68:71]
	v_mfma_f32_16x16x32_bf16 v[64:67], v[218:221], v[202:205], v[64:67]
	s_barrier
	s_setprio 0
	s_mov_b32 m0, s63
	ds_read_b128 v[170:173], v156 offset:49152
	ds_read_b128 v[174:177], v156 offset:50176
	ds_read_b128 v[178:181], v156 offset:51200
	ds_read_b128 v[182:185], v156 offset:52224
	ds_read_b128 v[186:189], v156 offset:53248
	ds_read_b128 v[190:193], v156 offset:54272
	ds_read_b128 v[194:197], v156 offset:55296
	ds_read_b128 v[202:205], v156 offset:56320
	global_load_lds_dwordx4 v128, s[100:101]
	s_mov_b32 m0, s64
	s_nop 0
	global_load_lds_dwordx4 v132, s[100:101]
	s_setprio 1
	s_barrier
; #define PG8_STAGE(bufoff, gbase, voff) do { _Pragma("unroll") for (int _i = 0; _i < 2; ++_i) \
;         __builtin_amdgcn_global_load_lds((const unsigned*)((const char*)(gbase) + (voff)[_i]), (LAS unsigned*)(lds + (bufoff) + ldsw + _i * 8192), 16, 0, 0); } while (0)
; #define PG8_WAIT_V(n) asm volatile("s_waitcnt vmcnt(" #n ")" ::: "memory")
; #define PG8_WAIT_L(n) asm volatile("s_waitcnt lgkmcnt(" #n ")" ::: "memory")
; #define PG8_BAR __builtin_amdgcn_s_barrier()
; #define PG8_SCHED __builtin_amdgcn_sched_barrier(0)
; template <class Epi>
; __device__ __forceinline__ void gemm_phase(LAS unsigned char* lds, const bf16_t* A, int lda, const bf16_t* Bt, int ldb, int M, int N, int K, int asel, const Epi& E, const int fixed_round = -1) {
;     ...
;             PG8_BAR; PG8_WAIT_L(0); PG8_MMA(1, 0, At, B0); PG8_BAR; PG8_SCHED;
;             PG8_STAGE(PG8_SB(1, 1), b3 + hstepB, voffB);
;             PG8_WAIT_V(6); PG8_BAR; PG8_MMA(1, 1, At, B1); PG8_BAR;
;     __device__ __forceinline__ void operator()(const AccT& acc, const Unit& u, int wr, int wc, int fr, int fq) const {
;         const int row0 = u.pm * BM + wr * 64 + fr; const bool isg = u.pn >= 8;
;         bf16_t* base = isg ? GB : XB; const int col0 = (u.pn & 7) * BM + wc * 32 + 8 * fq;
; #pragma unroll
;         for (int ai = 0; ai < 2; ++ai)
; #pragma unroll
;             for (int m = 0; m < 4; ++m) { bf16_t* rowp = base + (size_t)(row0 + ai * HALF + m * 16) * DM + col0;
; #pragma unroll
;                 for (int bj = 0; bj < 2; ++bj) { f32x4 v0 = acc[ai][bj][m][0], v1 = acc[ai][bj][m][1];
;                     if (isg) {
; #pragma unroll
;                         for (int j = 0; j < 4; ++j) { float a = v0[j], b = v1[j];
;                             const float ta = 1.5957691216057308f * (a + 0.044715f * a * a * a), tb = 1.5957691216057308f * (b + 0.044715f * b * b * b);
;                             v0[j] = a * __builtin_amdgcn_rcpf(1.0f + __expf(-ta)); v1[j] = b * __builtin_amdgcn_rcpf(1.0f + __expf(-tb)); } }
	s_waitcnt lgkmcnt(0)
	v_mfma_f32_16x16x32_bf16 v[60:63], v[146:149], v[170:173], v[60:63]
	v_mfma_f32_16x16x32_bf16 v[56:59], v[162:165], v[170:173], v[56:59]
	v_mfma_f32_16x16x32_bf16 v[44:47], v[146:149], v[178:181], v[44:47]
	v_mfma_f32_16x16x32_bf16 v[40:43], v[162:165], v[178:181], v[40:43]
	v_mfma_f32_16x16x32_bf16 v[28:31], v[146:149], v[186:189], v[28:31]
	v_mfma_f32_16x16x32_bf16 v[24:27], v[162:165], v[186:189], v[24:27]
	v_mfma_f32_16x16x32_bf16 v[12:15], v[146:149], v[194:197], v[12:15]
	v_mfma_f32_16x16x32_bf16 v[8:11], v[162:165], v[194:197], v[8:11]
	v_mfma_f32_16x16x32_bf16 v[60:63], v[158:161], v[174:177], v[60:63]
	v_mfma_f32_16x16x32_bf16 v[56:59], v[166:169], v[174:177], v[56:59]
	v_mfma_f32_16x16x32_bf16 v[44:47], v[158:161], v[182:185], v[44:47]
	v_mfma_f32_16x16x32_bf16 v[40:43], v[166:169], v[182:185], v[40:43]
	v_mfma_f32_16x16x32_bf16 v[28:31], v[158:161], v[190:193], v[28:31]
	v_mfma_f32_16x16x32_bf16 v[24:27], v[166:169], v[190:193], v[24:27]
	v_mfma_f32_16x16x32_bf16 v[12:15], v[158:161], v[202:205], v[12:15]
	v_mfma_f32_16x16x32_bf16 v[8:11], v[166:169], v[202:205], v[8:11]
	s_barrier
	s_setprio 0
	s_add_u32 s28, s52, 0x80080
	s_addc_u32 s29, s53, 0
	s_add_i32 s52, s84, s58
	s_mov_b32 m0, s52
	s_nop 0
	global_load_lds_dwordx4 v130, s[28:29]
	s_add_i32 m0, s52, 0x2000
	s_nop 0
	global_load_lds_dwordx4 v134, s[28:29]
	s_waitcnt vmcnt(6)
	s_setprio 1
	s_barrier
	v_mfma_f32_16x16x32_bf16 v[52:55], v[206:209], v[170:173], v[52:55]
	v_mfma_f32_16x16x32_bf16 v[48:51], v[214:217], v[170:173], v[48:51]
	v_mfma_f32_16x16x32_bf16 v[36:39], v[206:209], v[178:181], v[36:39]
	v_mfma_f32_16x16x32_bf16 v[32:35], v[214:217], v[178:181], v[32:35]
	v_mfma_f32_16x16x32_bf16 v[20:23], v[206:209], v[186:189], v[20:23]
	v_mfma_f32_16x16x32_bf16 v[16:19], v[214:217], v[186:189], v[16:19]
	v_mfma_f32_16x16x32_bf16 v[4:7], v[206:209], v[194:197], v[4:7]
	v_mfma_f32_16x16x32_bf16 v[0:3], v[214:217], v[194:197], v[0:3]
	v_mfma_f32_16x16x32_bf16 v[52:55], v[210:213], v[174:177], v[52:55]
	v_mfma_f32_16x16x32_bf16 v[48:51], v[218:221], v[174:177], v[48:51]
	v_mfma_f32_16x16x32_bf16 v[36:39], v[210:213], v[182:185], v[36:39]
	v_mfma_f32_16x16x32_bf16 v[32:35], v[218:221], v[182:185], v[32:35]
	v_mfma_f32_16x16x32_bf16 v[20:23], v[210:213], v[190:193], v[20:23]
	v_mfma_f32_16x16x32_bf16 v[16:19], v[218:221], v[190:193], v[16:19]
	v_mfma_f32_16x16x32_bf16 v[4:7], v[210:213], v[202:205], v[4:7]
	v_mfma_f32_16x16x32_bf16 v[0:3], v[218:221], v[202:205], v[0:3]
	s_setprio 0
	s_add_i32 s68, s68, 2
	s_add_u32 s50, s50, 0x100
	s_addc_u32 s51, s51, 0
	s_add_u32 s66, s66, 0x100
	s_addc_u32 s67, s67, 0
	s_cmp_gt_u32 s68, 29
	s_cbranch_scc0 .Lrot_7
	s_barrier
	s_cmp_gt_i32 s4, 7
	s_cselect_b64 s[50:51], -1, 0
	s_cmp_lt_i32 s4, 8
	s_cbranch_scc1 .LBB0_802
	v_mul_f32_e32 v136, 0x3d372713, v124
	v_mul_f32_e32 v136, v124, v136
	v_mul_f32_e32 v146, 0x3d372713, v120
	v_fma_f32 v136, v124, v136, v124
	v_mul_f32_e32 v146, v120, v146
	v_fma_f32 v146, v120, v146, v120
	v_mul_f32_e32 v136, 0xbfcc422a, v136
	v_mul_f32_e32 v136, 0x3fb8aa3b, v136
	v_mul_f32_e32 v146, 0xbfcc422a, v146
	v_exp_f32_e32 v136, v136
	v_mul_f32_e32 v146, 0x3fb8aa3b, v146
	v_exp_f32_e32 v147, v146
	v_mul_f32_e32 v150, 0x3d372713, v122
	v_add_f32_e32 v136, 1.0, v136
	v_rcp_f32_e32 v146, v136
	v_add_f32_e32 v136, 1.0, v147
	v_rcp_f32_e32 v148, v136
	v_mul_f32_e32 v136, 0x3d372713, v125
	v_mul_f32_e32 v136, v125, v136
	v_fma_f32 v136, v125, v136, v125
	v_mul_f32_e32 v136, 0xbfcc422a, v136
	v_mul_f32_e32 v136, 0x3fb8aa3b, v136
	v_exp_f32_e32 v136, v136
	v_mul_f32_e32 v147, 0x3d372713, v121
	v_mul_f32_e32 v147, v121, v147
	v_fma_f32 v149, v121, v147, v121
	v_add_f32_e32 v136, 1.0, v136
	v_rcp_f32_e32 v147, v136
	v_mul_f32_e32 v136, 0xbfcc422a, v149
	v_mul_f32_e32 v149, 0x3d372713, v126
	v_mul_f32_e32 v149, v126, v149
	v_fma_f32 v149, v126, v149, v126
	v_mul_f32_e32 v150, v122, v150
	v_fma_f32 v150, v122, v150, v122
	v_mul_f32_e32 v149, 0xbfcc422a, v149
	v_mul_f32_e32 v149, 0x3fb8aa3b, v149
	v_mul_f32_e32 v150, 0xbfcc422a, v150
	v_exp_f32_e32 v149, v149
	v_mul_f32_e32 v150, 0x3fb8aa3b, v150
	v_exp_f32_e32 v151, v150
	v_mul_f32_e32 v158, 0x3d372713, v123
	v_add_f32_e32 v149, 1.0, v149
	v_rcp_f32_e32 v150, v149
	v_add_f32_e32 v149, 1.0, v151
	v_mul_f32_e32 v151, 0x3d372713, v127
	v_mul_f32_e32 v151, v127, v151
	v_fma_f32 v151, v127, v151, v127
	v_mul_f32_e32 v158, v123, v158
	v_fma_f32 v158, v123, v158, v123
	v_mul_f32_e32 v151, 0xbfcc422a, v151
	v_mul_f32_e32 v151, 0x3fb8aa3b, v151
	v_mul_f32_e32 v158, 0xbfcc422a, v158
	v_mul_f32_e32 v136, 0x3fb8aa3b, v136
	v_exp_f32_e32 v151, v151
	v_mul_f32_e32 v158, 0x3fb8aa3b, v158
	v_exp_f32_e32 v136, v136
	v_exp_f32_e32 v159, v158
	v_rcp_f32_e32 v158, v149
	v_add_f32_e32 v149, 1.0, v151
	v_add_f32_e32 v136, 1.0, v136
	v_rcp_f32_e32 v151, v149
	v_add_f32_e32 v149, 1.0, v159
	v_rcp_f32_e32 v159, v149
	v_rcp_f32_e32 v149, v136
	v_pk_mul_f32 v[126:127], v[126:127], v[150:151]
	v_pk_mul_f32 v[124:125], v[124:125], v[146:147]
	v_pk_mul_f32 v[122:123], v[122:123], v[158:159]
	v_pk_mul_f32 v[120:121], v[120:121], v[148:149]

; #define PG8_STAGE(bufoff, gbase, voff) do { _Pragma("unroll") for (int _i = 0; _i < 2; ++_i) \
;         __builtin_amdgcn_global_load_lds((const unsigned*)((const char*)(gbase) + (voff)[_i]), (LAS unsigned*)(lds + (bufoff) + ldsw + _i * 8192), 16, 0, 0); } while (0)
; #define PG8_LDA(dst, b, h) do { _Pragma("unroll") for (int m = 0; m < 4; ++m) _Pragma("unroll") for (int k = 0; k < 2; ++k) dst[m][k] = *(const LAS bf16x8*)(lds + PG8_SA(b, h) + aoff + m * 2048 + k * 1024); } while (0)
; #define PG8_LDB(dst, b, h) do { _Pragma("unroll") for (int n = 0; n < 2; ++n) _Pragma("unroll") for (int k = 0; k < 2; ++k) dst[n][k] = *(const LAS bf16x8*)(lds + PG8_SB(b, h) + boff + n * 2048 + k * 1024); } while (0)
; #define PG8_WAIT_V(n) asm volatile("s_waitcnt vmcnt(" #n ")" ::: "memory")
; #define PG8_WAIT_L(n) asm volatile("s_waitcnt lgkmcnt(" #n ")" ::: "memory")
; #define PG8_BAR __builtin_amdgcn_s_barrier()
; #define PG8_SCHED __builtin_amdgcn_sched_barrier(0)
; template <class Epi>
; __device__ __forceinline__ void gemm_phase(LAS unsigned char* lds, const bf16_t* A, int lda, const bf16_t* Bt, int ldb, int M, int N, int K, int asel, const Epi& E, const int fixed_round = -1) {
;     ...
;             const bool last = (t == nt - 2);
;             const char* a1 = cA + (size_t)(t + 1) * kstep;
;             const char* a2 = last ? nA : cA + (size_t)(t + 2) * kstep; const char* b2 = last ? nB : cB + (size_t)(t + 2) * kstep;
;             const char* a3 = a2 + kstep; const char* b3 = b2 + kstep;
;             PG8_LDB(B0, 0, 0); PG8_SCHED; PG8_LDA(At, 0, 0); PG8_STAGE(PG8_SA(1, 1), a1 + hstepA, voffA);
;             PG8_WAIT_L(8); PG8_BAR; PG8_WAIT_L(0); PG8_MMA(0, 0, At, B0); PG8_BAR; PG8_SCHED;
;             PG8_LDB(B1, 0, 1); PG8_STAGE(PG8_SB(0, 0), b2, voffB);
;             PG8_BAR; PG8_WAIT_L(0); PG8_MMA(0, 1, At, B1); PG8_BAR;
;             PG8_LDA(At, 0, 1); PG8_STAGE(PG8_SA(0, 0), a2, voffA);
;             PG8_BAR; PG8_WAIT_L(0); PG8_MMA(1, 0, At, B0); PG8_BAR; PG8_SCHED;
;             PG8_STAGE(PG8_SB(0, 1), b2 + hstepB, voffB);
;             PG8_WAIT_V(6); PG8_BAR; PG8_MMA(1, 1, At, B1); PG8_BAR;
.LBB0_1081:
	ds_read_b128 v[146:149], v140
	ds_read_b128 v[150:153], v140 offset:1024
	ds_read_b128 v[160:163], v140 offset:2048
	ds_read_b128 v[166:169], v140 offset:3072
	s_mov_b32 m0, s57
	v_lshl_add_u64 v[156:157], v[136:137], 0, s[22:23]
	ds_read_b128 v[170:173], v141
	ds_read_b128 v[174:177], v141 offset:1024
	ds_read_b128 v[178:181], v141 offset:2048
	ds_read_b128 v[182:185], v141 offset:3072
	ds_read_b128 v[186:189], v141 offset:4096
	ds_read_b128 v[190:193], v141 offset:5120
	ds_read_b128 v[194:197], v141 offset:6144
	ds_read_b128 v[202:205], v141 offset:7168
	global_load_lds_dwordx4 v[156:157], off
	v_lshl_add_u64 v[156:157], v[138:139], 0, s[22:23]
	s_mov_b32 m0, s58
	s_nop 0
	global_load_lds_dwordx4 v[156:157], off
	s_waitcnt lgkmcnt(8)
	s_setprio 1
	s_barrier
	s_waitcnt lgkmcnt(0)
	v_mfma_f32_16x16x32_bf16 v[124:127], v[146:149], v[170:173], v[124:127]
	v_mfma_f32_16x16x32_bf16 v[120:123], v[160:163], v[170:173], v[120:123]
	v_mfma_f32_16x16x32_bf16 v[112:115], v[146:149], v[178:181], v[112:115]
	v_mfma_f32_16x16x32_bf16 v[104:107], v[160:163], v[178:181], v[104:107]
	v_mfma_f32_16x16x32_bf16 v[96:99], v[146:149], v[186:189], v[96:99]
	v_mfma_f32_16x16x32_bf16 v[88:91], v[160:163], v[186:189], v[88:91]
	v_mfma_f32_16x16x32_bf16 v[80:83], v[146:149], v[194:197], v[80:83]
	v_mfma_f32_16x16x32_bf16 v[72:75], v[160:163], v[194:197], v[72:75]
	v_mfma_f32_16x16x32_bf16 v[124:127], v[150:153], v[174:177], v[124:127]
	v_mfma_f32_16x16x32_bf16 v[120:123], v[166:169], v[174:177], v[120:123]
	v_mfma_f32_16x16x32_bf16 v[112:115], v[150:153], v[182:185], v[112:115]
	v_mfma_f32_16x16x32_bf16 v[104:107], v[166:169], v[182:185], v[104:107]
	v_mfma_f32_16x16x32_bf16 v[96:99], v[150:153], v[190:193], v[96:99]
	v_mfma_f32_16x16x32_bf16 v[88:91], v[166:169], v[190:193], v[88:91]
	v_mfma_f32_16x16x32_bf16 v[80:83], v[150:153], v[202:205], v[80:83]
	v_mfma_f32_16x16x32_bf16 v[72:75], v[166:169], v[202:205], v[72:75]
	s_barrier
	s_setprio 0
	s_add_u32 s28, s22, 0xdfa80080
	s_addc_u32 s29, s23, -1
	s_cmp_lg_u32 s56, 28
	s_cselect_b32 s28, s28, 0
	s_cselect_b32 s29, s29, 0
	s_add_u32 s46, s0, s28
	s_addc_u32 s47, s1, s29
	s_add_u32 s44, s2, s28
	s_addc_u32 s45, s3, s29
	s_mov_b32 m0, s59
	s_add_u32 s98, s44, s42
	s_addc_u32 s99, s45, s43
	ds_read_b128 v[206:209], v142
	ds_read_b128 v[210:213], v142 offset:1024
	ds_read_b128 v[214:217], v142 offset:2048
	ds_read_b128 v[218:221], v142 offset:3072
	global_load_lds_dwordx4 v130, s[44:45]
	s_mov_b32 m0, s60
	s_nop 0
	global_load_lds_dwordx4 v134, s[44:45]
	s_setprio 1
	s_barrier
	s_waitcnt lgkmcnt(0)
	v_mfma_f32_16x16x32_bf16 v[116:119], v[206:209], v[170:173], v[116:119]
	v_mfma_f32_16x16x32_bf16 v[108:111], v[214:217], v[170:173], v[108:111]
	v_mfma_f32_16x16x32_bf16 v[100:103], v[206:209], v[178:181], v[100:103]
	v_mfma_f32_16x16x32_bf16 v[92:95], v[214:217], v[178:181], v[92:95]
	v_mfma_f32_16x16x32_bf16 v[84:87], v[206:209], v[186:189], v[84:87]
	v_mfma_f32_16x16x32_bf16 v[76:79], v[214:217], v[186:189], v[76:79]
	v_mfma_f32_16x16x32_bf16 v[68:71], v[206:209], v[194:197], v[68:71]
	v_mfma_f32_16x16x32_bf16 v[64:67], v[214:217], v[194:197], v[64:67]
	v_mfma_f32_16x16x32_bf16 v[116:119], v[210:213], v[174:177], v[116:119]
	v_mfma_f32_16x16x32_bf16 v[108:111], v[218:221], v[174:177], v[108:111]
	v_mfma_f32_16x16x32_bf16 v[100:103], v[210:213], v[182:185], v[100:103]
	v_mfma_f32_16x16x32_bf16 v[92:95], v[218:221], v[182:185], v[92:95]
	v_mfma_f32_16x16x32_bf16 v[84:87], v[210:213], v[190:193], v[84:87]
	v_mfma_f32_16x16x32_bf16 v[76:79], v[218:221], v[190:193], v[76:79]
	v_mfma_f32_16x16x32_bf16 v[68:71], v[210:213], v[202:205], v[68:71]
	v_mfma_f32_16x16x32_bf16 v[64:67], v[218:221], v[202:205], v[64:67]
	s_barrier
	s_setprio 0
	s_mov_b32 m0, s49
	s_add_u32 s100, s46, s42
	s_addc_u32 s101, s47, s43
	ds_read_b128 v[170:173], v141 offset:16384
	ds_read_b128 v[174:177], v141 offset:17408
	ds_read_b128 v[178:181], v141 offset:18432
	ds_read_b128 v[182:185], v141 offset:19456
	ds_read_b128 v[186:189], v141 offset:20480
	ds_read_b128 v[190:193], v141 offset:21504
	ds_read_b128 v[194:197], v141 offset:22528
	ds_read_b128 v[202:205], v141 offset:23552
	global_load_lds_dwordx4 v128, s[46:47]
	s_mov_b32 m0, s50
	s_nop 0
	global_load_lds_dwordx4 v132, s[46:47]
	s_setprio 1
	s_barrier
	s_waitcnt lgkmcnt(0)
	v_mfma_f32_16x16x32_bf16 v[60:63], v[146:149], v[170:173], v[60:63]
	v_mfma_f32_16x16x32_bf16 v[56:59], v[160:163], v[170:173], v[56:59]
	v_mfma_f32_16x16x32_bf16 v[48:51], v[146:149], v[178:181], v[48:51]
	v_mfma_f32_16x16x32_bf16 v[40:43], v[160:163], v[178:181], v[40:43]
	v_mfma_f32_16x16x32_bf16 v[32:35], v[146:149], v[186:189], v[32:35]
	v_mfma_f32_16x16x32_bf16 v[24:27], v[160:163], v[186:189], v[24:27]
	v_mfma_f32_16x16x32_bf16 v[16:19], v[146:149], v[194:197], v[16:19]
	v_mfma_f32_16x16x32_bf16 v[8:11], v[160:163], v[194:197], v[8:11]
	v_mfma_f32_16x16x32_bf16 v[60:63], v[150:153], v[174:177], v[60:63]
	v_mfma_f32_16x16x32_bf16 v[56:59], v[166:169], v[174:177], v[56:59]
	v_mfma_f32_16x16x32_bf16 v[48:51], v[150:153], v[182:185], v[48:51]
	v_mfma_f32_16x16x32_bf16 v[40:43], v[166:169], v[182:185], v[40:43]
	v_mfma_f32_16x16x32_bf16 v[32:35], v[150:153], v[190:193], v[32:35]
	v_mfma_f32_16x16x32_bf16 v[24:27], v[166:169], v[190:193], v[24:27]
	v_mfma_f32_16x16x32_bf16 v[16:19], v[150:153], v[202:205], v[16:19]
	v_mfma_f32_16x16x32_bf16 v[8:11], v[166:169], v[202:205], v[8:11]
	s_barrier
	s_setprio 0
	s_add_u32 s28, s44, 0x80000
	s_addc_u32 s29, s45, 0
	s_mov_b32 m0, s61
	s_nop 0
	global_load_lds_dwordx4 v130, s[28:29]
	s_mov_b32 m0, s62
	s_nop 0
	global_load_lds_dwordx4 v134, s[28:29]
	s_waitcnt vmcnt(6)
	s_setprio 1
	s_barrier
; #define PG8_STAGE(bufoff, gbase, voff) do { _Pragma("unroll") for (int _i = 0; _i < 2; ++_i) \
;         __builtin_amdgcn_global_load_lds((const unsigned*)((const char*)(gbase) + (voff)[_i]), (LAS unsigned*)(lds + (bufoff) + ldsw + _i * 8192), 16, 0, 0); } while (0)
; #define PG8_LDA(dst, b, h) do { _Pragma("unroll") for (int m = 0; m < 4; ++m) _Pragma("unroll") for (int k = 0; k < 2; ++k) dst[m][k] = *(const LAS bf16x8*)(lds + PG8_SA(b, h) + aoff + m * 2048 + k * 1024); } while (0)
; #define PG8_LDB(dst, b, h) do { _Pragma("unroll") for (int n = 0; n < 2; ++n) _Pragma("unroll") for (int k = 0; k < 2; ++k) dst[n][k] = *(const LAS bf16x8*)(lds + PG8_SB(b, h) + boff + n * 2048 + k * 1024); } while (0)
; #define PG8_WAIT_V(n) asm volatile("s_waitcnt vmcnt(" #n ")" ::: "memory")
; #define PG8_WAIT_L(n) asm volatile("s_waitcnt lgkmcnt(" #n ")" ::: "memory")
; #define PG8_BAR __builtin_amdgcn_s_barrier()
; #define PG8_SCHED __builtin_amdgcn_sched_barrier(0)
; template <class Epi>
; __device__ __forceinline__ void gemm_phase(LAS unsigned char* lds, const bf16_t* A, int lda, const bf16_t* Bt, int ldb, int M, int N, int K, int asel, const Epi& E, const int fixed_round = -1) {
;     ...
;             PG8_WAIT_V(6); PG8_BAR; PG8_MMA(1, 1, At, B1); PG8_BAR;
;             PG8_LDB(B0, 1, 0); PG8_SCHED; PG8_LDA(At, 1, 0); PG8_STAGE(PG8_SA(0, 1), a2 + hstepA, voffA);
;             PG8_WAIT_L(8); PG8_BAR; PG8_WAIT_L(0); PG8_MMA(0, 0, At, B0); PG8_BAR; PG8_SCHED;
	v_mfma_f32_16x16x32_bf16 v[52:55], v[206:209], v[170:173], v[52:55]
	v_mfma_f32_16x16x32_bf16 v[44:47], v[214:217], v[170:173], v[44:47]
	v_mfma_f32_16x16x32_bf16 v[36:39], v[206:209], v[178:181], v[36:39]
	v_mfma_f32_16x16x32_bf16 v[28:31], v[214:217], v[178:181], v[28:31]
	v_mfma_f32_16x16x32_bf16 v[20:23], v[206:209], v[186:189], v[20:23]
	v_mfma_f32_16x16x32_bf16 v[12:15], v[214:217], v[186:189], v[12:15]
	v_mfma_f32_16x16x32_bf16 v[4:7], v[206:209], v[194:197], v[4:7]
	v_mfma_f32_16x16x32_bf16 v[0:3], v[214:217], v[194:197], v[0:3]
	v_mfma_f32_16x16x32_bf16 v[52:55], v[210:213], v[174:177], v[52:55]
	v_mfma_f32_16x16x32_bf16 v[44:47], v[218:221], v[174:177], v[44:47]
	v_mfma_f32_16x16x32_bf16 v[36:39], v[210:213], v[182:185], v[36:39]
	v_mfma_f32_16x16x32_bf16 v[28:31], v[218:221], v[182:185], v[28:31]
	v_mfma_f32_16x16x32_bf16 v[20:23], v[210:213], v[190:193], v[20:23]
	v_mfma_f32_16x16x32_bf16 v[12:15], v[218:221], v[190:193], v[12:15]
	v_mfma_f32_16x16x32_bf16 v[4:7], v[210:213], v[202:205], v[4:7]
	v_mfma_f32_16x16x32_bf16 v[0:3], v[218:221], v[202:205], v[0:3]
	s_barrier
	s_setprio 0
	ds_read_b128 v[146:149], v143
	ds_read_b128 v[150:153], v143 offset:1024
	ds_read_b128 v[160:163], v143 offset:2048
	ds_read_b128 v[166:169], v143 offset:3072
	s_add_u32 s28, s46, 0x80000
	s_addc_u32 s29, s47, 0
	s_mov_b32 m0, s52
	ds_read_b128 v[170:173], v141 offset:32768
	ds_read_b128 v[174:177], v141 offset:33792
	ds_read_b128 v[178:181], v141 offset:34816
	ds_read_b128 v[182:185], v141 offset:35840
	ds_read_b128 v[186:189], v141 offset:36864
	ds_read_b128 v[190:193], v141 offset:37888
	ds_read_b128 v[194:197], v141 offset:38912
	ds_read_b128 v[202:205], v141 offset:39936
	global_load_lds_dwordx4 v128, s[28:29]
	s_mov_b32 m0, s53
	s_nop 0
	global_load_lds_dwordx4 v132, s[28:29]
	s_waitcnt lgkmcnt(8)
	s_setprio 1
	s_barrier
	s_waitcnt lgkmcnt(0)
	v_mfma_f32_16x16x32_bf16 v[124:127], v[146:149], v[170:173], v[124:127]
	v_mfma_f32_16x16x32_bf16 v[120:123], v[160:163], v[170:173], v[120:123]
	v_mfma_f32_16x16x32_bf16 v[112:115], v[146:149], v[178:181], v[112:115]
	v_mfma_f32_16x16x32_bf16 v[104:107], v[160:163], v[178:181], v[104:107]
	v_mfma_f32_16x16x32_bf16 v[96:99], v[146:149], v[186:189], v[96:99]
	v_mfma_f32_16x16x32_bf16 v[88:91], v[160:163], v[186:189], v[88:91]
	v_mfma_f32_16x16x32_bf16 v[80:83], v[146:149], v[194:197], v[80:83]
	v_mfma_f32_16x16x32_bf16 v[72:75], v[160:163], v[194:197], v[72:75]
	v_mfma_f32_16x16x32_bf16 v[124:127], v[150:153], v[174:177], v[124:127]
	v_mfma_f32_16x16x32_bf16 v[120:123], v[166:169], v[174:177], v[120:123]
	v_mfma_f32_16x16x32_bf16 v[112:115], v[150:153], v[182:185], v[112:115]
	v_mfma_f32_16x16x32_bf16 v[104:107], v[166:169], v[182:185], v[104:107]
	v_mfma_f32_16x16x32_bf16 v[96:99], v[150:153], v[190:193], v[96:99]
	v_mfma_f32_16x16x32_bf16 v[88:91], v[166:169], v[190:193], v[88:91]
	v_mfma_f32_16x16x32_bf16 v[80:83], v[150:153], v[202:205], v[80:83]
	v_mfma_f32_16x16x32_bf16 v[72:75], v[166:169], v[202:205], v[72:75]
	s_barrier
	s_setprio 0
	s_mov_b32 m0, s63
	ds_read_b128 v[206:209], v144
	ds_read_b128 v[210:213], v144 offset:1024
	ds_read_b128 v[214:217], v144 offset:2048
	ds_read_b128 v[218:221], v144 offset:3072
	global_load_lds_dwordx4 v130, s[98:99]
	s_mov_b32 m0, s64
	s_nop 0
	global_load_lds_dwordx4 v134, s[98:99]
	s_setprio 1
	s_barrier
; #define PG8_STAGE(bufoff, gbase, voff) do { _Pragma("unroll") for (int _i = 0; _i < 2; ++_i) \
;         __builtin_amdgcn_global_load_lds((const unsigned*)((const char*)(gbase) + (voff)[_i]), (LAS unsigned*)(lds + (bufoff) + ldsw + _i * 8192), 16, 0, 0); } while (0)
; #define PG8_LDA(dst, b, h) do { _Pragma("unroll") for (int m = 0; m < 4; ++m) _Pragma("unroll") for (int k = 0; k < 2; ++k) dst[m][k] = *(const LAS bf16x8*)(lds + PG8_SA(b, h) + aoff + m * 2048 + k * 1024); } while (0)
; #define PG8_LDB(dst, b, h) do { _Pragma("unroll") for (int n = 0; n < 2; ++n) _Pragma("unroll") for (int k = 0; k < 2; ++k) dst[n][k] = *(const LAS bf16x8*)(lds + PG8_SB(b, h) + boff + n * 2048 + k * 1024); } while (0)
; #define PG8_WAIT_V(n) asm volatile("s_waitcnt vmcnt(" #n ")" ::: "memory")
; #define PG8_WAIT_L(n) asm volatile("s_waitcnt lgkmcnt(" #n ")" ::: "memory")
; #define PG8_BAR __builtin_amdgcn_s_barrier()
; #define PG8_SCHED __builtin_amdgcn_sched_barrier(0)
; template <class Epi>
; __device__ __forceinline__ void gemm_phase(LAS unsigned char* lds, const bf16_t* A, int lda, const bf16_t* Bt, int ldb, int M, int N, int K, int asel, const Epi& E, const int fixed_round = -1) {
;     ...
;             PG8_WAIT_L(8); PG8_BAR; PG8_WAIT_L(0); PG8_MMA(0, 0, At, B0); PG8_BAR; PG8_SCHED;
;             PG8_LDB(B1, 1, 1); PG8_STAGE(PG8_SB(1, 0), b3, voffB);
;             PG8_BAR; PG8_WAIT_L(0); PG8_MMA(0, 1, At, B1); PG8_BAR;
;             PG8_LDA(At, 1, 1); PG8_STAGE(PG8_SA(1, 0), a3, voffA);
;             PG8_BAR; PG8_WAIT_L(0); PG8_MMA(1, 0, At, B0); PG8_BAR; PG8_SCHED;
;             PG8_STAGE(PG8_SB(1, 1), b3 + hstepB, voffB);
;             PG8_WAIT_V(6); PG8_BAR; PG8_MMA(1, 1, At, B1); PG8_BAR;
;     ...
;     PG8_WAIT_V(0);
;     if (wr == 0) PG8_BAR;
;     PG8_BAR;
	s_waitcnt lgkmcnt(0)
	v_mfma_f32_16x16x32_bf16 v[116:119], v[206:209], v[170:173], v[116:119]
	v_mfma_f32_16x16x32_bf16 v[108:111], v[214:217], v[170:173], v[108:111]
	v_mfma_f32_16x16x32_bf16 v[100:103], v[206:209], v[178:181], v[100:103]
	v_mfma_f32_16x16x32_bf16 v[92:95], v[214:217], v[178:181], v[92:95]
	v_mfma_f32_16x16x32_bf16 v[84:87], v[206:209], v[186:189], v[84:87]
	v_mfma_f32_16x16x32_bf16 v[76:79], v[214:217], v[186:189], v[76:79]
	v_mfma_f32_16x16x32_bf16 v[68:71], v[206:209], v[194:197], v[68:71]
	v_mfma_f32_16x16x32_bf16 v[64:67], v[214:217], v[194:197], v[64:67]
	v_mfma_f32_16x16x32_bf16 v[116:119], v[210:213], v[174:177], v[116:119]
	v_mfma_f32_16x16x32_bf16 v[108:111], v[218:221], v[174:177], v[108:111]
	v_mfma_f32_16x16x32_bf16 v[100:103], v[210:213], v[182:185], v[100:103]
	v_mfma_f32_16x16x32_bf16 v[92:95], v[218:221], v[182:185], v[92:95]
	v_mfma_f32_16x16x32_bf16 v[84:87], v[210:213], v[190:193], v[84:87]
	v_mfma_f32_16x16x32_bf16 v[76:79], v[218:221], v[190:193], v[76:79]
	v_mfma_f32_16x16x32_bf16 v[68:71], v[210:213], v[202:205], v[68:71]
	v_mfma_f32_16x16x32_bf16 v[64:67], v[218:221], v[202:205], v[64:67]
	s_barrier
	s_setprio 0
	s_mov_b32 m0, s54
	ds_read_b128 v[170:173], v141 offset:49152
	ds_read_b128 v[174:177], v141 offset:50176
	ds_read_b128 v[178:181], v141 offset:51200
	ds_read_b128 v[182:185], v141 offset:52224
	ds_read_b128 v[186:189], v141 offset:53248
	ds_read_b128 v[190:193], v141 offset:54272
	ds_read_b128 v[194:197], v141 offset:55296
	ds_read_b128 v[202:205], v141 offset:56320
	global_load_lds_dwordx4 v128, s[100:101]
	s_mov_b32 m0, s55
	s_nop 0
	global_load_lds_dwordx4 v132, s[100:101]
	s_setprio 1
	s_barrier
	s_waitcnt lgkmcnt(0)
	v_mfma_f32_16x16x32_bf16 v[60:63], v[146:149], v[170:173], v[60:63]
	v_mfma_f32_16x16x32_bf16 v[56:59], v[160:163], v[170:173], v[56:59]
	v_mfma_f32_16x16x32_bf16 v[48:51], v[146:149], v[178:181], v[48:51]
	v_mfma_f32_16x16x32_bf16 v[40:43], v[160:163], v[178:181], v[40:43]
	v_mfma_f32_16x16x32_bf16 v[32:35], v[146:149], v[186:189], v[32:35]
	v_mfma_f32_16x16x32_bf16 v[24:27], v[160:163], v[186:189], v[24:27]
	v_mfma_f32_16x16x32_bf16 v[16:19], v[146:149], v[194:197], v[16:19]
	v_mfma_f32_16x16x32_bf16 v[8:11], v[160:163], v[194:197], v[8:11]
	v_mfma_f32_16x16x32_bf16 v[60:63], v[150:153], v[174:177], v[60:63]
	v_mfma_f32_16x16x32_bf16 v[56:59], v[166:169], v[174:177], v[56:59]
	v_mfma_f32_16x16x32_bf16 v[48:51], v[150:153], v[182:185], v[48:51]
	v_mfma_f32_16x16x32_bf16 v[40:43], v[166:169], v[182:185], v[40:43]
	v_mfma_f32_16x16x32_bf16 v[32:35], v[150:153], v[190:193], v[32:35]
	v_mfma_f32_16x16x32_bf16 v[24:27], v[166:169], v[190:193], v[24:27]
	v_mfma_f32_16x16x32_bf16 v[16:19], v[150:153], v[202:205], v[16:19]
	v_mfma_f32_16x16x32_bf16 v[8:11], v[166:169], v[202:205], v[8:11]
	s_barrier
	s_setprio 0
	s_add_u32 s28, s44, 0x80080
	s_addc_u32 s29, s45, 0
	s_mov_b32 m0, s65
	s_nop 0
	global_load_lds_dwordx4 v130, s[28:29]
	s_mov_b32 m0, s66
	s_nop 0
	global_load_lds_dwordx4 v134, s[28:29]
	s_waitcnt vmcnt(6)
	s_setprio 1
	s_barrier
	v_mfma_f32_16x16x32_bf16 v[52:55], v[206:209], v[170:173], v[52:55]
	v_mfma_f32_16x16x32_bf16 v[44:47], v[214:217], v[170:173], v[44:47]
	v_mfma_f32_16x16x32_bf16 v[36:39], v[206:209], v[178:181], v[36:39]
	v_mfma_f32_16x16x32_bf16 v[28:31], v[214:217], v[178:181], v[28:31]
	v_mfma_f32_16x16x32_bf16 v[20:23], v[206:209], v[186:189], v[20:23]
	v_mfma_f32_16x16x32_bf16 v[12:15], v[214:217], v[186:189], v[12:15]
	v_mfma_f32_16x16x32_bf16 v[4:7], v[206:209], v[194:197], v[4:7]
	v_mfma_f32_16x16x32_bf16 v[0:3], v[214:217], v[194:197], v[0:3]
	v_mfma_f32_16x16x32_bf16 v[52:55], v[210:213], v[174:177], v[52:55]
	v_mfma_f32_16x16x32_bf16 v[44:47], v[218:221], v[174:177], v[44:47]
	v_mfma_f32_16x16x32_bf16 v[36:39], v[210:213], v[182:185], v[36:39]
	v_mfma_f32_16x16x32_bf16 v[28:31], v[218:221], v[182:185], v[28:31]
	v_mfma_f32_16x16x32_bf16 v[20:23], v[210:213], v[190:193], v[20:23]
	v_mfma_f32_16x16x32_bf16 v[12:15], v[218:221], v[190:193], v[12:15]
	v_mfma_f32_16x16x32_bf16 v[4:7], v[210:213], v[202:205], v[4:7]
	v_mfma_f32_16x16x32_bf16 v[0:3], v[218:221], v[202:205], v[0:3]
	s_setprio 0
	s_add_i32 s56, s56, 2
	s_add_u32 s22, s22, 0x100
	s_addc_u32 s23, s23, 0
	s_cmp_lt_u32 s56, 30
	s_cbranch_scc1 .Lrot_8
	s_barrier
	s_waitcnt vmcnt(0)
	s_cmpk_gt_u32 s48, 0xff
	s_cbranch_scc1 .LBB0_1084
	s_barrier

; #define PG8_STAGE(bufoff, gbase, voff) do { _Pragma("unroll") for (int _i = 0; _i < 2; ++_i) \
;         __builtin_amdgcn_global_load_lds((const unsigned*)((const char*)(gbase) + (voff)[_i]), (LAS unsigned*)(lds + (bufoff) + ldsw + _i * 8192), 16, 0, 0); } while (0)
; #define PG8_LDA(dst, b, h) do { _Pragma("unroll") for (int m = 0; m < 4; ++m) _Pragma("unroll") for (int k = 0; k < 2; ++k) dst[m][k] = *(const LAS bf16x8*)(lds + PG8_SA(b, h) + aoff + m * 2048 + k * 1024); } while (0)
; #define PG8_LDB(dst, b, h) do { _Pragma("unroll") for (int n = 0; n < 2; ++n) _Pragma("unroll") for (int k = 0; k < 2; ++k) dst[n][k] = *(const LAS bf16x8*)(lds + PG8_SB(b, h) + boff + n * 2048 + k * 1024); } while (0)
; #define PG8_WAIT_V(n) asm volatile("s_waitcnt vmcnt(" #n ")" ::: "memory")
; #define PG8_WAIT_L(n) asm volatile("s_waitcnt lgkmcnt(" #n ")" ::: "memory")
; #define PG8_BAR __builtin_amdgcn_s_barrier()
; #define PG8_SCHED __builtin_amdgcn_sched_barrier(0)
; template <class Epi>
; __device__ __forceinline__ void gemm_phase(LAS unsigned char* lds, const bf16_t* A, int lda, const bf16_t* Bt, int ldb, int M, int N, int K, int asel, const Epi& E, const int fixed_round = -1) {
;     ...
;             const bool last = (t == nt - 2);
;             const char* a1 = cA + (size_t)(t + 1) * kstep;
;             const char* a2 = last ? nA : cA + (size_t)(t + 2) * kstep; const char* b2 = last ? nB : cB + (size_t)(t + 2) * kstep;
;             const char* a3 = a2 + kstep; const char* b3 = b2 + kstep;
;             PG8_LDB(B0, 0, 0); PG8_SCHED; PG8_LDA(At, 0, 0); PG8_STAGE(PG8_SA(1, 1), a1 + hstepA, voffA);
;             PG8_WAIT_L(8); PG8_BAR; PG8_WAIT_L(0); PG8_MMA(0, 0, At, B0); PG8_BAR; PG8_SCHED;
;             PG8_LDB(B1, 0, 1); PG8_STAGE(PG8_SB(0, 0), b2, voffB);
;             PG8_BAR; PG8_WAIT_L(0); PG8_MMA(0, 1, At, B1); PG8_BAR;
;             PG8_LDA(At, 0, 1); PG8_STAGE(PG8_SA(0, 0), a2, voffA);
;             PG8_BAR; PG8_WAIT_L(0); PG8_MMA(1, 0, At, B0); PG8_BAR; PG8_SCHED;
;             PG8_STAGE(PG8_SB(0, 1), b2 + hstepB, voffB);
;             PG8_WAIT_V(6); PG8_BAR; PG8_MMA(1, 1, At, B1); PG8_BAR;
.LBB0_1120:
	ds_read_b128 v[146:149], v138
	ds_read_b128 v[150:153], v138 offset:1024
	ds_read_b128 v[160:163], v138 offset:2048
	ds_read_b128 v[166:169], v138 offset:3072
	s_mov_b32 m0, s41
	v_lshl_add_u64 v[156:157], v[134:135], 0, s[6:7]
	ds_read_b128 v[170:173], v139
	ds_read_b128 v[174:177], v139 offset:1024
	ds_read_b128 v[178:181], v139 offset:2048
	ds_read_b128 v[182:185], v139 offset:3072
	ds_read_b128 v[186:189], v139 offset:4096
	ds_read_b128 v[190:193], v139 offset:5120
	ds_read_b128 v[194:197], v139 offset:6144
	ds_read_b128 v[202:205], v139 offset:7168
	global_load_lds_dwordx4 v[156:157], off
	v_lshl_add_u64 v[156:157], v[136:137], 0, s[6:7]
	s_mov_b32 m0, s58
	s_nop 0
	global_load_lds_dwordx4 v[156:157], off
	s_waitcnt lgkmcnt(8)
	s_setprio 1
	s_barrier
	s_waitcnt lgkmcnt(0)
	v_mfma_f32_16x16x32_bf16 v[124:127], v[146:149], v[170:173], v[124:127]
	v_mfma_f32_16x16x32_bf16 v[120:123], v[160:163], v[170:173], v[120:123]
	v_mfma_f32_16x16x32_bf16 v[112:115], v[146:149], v[178:181], v[112:115]
	v_mfma_f32_16x16x32_bf16 v[104:107], v[160:163], v[178:181], v[104:107]
	v_mfma_f32_16x16x32_bf16 v[96:99], v[146:149], v[186:189], v[96:99]
	v_mfma_f32_16x16x32_bf16 v[88:91], v[160:163], v[186:189], v[88:91]
	v_mfma_f32_16x16x32_bf16 v[80:83], v[146:149], v[194:197], v[80:83]
	v_mfma_f32_16x16x32_bf16 v[72:75], v[160:163], v[194:197], v[72:75]
	v_mfma_f32_16x16x32_bf16 v[124:127], v[150:153], v[174:177], v[124:127]
	v_mfma_f32_16x16x32_bf16 v[120:123], v[166:169], v[174:177], v[120:123]
	v_mfma_f32_16x16x32_bf16 v[112:115], v[150:153], v[182:185], v[112:115]
	v_mfma_f32_16x16x32_bf16 v[104:107], v[166:169], v[182:185], v[104:107]
	v_mfma_f32_16x16x32_bf16 v[96:99], v[150:153], v[190:193], v[96:99]
	v_mfma_f32_16x16x32_bf16 v[88:91], v[166:169], v[190:193], v[88:91]
	v_mfma_f32_16x16x32_bf16 v[80:83], v[150:153], v[202:205], v[80:83]
	v_mfma_f32_16x16x32_bf16 v[72:75], v[166:169], v[202:205], v[72:75]
	s_barrier
	s_setprio 0
	s_add_u32 s22, s6, 0xdfa80080
	s_addc_u32 s23, s7, -1
	s_cmp_lg_u32 s40, 28
	s_cselect_b32 s22, s22, 0
	s_cselect_b32 s23, s23, 0
	s_add_u32 s24, s0, s22
	s_addc_u32 s25, s1, s23
	s_add_u32 s22, s2, s22
	s_addc_u32 s23, s3, s23
	s_mov_b32 m0, s59
	s_add_u32 s98, s22, s4
	s_addc_u32 s99, s23, s5
	ds_read_b128 v[206:209], v140
	ds_read_b128 v[210:213], v140 offset:1024
	ds_read_b128 v[214:217], v140 offset:2048
	ds_read_b128 v[218:221], v140 offset:3072
	global_load_lds_dwordx4 v144, s[22:23]
	s_mov_b32 m0, s60
	s_nop 0
	global_load_lds_dwordx4 v132, s[22:23]
	s_setprio 1
	s_barrier
	s_waitcnt lgkmcnt(0)
	v_mfma_f32_16x16x32_bf16 v[116:119], v[206:209], v[170:173], v[116:119]
	v_mfma_f32_16x16x32_bf16 v[108:111], v[214:217], v[170:173], v[108:111]
	v_mfma_f32_16x16x32_bf16 v[100:103], v[206:209], v[178:181], v[100:103]
	v_mfma_f32_16x16x32_bf16 v[92:95], v[214:217], v[178:181], v[92:95]
	v_mfma_f32_16x16x32_bf16 v[84:87], v[206:209], v[186:189], v[84:87]
	v_mfma_f32_16x16x32_bf16 v[76:79], v[214:217], v[186:189], v[76:79]
	v_mfma_f32_16x16x32_bf16 v[68:71], v[206:209], v[194:197], v[68:71]
	v_mfma_f32_16x16x32_bf16 v[64:67], v[214:217], v[194:197], v[64:67]
	v_mfma_f32_16x16x32_bf16 v[116:119], v[210:213], v[174:177], v[116:119]
	v_mfma_f32_16x16x32_bf16 v[108:111], v[218:221], v[174:177], v[108:111]
	v_mfma_f32_16x16x32_bf16 v[100:103], v[210:213], v[182:185], v[100:103]
	v_mfma_f32_16x16x32_bf16 v[92:95], v[218:221], v[182:185], v[92:95]
	v_mfma_f32_16x16x32_bf16 v[84:87], v[210:213], v[190:193], v[84:87]
	v_mfma_f32_16x16x32_bf16 v[76:79], v[218:221], v[190:193], v[76:79]
	v_mfma_f32_16x16x32_bf16 v[68:71], v[210:213], v[202:205], v[68:71]
	v_mfma_f32_16x16x32_bf16 v[64:67], v[218:221], v[202:205], v[64:67]
	s_barrier
	s_setprio 0
	s_mov_b32 m0, s52
	s_add_u32 s100, s24, s4
	s_addc_u32 s101, s25, s5
	ds_read_b128 v[170:173], v139 offset:16384
	ds_read_b128 v[174:177], v139 offset:17408
	ds_read_b128 v[178:181], v139 offset:18432
	ds_read_b128 v[182:185], v139 offset:19456
	ds_read_b128 v[186:189], v139 offset:20480
	ds_read_b128 v[190:193], v139 offset:21504
	ds_read_b128 v[194:197], v139 offset:22528
	ds_read_b128 v[202:205], v139 offset:23552
	global_load_lds_dwordx4 v128, s[24:25]
	s_mov_b32 m0, s53
	s_nop 0
	global_load_lds_dwordx4 v130, s[24:25]
	s_setprio 1
	s_barrier
	s_waitcnt lgkmcnt(0)
	v_mfma_f32_16x16x32_bf16 v[60:63], v[146:149], v[170:173], v[60:63]
	v_mfma_f32_16x16x32_bf16 v[56:59], v[160:163], v[170:173], v[56:59]
	v_mfma_f32_16x16x32_bf16 v[48:51], v[146:149], v[178:181], v[48:51]
	v_mfma_f32_16x16x32_bf16 v[40:43], v[160:163], v[178:181], v[40:43]
	v_mfma_f32_16x16x32_bf16 v[32:35], v[146:149], v[186:189], v[32:35]
	v_mfma_f32_16x16x32_bf16 v[24:27], v[160:163], v[186:189], v[24:27]
	v_mfma_f32_16x16x32_bf16 v[16:19], v[146:149], v[194:197], v[16:19]
	v_mfma_f32_16x16x32_bf16 v[8:11], v[160:163], v[194:197], v[8:11]
	v_mfma_f32_16x16x32_bf16 v[60:63], v[150:153], v[174:177], v[60:63]
	v_mfma_f32_16x16x32_bf16 v[56:59], v[166:169], v[174:177], v[56:59]
	v_mfma_f32_16x16x32_bf16 v[48:51], v[150:153], v[182:185], v[48:51]
	v_mfma_f32_16x16x32_bf16 v[40:43], v[166:169], v[182:185], v[40:43]
	v_mfma_f32_16x16x32_bf16 v[32:35], v[150:153], v[190:193], v[32:35]
	v_mfma_f32_16x16x32_bf16 v[24:27], v[166:169], v[190:193], v[24:27]
	v_mfma_f32_16x16x32_bf16 v[16:19], v[150:153], v[202:205], v[16:19]
	v_mfma_f32_16x16x32_bf16 v[8:11], v[166:169], v[202:205], v[8:11]
	s_barrier
	s_setprio 0
	s_add_u32 s28, s22, 0x80000
	s_addc_u32 s29, s23, 0
	s_mov_b32 m0, s61
	s_nop 0
	global_load_lds_dwordx4 v144, s[28:29]
	s_mov_b32 m0, s62
	s_nop 0
	global_load_lds_dwordx4 v132, s[28:29]
	s_waitcnt vmcnt(6)
	s_setprio 1
	s_barrier
; #define PG8_STAGE(bufoff, gbase, voff) do { _Pragma("unroll") for (int _i = 0; _i < 2; ++_i) \
;         __builtin_amdgcn_global_load_lds((const unsigned*)((const char*)(gbase) + (voff)[_i]), (LAS unsigned*)(lds + (bufoff) + ldsw + _i * 8192), 16, 0, 0); } while (0)
; #define PG8_LDA(dst, b, h) do { _Pragma("unroll") for (int m = 0; m < 4; ++m) _Pragma("unroll") for (int k = 0; k < 2; ++k) dst[m][k] = *(const LAS bf16x8*)(lds + PG8_SA(b, h) + aoff + m * 2048 + k * 1024); } while (0)
; #define PG8_LDB(dst, b, h) do { _Pragma("unroll") for (int n = 0; n < 2; ++n) _Pragma("unroll") for (int k = 0; k < 2; ++k) dst[n][k] = *(const LAS bf16x8*)(lds + PG8_SB(b, h) + boff + n * 2048 + k * 1024); } while (0)
; #define PG8_WAIT_V(n) asm volatile("s_waitcnt vmcnt(" #n ")" ::: "memory")
; #define PG8_WAIT_L(n) asm volatile("s_waitcnt lgkmcnt(" #n ")" ::: "memory")
; #define PG8_BAR __builtin_amdgcn_s_barrier()
; #define PG8_SCHED __builtin_amdgcn_sched_barrier(0)
; template <class Epi>
; __device__ __forceinline__ void gemm_phase(LAS unsigned char* lds, const bf16_t* A, int lda, const bf16_t* Bt, int ldb, int M, int N, int K, int asel, const Epi& E, const int fixed_round = -1) {
;     ...
;             PG8_WAIT_V(6); PG8_BAR; PG8_MMA(1, 1, At, B1); PG8_BAR;
;             PG8_LDB(B0, 1, 0); PG8_SCHED; PG8_LDA(At, 1, 0); PG8_STAGE(PG8_SA(0, 1), a2 + hstepA, voffA);
;             PG8_WAIT_L(8); PG8_BAR; PG8_WAIT_L(0); PG8_MMA(0, 0, At, B0); PG8_BAR; PG8_SCHED;
	v_mfma_f32_16x16x32_bf16 v[52:55], v[206:209], v[170:173], v[52:55]
	v_mfma_f32_16x16x32_bf16 v[44:47], v[214:217], v[170:173], v[44:47]
	v_mfma_f32_16x16x32_bf16 v[36:39], v[206:209], v[178:181], v[36:39]
	v_mfma_f32_16x16x32_bf16 v[28:31], v[214:217], v[178:181], v[28:31]
	v_mfma_f32_16x16x32_bf16 v[20:23], v[206:209], v[186:189], v[20:23]
	v_mfma_f32_16x16x32_bf16 v[12:15], v[214:217], v[186:189], v[12:15]
	v_mfma_f32_16x16x32_bf16 v[4:7], v[206:209], v[194:197], v[4:7]
	v_mfma_f32_16x16x32_bf16 v[0:3], v[214:217], v[194:197], v[0:3]
	v_mfma_f32_16x16x32_bf16 v[52:55], v[210:213], v[174:177], v[52:55]
	v_mfma_f32_16x16x32_bf16 v[44:47], v[218:221], v[174:177], v[44:47]
	v_mfma_f32_16x16x32_bf16 v[36:39], v[210:213], v[182:185], v[36:39]
	v_mfma_f32_16x16x32_bf16 v[28:31], v[218:221], v[182:185], v[28:31]
	v_mfma_f32_16x16x32_bf16 v[20:23], v[210:213], v[190:193], v[20:23]
	v_mfma_f32_16x16x32_bf16 v[12:15], v[218:221], v[190:193], v[12:15]
	v_mfma_f32_16x16x32_bf16 v[4:7], v[210:213], v[202:205], v[4:7]
	v_mfma_f32_16x16x32_bf16 v[0:3], v[218:221], v[202:205], v[0:3]
	s_barrier
	s_setprio 0
	ds_read_b128 v[146:149], v141
	ds_read_b128 v[150:153], v141 offset:1024
	ds_read_b128 v[160:163], v141 offset:2048
	ds_read_b128 v[166:169], v141 offset:3072
	s_add_u32 s24, s24, 0x80000
	s_addc_u32 s25, s25, 0
	s_mov_b32 m0, s54
	ds_read_b128 v[170:173], v139 offset:32768
	ds_read_b128 v[174:177], v139 offset:33792
	ds_read_b128 v[178:181], v139 offset:34816
	ds_read_b128 v[182:185], v139 offset:35840
	ds_read_b128 v[186:189], v139 offset:36864
	ds_read_b128 v[190:193], v139 offset:37888
	ds_read_b128 v[194:197], v139 offset:38912
	ds_read_b128 v[202:205], v139 offset:39936
	global_load_lds_dwordx4 v128, s[24:25]
	s_mov_b32 m0, s55
	s_nop 0
	global_load_lds_dwordx4 v130, s[24:25]
	s_waitcnt lgkmcnt(8)
	s_setprio 1
	s_barrier
	s_waitcnt lgkmcnt(0)
	v_mfma_f32_16x16x32_bf16 v[124:127], v[146:149], v[170:173], v[124:127]
	v_mfma_f32_16x16x32_bf16 v[120:123], v[160:163], v[170:173], v[120:123]
	v_mfma_f32_16x16x32_bf16 v[112:115], v[146:149], v[178:181], v[112:115]
	v_mfma_f32_16x16x32_bf16 v[104:107], v[160:163], v[178:181], v[104:107]
	v_mfma_f32_16x16x32_bf16 v[96:99], v[146:149], v[186:189], v[96:99]
	v_mfma_f32_16x16x32_bf16 v[88:91], v[160:163], v[186:189], v[88:91]
	v_mfma_f32_16x16x32_bf16 v[80:83], v[146:149], v[194:197], v[80:83]
	v_mfma_f32_16x16x32_bf16 v[72:75], v[160:163], v[194:197], v[72:75]
	v_mfma_f32_16x16x32_bf16 v[124:127], v[150:153], v[174:177], v[124:127]
	v_mfma_f32_16x16x32_bf16 v[120:123], v[166:169], v[174:177], v[120:123]
	v_mfma_f32_16x16x32_bf16 v[112:115], v[150:153], v[182:185], v[112:115]
	v_mfma_f32_16x16x32_bf16 v[104:107], v[166:169], v[182:185], v[104:107]
	v_mfma_f32_16x16x32_bf16 v[96:99], v[150:153], v[190:193], v[96:99]
	v_mfma_f32_16x16x32_bf16 v[88:91], v[166:169], v[190:193], v[88:91]
	v_mfma_f32_16x16x32_bf16 v[80:83], v[150:153], v[202:205], v[80:83]
	v_mfma_f32_16x16x32_bf16 v[72:75], v[166:169], v[202:205], v[72:75]
	s_barrier
	s_setprio 0
	s_mov_b32 m0, s63
	ds_read_b128 v[206:209], v142
	ds_read_b128 v[210:213], v142 offset:1024
	ds_read_b128 v[214:217], v142 offset:2048
	ds_read_b128 v[218:221], v142 offset:3072
	global_load_lds_dwordx4 v144, s[98:99]
	s_mov_b32 m0, s64
	s_nop 0
	global_load_lds_dwordx4 v132, s[98:99]
	s_setprio 1
	s_barrier
; #define PG8_STAGE(bufoff, gbase, voff) do { _Pragma("unroll") for (int _i = 0; _i < 2; ++_i) \
;         __builtin_amdgcn_global_load_lds((const unsigned*)((const char*)(gbase) + (voff)[_i]), (LAS unsigned*)(lds + (bufoff) + ldsw + _i * 8192), 16, 0, 0); } while (0)
; #define PG8_LDA(dst, b, h) do { _Pragma("unroll") for (int m = 0; m < 4; ++m) _Pragma("unroll") for (int k = 0; k < 2; ++k) dst[m][k] = *(const LAS bf16x8*)(lds + PG8_SA(b, h) + aoff + m * 2048 + k * 1024); } while (0)
; #define PG8_LDB(dst, b, h) do { _Pragma("unroll") for (int n = 0; n < 2; ++n) _Pragma("unroll") for (int k = 0; k < 2; ++k) dst[n][k] = *(const LAS bf16x8*)(lds + PG8_SB(b, h) + boff + n * 2048 + k * 1024); } while (0)
; #define PG8_WAIT_V(n) asm volatile("s_waitcnt vmcnt(" #n ")" ::: "memory")
; #define PG8_WAIT_L(n) asm volatile("s_waitcnt lgkmcnt(" #n ")" ::: "memory")
; #define PG8_BAR __builtin_amdgcn_s_barrier()
; #define PG8_SCHED __builtin_amdgcn_sched_barrier(0)
; template <class Epi>
; __device__ __forceinline__ void gemm_phase(LAS unsigned char* lds, const bf16_t* A, int lda, const bf16_t* Bt, int ldb, int M, int N, int K, int asel, const Epi& E, const int fixed_round = -1) {
;     ...
;             PG8_WAIT_L(8); PG8_BAR; PG8_WAIT_L(0); PG8_MMA(0, 0, At, B0); PG8_BAR; PG8_SCHED;
;             PG8_LDB(B1, 1, 1); PG8_STAGE(PG8_SB(1, 0), b3, voffB);
;             PG8_BAR; PG8_WAIT_L(0); PG8_MMA(0, 1, At, B1); PG8_BAR;
;             PG8_LDA(At, 1, 1); PG8_STAGE(PG8_SA(1, 0), a3, voffA);
;             PG8_BAR; PG8_WAIT_L(0); PG8_MMA(1, 0, At, B0); PG8_BAR; PG8_SCHED;
;             PG8_STAGE(PG8_SB(1, 1), b3 + hstepB, voffB);
;             PG8_WAIT_V(6); PG8_BAR; PG8_MMA(1, 1, At, B1); PG8_BAR;
;     ...
;     PG8_WAIT_V(0);
;     if (wr == 0) PG8_BAR;
;     PG8_BAR;
	s_waitcnt lgkmcnt(0)
	v_mfma_f32_16x16x32_bf16 v[116:119], v[206:209], v[170:173], v[116:119]
	v_mfma_f32_16x16x32_bf16 v[108:111], v[214:217], v[170:173], v[108:111]
	v_mfma_f32_16x16x32_bf16 v[100:103], v[206:209], v[178:181], v[100:103]
	v_mfma_f32_16x16x32_bf16 v[92:95], v[214:217], v[178:181], v[92:95]
	v_mfma_f32_16x16x32_bf16 v[84:87], v[206:209], v[186:189], v[84:87]
	v_mfma_f32_16x16x32_bf16 v[76:79], v[214:217], v[186:189], v[76:79]
	v_mfma_f32_16x16x32_bf16 v[68:71], v[206:209], v[194:197], v[68:71]
	v_mfma_f32_16x16x32_bf16 v[64:67], v[214:217], v[194:197], v[64:67]
	v_mfma_f32_16x16x32_bf16 v[116:119], v[210:213], v[174:177], v[116:119]
	v_mfma_f32_16x16x32_bf16 v[108:111], v[218:221], v[174:177], v[108:111]
	v_mfma_f32_16x16x32_bf16 v[100:103], v[210:213], v[182:185], v[100:103]
	v_mfma_f32_16x16x32_bf16 v[92:95], v[218:221], v[182:185], v[92:95]
	v_mfma_f32_16x16x32_bf16 v[84:87], v[210:213], v[190:193], v[84:87]
	v_mfma_f32_16x16x32_bf16 v[76:79], v[218:221], v[190:193], v[76:79]
	v_mfma_f32_16x16x32_bf16 v[68:71], v[210:213], v[202:205], v[68:71]
	v_mfma_f32_16x16x32_bf16 v[64:67], v[218:221], v[202:205], v[64:67]
	s_barrier
	s_setprio 0
	s_mov_b32 m0, s56
	ds_read_b128 v[170:173], v139 offset:49152
	ds_read_b128 v[174:177], v139 offset:50176
	ds_read_b128 v[178:181], v139 offset:51200
	ds_read_b128 v[182:185], v139 offset:52224
	ds_read_b128 v[186:189], v139 offset:53248
	ds_read_b128 v[190:193], v139 offset:54272
	ds_read_b128 v[194:197], v139 offset:55296
	ds_read_b128 v[202:205], v139 offset:56320
	global_load_lds_dwordx4 v128, s[100:101]
	s_mov_b32 m0, s57
	s_nop 0
	global_load_lds_dwordx4 v130, s[100:101]
	s_setprio 1
	s_barrier
	s_waitcnt lgkmcnt(0)
	v_mfma_f32_16x16x32_bf16 v[60:63], v[146:149], v[170:173], v[60:63]
	v_mfma_f32_16x16x32_bf16 v[56:59], v[160:163], v[170:173], v[56:59]
	v_mfma_f32_16x16x32_bf16 v[48:51], v[146:149], v[178:181], v[48:51]
	v_mfma_f32_16x16x32_bf16 v[40:43], v[160:163], v[178:181], v[40:43]
	v_mfma_f32_16x16x32_bf16 v[32:35], v[146:149], v[186:189], v[32:35]
	v_mfma_f32_16x16x32_bf16 v[24:27], v[160:163], v[186:189], v[24:27]
	v_mfma_f32_16x16x32_bf16 v[16:19], v[146:149], v[194:197], v[16:19]
	v_mfma_f32_16x16x32_bf16 v[8:11], v[160:163], v[194:197], v[8:11]
	v_mfma_f32_16x16x32_bf16 v[60:63], v[150:153], v[174:177], v[60:63]
	v_mfma_f32_16x16x32_bf16 v[56:59], v[166:169], v[174:177], v[56:59]
	v_mfma_f32_16x16x32_bf16 v[48:51], v[150:153], v[182:185], v[48:51]
	v_mfma_f32_16x16x32_bf16 v[40:43], v[166:169], v[182:185], v[40:43]
	v_mfma_f32_16x16x32_bf16 v[32:35], v[150:153], v[190:193], v[32:35]
	v_mfma_f32_16x16x32_bf16 v[24:27], v[166:169], v[190:193], v[24:27]
	v_mfma_f32_16x16x32_bf16 v[16:19], v[150:153], v[202:205], v[16:19]
	v_mfma_f32_16x16x32_bf16 v[8:11], v[166:169], v[202:205], v[8:11]
	s_barrier
	s_setprio 0
	s_add_u32 s22, s22, 0x80080
	s_addc_u32 s23, s23, 0
	s_mov_b32 m0, s65
	s_nop 0
	global_load_lds_dwordx4 v144, s[22:23]
	s_mov_b32 m0, s66
	s_nop 0
	global_load_lds_dwordx4 v132, s[22:23]
	s_waitcnt vmcnt(6)
	s_setprio 1
	s_barrier
	v_mfma_f32_16x16x32_bf16 v[52:55], v[206:209], v[170:173], v[52:55]
	v_mfma_f32_16x16x32_bf16 v[44:47], v[214:217], v[170:173], v[44:47]
	v_mfma_f32_16x16x32_bf16 v[36:39], v[206:209], v[178:181], v[36:39]
	v_mfma_f32_16x16x32_bf16 v[28:31], v[214:217], v[178:181], v[28:31]
	v_mfma_f32_16x16x32_bf16 v[20:23], v[206:209], v[186:189], v[20:23]
	v_mfma_f32_16x16x32_bf16 v[12:15], v[214:217], v[186:189], v[12:15]
	v_mfma_f32_16x16x32_bf16 v[4:7], v[206:209], v[194:197], v[4:7]
	v_mfma_f32_16x16x32_bf16 v[0:3], v[214:217], v[194:197], v[0:3]
	v_mfma_f32_16x16x32_bf16 v[52:55], v[210:213], v[174:177], v[52:55]
	v_mfma_f32_16x16x32_bf16 v[44:47], v[218:221], v[174:177], v[44:47]
	v_mfma_f32_16x16x32_bf16 v[36:39], v[210:213], v[182:185], v[36:39]
	v_mfma_f32_16x16x32_bf16 v[28:31], v[218:221], v[182:185], v[28:31]
	v_mfma_f32_16x16x32_bf16 v[20:23], v[210:213], v[190:193], v[20:23]
	v_mfma_f32_16x16x32_bf16 v[12:15], v[218:221], v[190:193], v[12:15]
	v_mfma_f32_16x16x32_bf16 v[4:7], v[210:213], v[202:205], v[4:7]
	v_mfma_f32_16x16x32_bf16 v[0:3], v[218:221], v[202:205], v[0:3]
	s_setprio 0
	s_add_i32 s40, s40, 2
	s_add_u32 s6, s6, 0x100
	s_addc_u32 s7, s7, 0
	s_cmp_lt_u32 s40, 30
	s_cbranch_scc1 .Lrot_9
	s_barrier
	s_waitcnt vmcnt(0)
	s_cmpk_gt_u32 s51, 0xff
	s_cbranch_scc1 .LBB0_1123
	s_barrier

; #define PG8_STAGE(bufoff, gbase, voff) do { _Pragma("unroll") for (int _i = 0; _i < 2; ++_i) \
;         __builtin_amdgcn_global_load_lds((const unsigned*)((const char*)(gbase) + (voff)[_i]), (LAS unsigned*)(lds + (bufoff) + ldsw + _i * 8192), 16, 0, 0); } while (0)
; #define PG8_LDA(dst, b, h) do { _Pragma("unroll") for (int m = 0; m < 4; ++m) _Pragma("unroll") for (int k = 0; k < 2; ++k) dst[m][k] = *(const LAS bf16x8*)(lds + PG8_SA(b, h) + aoff + m * 2048 + k * 1024); } while (0)
; #define PG8_LDB(dst, b, h) do { _Pragma("unroll") for (int n = 0; n < 2; ++n) _Pragma("unroll") for (int k = 0; k < 2; ++k) dst[n][k] = *(const LAS bf16x8*)(lds + PG8_SB(b, h) + boff + n * 2048 + k * 1024); } while (0)
; #define PG8_WAIT_V(n) asm volatile("s_waitcnt vmcnt(" #n ")" ::: "memory")
; #define PG8_WAIT_L(n) asm volatile("s_waitcnt lgkmcnt(" #n ")" ::: "memory")
; #define PG8_BAR __builtin_amdgcn_s_barrier()
; #define PG8_SCHED __builtin_amdgcn_sched_barrier(0)
; template <class Epi>
; __device__ __forceinline__ void gemm_phase(LAS unsigned char* lds, const bf16_t* A, int lda, const bf16_t* Bt, int ldb, int M, int N, int K, int asel, const Epi& E, const int fixed_round = -1) {
;     ...
;         const char* nA = has_next ? PG8_ABASE(nxt) : cA; const char* nB = has_next ? (const char*)Bt + (size_t)nxt.pn * tstepB : cB;
;         for (int t = 0; t < nt; t += 2) {
;             const bool last = (t == nt - 2);
;             const char* a1 = cA + (size_t)(t + 1) * kstep;
;             const char* a2 = last ? nA : cA + (size_t)(t + 2) * kstep; const char* b2 = last ? nB : cB + (size_t)(t + 2) * kstep;
;             const char* a3 = a2 + kstep; const char* b3 = b2 + kstep;
;             PG8_LDB(B0, 0, 0); PG8_SCHED; PG8_LDA(At, 0, 0); PG8_STAGE(PG8_SA(1, 1), a1 + hstepA, voffA);
;             PG8_WAIT_L(8); PG8_BAR; PG8_WAIT_L(0); PG8_MMA(0, 0, At, B0); PG8_BAR; PG8_SCHED;
;             PG8_LDB(B1, 0, 1); PG8_STAGE(PG8_SB(0, 0), b2, voffB);
;             PG8_BAR; PG8_WAIT_L(0); PG8_MMA(0, 1, At, B1); PG8_BAR;
;             PG8_LDA(At, 0, 1); PG8_STAGE(PG8_SA(0, 0), a2, voffA);
;             PG8_BAR; PG8_WAIT_L(0); PG8_MMA(1, 0, At, B0); PG8_BAR; PG8_SCHED;
;             PG8_STAGE(PG8_SB(0, 1), b2 + hstepB, voffB);
;             PG8_WAIT_V(6); PG8_BAR; PG8_MMA(1, 1, At, B1); PG8_BAR;
.LBB0_1223:
	ds_read_b128 v[152:155], v149
	ds_read_b128 v[156:159], v149 offset:1024
	ds_read_b128 v[160:163], v149 offset:2048
	ds_read_b128 v[164:167], v149 offset:3072
	s_add_i32 m0, s45, 0xc000
	ds_read_b128 v[168:171], v150
	ds_read_b128 v[172:175], v150 offset:1024
	ds_read_b128 v[176:179], v150 offset:2048
	ds_read_b128 v[180:183], v150 offset:3072
	ds_read_b128 v[184:187], v150 offset:4096
	ds_read_b128 v[188:191], v150 offset:5120
	ds_read_b128 v[192:195], v150 offset:6144
	ds_read_b128 v[196:199], v150 offset:7168
	global_load_lds_dwordx4 v136, s[46:47]
	s_add_i32 m0, s45, 0xe000
	s_nop 0
	global_load_lds_dwordx4 v138, s[46:47]
	s_waitcnt lgkmcnt(8)
	s_setprio 1
	s_barrier
	s_waitcnt lgkmcnt(0)
	v_mfma_f32_16x16x32_bf16 v[124:127], v[152:155], v[168:171], v[124:127]
	v_mfma_f32_16x16x32_bf16 v[120:123], v[160:163], v[168:171], v[120:123]
	v_mfma_f32_16x16x32_bf16 v[108:111], v[152:155], v[176:179], v[108:111]
	v_mfma_f32_16x16x32_bf16 v[104:107], v[160:163], v[176:179], v[104:107]
	v_mfma_f32_16x16x32_bf16 v[92:95], v[152:155], v[184:187], v[92:95]
	v_mfma_f32_16x16x32_bf16 v[88:91], v[160:163], v[184:187], v[88:91]
	v_mfma_f32_16x16x32_bf16 v[76:79], v[152:155], v[192:195], v[76:79]
	v_mfma_f32_16x16x32_bf16 v[72:75], v[160:163], v[192:195], v[72:75]
	v_mfma_f32_16x16x32_bf16 v[124:127], v[156:159], v[172:175], v[124:127]
	v_mfma_f32_16x16x32_bf16 v[120:123], v[164:167], v[172:175], v[120:123]
	v_mfma_f32_16x16x32_bf16 v[108:111], v[156:159], v[180:183], v[108:111]
	v_mfma_f32_16x16x32_bf16 v[104:107], v[164:167], v[180:183], v[104:107]
	v_mfma_f32_16x16x32_bf16 v[92:95], v[156:159], v[188:191], v[92:95]
	v_mfma_f32_16x16x32_bf16 v[88:91], v[164:167], v[188:191], v[88:91]
	v_mfma_f32_16x16x32_bf16 v[76:79], v[156:159], v[196:199], v[76:79]
	v_mfma_f32_16x16x32_bf16 v[72:75], v[164:167], v[196:199], v[72:75]
	s_barrier
	s_setprio 0
	s_add_u32 s48, s46, 0xfff80080
	s_addc_u32 s49, s47, -1
	s_cmp_eq_u32 s70, 28
	s_cselect_b32 s51, s29, s49
	s_cselect_b32 s50, s66, s48
	s_cselect_b32 s49, s25, s69
	s_cselect_b32 s48, s67, s68
	s_add_i32 s71, s81, s54
	s_add_u32 s98, s48, s2
	s_addc_u32 s99, s49, s3
	s_mov_b32 m0, s71
	ds_read_b128 v[202:205], v151
	ds_read_b128 v[206:209], v151 offset:1024
	ds_read_b128 v[210:213], v151 offset:2048
	ds_read_b128 v[214:217], v151 offset:3072
	global_load_lds_dwordx4 v130, s[48:49]
	s_add_i32 m0, s71, 0x2000
	s_nop 0
	global_load_lds_dwordx4 v134, s[48:49]
	s_setprio 1
	s_barrier
	s_waitcnt lgkmcnt(0)
	v_mfma_f32_16x16x32_bf16 v[116:119], v[202:205], v[168:171], v[116:119]
	v_mfma_f32_16x16x32_bf16 v[112:115], v[210:213], v[168:171], v[112:115]
	v_mfma_f32_16x16x32_bf16 v[100:103], v[202:205], v[176:179], v[100:103]
	v_mfma_f32_16x16x32_bf16 v[96:99], v[210:213], v[176:179], v[96:99]
	v_mfma_f32_16x16x32_bf16 v[84:87], v[202:205], v[184:187], v[84:87]
	v_mfma_f32_16x16x32_bf16 v[80:83], v[210:213], v[184:187], v[80:83]
	v_mfma_f32_16x16x32_bf16 v[68:71], v[202:205], v[192:195], v[68:71]
	v_mfma_f32_16x16x32_bf16 v[64:67], v[210:213], v[192:195], v[64:67]
	v_mfma_f32_16x16x32_bf16 v[116:119], v[206:209], v[172:175], v[116:119]
	v_mfma_f32_16x16x32_bf16 v[112:115], v[214:217], v[172:175], v[112:115]
	v_mfma_f32_16x16x32_bf16 v[100:103], v[206:209], v[180:183], v[100:103]
	v_mfma_f32_16x16x32_bf16 v[96:99], v[214:217], v[180:183], v[96:99]
	v_mfma_f32_16x16x32_bf16 v[84:87], v[206:209], v[188:191], v[84:87]
	v_mfma_f32_16x16x32_bf16 v[80:83], v[214:217], v[188:191], v[80:83]
	v_mfma_f32_16x16x32_bf16 v[68:71], v[206:209], v[196:199], v[68:71]
	v_mfma_f32_16x16x32_bf16 v[64:67], v[214:217], v[196:199], v[64:67]
	s_barrier
	s_setprio 0
	s_mov_b32 m0, s45
	s_add_u32 s100, s50, s2
	s_addc_u32 s101, s51, s3
	ds_read_b128 v[168:171], v150 offset:16384
	ds_read_b128 v[172:175], v150 offset:17408
	ds_read_b128 v[176:179], v150 offset:18432
	ds_read_b128 v[180:183], v150 offset:19456
	ds_read_b128 v[184:187], v150 offset:20480
	ds_read_b128 v[188:191], v150 offset:21504
	ds_read_b128 v[192:195], v150 offset:22528
	ds_read_b128 v[196:199], v150 offset:23552
	global_load_lds_dwordx4 v128, s[50:51]
	s_mov_b32 m0, s55
	s_nop 0
	global_load_lds_dwordx4 v132, s[50:51]
	s_setprio 1
	s_barrier
	s_waitcnt lgkmcnt(0)
	v_mfma_f32_16x16x32_bf16 v[60:63], v[152:155], v[168:171], v[60:63]
	v_mfma_f32_16x16x32_bf16 v[56:59], v[160:163], v[168:171], v[56:59]
	v_mfma_f32_16x16x32_bf16 v[44:47], v[152:155], v[176:179], v[44:47]
	v_mfma_f32_16x16x32_bf16 v[40:43], v[160:163], v[176:179], v[40:43]
	v_mfma_f32_16x16x32_bf16 v[28:31], v[152:155], v[184:187], v[28:31]
	v_mfma_f32_16x16x32_bf16 v[24:27], v[160:163], v[184:187], v[24:27]
	v_mfma_f32_16x16x32_bf16 v[12:15], v[152:155], v[192:195], v[12:15]
	v_mfma_f32_16x16x32_bf16 v[8:11], v[160:163], v[192:195], v[8:11]
	v_mfma_f32_16x16x32_bf16 v[60:63], v[156:159], v[172:175], v[60:63]
	v_mfma_f32_16x16x32_bf16 v[56:59], v[164:167], v[172:175], v[56:59]
	v_mfma_f32_16x16x32_bf16 v[44:47], v[156:159], v[180:183], v[44:47]
	v_mfma_f32_16x16x32_bf16 v[40:43], v[164:167], v[180:183], v[40:43]
	v_mfma_f32_16x16x32_bf16 v[28:31], v[156:159], v[188:191], v[28:31]
	v_mfma_f32_16x16x32_bf16 v[24:27], v[164:167], v[188:191], v[24:27]
	v_mfma_f32_16x16x32_bf16 v[12:15], v[156:159], v[196:199], v[12:15]
	v_mfma_f32_16x16x32_bf16 v[8:11], v[164:167], v[196:199], v[8:11]
	s_barrier
	s_setprio 0
	s_add_u32 s72, s48, 0x80000
	s_addc_u32 s73, s49, 0
	s_add_i32 s71, s82, s54
	s_mov_b32 m0, s71
	s_nop 0
	global_load_lds_dwordx4 v130, s[72:73]
	s_add_i32 m0, s71, 0x2000
	s_nop 0
	global_load_lds_dwordx4 v134, s[72:73]
	s_waitcnt vmcnt(6)
	s_setprio 1
	s_barrier
; #define PG8_STAGE(bufoff, gbase, voff) do { _Pragma("unroll") for (int _i = 0; _i < 2; ++_i) \
;         __builtin_amdgcn_global_load_lds((const unsigned*)((const char*)(gbase) + (voff)[_i]), (LAS unsigned*)(lds + (bufoff) + ldsw + _i * 8192), 16, 0, 0); } while (0)
; #define PG8_LDA(dst, b, h) do { _Pragma("unroll") for (int m = 0; m < 4; ++m) _Pragma("unroll") for (int k = 0; k < 2; ++k) dst[m][k] = *(const LAS bf16x8*)(lds + PG8_SA(b, h) + aoff + m * 2048 + k * 1024); } while (0)
; #define PG8_LDB(dst, b, h) do { _Pragma("unroll") for (int n = 0; n < 2; ++n) _Pragma("unroll") for (int k = 0; k < 2; ++k) dst[n][k] = *(const LAS bf16x8*)(lds + PG8_SB(b, h) + boff + n * 2048 + k * 1024); } while (0)
; #define PG8_WAIT_V(n) asm volatile("s_waitcnt vmcnt(" #n ")" ::: "memory")
; #define PG8_WAIT_L(n) asm volatile("s_waitcnt lgkmcnt(" #n ")" ::: "memory")
; #define PG8_BAR __builtin_amdgcn_s_barrier()
; #define PG8_SCHED __builtin_amdgcn_sched_barrier(0)
; template <class Epi>
; __device__ __forceinline__ void gemm_phase(LAS unsigned char* lds, const bf16_t* A, int lda, const bf16_t* Bt, int ldb, int M, int N, int K, int asel, const Epi& E, const int fixed_round = -1) {
;     ...
;             PG8_WAIT_V(6); PG8_BAR; PG8_MMA(1, 1, At, B1); PG8_BAR;
;             PG8_LDB(B0, 1, 0); PG8_SCHED; PG8_LDA(At, 1, 0); PG8_STAGE(PG8_SA(0, 1), a2 + hstepA, voffA);
;             PG8_WAIT_L(8); PG8_BAR; PG8_WAIT_L(0); PG8_MMA(0, 0, At, B0); PG8_BAR; PG8_SCHED;
;             PG8_LDB(B1, 1, 1); PG8_STAGE(PG8_SB(1, 0), b3, voffB);
;             PG8_BAR; PG8_WAIT_L(0); PG8_MMA(0, 1, At, B1); PG8_BAR;
;             PG8_LDA(At, 1, 1); PG8_STAGE(PG8_SA(1, 0), a3, voffA);
;             PG8_BAR; PG8_WAIT_L(0); PG8_MMA(1, 0, At, B0); PG8_BAR; PG8_SCHED;
	v_mfma_f32_16x16x32_bf16 v[52:55], v[202:205], v[168:171], v[52:55]
	v_mfma_f32_16x16x32_bf16 v[48:51], v[210:213], v[168:171], v[48:51]
	v_mfma_f32_16x16x32_bf16 v[36:39], v[202:205], v[176:179], v[36:39]
	v_mfma_f32_16x16x32_bf16 v[32:35], v[210:213], v[176:179], v[32:35]
	v_mfma_f32_16x16x32_bf16 v[20:23], v[202:205], v[184:187], v[20:23]
	v_mfma_f32_16x16x32_bf16 v[16:19], v[210:213], v[184:187], v[16:19]
	v_mfma_f32_16x16x32_bf16 v[4:7], v[202:205], v[192:195], v[4:7]
	v_mfma_f32_16x16x32_bf16 v[0:3], v[210:213], v[192:195], v[0:3]
	v_mfma_f32_16x16x32_bf16 v[52:55], v[206:209], v[172:175], v[52:55]
	v_mfma_f32_16x16x32_bf16 v[48:51], v[214:217], v[172:175], v[48:51]
	v_mfma_f32_16x16x32_bf16 v[36:39], v[206:209], v[180:183], v[36:39]
	v_mfma_f32_16x16x32_bf16 v[32:35], v[214:217], v[180:183], v[32:35]
	v_mfma_f32_16x16x32_bf16 v[20:23], v[206:209], v[188:191], v[20:23]
	v_mfma_f32_16x16x32_bf16 v[16:19], v[214:217], v[188:191], v[16:19]
	v_mfma_f32_16x16x32_bf16 v[4:7], v[206:209], v[196:199], v[4:7]
	v_mfma_f32_16x16x32_bf16 v[0:3], v[214:217], v[196:199], v[0:3]
	s_barrier
	s_setprio 0
	v_add_u32_e32 v164, s83, v147
	ds_read_b128 v[152:155], v164
	ds_read_b128 v[156:159], v164 offset:1024
	ds_read_b128 v[160:163], v164 offset:2048
	ds_read_b128 v[164:167], v164 offset:3072
	s_add_u32 s50, s50, 0x80000
	s_addc_u32 s51, s51, 0
	s_mov_b32 m0, s56
	ds_read_b128 v[168:171], v150 offset:32768
	ds_read_b128 v[172:175], v150 offset:33792
	ds_read_b128 v[176:179], v150 offset:34816
	ds_read_b128 v[180:183], v150 offset:35840
	ds_read_b128 v[184:187], v150 offset:36864
	ds_read_b128 v[188:191], v150 offset:37888
	ds_read_b128 v[192:195], v150 offset:38912
	ds_read_b128 v[196:199], v150 offset:39936
	global_load_lds_dwordx4 v128, s[50:51]
	s_mov_b32 m0, s57
	s_nop 0
	global_load_lds_dwordx4 v132, s[50:51]
	s_waitcnt lgkmcnt(8)
	s_setprio 1
	s_barrier
	s_waitcnt lgkmcnt(0)
	v_mfma_f32_16x16x32_bf16 v[124:127], v[152:155], v[168:171], v[124:127]
	v_mfma_f32_16x16x32_bf16 v[120:123], v[160:163], v[168:171], v[120:123]
	v_mfma_f32_16x16x32_bf16 v[108:111], v[152:155], v[176:179], v[108:111]
	v_mfma_f32_16x16x32_bf16 v[104:107], v[160:163], v[176:179], v[104:107]
	v_mfma_f32_16x16x32_bf16 v[92:95], v[152:155], v[184:187], v[92:95]
	v_mfma_f32_16x16x32_bf16 v[88:91], v[160:163], v[184:187], v[88:91]
	v_mfma_f32_16x16x32_bf16 v[76:79], v[152:155], v[192:195], v[76:79]
	v_mfma_f32_16x16x32_bf16 v[72:75], v[160:163], v[192:195], v[72:75]
	v_mfma_f32_16x16x32_bf16 v[124:127], v[156:159], v[172:175], v[124:127]
	v_mfma_f32_16x16x32_bf16 v[120:123], v[164:167], v[172:175], v[120:123]
	v_mfma_f32_16x16x32_bf16 v[108:111], v[156:159], v[180:183], v[108:111]
	v_mfma_f32_16x16x32_bf16 v[104:107], v[164:167], v[180:183], v[104:107]
	v_mfma_f32_16x16x32_bf16 v[92:95], v[156:159], v[188:191], v[92:95]
	v_mfma_f32_16x16x32_bf16 v[88:91], v[164:167], v[188:191], v[88:91]
	v_mfma_f32_16x16x32_bf16 v[76:79], v[156:159], v[196:199], v[76:79]
	v_mfma_f32_16x16x32_bf16 v[72:75], v[164:167], v[196:199], v[72:75]
	s_barrier
	s_setprio 0
	s_add_i32 s50, s83, s54
	v_add_u32_e32 v214, s84, v147
	s_mov_b32 m0, s50
	ds_read_b128 v[202:205], v214
	ds_read_b128 v[206:209], v214 offset:1024
	ds_read_b128 v[210:213], v214 offset:2048
	ds_read_b128 v[214:217], v214 offset:3072
	global_load_lds_dwordx4 v130, s[98:99]
	s_add_i32 m0, s50, 0x2000
	s_nop 0
	global_load_lds_dwordx4 v134, s[98:99]
	s_setprio 1
	s_barrier
	s_waitcnt lgkmcnt(0)
	v_mfma_f32_16x16x32_bf16 v[116:119], v[202:205], v[168:171], v[116:119]
	v_mfma_f32_16x16x32_bf16 v[112:115], v[210:213], v[168:171], v[112:115]
	v_mfma_f32_16x16x32_bf16 v[100:103], v[202:205], v[176:179], v[100:103]
	v_mfma_f32_16x16x32_bf16 v[96:99], v[210:213], v[176:179], v[96:99]
	v_mfma_f32_16x16x32_bf16 v[84:87], v[202:205], v[184:187], v[84:87]
	v_mfma_f32_16x16x32_bf16 v[80:83], v[210:213], v[184:187], v[80:83]
	v_mfma_f32_16x16x32_bf16 v[68:71], v[202:205], v[192:195], v[68:71]
	v_mfma_f32_16x16x32_bf16 v[64:67], v[210:213], v[192:195], v[64:67]
	v_mfma_f32_16x16x32_bf16 v[116:119], v[206:209], v[172:175], v[116:119]
	v_mfma_f32_16x16x32_bf16 v[112:115], v[214:217], v[172:175], v[112:115]
	v_mfma_f32_16x16x32_bf16 v[100:103], v[206:209], v[180:183], v[100:103]
	v_mfma_f32_16x16x32_bf16 v[96:99], v[214:217], v[180:183], v[96:99]
	v_mfma_f32_16x16x32_bf16 v[84:87], v[206:209], v[188:191], v[84:87]
	v_mfma_f32_16x16x32_bf16 v[80:83], v[214:217], v[188:191], v[80:83]
	v_mfma_f32_16x16x32_bf16 v[68:71], v[206:209], v[196:199], v[68:71]
	v_mfma_f32_16x16x32_bf16 v[64:67], v[214:217], v[196:199], v[64:67]
	s_barrier
	s_setprio 0
	s_mov_b32 m0, s59
	ds_read_b128 v[168:171], v150 offset:49152
	ds_read_b128 v[172:175], v150 offset:50176
	ds_read_b128 v[176:179], v150 offset:51200
	ds_read_b128 v[180:183], v150 offset:52224
	ds_read_b128 v[184:187], v150 offset:53248
	ds_read_b128 v[188:191], v150 offset:54272
	ds_read_b128 v[192:195], v150 offset:55296
	ds_read_b128 v[196:199], v150 offset:56320
	global_load_lds_dwordx4 v128, s[100:101]
	s_mov_b32 m0, s60
	s_nop 0
	global_load_lds_dwordx4 v132, s[100:101]
	s_setprio 1
	s_barrier
; __device__ __forceinline__ unsigned cvt_pk_bf16(float lo, float hi) { const bf16x2_t r = __builtin_convertvector((f32x2){lo, hi}, bf16x2_t); return __builtin_bit_cast(unsigned, r); }
; #define PG8_STAGE(bufoff, gbase, voff) do { _Pragma("unroll") for (int _i = 0; _i < 2; ++_i) \
;         __builtin_amdgcn_global_load_lds((const unsigned*)((const char*)(gbase) + (voff)[_i]), (LAS unsigned*)(lds + (bufoff) + ldsw + _i * 8192), 16, 0, 0); } while (0)
; #define PG8_LDA(dst, b, h) do { _Pragma("unroll") for (int m = 0; m < 4; ++m) _Pragma("unroll") for (int k = 0; k < 2; ++k) dst[m][k] = *(const LAS bf16x8*)(lds + PG8_SA(b, h) + aoff + m * 2048 + k * 1024); } while (0)
; #define PG8_WAIT_V(n) asm volatile("s_waitcnt vmcnt(" #n ")" ::: "memory")
; #define PG8_WAIT_L(n) asm volatile("s_waitcnt lgkmcnt(" #n ")" ::: "memory")
; #define PG8_BAR __builtin_amdgcn_s_barrier()
; #define PG8_SCHED __builtin_amdgcn_sched_barrier(0)
; template <class Epi>
; __device__ __forceinline__ void gemm_phase(LAS unsigned char* lds, const bf16_t* A, int lda, const bf16_t* Bt, int ldb, int M, int N, int K, int asel, const Epi& E, const int fixed_round = -1) {
;     ...
;             PG8_LDA(At, 1, 1); PG8_STAGE(PG8_SA(1, 0), a3, voffA);
;             PG8_BAR; PG8_WAIT_L(0); PG8_MMA(1, 0, At, B0); PG8_BAR; PG8_SCHED;
;             PG8_STAGE(PG8_SB(1, 1), b3 + hstepB, voffB);
;             PG8_WAIT_V(6); PG8_BAR; PG8_MMA(1, 1, At, B1); PG8_BAR;
;     __device__ __forceinline__ void operator()(const AccT& acc, const Unit& u, int wr, int wc, int fr, int fq) const {
;         const int row0 = u.pm * BM + wr * 64 + fr, col0 = u.pn * BM + wc * 32 + 8 * fq;
; #pragma unroll
;         for (int ai = 0; ai < 2; ++ai)
; #pragma unroll
;             for (int m = 0; m < 4; ++m) { bf16_t* rowp = O + (size_t)(row0 + ai * HALF + m * 16) * DFF + col0;
; #pragma unroll
;                 for (int bj = 0; bj < 2; ++bj) { f32x4 v0 = acc[ai][bj][m][0], v1 = acc[ai][bj][m][1];
; #pragma unroll
;                     for (int j = 0; j < 4; ++j) { float a = fmaxf(v0[j], 0.f), b = fmaxf(v1[j], 0.f); v0[j] = a * a; v1[j] = b * b; }
;                     u32x4 w; w.x = cvt_pk_bf16(v0[0], v0[1]); w.y = cvt_pk_bf16(v0[2], v0[3]); w.z = cvt_pk_bf16(v1[0], v1[1]); w.w = cvt_pk_bf16(v1[2], v1[3]);
;                     *(u32x4*)(rowp + bj * HALF) = w; } }
	s_waitcnt lgkmcnt(0)
	v_mfma_f32_16x16x32_bf16 v[60:63], v[152:155], v[168:171], v[60:63]
	v_mfma_f32_16x16x32_bf16 v[56:59], v[160:163], v[168:171], v[56:59]
	v_mfma_f32_16x16x32_bf16 v[44:47], v[152:155], v[176:179], v[44:47]
	v_mfma_f32_16x16x32_bf16 v[40:43], v[160:163], v[176:179], v[40:43]
	v_mfma_f32_16x16x32_bf16 v[28:31], v[152:155], v[184:187], v[28:31]
	v_mfma_f32_16x16x32_bf16 v[24:27], v[160:163], v[184:187], v[24:27]
	v_mfma_f32_16x16x32_bf16 v[12:15], v[152:155], v[192:195], v[12:15]
	v_mfma_f32_16x16x32_bf16 v[8:11], v[160:163], v[192:195], v[8:11]
	v_mfma_f32_16x16x32_bf16 v[60:63], v[156:159], v[172:175], v[60:63]
	v_mfma_f32_16x16x32_bf16 v[56:59], v[164:167], v[172:175], v[56:59]
	v_mfma_f32_16x16x32_bf16 v[44:47], v[156:159], v[180:183], v[44:47]
	v_mfma_f32_16x16x32_bf16 v[40:43], v[164:167], v[180:183], v[40:43]
	v_mfma_f32_16x16x32_bf16 v[28:31], v[156:159], v[188:191], v[28:31]
	v_mfma_f32_16x16x32_bf16 v[24:27], v[164:167], v[188:191], v[24:27]
	v_mfma_f32_16x16x32_bf16 v[12:15], v[156:159], v[196:199], v[12:15]
	v_mfma_f32_16x16x32_bf16 v[8:11], v[164:167], v[196:199], v[8:11]
	s_barrier
	s_setprio 0
	s_add_u32 s48, s48, 0x80080
	s_addc_u32 s49, s49, 0
	s_add_i32 s50, s84, s54
	s_mov_b32 m0, s50
	s_nop 0
	global_load_lds_dwordx4 v130, s[48:49]
	s_add_i32 m0, s50, 0x2000
	s_nop 0
	global_load_lds_dwordx4 v134, s[48:49]
	s_waitcnt vmcnt(6)
	s_setprio 1
	s_barrier
	v_mfma_f32_16x16x32_bf16 v[52:55], v[202:205], v[168:171], v[52:55]
	v_mfma_f32_16x16x32_bf16 v[48:51], v[210:213], v[168:171], v[48:51]
	v_mfma_f32_16x16x32_bf16 v[36:39], v[202:205], v[176:179], v[36:39]
	v_mfma_f32_16x16x32_bf16 v[32:35], v[210:213], v[176:179], v[32:35]
	v_mfma_f32_16x16x32_bf16 v[20:23], v[202:205], v[184:187], v[20:23]
	v_mfma_f32_16x16x32_bf16 v[16:19], v[210:213], v[184:187], v[16:19]
	v_mfma_f32_16x16x32_bf16 v[4:7], v[202:205], v[192:195], v[4:7]
	v_mfma_f32_16x16x32_bf16 v[0:3], v[210:213], v[192:195], v[0:3]
	v_mfma_f32_16x16x32_bf16 v[52:55], v[206:209], v[172:175], v[52:55]
	v_mfma_f32_16x16x32_bf16 v[48:51], v[214:217], v[172:175], v[48:51]
	v_mfma_f32_16x16x32_bf16 v[36:39], v[206:209], v[180:183], v[36:39]
	v_mfma_f32_16x16x32_bf16 v[32:35], v[214:217], v[180:183], v[32:35]
	v_mfma_f32_16x16x32_bf16 v[20:23], v[206:209], v[188:191], v[20:23]
	v_mfma_f32_16x16x32_bf16 v[16:19], v[214:217], v[188:191], v[16:19]
	v_mfma_f32_16x16x32_bf16 v[4:7], v[206:209], v[196:199], v[4:7]
	v_mfma_f32_16x16x32_bf16 v[0:3], v[214:217], v[196:199], v[0:3]
	s_setprio 0
	s_add_i32 s70, s70, 2
	s_add_u32 s46, s46, 0x100
	s_addc_u32 s47, s47, 0
	s_add_u32 s68, s68, 0x100
	s_addc_u32 s69, s69, 0
	s_cmp_gt_u32 s70, 29
	s_cbranch_scc0 .Lrot_10
	s_barrier
	v_lshl_add_u32 v152, s44, 8, v146
	v_lshl_or_b32 v144, s65, 8, v148
	v_ashrrev_i32_e32 v153, 31, v152
	v_readlane_b32 s46, v254, 60
	v_ashrrev_i32_e32 v145, 31, v144
	v_lshlrev_b64 v[154:155], 14, v[152:153]
	v_readlane_b32 s47, v254, 61
	v_lshl_add_u64 v[154:155], s[46:47], 0, v[154:155]
	v_lshlrev_b64 v[156:157], 1, v[144:145]
	v_max_f32_e32 v120, 0, v120
	v_max_f32_e32 v121, 0, v121
	v_lshl_add_u64 v[144:145], v[154:155], 0, v[156:157]
	v_pk_mul_f32 v[154:155], v[120:121], v[120:121]
	v_max_f32_e32 v121, v122, v122
	v_max_f32_e32 v120, v126, v126
	v_max_f32_e32 v122, 0, v121
	v_max_f32_e32 v121, v127, v127
	v_max_f32_e32 v124, 0, v124
	v_max_f32_e32 v125, 0, v125
	v_max_f32_e32 v120, 0, v120
	v_max_f32_e32 v121, 0, v121
	v_max_f32_e32 v123, 0, v123
	v_pk_mul_f32 v[124:125], v[124:125], v[124:125]
	v_pk_mul_f32 v[126:127], v[120:121], v[120:121]
	v_pk_mul_f32 v[158:159], v[122:123], v[122:123]
	v_cvt_pk_bf16_f32 v120, v124, v125
	v_cvt_pk_bf16_f32 v121, v126, v127
	v_cvt_pk_bf16_f32 v122, v154, v155
	v_cvt_pk_bf16_f32 v123, v158, v159
	v_max_f32_e32 v112, 0, v112
	v_max_f32_e32 v113, 0, v113
	global_store_dwordx4 v[144:145], v[120:123], off
	s_nop 1
	v_pk_mul_f32 v[120:121], v[112:113], v[112:113]
	v_max_f32_e32 v113, v114, v114
	v_max_f32_e32 v112, v118, v118
	v_max_f32_e32 v114, 0, v113
	v_max_f32_e32 v113, v119, v119
	v_max_f32_e32 v116, 0, v116
	v_max_f32_e32 v117, 0, v117
	v_max_f32_e32 v112, 0, v112
	v_max_f32_e32 v113, 0, v113
	v_max_f32_e32 v115, 0, v115
	v_pk_mul_f32 v[116:117], v[116:117], v[116:117]
	v_pk_mul_f32 v[118:119], v[112:113], v[112:113]
	v_pk_mul_f32 v[122:123], v[114:115], v[114:115]
	v_cvt_pk_bf16_f32 v112, v116, v117
	v_cvt_pk_bf16_f32 v113, v118, v119
	v_cvt_pk_bf16_f32 v114, v120, v121
	v_cvt_pk_bf16_f32 v115, v122, v123
	v_max_f32_e32 v104, 0, v104
	v_max_f32_e32 v105, 0, v105
	global_store_dwordx4 v[144:145], v[112:115], off offset:256
	s_nop 1
	v_or_b32_e32 v112, 16, v152
	v_pk_mul_f32 v[114:115], v[104:105], v[104:105]
	v_max_f32_e32 v105, v106, v106
	v_ashrrev_i32_e32 v113, 31, v112
	v_max_f32_e32 v104, v110, v110
	v_max_f32_e32 v106, 0, v105
	v_max_f32_e32 v105, v111, v111
	v_lshlrev_b64 v[112:113], 14, v[112:113]
	v_max_f32_e32 v108, 0, v108
	v_max_f32_e32 v109, 0, v109
	v_max_f32_e32 v104, 0, v104
	v_max_f32_e32 v105, 0, v105
	v_max_f32_e32 v107, 0, v107
	v_lshl_add_u64 v[112:113], s[46:47], 0, v[112:113]
	v_pk_mul_f32 v[108:109], v[108:109], v[108:109]
	v_pk_mul_f32 v[110:111], v[104:105], v[104:105]
	v_pk_mul_f32 v[116:117], v[106:107], v[106:107]
	v_lshl_add_u64 v[112:113], v[112:113], 0, v[156:157]
	v_cvt_pk_bf16_f32 v104, v108, v109
	v_cvt_pk_bf16_f32 v105, v110, v111
	v_cvt_pk_bf16_f32 v106, v114, v115
	v_cvt_pk_bf16_f32 v107, v116, v117
	v_max_f32_e32 v96, 0, v96
	v_max_f32_e32 v97, 0, v97
	global_store_dwordx4 v[112:113], v[104:107], off
	s_nop 1
	v_pk_mul_f32 v[104:105], v[96:97], v[96:97]
	v_max_f32_e32 v97, v98, v98
	v_max_f32_e32 v96, v102, v102
; __device__ __forceinline__ unsigned cvt_pk_bf16(float lo, float hi) { const bf16x2_t r = __builtin_convertvector((f32x2){lo, hi}, bf16x2_t); return __builtin_bit_cast(unsigned, r); }
;     __device__ __forceinline__ void operator()(const AccT& acc, const Unit& u, int wr, int wc, int fr, int fq) const {
;         const int row0 = u.pm * BM + wr * 64 + fr, col0 = u.pn * BM + wc * 32 + 8 * fq;
; #pragma unroll
;         for (int ai = 0; ai < 2; ++ai)
; #pragma unroll
;             for (int m = 0; m < 4; ++m) { bf16_t* rowp = O + (size_t)(row0 + ai * HALF + m * 16) * DFF + col0;
; #pragma unroll
;                 for (int bj = 0; bj < 2; ++bj) { f32x4 v0 = acc[ai][bj][m][0], v1 = acc[ai][bj][m][1];
; #pragma unroll
;                     for (int j = 0; j < 4; ++j) { float a = fmaxf(v0[j], 0.f), b = fmaxf(v1[j], 0.f); v0[j] = a * a; v1[j] = b * b; }
;                     u32x4 w; w.x = cvt_pk_bf16(v0[0], v0[1]); w.y = cvt_pk_bf16(v0[2], v0[3]); w.z = cvt_pk_bf16(v1[0], v1[1]); w.w = cvt_pk_bf16(v1[2], v1[3]);
;                     *(u32x4*)(rowp + bj * HALF) = w; } }
	v_max_f32_e32 v98, 0, v97
	v_max_f32_e32 v97, v103, v103
	v_max_f32_e32 v100, 0, v100
	v_max_f32_e32 v101, 0, v101
	v_max_f32_e32 v96, 0, v96
	v_max_f32_e32 v97, 0, v97
	v_max_f32_e32 v99, 0, v99
	v_pk_mul_f32 v[100:101], v[100:101], v[100:101]
	v_pk_mul_f32 v[102:103], v[96:97], v[96:97]
	v_pk_mul_f32 v[106:107], v[98:99], v[98:99]
	v_cvt_pk_bf16_f32 v96, v100, v101
	v_cvt_pk_bf16_f32 v97, v102, v103
	v_cvt_pk_bf16_f32 v98, v104, v105
	v_cvt_pk_bf16_f32 v99, v106, v107
	v_max_f32_e32 v88, 0, v88
	v_max_f32_e32 v89, 0, v89
	global_store_dwordx4 v[112:113], v[96:99], off offset:256
	s_nop 1
	v_or_b32_e32 v96, 32, v152
	v_pk_mul_f32 v[98:99], v[88:89], v[88:89]
	v_max_f32_e32 v89, v90, v90
	v_ashrrev_i32_e32 v97, 31, v96
	v_max_f32_e32 v88, v94, v94
	v_max_f32_e32 v90, 0, v89
	v_max_f32_e32 v89, v95, v95
	v_lshlrev_b64 v[96:97], 14, v[96:97]
	v_max_f32_e32 v92, 0, v92
	v_max_f32_e32 v93, 0, v93
	v_max_f32_e32 v88, 0, v88
	v_max_f32_e32 v89, 0, v89
	v_max_f32_e32 v91, 0, v91
	v_lshl_add_u64 v[96:97], s[46:47], 0, v[96:97]
	v_pk_mul_f32 v[92:93], v[92:93], v[92:93]
	v_pk_mul_f32 v[94:95], v[88:89], v[88:89]
	v_pk_mul_f32 v[100:101], v[90:91], v[90:91]
	v_lshl_add_u64 v[96:97], v[96:97], 0, v[156:157]
	v_cvt_pk_bf16_f32 v88, v92, v93
	v_cvt_pk_bf16_f32 v89, v94, v95
	v_cvt_pk_bf16_f32 v90, v98, v99
	v_cvt_pk_bf16_f32 v91, v100, v101
	v_max_f32_e32 v80, 0, v80
	v_max_f32_e32 v81, 0, v81
	global_store_dwordx4 v[96:97], v[88:91], off
	s_nop 1
	v_pk_mul_f32 v[88:89], v[80:81], v[80:81]
	v_max_f32_e32 v81, v82, v82
	v_max_f32_e32 v80, v86, v86
	v_max_f32_e32 v82, 0, v81
	v_max_f32_e32 v81, v87, v87
	v_max_f32_e32 v84, 0, v84
	v_max_f32_e32 v85, 0, v85
	v_max_f32_e32 v80, 0, v80
	v_max_f32_e32 v81, 0, v81
	v_max_f32_e32 v83, 0, v83
	v_pk_mul_f32 v[84:85], v[84:85], v[84:85]
	v_pk_mul_f32 v[86:87], v[80:81], v[80:81]
	v_pk_mul_f32 v[90:91], v[82:83], v[82:83]
	v_cvt_pk_bf16_f32 v80, v84, v85
	v_cvt_pk_bf16_f32 v81, v86, v87
	v_cvt_pk_bf16_f32 v82, v88, v89
	v_cvt_pk_bf16_f32 v83, v90, v91
	v_max_f32_e32 v72, 0, v72
	v_max_f32_e32 v73, 0, v73
	global_store_dwordx4 v[96:97], v[80:83], off offset:256
	s_nop 1
	v_or_b32_e32 v80, 48, v152
	v_pk_mul_f32 v[82:83], v[72:73], v[72:73]
	v_max_f32_e32 v73, v74, v74
	v_ashrrev_i32_e32 v81, 31, v80
	v_max_f32_e32 v72, v78, v78
	v_max_f32_e32 v74, 0, v73
	v_max_f32_e32 v73, v79, v79
	v_lshlrev_b64 v[80:81], 14, v[80:81]
	v_max_f32_e32 v76, 0, v76
	v_max_f32_e32 v77, 0, v77
	v_max_f32_e32 v72, 0, v72
	v_max_f32_e32 v73, 0, v73
	v_max_f32_e32 v75, 0, v75
	v_lshl_add_u64 v[80:81], s[46:47], 0, v[80:81]
	v_pk_mul_f32 v[76:77], v[76:77], v[76:77]
	v_pk_mul_f32 v[78:79], v[72:73], v[72:73]
	v_pk_mul_f32 v[84:85], v[74:75], v[74:75]
	v_lshl_add_u64 v[80:81], v[80:81], 0, v[156:157]
	v_cvt_pk_bf16_f32 v72, v76, v77
	v_cvt_pk_bf16_f32 v73, v78, v79
	v_cvt_pk_bf16_f32 v74, v82, v83
	v_cvt_pk_bf16_f32 v75, v84, v85
	v_max_f32_e32 v64, 0, v64
	v_max_f32_e32 v65, 0, v65
	global_store_dwordx4 v[80:81], v[72:75], off
	s_nop 1
	v_pk_mul_f32 v[72:73], v[64:65], v[64:65]
	v_max_f32_e32 v65, v66, v66
	v_max_f32_e32 v64, v70, v70
	v_max_f32_e32 v66, 0, v65
	v_max_f32_e32 v65, v71, v71
	v_max_f32_e32 v68, 0, v68
	v_max_f32_e32 v69, 0, v69
	v_max_f32_e32 v64, 0, v64
	v_max_f32_e32 v65, 0, v65
	v_max_f32_e32 v67, 0, v67
	v_pk_mul_f32 v[68:69], v[68:69], v[68:69]
	v_pk_mul_f32 v[70:71], v[64:65], v[64:65]
	v_pk_mul_f32 v[74:75], v[66:67], v[66:67]
	v_cvt_pk_bf16_f32 v64, v68, v69
	v_cvt_pk_bf16_f32 v65, v70, v71
	v_cvt_pk_bf16_f32 v66, v72, v73
	v_cvt_pk_bf16_f32 v67, v74, v75
	v_max_f32_e32 v56, 0, v56
	v_max_f32_e32 v57, 0, v57
	global_store_dwordx4 v[80:81], v[64:67], off offset:256
	s_nop 1
	v_pk_mul_f32 v[66:67], v[56:57], v[56:57]
	v_max_f32_e32 v57, v58, v58
	v_max_f32_e32 v60, 0, v60
	v_max_f32_e32 v61, 0, v61
	v_max_f32_e32 v56, v62, v62
	v_max_f32_e32 v58, 0, v57
	v_max_f32_e32 v57, v63, v63
	v_pk_mul_f32 v[60:61], v[60:61], v[60:61]
	v_max_f32_e32 v56, 0, v56
	v_max_f32_e32 v57, 0, v57
	v_max_f32_e32 v59, 0, v59
	v_pk_mul_f32 v[62:63], v[56:57], v[56:57]
	v_pk_mul_f32 v[68:69], v[58:59], v[58:59]
	v_cvt_pk_bf16_f32 v56, v60, v61
	v_add_co_u32_e32 v60, vcc, s61, v144
	v_cvt_pk_bf16_f32 v57, v62, v63
	v_cvt_pk_bf16_f32 v58, v66, v67
	v_cvt_pk_bf16_f32 v59, v68, v69
	v_addc_co_u32_e32 v61, vcc, 0, v145, vcc
	v_max_f32_e32 v48, 0, v48
	v_max_f32_e32 v49, 0, v49
	global_store_dwordx4 v[60:61], v[56:59], off
	s_nop 1
	v_pk_mul_f32 v[56:57], v[48:49], v[48:49]
	v_max_f32_e32 v49, v50, v50
	v_max_f32_e32 v48, v54, v54
	v_max_f32_e32 v50, 0, v49
	v_max_f32_e32 v49, v55, v55
	v_max_f32_e32 v52, 0, v52
	v_max_f32_e32 v53, 0, v53
	v_max_f32_e32 v48, 0, v48
	v_max_f32_e32 v49, 0, v49
	v_max_f32_e32 v51, 0, v51
	s_mov_b64 s[46:47], 0x200000
	v_pk_mul_f32 v[52:53], v[52:53], v[52:53]
	v_pk_mul_f32 v[54:55], v[48:49], v[48:49]
	v_pk_mul_f32 v[58:59], v[50:51], v[50:51]
; __device__ __forceinline__ unsigned cvt_pk_bf16(float lo, float hi) { const bf16x2_t r = __builtin_convertvector((f32x2){lo, hi}, bf16x2_t); return __builtin_bit_cast(unsigned, r); }
; #define PG8_WAIT_V(n) asm volatile("s_waitcnt vmcnt(" #n ")" ::: "memory")
; #define PG8_BAR __builtin_amdgcn_s_barrier()
; template <class Epi>
; __device__ __forceinline__ void gemm_phase(LAS unsigned char* lds, const bf16_t* A, int lda, const bf16_t* Bt, int ldb, int M, int N, int K, int asel, const Epi& E, const int fixed_round = -1) {
;     ...
;         if (!has_next) break;
; #pragma unroll
;         for (int a = 0; a < 2; ++a)
; #pragma unroll
;             for (int b = 0; b < 2; ++b)
; #pragma unroll
;                 for (int m = 0; m < 4; ++m)
; #pragma unroll
;                     for (int n = 0; n < 2; ++n) acc[a][b][m][n] = (f32x4){0.f, 0.f, 0.f, 0.f};
;         cur = nxt; cA = nA; cB = nB; ++ui;
;     }
;     PG8_WAIT_V(0);
;     if (wr == 0) PG8_BAR;
;     PG8_BAR;
;     __device__ __forceinline__ void operator()(const AccT& acc, const Unit& u, int wr, int wc, int fr, int fq) const {
;         const int row0 = u.pm * BM + wr * 64 + fr, col0 = u.pn * BM + wc * 32 + 8 * fq;
; #pragma unroll
;         for (int ai = 0; ai < 2; ++ai)
; #pragma unroll
;             for (int m = 0; m < 4; ++m) { bf16_t* rowp = O + (size_t)(row0 + ai * HALF + m * 16) * DFF + col0;
; #pragma unroll
;                 for (int bj = 0; bj < 2; ++bj) { f32x4 v0 = acc[ai][bj][m][0], v1 = acc[ai][bj][m][1];
; #pragma unroll
;                     for (int j = 0; j < 4; ++j) { float a = fmaxf(v0[j], 0.f), b = fmaxf(v1[j], 0.f); v0[j] = a * a; v1[j] = b * b; }
;                     u32x4 w; w.x = cvt_pk_bf16(v0[0], v0[1]); w.y = cvt_pk_bf16(v0[2], v0[3]); w.z = cvt_pk_bf16(v1[0], v1[1]); w.w = cvt_pk_bf16(v1[2], v1[3]);
;                     *(u32x4*)(rowp + bj * HALF) = w; } }
	v_lshl_add_u64 v[64:65], v[144:145], 0, s[46:47]
	v_cvt_pk_bf16_f32 v48, v52, v53
	v_cvt_pk_bf16_f32 v49, v54, v55
	v_cvt_pk_bf16_f32 v50, v56, v57
	v_cvt_pk_bf16_f32 v51, v58, v59
	v_max_f32_e32 v40, 0, v40
	v_max_f32_e32 v41, 0, v41
	global_store_dwordx4 v[64:65], v[48:51], off offset:256
	s_nop 1
	v_pk_mul_f32 v[50:51], v[40:41], v[40:41]
	v_max_f32_e32 v41, v42, v42
	v_max_f32_e32 v44, 0, v44
	v_max_f32_e32 v45, 0, v45
	v_max_f32_e32 v40, v46, v46
	v_max_f32_e32 v42, 0, v41
	v_max_f32_e32 v41, v47, v47
	v_pk_mul_f32 v[44:45], v[44:45], v[44:45]
	v_max_f32_e32 v40, 0, v40
	v_max_f32_e32 v41, 0, v41
	v_max_f32_e32 v43, 0, v43
	v_pk_mul_f32 v[46:47], v[40:41], v[40:41]
	v_pk_mul_f32 v[52:53], v[42:43], v[42:43]
	v_cvt_pk_bf16_f32 v40, v44, v45
	v_add_co_u32_e32 v44, vcc, s62, v144
	v_cvt_pk_bf16_f32 v41, v46, v47
	v_cvt_pk_bf16_f32 v42, v50, v51
	v_cvt_pk_bf16_f32 v43, v52, v53
	v_addc_co_u32_e32 v45, vcc, 0, v145, vcc
	v_max_f32_e32 v32, 0, v32
	v_max_f32_e32 v33, 0, v33
	global_store_dwordx4 v[44:45], v[40:43], off
	s_nop 1
	v_pk_mul_f32 v[40:41], v[32:33], v[32:33]
	v_max_f32_e32 v33, v34, v34
	v_max_f32_e32 v32, v38, v38
	v_max_f32_e32 v34, 0, v33
	v_max_f32_e32 v33, v39, v39
	v_max_f32_e32 v36, 0, v36
	v_max_f32_e32 v37, 0, v37
	v_max_f32_e32 v32, 0, v32
	v_max_f32_e32 v33, 0, v33
	v_max_f32_e32 v35, 0, v35
	v_pk_mul_f32 v[36:37], v[36:37], v[36:37]
	v_pk_mul_f32 v[38:39], v[32:33], v[32:33]
	v_pk_mul_f32 v[42:43], v[34:35], v[34:35]
	v_lshl_add_u64 v[48:49], v[144:145], 0, s[4:5]
	v_cvt_pk_bf16_f32 v32, v36, v37
	v_cvt_pk_bf16_f32 v33, v38, v39
	v_cvt_pk_bf16_f32 v34, v40, v41
	v_cvt_pk_bf16_f32 v35, v42, v43
	v_max_f32_e32 v24, 0, v24
	v_max_f32_e32 v25, 0, v25
	global_store_dwordx4 v[48:49], v[32:35], off offset:256
	s_nop 1
	v_pk_mul_f32 v[34:35], v[24:25], v[24:25]
	v_max_f32_e32 v25, v26, v26
	v_max_f32_e32 v28, 0, v28
	v_max_f32_e32 v29, 0, v29
	v_max_f32_e32 v24, v30, v30
	v_max_f32_e32 v26, 0, v25
	v_max_f32_e32 v25, v31, v31
	v_pk_mul_f32 v[28:29], v[28:29], v[28:29]
	v_max_f32_e32 v24, 0, v24
	v_max_f32_e32 v25, 0, v25
	v_max_f32_e32 v27, 0, v27
	v_pk_mul_f32 v[30:31], v[24:25], v[24:25]
	v_pk_mul_f32 v[36:37], v[26:27], v[26:27]
	v_cvt_pk_bf16_f32 v24, v28, v29
	v_add_co_u32_e32 v28, vcc, s63, v144
	v_cvt_pk_bf16_f32 v25, v30, v31
	v_cvt_pk_bf16_f32 v26, v34, v35
	v_cvt_pk_bf16_f32 v27, v36, v37
	v_addc_co_u32_e32 v29, vcc, 0, v145, vcc
	v_max_f32_e32 v16, 0, v16
	v_max_f32_e32 v17, 0, v17
	global_store_dwordx4 v[28:29], v[24:27], off
	s_nop 1
	v_pk_mul_f32 v[24:25], v[16:17], v[16:17]
	v_max_f32_e32 v17, v18, v18
	v_max_f32_e32 v16, v22, v22
	v_max_f32_e32 v18, 0, v17
	v_max_f32_e32 v17, v23, v23
	v_max_f32_e32 v20, 0, v20
	v_max_f32_e32 v21, 0, v21
	v_max_f32_e32 v16, 0, v16
	v_max_f32_e32 v17, 0, v17
	v_max_f32_e32 v19, 0, v19
	v_pk_mul_f32 v[20:21], v[20:21], v[20:21]
	v_pk_mul_f32 v[22:23], v[16:17], v[16:17]
	v_pk_mul_f32 v[26:27], v[18:19], v[18:19]
	v_lshl_add_u64 v[32:33], v[144:145], 0, s[6:7]
	v_cvt_pk_bf16_f32 v16, v20, v21
	v_cvt_pk_bf16_f32 v17, v22, v23
	v_cvt_pk_bf16_f32 v18, v24, v25
	v_cvt_pk_bf16_f32 v19, v26, v27
	v_max_f32_e32 v8, 0, v8
	v_max_f32_e32 v9, 0, v9
	global_store_dwordx4 v[32:33], v[16:19], off offset:256
	s_nop 1
	v_pk_mul_f32 v[18:19], v[8:9], v[8:9]
	v_max_f32_e32 v9, v10, v10
	v_max_f32_e32 v12, 0, v12
	v_max_f32_e32 v13, 0, v13
	v_max_f32_e32 v8, v14, v14
	v_max_f32_e32 v10, 0, v9
	v_max_f32_e32 v9, v15, v15
	v_pk_mul_f32 v[12:13], v[12:13], v[12:13]
	v_max_f32_e32 v8, 0, v8
	v_max_f32_e32 v9, 0, v9
	v_max_f32_e32 v11, 0, v11
	v_pk_mul_f32 v[14:15], v[8:9], v[8:9]
	v_pk_mul_f32 v[20:21], v[10:11], v[10:11]
	v_cvt_pk_bf16_f32 v8, v12, v13
	v_add_co_u32_e32 v12, vcc, s64, v144
	v_cvt_pk_bf16_f32 v9, v14, v15
	v_cvt_pk_bf16_f32 v10, v18, v19
	v_cvt_pk_bf16_f32 v11, v20, v21
	v_addc_co_u32_e32 v13, vcc, 0, v145, vcc
	v_max_f32_e32 v0, 0, v0
	v_max_f32_e32 v1, 0, v1
	global_store_dwordx4 v[12:13], v[8:11], off
	s_nop 1
	v_pk_mul_f32 v[8:9], v[0:1], v[0:1]
	v_max_f32_e32 v1, v2, v2
	v_max_f32_e32 v0, v6, v6
	v_max_f32_e32 v2, 0, v1
	v_max_f32_e32 v1, v7, v7
	v_max_f32_e32 v4, 0, v4
	v_max_f32_e32 v5, 0, v5
	v_max_f32_e32 v0, 0, v0
	v_max_f32_e32 v1, 0, v1
	v_max_f32_e32 v3, 0, v3
	v_pk_mul_f32 v[4:5], v[4:5], v[4:5]
	v_pk_mul_f32 v[6:7], v[0:1], v[0:1]
	v_pk_mul_f32 v[10:11], v[2:3], v[2:3]
	v_lshl_add_u64 v[16:17], v[144:145], 0, s[22:23]
	v_cvt_pk_bf16_f32 v0, v4, v5
	v_cvt_pk_bf16_f32 v1, v6, v7
	v_cvt_pk_bf16_f32 v2, v8, v9
	v_cvt_pk_bf16_f32 v3, v10, v11
	s_and_b64 vcc, exec, s[0:1]
	s_mov_b32 s65, s24
	s_mov_b32 s44, s28
	s_mov_b64 s[48:49], s[42:43]
	s_mov_b64 s[46:47], s[40:41]
	s_mov_b64 s[70:71], s[26:27]
	global_store_dwordx4 v[16:17], v[0:3], off offset:256
	s_cbranch_vccz .LBB0_1216
	s_waitcnt vmcnt(0)
	s_cmpk_gt_u32 s33, 0xff
	s_cbranch_scc1 .LBB0_1227
	s_barrier

; #define PG8_STAGE(bufoff, gbase, voff) do { _Pragma("unroll") for (int _i = 0; _i < 2; ++_i) \
;         __builtin_amdgcn_global_load_lds((const unsigned*)((const char*)(gbase) + (voff)[_i]), (LAS unsigned*)(lds + (bufoff) + ldsw + _i * 8192), 16, 0, 0); } while (0)
; #define PG8_LDA(dst, b, h) do { _Pragma("unroll") for (int m = 0; m < 4; ++m) _Pragma("unroll") for (int k = 0; k < 2; ++k) dst[m][k] = *(const LAS bf16x8*)(lds + PG8_SA(b, h) + aoff + m * 2048 + k * 1024); } while (0)
; #define PG8_LDB(dst, b, h) do { _Pragma("unroll") for (int n = 0; n < 2; ++n) _Pragma("unroll") for (int k = 0; k < 2; ++k) dst[n][k] = *(const LAS bf16x8*)(lds + PG8_SB(b, h) + boff + n * 2048 + k * 1024); } while (0)
; #define PG8_WAIT_V(n) asm volatile("s_waitcnt vmcnt(" #n ")" ::: "memory")
; #define PG8_WAIT_L(n) asm volatile("s_waitcnt lgkmcnt(" #n ")" ::: "memory")
; #define PG8_BAR __builtin_amdgcn_s_barrier()
; #define PG8_SCHED __builtin_amdgcn_sched_barrier(0)
; template <class Epi>
; __device__ __forceinline__ void gemm_phase(LAS unsigned char* lds, const bf16_t* A, int lda, const bf16_t* Bt, int ldb, int M, int N, int K, int asel, const Epi& E, const int fixed_round = -1) {
;     ...
;         const char* nA = has_next ? PG8_ABASE(nxt) : cA; const char* nB = has_next ? (const char*)Bt + (size_t)nxt.pn * tstepB : cB;
;         for (int t = 0; t < nt; t += 2) {
;             const bool last = (t == nt - 2);
;             const char* a1 = cA + (size_t)(t + 1) * kstep;
;             const char* a2 = last ? nA : cA + (size_t)(t + 2) * kstep; const char* b2 = last ? nB : cB + (size_t)(t + 2) * kstep;
;             const char* a3 = a2 + kstep; const char* b3 = b2 + kstep;
;             PG8_LDB(B0, 0, 0); PG8_SCHED; PG8_LDA(At, 0, 0); PG8_STAGE(PG8_SA(1, 1), a1 + hstepA, voffA);
;             PG8_WAIT_L(8); PG8_BAR; PG8_WAIT_L(0); PG8_MMA(0, 0, At, B0); PG8_BAR; PG8_SCHED;
;             PG8_LDB(B1, 0, 1); PG8_STAGE(PG8_SB(0, 0), b2, voffB);
;             PG8_BAR; PG8_WAIT_L(0); PG8_MMA(0, 1, At, B1); PG8_BAR;
;             PG8_LDA(At, 0, 1); PG8_STAGE(PG8_SA(0, 0), a2, voffA);
;             PG8_BAR; PG8_WAIT_L(0); PG8_MMA(1, 0, At, B0); PG8_BAR; PG8_SCHED;
;             PG8_STAGE(PG8_SB(0, 1), b2 + hstepB, voffB);
;             PG8_WAIT_V(6); PG8_BAR; PG8_MMA(1, 1, At, B1); PG8_BAR;
.LBB0_1283:
	ds_read_b128 v[146:149], v124
	ds_read_b128 v[150:153], v124 offset:1024
	ds_read_b128 v[154:157], v124 offset:2048
	ds_read_b128 v[158:161], v124 offset:3072
	s_mov_b32 m0, s47
	v_lshl_add_u64 v[194:195], v[120:121], 0, s[22:23]
	ds_read_b128 v[162:165], v125
	ds_read_b128 v[166:169], v125 offset:1024
	ds_read_b128 v[170:173], v125 offset:2048
	ds_read_b128 v[174:177], v125 offset:3072
	ds_read_b128 v[178:181], v125 offset:4096
	ds_read_b128 v[182:185], v125 offset:5120
	ds_read_b128 v[186:189], v125 offset:6144
	ds_read_b128 v[190:193], v125 offset:7168
	global_load_lds_dwordx4 v[194:195], off
	v_lshl_add_u64 v[194:195], v[122:123], 0, s[22:23]
	s_mov_b32 m0, s48
	s_nop 0
	global_load_lds_dwordx4 v[194:195], off
	s_waitcnt lgkmcnt(8)
	s_setprio 1
	s_barrier
	s_waitcnt lgkmcnt(0)
	v_mfma_f32_16x16x32_bf16 v[140:143], v[146:149], v[162:165], v[140:143]
	v_mfma_f32_16x16x32_bf16 v[136:139], v[154:157], v[162:165], v[136:139]
	v_mfma_f32_16x16x32_bf16 v[108:111], v[146:149], v[170:173], v[108:111]
	v_mfma_f32_16x16x32_bf16 v[104:107], v[154:157], v[170:173], v[104:107]
	v_mfma_f32_16x16x32_bf16 v[92:95], v[146:149], v[178:181], v[92:95]
	v_mfma_f32_16x16x32_bf16 v[88:91], v[154:157], v[178:181], v[88:91]
	v_mfma_f32_16x16x32_bf16 v[76:79], v[146:149], v[186:189], v[76:79]
	v_mfma_f32_16x16x32_bf16 v[72:75], v[154:157], v[186:189], v[72:75]
	v_mfma_f32_16x16x32_bf16 v[140:143], v[150:153], v[166:169], v[140:143]
	v_mfma_f32_16x16x32_bf16 v[136:139], v[158:161], v[166:169], v[136:139]
	v_mfma_f32_16x16x32_bf16 v[108:111], v[150:153], v[174:177], v[108:111]
	v_mfma_f32_16x16x32_bf16 v[104:107], v[158:161], v[174:177], v[104:107]
	v_mfma_f32_16x16x32_bf16 v[92:95], v[150:153], v[182:185], v[92:95]
	v_mfma_f32_16x16x32_bf16 v[88:91], v[158:161], v[182:185], v[88:91]
	v_mfma_f32_16x16x32_bf16 v[76:79], v[150:153], v[190:193], v[76:79]
	v_mfma_f32_16x16x32_bf16 v[72:75], v[158:161], v[190:193], v[72:75]
	s_barrier
	s_setprio 0
	s_add_u32 s24, s16, s22
	s_addc_u32 s25, s17, s23
	s_add_u32 s24, s24, 0x18500100
	s_addc_u32 s25, s25, 0
	s_add_u32 s57, s28, s22
	s_addc_u32 s58, s29, s23
	s_cmpk_eq_i32 s22, 0x3f00
	s_cselect_b32 s27, s87, s25
	s_cselect_b32 s26, s86, s24
	s_cselect_b32 s25, s3, s58
	s_cselect_b32 s24, s2, s57
	s_mov_b32 m0, s49
	s_add_u32 s98, s24, s0
	s_addc_u32 s99, s25, s1
	ds_read_b128 v[194:197], v126
	ds_read_b128 v[204:207], v126 offset:1024
	ds_read_b128 v[208:211], v126 offset:2048
	ds_read_b128 v[212:215], v126 offset:3072
	global_load_lds_dwordx4 v114, s[24:25]
	s_mov_b32 m0, s50
	s_nop 0
	global_load_lds_dwordx4 v118, s[24:25]
	s_setprio 1
	s_barrier
	s_waitcnt lgkmcnt(0)
	v_mfma_f32_16x16x32_bf16 v[132:135], v[194:197], v[162:165], v[132:135]
	v_mfma_f32_16x16x32_bf16 v[128:131], v[208:211], v[162:165], v[128:131]
	v_mfma_f32_16x16x32_bf16 v[100:103], v[194:197], v[170:173], v[100:103]
	v_mfma_f32_16x16x32_bf16 v[96:99], v[208:211], v[170:173], v[96:99]
	v_mfma_f32_16x16x32_bf16 v[84:87], v[194:197], v[178:181], v[84:87]
	v_mfma_f32_16x16x32_bf16 v[80:83], v[208:211], v[178:181], v[80:83]
	v_mfma_f32_16x16x32_bf16 v[68:71], v[194:197], v[186:189], v[68:71]
	v_mfma_f32_16x16x32_bf16 v[64:67], v[208:211], v[186:189], v[64:67]
	v_mfma_f32_16x16x32_bf16 v[132:135], v[204:207], v[166:169], v[132:135]
	v_mfma_f32_16x16x32_bf16 v[128:131], v[212:215], v[166:169], v[128:131]
	v_mfma_f32_16x16x32_bf16 v[100:103], v[204:207], v[174:177], v[100:103]
	v_mfma_f32_16x16x32_bf16 v[96:99], v[212:215], v[174:177], v[96:99]
	v_mfma_f32_16x16x32_bf16 v[84:87], v[204:207], v[182:185], v[84:87]
	v_mfma_f32_16x16x32_bf16 v[80:83], v[212:215], v[182:185], v[80:83]
	v_mfma_f32_16x16x32_bf16 v[68:71], v[204:207], v[190:193], v[68:71]
	v_mfma_f32_16x16x32_bf16 v[64:67], v[212:215], v[190:193], v[64:67]
	s_barrier
	s_setprio 0
	s_mov_b32 m0, s40
	s_add_u32 s100, s26, s0
	s_addc_u32 s101, s27, s1
	ds_read_b128 v[162:165], v125 offset:16384
	ds_read_b128 v[166:169], v125 offset:17408
	ds_read_b128 v[170:173], v125 offset:18432
	ds_read_b128 v[174:177], v125 offset:19456
	ds_read_b128 v[178:181], v125 offset:20480
	ds_read_b128 v[182:185], v125 offset:21504
	ds_read_b128 v[186:189], v125 offset:22528
	ds_read_b128 v[190:193], v125 offset:23552
	global_load_lds_dwordx4 v112, s[26:27]
	s_mov_b32 m0, s41
	s_nop 0
	global_load_lds_dwordx4 v116, s[26:27]
	s_setprio 1
	s_barrier
	s_waitcnt lgkmcnt(0)
	v_mfma_f32_16x16x32_bf16 v[60:63], v[146:149], v[162:165], v[60:63]
	v_mfma_f32_16x16x32_bf16 v[56:59], v[154:157], v[162:165], v[56:59]
	v_mfma_f32_16x16x32_bf16 v[44:47], v[146:149], v[170:173], v[44:47]
	v_mfma_f32_16x16x32_bf16 v[40:43], v[154:157], v[170:173], v[40:43]
	v_mfma_f32_16x16x32_bf16 v[28:31], v[146:149], v[178:181], v[28:31]
	v_mfma_f32_16x16x32_bf16 v[24:27], v[154:157], v[178:181], v[24:27]
	v_mfma_f32_16x16x32_bf16 v[12:15], v[146:149], v[186:189], v[12:15]
	v_mfma_f32_16x16x32_bf16 v[8:11], v[154:157], v[186:189], v[8:11]
	v_mfma_f32_16x16x32_bf16 v[60:63], v[150:153], v[166:169], v[60:63]
	v_mfma_f32_16x16x32_bf16 v[56:59], v[158:161], v[166:169], v[56:59]
	v_mfma_f32_16x16x32_bf16 v[44:47], v[150:153], v[174:177], v[44:47]
	v_mfma_f32_16x16x32_bf16 v[40:43], v[158:161], v[174:177], v[40:43]
	v_mfma_f32_16x16x32_bf16 v[28:31], v[150:153], v[182:185], v[28:31]
	v_mfma_f32_16x16x32_bf16 v[24:27], v[158:161], v[182:185], v[24:27]
	v_mfma_f32_16x16x32_bf16 v[12:15], v[150:153], v[190:193], v[12:15]
	v_mfma_f32_16x16x32_bf16 v[8:11], v[158:161], v[190:193], v[8:11]
	s_barrier
	s_setprio 0
	s_add_u32 s58, s24, 0x200000
	s_addc_u32 s59, s25, 0
	s_mov_b32 m0, s51
	s_nop 0
	global_load_lds_dwordx4 v114, s[58:59]
	s_mov_b32 m0, s52
	s_nop 0
	global_load_lds_dwordx4 v118, s[58:59]
	s_waitcnt vmcnt(6)
	s_setprio 1
	s_barrier
; #define PG8_STAGE(bufoff, gbase, voff) do { _Pragma("unroll") for (int _i = 0; _i < 2; ++_i) \
;         __builtin_amdgcn_global_load_lds((const unsigned*)((const char*)(gbase) + (voff)[_i]), (LAS unsigned*)(lds + (bufoff) + ldsw + _i * 8192), 16, 0, 0); } while (0)
; #define PG8_LDA(dst, b, h) do { _Pragma("unroll") for (int m = 0; m < 4; ++m) _Pragma("unroll") for (int k = 0; k < 2; ++k) dst[m][k] = *(const LAS bf16x8*)(lds + PG8_SA(b, h) + aoff + m * 2048 + k * 1024); } while (0)
; #define PG8_LDB(dst, b, h) do { _Pragma("unroll") for (int n = 0; n < 2; ++n) _Pragma("unroll") for (int k = 0; k < 2; ++k) dst[n][k] = *(const LAS bf16x8*)(lds + PG8_SB(b, h) + boff + n * 2048 + k * 1024); } while (0)
; #define PG8_WAIT_V(n) asm volatile("s_waitcnt vmcnt(" #n ")" ::: "memory")
; #define PG8_WAIT_L(n) asm volatile("s_waitcnt lgkmcnt(" #n ")" ::: "memory")
; #define PG8_BAR __builtin_amdgcn_s_barrier()
; #define PG8_SCHED __builtin_amdgcn_sched_barrier(0)
; template <class Epi>
; __device__ __forceinline__ void gemm_phase(LAS unsigned char* lds, const bf16_t* A, int lda, const bf16_t* Bt, int ldb, int M, int N, int K, int asel, const Epi& E, const int fixed_round = -1) {
;     ...
;             PG8_WAIT_V(6); PG8_BAR; PG8_MMA(1, 1, At, B1); PG8_BAR;
;             PG8_LDB(B0, 1, 0); PG8_SCHED; PG8_LDA(At, 1, 0); PG8_STAGE(PG8_SA(0, 1), a2 + hstepA, voffA);
;             PG8_WAIT_L(8); PG8_BAR; PG8_WAIT_L(0); PG8_MMA(0, 0, At, B0); PG8_BAR; PG8_SCHED;
;             PG8_LDB(B1, 1, 1); PG8_STAGE(PG8_SB(1, 0), b3, voffB);
;             PG8_BAR; PG8_WAIT_L(0); PG8_MMA(0, 1, At, B1); PG8_BAR;
;             PG8_LDA(At, 1, 1); PG8_STAGE(PG8_SA(1, 0), a3, voffA);
;             PG8_BAR; PG8_WAIT_L(0); PG8_MMA(1, 0, At, B0); PG8_BAR; PG8_SCHED;
	v_mfma_f32_16x16x32_bf16 v[52:55], v[194:197], v[162:165], v[52:55]
	v_mfma_f32_16x16x32_bf16 v[48:51], v[208:211], v[162:165], v[48:51]
	v_mfma_f32_16x16x32_bf16 v[36:39], v[194:197], v[170:173], v[36:39]
	v_mfma_f32_16x16x32_bf16 v[32:35], v[208:211], v[170:173], v[32:35]
	v_mfma_f32_16x16x32_bf16 v[20:23], v[194:197], v[178:181], v[20:23]
	v_mfma_f32_16x16x32_bf16 v[16:19], v[208:211], v[178:181], v[16:19]
	v_mfma_f32_16x16x32_bf16 v[4:7], v[194:197], v[186:189], v[4:7]
	v_mfma_f32_16x16x32_bf16 v[0:3], v[208:211], v[186:189], v[0:3]
	v_mfma_f32_16x16x32_bf16 v[52:55], v[204:207], v[166:169], v[52:55]
	v_mfma_f32_16x16x32_bf16 v[48:51], v[212:215], v[166:169], v[48:51]
	v_mfma_f32_16x16x32_bf16 v[36:39], v[204:207], v[174:177], v[36:39]
	v_mfma_f32_16x16x32_bf16 v[32:35], v[212:215], v[174:177], v[32:35]
	v_mfma_f32_16x16x32_bf16 v[20:23], v[204:207], v[182:185], v[20:23]
	v_mfma_f32_16x16x32_bf16 v[16:19], v[212:215], v[182:185], v[16:19]
	v_mfma_f32_16x16x32_bf16 v[4:7], v[204:207], v[190:193], v[4:7]
	v_mfma_f32_16x16x32_bf16 v[0:3], v[212:215], v[190:193], v[0:3]
	s_barrier
	s_setprio 0
	ds_read_b128 v[146:149], v127
	ds_read_b128 v[150:153], v127 offset:1024
	ds_read_b128 v[154:157], v127 offset:2048
	ds_read_b128 v[158:161], v127 offset:3072
	s_add_u32 s26, s26, 0x200000
	s_addc_u32 s27, s27, 0
	s_mov_b32 m0, s42
	ds_read_b128 v[162:165], v125 offset:32768
	ds_read_b128 v[166:169], v125 offset:33792
	ds_read_b128 v[170:173], v125 offset:34816
	ds_read_b128 v[174:177], v125 offset:35840
	ds_read_b128 v[178:181], v125 offset:36864
	ds_read_b128 v[182:185], v125 offset:37888
	ds_read_b128 v[186:189], v125 offset:38912
	ds_read_b128 v[190:193], v125 offset:39936
	global_load_lds_dwordx4 v112, s[26:27]
	s_mov_b32 m0, s43
	s_nop 0
	global_load_lds_dwordx4 v116, s[26:27]
	s_waitcnt lgkmcnt(8)
	s_setprio 1
	s_barrier
	s_waitcnt lgkmcnt(0)
	v_mfma_f32_16x16x32_bf16 v[140:143], v[146:149], v[162:165], v[140:143]
	v_mfma_f32_16x16x32_bf16 v[136:139], v[154:157], v[162:165], v[136:139]
	v_mfma_f32_16x16x32_bf16 v[108:111], v[146:149], v[170:173], v[108:111]
	v_mfma_f32_16x16x32_bf16 v[104:107], v[154:157], v[170:173], v[104:107]
	v_mfma_f32_16x16x32_bf16 v[92:95], v[146:149], v[178:181], v[92:95]
	v_mfma_f32_16x16x32_bf16 v[88:91], v[154:157], v[178:181], v[88:91]
	v_mfma_f32_16x16x32_bf16 v[76:79], v[146:149], v[186:189], v[76:79]
	v_mfma_f32_16x16x32_bf16 v[72:75], v[154:157], v[186:189], v[72:75]
	v_mfma_f32_16x16x32_bf16 v[140:143], v[150:153], v[166:169], v[140:143]
	v_mfma_f32_16x16x32_bf16 v[136:139], v[158:161], v[166:169], v[136:139]
	v_mfma_f32_16x16x32_bf16 v[108:111], v[150:153], v[174:177], v[108:111]
	v_mfma_f32_16x16x32_bf16 v[104:107], v[158:161], v[174:177], v[104:107]
	v_mfma_f32_16x16x32_bf16 v[92:95], v[150:153], v[182:185], v[92:95]
	v_mfma_f32_16x16x32_bf16 v[88:91], v[158:161], v[182:185], v[88:91]
	v_mfma_f32_16x16x32_bf16 v[76:79], v[150:153], v[190:193], v[76:79]
	v_mfma_f32_16x16x32_bf16 v[72:75], v[158:161], v[190:193], v[72:75]
	s_barrier
	s_setprio 0
	s_mov_b32 m0, s53
	ds_read_b128 v[194:197], v144
	ds_read_b128 v[204:207], v144 offset:1024
	ds_read_b128 v[208:211], v144 offset:2048
	ds_read_b128 v[212:215], v144 offset:3072
	global_load_lds_dwordx4 v114, s[98:99]
	s_mov_b32 m0, s54
	s_nop 0
	global_load_lds_dwordx4 v118, s[98:99]
	s_setprio 1
	s_barrier
	s_waitcnt lgkmcnt(0)
	v_mfma_f32_16x16x32_bf16 v[132:135], v[194:197], v[162:165], v[132:135]
	v_mfma_f32_16x16x32_bf16 v[128:131], v[208:211], v[162:165], v[128:131]
	v_mfma_f32_16x16x32_bf16 v[100:103], v[194:197], v[170:173], v[100:103]
	v_mfma_f32_16x16x32_bf16 v[96:99], v[208:211], v[170:173], v[96:99]
	v_mfma_f32_16x16x32_bf16 v[84:87], v[194:197], v[178:181], v[84:87]
	v_mfma_f32_16x16x32_bf16 v[80:83], v[208:211], v[178:181], v[80:83]
	v_mfma_f32_16x16x32_bf16 v[68:71], v[194:197], v[186:189], v[68:71]
	v_mfma_f32_16x16x32_bf16 v[64:67], v[208:211], v[186:189], v[64:67]
	v_mfma_f32_16x16x32_bf16 v[132:135], v[204:207], v[166:169], v[132:135]
	v_mfma_f32_16x16x32_bf16 v[128:131], v[212:215], v[166:169], v[128:131]
	v_mfma_f32_16x16x32_bf16 v[100:103], v[204:207], v[174:177], v[100:103]
	v_mfma_f32_16x16x32_bf16 v[96:99], v[212:215], v[174:177], v[96:99]
	v_mfma_f32_16x16x32_bf16 v[84:87], v[204:207], v[182:185], v[84:87]
	v_mfma_f32_16x16x32_bf16 v[80:83], v[212:215], v[182:185], v[80:83]
	v_mfma_f32_16x16x32_bf16 v[68:71], v[204:207], v[190:193], v[68:71]
	v_mfma_f32_16x16x32_bf16 v[64:67], v[212:215], v[190:193], v[64:67]
	s_barrier
; #define PG8_STAGE(bufoff, gbase, voff) do { _Pragma("unroll") for (int _i = 0; _i < 2; ++_i) \
;         __builtin_amdgcn_global_load_lds((const unsigned*)((const char*)(gbase) + (voff)[_i]), (LAS unsigned*)(lds + (bufoff) + ldsw + _i * 8192), 16, 0, 0); } while (0)
; #define PG8_LDA(dst, b, h) do { _Pragma("unroll") for (int m = 0; m < 4; ++m) _Pragma("unroll") for (int k = 0; k < 2; ++k) dst[m][k] = *(const LAS bf16x8*)(lds + PG8_SA(b, h) + aoff + m * 2048 + k * 1024); } while (0)
; #define PG8_WAIT_V(n) asm volatile("s_waitcnt vmcnt(" #n ")" ::: "memory")
; #define PG8_WAIT_L(n) asm volatile("s_waitcnt lgkmcnt(" #n ")" ::: "memory")
; #define PG8_BAR __builtin_amdgcn_s_barrier()
; #define PG8_SCHED __builtin_amdgcn_sched_barrier(0)
; template <class Epi>
; __device__ __forceinline__ void gemm_phase(LAS unsigned char* lds, const bf16_t* A, int lda, const bf16_t* Bt, int ldb, int M, int N, int K, int asel, const Epi& E, const int fixed_round = -1) {
;     ...
;             PG8_LDA(At, 1, 1); PG8_STAGE(PG8_SA(1, 0), a3, voffA);
;             PG8_BAR; PG8_WAIT_L(0); PG8_MMA(1, 0, At, B0); PG8_BAR; PG8_SCHED;
;             PG8_STAGE(PG8_SB(1, 1), b3 + hstepB, voffB);
;             PG8_WAIT_V(6); PG8_BAR; PG8_MMA(1, 1, At, B1); PG8_BAR;
;     ...
;     PG8_WAIT_V(0);
;     if (wr == 0) PG8_BAR;
;     PG8_BAR;
	s_setprio 0
	s_mov_b32 m0, s44
	ds_read_b128 v[162:165], v125 offset:49152
	ds_read_b128 v[166:169], v125 offset:50176
	ds_read_b128 v[170:173], v125 offset:51200
	ds_read_b128 v[174:177], v125 offset:52224
	ds_read_b128 v[178:181], v125 offset:53248
	ds_read_b128 v[182:185], v125 offset:54272
	ds_read_b128 v[186:189], v125 offset:55296
	ds_read_b128 v[190:193], v125 offset:56320
	global_load_lds_dwordx4 v112, s[100:101]
	s_mov_b32 m0, s45
	s_nop 0
	global_load_lds_dwordx4 v116, s[100:101]
	s_setprio 1
	s_barrier
	s_waitcnt lgkmcnt(0)
	v_mfma_f32_16x16x32_bf16 v[60:63], v[146:149], v[162:165], v[60:63]
	v_mfma_f32_16x16x32_bf16 v[56:59], v[154:157], v[162:165], v[56:59]
	v_mfma_f32_16x16x32_bf16 v[44:47], v[146:149], v[170:173], v[44:47]
	v_mfma_f32_16x16x32_bf16 v[40:43], v[154:157], v[170:173], v[40:43]
	v_mfma_f32_16x16x32_bf16 v[28:31], v[146:149], v[178:181], v[28:31]
	v_mfma_f32_16x16x32_bf16 v[24:27], v[154:157], v[178:181], v[24:27]
	v_mfma_f32_16x16x32_bf16 v[12:15], v[146:149], v[186:189], v[12:15]
	v_mfma_f32_16x16x32_bf16 v[8:11], v[154:157], v[186:189], v[8:11]
	v_mfma_f32_16x16x32_bf16 v[60:63], v[150:153], v[166:169], v[60:63]
	v_mfma_f32_16x16x32_bf16 v[56:59], v[158:161], v[166:169], v[56:59]
	v_mfma_f32_16x16x32_bf16 v[44:47], v[150:153], v[174:177], v[44:47]
	v_mfma_f32_16x16x32_bf16 v[40:43], v[158:161], v[174:177], v[40:43]
	v_mfma_f32_16x16x32_bf16 v[28:31], v[150:153], v[182:185], v[28:31]
	v_mfma_f32_16x16x32_bf16 v[24:27], v[158:161], v[182:185], v[24:27]
	v_mfma_f32_16x16x32_bf16 v[12:15], v[150:153], v[190:193], v[12:15]
	v_mfma_f32_16x16x32_bf16 v[8:11], v[158:161], v[190:193], v[8:11]
	s_barrier
	s_setprio 0
	s_add_u32 s24, s24, 0x200080
	s_addc_u32 s25, s25, 0
	s_mov_b32 m0, s55
	s_nop 0
	global_load_lds_dwordx4 v114, s[24:25]
	s_mov_b32 m0, s56
	s_nop 0
	global_load_lds_dwordx4 v118, s[24:25]
	s_waitcnt vmcnt(6)
	s_setprio 1
	s_barrier
	v_mfma_f32_16x16x32_bf16 v[52:55], v[194:197], v[162:165], v[52:55]
	v_mfma_f32_16x16x32_bf16 v[48:51], v[208:211], v[162:165], v[48:51]
	v_mfma_f32_16x16x32_bf16 v[36:39], v[194:197], v[170:173], v[36:39]
	v_mfma_f32_16x16x32_bf16 v[32:35], v[208:211], v[170:173], v[32:35]
	v_mfma_f32_16x16x32_bf16 v[20:23], v[194:197], v[178:181], v[20:23]
	v_mfma_f32_16x16x32_bf16 v[16:19], v[208:211], v[178:181], v[16:19]
	v_mfma_f32_16x16x32_bf16 v[4:7], v[194:197], v[186:189], v[4:7]
	v_mfma_f32_16x16x32_bf16 v[0:3], v[208:211], v[186:189], v[0:3]
	v_mfma_f32_16x16x32_bf16 v[52:55], v[204:207], v[166:169], v[52:55]
	v_mfma_f32_16x16x32_bf16 v[48:51], v[212:215], v[166:169], v[48:51]
	v_mfma_f32_16x16x32_bf16 v[36:39], v[204:207], v[174:177], v[36:39]
	v_mfma_f32_16x16x32_bf16 v[32:35], v[212:215], v[174:177], v[32:35]
	v_mfma_f32_16x16x32_bf16 v[20:23], v[204:207], v[182:185], v[20:23]
	v_mfma_f32_16x16x32_bf16 v[16:19], v[212:215], v[182:185], v[16:19]
	v_mfma_f32_16x16x32_bf16 v[4:7], v[204:207], v[190:193], v[4:7]
	v_mfma_f32_16x16x32_bf16 v[0:3], v[212:215], v[190:193], v[0:3]
	s_setprio 0
	s_add_i32 s46, s46, 2
	s_add_u32 s22, s22, 0x100
	s_addc_u32 s23, s23, 0
	s_cmpk_lt_u32 s46, 0x7e
	s_cbranch_scc1 .Lrot_11
	s_barrier
	s_waitcnt vmcnt(0)
	v_readlane_b32 s48, v254, 0
	s_cmpk_gt_u32 s33, 0xff
	v_readlane_b32 s54, v254, 6
	v_readlane_b32 s55, v254, 7
	v_readlane_b32 s49, v254, 1
	v_readlane_b32 s50, v254, 2
	v_readlane_b32 s51, v254, 3
	v_readlane_b32 s52, v254, 4
	v_readlane_b32 s53, v254, 5
	s_cbranch_scc1 .LBB0_1286
	s_barrier

; #define PG8_STAGE(bufoff, gbase, voff) do { _Pragma("unroll") for (int _i = 0; _i < 2; ++_i) \
;         __builtin_amdgcn_global_load_lds((const unsigned*)((const char*)(gbase) + (voff)[_i]), (LAS unsigned*)(lds + (bufoff) + ldsw + _i * 8192), 16, 0, 0); } while (0)
; #define PG8_LDA(dst, b, h) do { _Pragma("unroll") for (int m = 0; m < 4; ++m) _Pragma("unroll") for (int k = 0; k < 2; ++k) dst[m][k] = *(const LAS bf16x8*)(lds + PG8_SA(b, h) + aoff + m * 2048 + k * 1024); } while (0)
; #define PG8_LDB(dst, b, h) do { _Pragma("unroll") for (int n = 0; n < 2; ++n) _Pragma("unroll") for (int k = 0; k < 2; ++k) dst[n][k] = *(const LAS bf16x8*)(lds + PG8_SB(b, h) + boff + n * 2048 + k * 1024); } while (0)
; #define PG8_WAIT_V(n) asm volatile("s_waitcnt vmcnt(" #n ")" ::: "memory")
; #define PG8_WAIT_L(n) asm volatile("s_waitcnt lgkmcnt(" #n ")" ::: "memory")
; #define PG8_BAR __builtin_amdgcn_s_barrier()
; #define PG8_SCHED __builtin_amdgcn_sched_barrier(0)
; template <class Epi>
; __device__ __forceinline__ void gemm_phase(LAS unsigned char* lds, const bf16_t* A, int lda, const bf16_t* Bt, int ldb, int M, int N, int K, int asel, const Epi& E, const int fixed_round = -1) {
;     ...
;         const char* nA = has_next ? PG8_ABASE(nxt) : cA; const char* nB = has_next ? (const char*)Bt + (size_t)nxt.pn * tstepB : cB;
;         for (int t = 0; t < nt; t += 2) {
;             const bool last = (t == nt - 2);
;             const char* a1 = cA + (size_t)(t + 1) * kstep;
;             const char* a2 = last ? nA : cA + (size_t)(t + 2) * kstep; const char* b2 = last ? nB : cB + (size_t)(t + 2) * kstep;
;             const char* a3 = a2 + kstep; const char* b3 = b2 + kstep;
;             PG8_LDB(B0, 0, 0); PG8_SCHED; PG8_LDA(At, 0, 0); PG8_STAGE(PG8_SA(1, 1), a1 + hstepA, voffA);
;             PG8_WAIT_L(8); PG8_BAR; PG8_WAIT_L(0); PG8_MMA(0, 0, At, B0); PG8_BAR; PG8_SCHED;
;             PG8_LDB(B1, 0, 1); PG8_STAGE(PG8_SB(0, 0), b2, voffB);
;             PG8_BAR; PG8_WAIT_L(0); PG8_MMA(0, 1, At, B1); PG8_BAR;
;             PG8_LDA(At, 0, 1); PG8_STAGE(PG8_SA(0, 0), a2, voffA);
;             PG8_BAR; PG8_WAIT_L(0); PG8_MMA(1, 0, At, B0); PG8_BAR; PG8_SCHED;
;             PG8_STAGE(PG8_SB(0, 1), b2 + hstepB, voffB);
;             PG8_WAIT_V(6); PG8_BAR; PG8_MMA(1, 1, At, B1); PG8_BAR;
.LBB0_1322:
	ds_read_b128 v[144:147], v122
	ds_read_b128 v[148:151], v122 offset:1024
	ds_read_b128 v[152:155], v122 offset:2048
	ds_read_b128 v[156:159], v122 offset:3072
	s_mov_b32 m0, s35
	v_lshl_add_u64 v[192:193], v[118:119], 0, s[6:7]
	ds_read_b128 v[160:163], v123
	ds_read_b128 v[164:167], v123 offset:1024
	ds_read_b128 v[168:171], v123 offset:2048
	ds_read_b128 v[172:175], v123 offset:3072
	ds_read_b128 v[176:179], v123 offset:4096
	ds_read_b128 v[180:183], v123 offset:5120
	ds_read_b128 v[184:187], v123 offset:6144
	ds_read_b128 v[188:191], v123 offset:7168
	global_load_lds_dwordx4 v[192:193], off
	v_lshl_add_u64 v[192:193], v[120:121], 0, s[6:7]
	s_mov_b32 m0, s40
	s_nop 0
	global_load_lds_dwordx4 v[192:193], off
	s_waitcnt lgkmcnt(8)
	s_setprio 1
	s_barrier
	s_waitcnt lgkmcnt(0)
	v_mfma_f32_16x16x32_bf16 v[140:143], v[144:147], v[160:163], v[140:143]
	v_mfma_f32_16x16x32_bf16 v[136:139], v[152:155], v[160:163], v[136:139]
	v_mfma_f32_16x16x32_bf16 v[108:111], v[144:147], v[168:171], v[108:111]
	v_mfma_f32_16x16x32_bf16 v[104:107], v[152:155], v[168:171], v[104:107]
	v_mfma_f32_16x16x32_bf16 v[92:95], v[144:147], v[176:179], v[92:95]
	v_mfma_f32_16x16x32_bf16 v[88:91], v[152:155], v[176:179], v[88:91]
	v_mfma_f32_16x16x32_bf16 v[76:79], v[144:147], v[184:187], v[76:79]
	v_mfma_f32_16x16x32_bf16 v[72:75], v[152:155], v[184:187], v[72:75]
	v_mfma_f32_16x16x32_bf16 v[140:143], v[148:151], v[164:167], v[140:143]
	v_mfma_f32_16x16x32_bf16 v[136:139], v[156:159], v[164:167], v[136:139]
	v_mfma_f32_16x16x32_bf16 v[108:111], v[148:151], v[172:175], v[108:111]
	v_mfma_f32_16x16x32_bf16 v[104:107], v[156:159], v[172:175], v[104:107]
	v_mfma_f32_16x16x32_bf16 v[92:95], v[148:151], v[180:183], v[92:95]
	v_mfma_f32_16x16x32_bf16 v[88:91], v[156:159], v[180:183], v[88:91]
	v_mfma_f32_16x16x32_bf16 v[76:79], v[148:151], v[188:191], v[76:79]
	v_mfma_f32_16x16x32_bf16 v[72:75], v[156:159], v[188:191], v[72:75]
	s_barrier
	s_setprio 0
	s_add_u32 s8, s4, s6
	s_addc_u32 s9, s5, s7
	s_add_u32 s8, s8, 0x18500100
	s_addc_u32 s9, s9, 0
	s_add_u32 s49, s28, s6
	s_addc_u32 s50, s29, s7
	s_cmpk_eq_i32 s6, 0x3f00
	s_cselect_b32 s13, s11, s9
	s_cselect_b32 s12, s10, s8
	s_cselect_b32 s9, s3, s50
	s_cselect_b32 s8, s2, s49
	s_mov_b32 m0, s41
	s_add_u32 s98, s8, s0
	s_addc_u32 s99, s9, s1
	ds_read_b128 v[192:195], v124
	ds_read_b128 v[196:199], v124 offset:1024
	ds_read_b128 v[204:207], v124 offset:2048
	ds_read_b128 v[208:211], v124 offset:3072
	global_load_lds_dwordx4 v202, s[8:9]
	s_mov_b32 m0, s42
	s_nop 0
	global_load_lds_dwordx4 v116, s[8:9]
	s_setprio 1
	s_barrier
	s_waitcnt lgkmcnt(0)
	v_mfma_f32_16x16x32_bf16 v[132:135], v[192:195], v[160:163], v[132:135]
	v_mfma_f32_16x16x32_bf16 v[128:131], v[204:207], v[160:163], v[128:131]
	v_mfma_f32_16x16x32_bf16 v[100:103], v[192:195], v[168:171], v[100:103]
	v_mfma_f32_16x16x32_bf16 v[96:99], v[204:207], v[168:171], v[96:99]
	v_mfma_f32_16x16x32_bf16 v[84:87], v[192:195], v[176:179], v[84:87]
	v_mfma_f32_16x16x32_bf16 v[80:83], v[204:207], v[176:179], v[80:83]
	v_mfma_f32_16x16x32_bf16 v[68:71], v[192:195], v[184:187], v[68:71]
	v_mfma_f32_16x16x32_bf16 v[64:67], v[204:207], v[184:187], v[64:67]
	v_mfma_f32_16x16x32_bf16 v[132:135], v[196:199], v[164:167], v[132:135]
	v_mfma_f32_16x16x32_bf16 v[128:131], v[208:211], v[164:167], v[128:131]
	v_mfma_f32_16x16x32_bf16 v[100:103], v[196:199], v[172:175], v[100:103]
	v_mfma_f32_16x16x32_bf16 v[96:99], v[208:211], v[172:175], v[96:99]
	v_mfma_f32_16x16x32_bf16 v[84:87], v[196:199], v[180:183], v[84:87]
	v_mfma_f32_16x16x32_bf16 v[80:83], v[208:211], v[180:183], v[80:83]
	v_mfma_f32_16x16x32_bf16 v[68:71], v[196:199], v[188:191], v[68:71]
	v_mfma_f32_16x16x32_bf16 v[64:67], v[208:211], v[188:191], v[64:67]
	s_barrier
	s_setprio 0
	s_mov_b32 m0, s19
	s_add_u32 s100, s12, s0
	s_addc_u32 s101, s13, s1
	ds_read_b128 v[160:163], v123 offset:16384
	ds_read_b128 v[164:167], v123 offset:17408
	ds_read_b128 v[168:171], v123 offset:18432
	ds_read_b128 v[172:175], v123 offset:19456
	ds_read_b128 v[176:179], v123 offset:20480
	ds_read_b128 v[180:183], v123 offset:21504
	ds_read_b128 v[184:187], v123 offset:22528
	ds_read_b128 v[188:191], v123 offset:23552
	global_load_lds_dwordx4 v112, s[12:13]
	s_mov_b32 m0, s30
	s_nop 0
	global_load_lds_dwordx4 v114, s[12:13]
	s_setprio 1
	s_barrier
	s_waitcnt lgkmcnt(0)
	v_mfma_f32_16x16x32_bf16 v[60:63], v[144:147], v[160:163], v[60:63]
	v_mfma_f32_16x16x32_bf16 v[56:59], v[152:155], v[160:163], v[56:59]
	v_mfma_f32_16x16x32_bf16 v[44:47], v[144:147], v[168:171], v[44:47]
	v_mfma_f32_16x16x32_bf16 v[40:43], v[152:155], v[168:171], v[40:43]
	v_mfma_f32_16x16x32_bf16 v[28:31], v[144:147], v[176:179], v[28:31]
	v_mfma_f32_16x16x32_bf16 v[24:27], v[152:155], v[176:179], v[24:27]
	v_mfma_f32_16x16x32_bf16 v[12:15], v[144:147], v[184:187], v[12:15]
	v_mfma_f32_16x16x32_bf16 v[8:11], v[152:155], v[184:187], v[8:11]
	v_mfma_f32_16x16x32_bf16 v[60:63], v[148:151], v[164:167], v[60:63]
	v_mfma_f32_16x16x32_bf16 v[56:59], v[156:159], v[164:167], v[56:59]
	v_mfma_f32_16x16x32_bf16 v[44:47], v[148:151], v[172:175], v[44:47]
	v_mfma_f32_16x16x32_bf16 v[40:43], v[156:159], v[172:175], v[40:43]
	v_mfma_f32_16x16x32_bf16 v[28:31], v[148:151], v[180:183], v[28:31]
	v_mfma_f32_16x16x32_bf16 v[24:27], v[156:159], v[180:183], v[24:27]
	v_mfma_f32_16x16x32_bf16 v[12:15], v[148:151], v[188:191], v[12:15]
	v_mfma_f32_16x16x32_bf16 v[8:11], v[156:159], v[188:191], v[8:11]
	s_barrier
	s_setprio 0
	s_add_u32 s50, s8, 0x200000
	s_addc_u32 s51, s9, 0
	s_mov_b32 m0, s43
	s_nop 0
	global_load_lds_dwordx4 v202, s[50:51]
	s_mov_b32 m0, s44
	s_nop 0
	global_load_lds_dwordx4 v116, s[50:51]
	s_waitcnt vmcnt(6)
	s_setprio 1
	s_barrier
; #define PG8_STAGE(bufoff, gbase, voff) do { _Pragma("unroll") for (int _i = 0; _i < 2; ++_i) \
;         __builtin_amdgcn_global_load_lds((const unsigned*)((const char*)(gbase) + (voff)[_i]), (LAS unsigned*)(lds + (bufoff) + ldsw + _i * 8192), 16, 0, 0); } while (0)
; #define PG8_LDA(dst, b, h) do { _Pragma("unroll") for (int m = 0; m < 4; ++m) _Pragma("unroll") for (int k = 0; k < 2; ++k) dst[m][k] = *(const LAS bf16x8*)(lds + PG8_SA(b, h) + aoff + m * 2048 + k * 1024); } while (0)
; #define PG8_LDB(dst, b, h) do { _Pragma("unroll") for (int n = 0; n < 2; ++n) _Pragma("unroll") for (int k = 0; k < 2; ++k) dst[n][k] = *(const LAS bf16x8*)(lds + PG8_SB(b, h) + boff + n * 2048 + k * 1024); } while (0)
; #define PG8_WAIT_V(n) asm volatile("s_waitcnt vmcnt(" #n ")" ::: "memory")
; #define PG8_WAIT_L(n) asm volatile("s_waitcnt lgkmcnt(" #n ")" ::: "memory")
; #define PG8_BAR __builtin_amdgcn_s_barrier()
; #define PG8_SCHED __builtin_amdgcn_sched_barrier(0)
; template <class Epi>
; __device__ __forceinline__ void gemm_phase(LAS unsigned char* lds, const bf16_t* A, int lda, const bf16_t* Bt, int ldb, int M, int N, int K, int asel, const Epi& E, const int fixed_round = -1) {
;     ...
;             PG8_WAIT_V(6); PG8_BAR; PG8_MMA(1, 1, At, B1); PG8_BAR;
;             PG8_LDB(B0, 1, 0); PG8_SCHED; PG8_LDA(At, 1, 0); PG8_STAGE(PG8_SA(0, 1), a2 + hstepA, voffA);
;             PG8_WAIT_L(8); PG8_BAR; PG8_WAIT_L(0); PG8_MMA(0, 0, At, B0); PG8_BAR; PG8_SCHED;
;             PG8_LDB(B1, 1, 1); PG8_STAGE(PG8_SB(1, 0), b3, voffB);
;             PG8_BAR; PG8_WAIT_L(0); PG8_MMA(0, 1, At, B1); PG8_BAR;
;             PG8_LDA(At, 1, 1); PG8_STAGE(PG8_SA(1, 0), a3, voffA);
	v_mfma_f32_16x16x32_bf16 v[52:55], v[192:195], v[160:163], v[52:55]
	v_mfma_f32_16x16x32_bf16 v[48:51], v[204:207], v[160:163], v[48:51]
	v_mfma_f32_16x16x32_bf16 v[36:39], v[192:195], v[168:171], v[36:39]
	v_mfma_f32_16x16x32_bf16 v[32:35], v[204:207], v[168:171], v[32:35]
	v_mfma_f32_16x16x32_bf16 v[20:23], v[192:195], v[176:179], v[20:23]
	v_mfma_f32_16x16x32_bf16 v[16:19], v[204:207], v[176:179], v[16:19]
	v_mfma_f32_16x16x32_bf16 v[4:7], v[192:195], v[184:187], v[4:7]
	v_mfma_f32_16x16x32_bf16 v[0:3], v[204:207], v[184:187], v[0:3]
	v_mfma_f32_16x16x32_bf16 v[52:55], v[196:199], v[164:167], v[52:55]
	v_mfma_f32_16x16x32_bf16 v[48:51], v[208:211], v[164:167], v[48:51]
	v_mfma_f32_16x16x32_bf16 v[36:39], v[196:199], v[172:175], v[36:39]
	v_mfma_f32_16x16x32_bf16 v[32:35], v[208:211], v[172:175], v[32:35]
	v_mfma_f32_16x16x32_bf16 v[20:23], v[196:199], v[180:183], v[20:23]
	v_mfma_f32_16x16x32_bf16 v[16:19], v[208:211], v[180:183], v[16:19]
	v_mfma_f32_16x16x32_bf16 v[4:7], v[196:199], v[188:191], v[4:7]
	v_mfma_f32_16x16x32_bf16 v[0:3], v[208:211], v[188:191], v[0:3]
	s_barrier
	s_setprio 0
	ds_read_b128 v[144:147], v125
	ds_read_b128 v[148:151], v125 offset:1024
	ds_read_b128 v[152:155], v125 offset:2048
	ds_read_b128 v[156:159], v125 offset:3072
	s_add_u32 s12, s12, 0x200000
	s_addc_u32 s13, s13, 0
	s_mov_b32 m0, s31
	ds_read_b128 v[160:163], v123 offset:32768
	ds_read_b128 v[164:167], v123 offset:33792
	ds_read_b128 v[168:171], v123 offset:34816
	ds_read_b128 v[172:175], v123 offset:35840
	ds_read_b128 v[176:179], v123 offset:36864
	ds_read_b128 v[180:183], v123 offset:37888
	ds_read_b128 v[184:187], v123 offset:38912
	ds_read_b128 v[188:191], v123 offset:39936
	global_load_lds_dwordx4 v112, s[12:13]
	s_mov_b32 m0, s33
	s_nop 0
	global_load_lds_dwordx4 v114, s[12:13]
	s_waitcnt lgkmcnt(8)
	s_setprio 1
	s_barrier
	s_waitcnt lgkmcnt(0)
	v_mfma_f32_16x16x32_bf16 v[140:143], v[144:147], v[160:163], v[140:143]
	v_mfma_f32_16x16x32_bf16 v[136:139], v[152:155], v[160:163], v[136:139]
	v_mfma_f32_16x16x32_bf16 v[108:111], v[144:147], v[168:171], v[108:111]
	v_mfma_f32_16x16x32_bf16 v[104:107], v[152:155], v[168:171], v[104:107]
	v_mfma_f32_16x16x32_bf16 v[92:95], v[144:147], v[176:179], v[92:95]
	v_mfma_f32_16x16x32_bf16 v[88:91], v[152:155], v[176:179], v[88:91]
	v_mfma_f32_16x16x32_bf16 v[76:79], v[144:147], v[184:187], v[76:79]
	v_mfma_f32_16x16x32_bf16 v[72:75], v[152:155], v[184:187], v[72:75]
	v_mfma_f32_16x16x32_bf16 v[140:143], v[148:151], v[164:167], v[140:143]
	v_mfma_f32_16x16x32_bf16 v[136:139], v[156:159], v[164:167], v[136:139]
	v_mfma_f32_16x16x32_bf16 v[108:111], v[148:151], v[172:175], v[108:111]
	v_mfma_f32_16x16x32_bf16 v[104:107], v[156:159], v[172:175], v[104:107]
	v_mfma_f32_16x16x32_bf16 v[92:95], v[148:151], v[180:183], v[92:95]
	v_mfma_f32_16x16x32_bf16 v[88:91], v[156:159], v[180:183], v[88:91]
	v_mfma_f32_16x16x32_bf16 v[76:79], v[148:151], v[188:191], v[76:79]
	v_mfma_f32_16x16x32_bf16 v[72:75], v[156:159], v[188:191], v[72:75]
	s_barrier
	s_setprio 0
	s_mov_b32 m0, s45
	ds_read_b128 v[192:195], v126
	ds_read_b128 v[196:199], v126 offset:1024
	ds_read_b128 v[204:207], v126 offset:2048
	ds_read_b128 v[208:211], v126 offset:3072
	global_load_lds_dwordx4 v202, s[98:99]
	s_mov_b32 m0, s46
	s_nop 0
	global_load_lds_dwordx4 v116, s[98:99]
	s_setprio 1
	s_barrier
; #define PG8_STAGE(bufoff, gbase, voff) do { _Pragma("unroll") for (int _i = 0; _i < 2; ++_i) \
;         __builtin_amdgcn_global_load_lds((const unsigned*)((const char*)(gbase) + (voff)[_i]), (LAS unsigned*)(lds + (bufoff) + ldsw + _i * 8192), 16, 0, 0); } while (0)
; #define PG8_LDA(dst, b, h) do { _Pragma("unroll") for (int m = 0; m < 4; ++m) _Pragma("unroll") for (int k = 0; k < 2; ++k) dst[m][k] = *(const LAS bf16x8*)(lds + PG8_SA(b, h) + aoff + m * 2048 + k * 1024); } while (0)
; #define PG8_WAIT_V(n) asm volatile("s_waitcnt vmcnt(" #n ")" ::: "memory")
; #define PG8_WAIT_L(n) asm volatile("s_waitcnt lgkmcnt(" #n ")" ::: "memory")
; #define PG8_BAR __builtin_amdgcn_s_barrier()
; #define PG8_SCHED __builtin_amdgcn_sched_barrier(0)
; template <class Epi>
; __device__ __forceinline__ void gemm_phase(LAS unsigned char* lds, const bf16_t* A, int lda, const bf16_t* Bt, int ldb, int M, int N, int K, int asel, const Epi& E, const int fixed_round = -1) {
;     ...
;             PG8_LDA(At, 1, 1); PG8_STAGE(PG8_SA(1, 0), a3, voffA);
;             PG8_BAR; PG8_WAIT_L(0); PG8_MMA(1, 0, At, B0); PG8_BAR; PG8_SCHED;
;             PG8_STAGE(PG8_SB(1, 1), b3 + hstepB, voffB);
;             PG8_WAIT_V(6); PG8_BAR; PG8_MMA(1, 1, At, B1); PG8_BAR;
;     ...
;     PG8_WAIT_V(0);
;     if (wr == 0) PG8_BAR;
;     PG8_BAR;
	s_waitcnt lgkmcnt(0)
	v_mfma_f32_16x16x32_bf16 v[132:135], v[192:195], v[160:163], v[132:135]
	v_mfma_f32_16x16x32_bf16 v[128:131], v[204:207], v[160:163], v[128:131]
	v_mfma_f32_16x16x32_bf16 v[100:103], v[192:195], v[168:171], v[100:103]
	v_mfma_f32_16x16x32_bf16 v[96:99], v[204:207], v[168:171], v[96:99]
	v_mfma_f32_16x16x32_bf16 v[84:87], v[192:195], v[176:179], v[84:87]
	v_mfma_f32_16x16x32_bf16 v[80:83], v[204:207], v[176:179], v[80:83]
	v_mfma_f32_16x16x32_bf16 v[68:71], v[192:195], v[184:187], v[68:71]
	v_mfma_f32_16x16x32_bf16 v[64:67], v[204:207], v[184:187], v[64:67]
	v_mfma_f32_16x16x32_bf16 v[132:135], v[196:199], v[164:167], v[132:135]
	v_mfma_f32_16x16x32_bf16 v[128:131], v[208:211], v[164:167], v[128:131]
	v_mfma_f32_16x16x32_bf16 v[100:103], v[196:199], v[172:175], v[100:103]
	v_mfma_f32_16x16x32_bf16 v[96:99], v[208:211], v[172:175], v[96:99]
	v_mfma_f32_16x16x32_bf16 v[84:87], v[196:199], v[180:183], v[84:87]
	v_mfma_f32_16x16x32_bf16 v[80:83], v[208:211], v[180:183], v[80:83]
	v_mfma_f32_16x16x32_bf16 v[68:71], v[196:199], v[188:191], v[68:71]
	v_mfma_f32_16x16x32_bf16 v[64:67], v[208:211], v[188:191], v[64:67]
	s_barrier
	s_setprio 0
	s_mov_b32 m0, s36
	ds_read_b128 v[160:163], v123 offset:49152
	ds_read_b128 v[164:167], v123 offset:50176
	ds_read_b128 v[168:171], v123 offset:51200
	ds_read_b128 v[172:175], v123 offset:52224
	ds_read_b128 v[176:179], v123 offset:53248
	ds_read_b128 v[180:183], v123 offset:54272
	ds_read_b128 v[184:187], v123 offset:55296
	ds_read_b128 v[188:191], v123 offset:56320
	global_load_lds_dwordx4 v112, s[100:101]
	s_mov_b32 m0, s37
	s_nop 0
	global_load_lds_dwordx4 v114, s[100:101]
	s_setprio 1
	s_barrier
	s_waitcnt lgkmcnt(0)
	v_mfma_f32_16x16x32_bf16 v[60:63], v[144:147], v[160:163], v[60:63]
	v_mfma_f32_16x16x32_bf16 v[56:59], v[152:155], v[160:163], v[56:59]
	v_mfma_f32_16x16x32_bf16 v[44:47], v[144:147], v[168:171], v[44:47]
	v_mfma_f32_16x16x32_bf16 v[40:43], v[152:155], v[168:171], v[40:43]
	v_mfma_f32_16x16x32_bf16 v[28:31], v[144:147], v[176:179], v[28:31]
	v_mfma_f32_16x16x32_bf16 v[24:27], v[152:155], v[176:179], v[24:27]
	v_mfma_f32_16x16x32_bf16 v[12:15], v[144:147], v[184:187], v[12:15]
	v_mfma_f32_16x16x32_bf16 v[8:11], v[152:155], v[184:187], v[8:11]
	v_mfma_f32_16x16x32_bf16 v[60:63], v[148:151], v[164:167], v[60:63]
	v_mfma_f32_16x16x32_bf16 v[56:59], v[156:159], v[164:167], v[56:59]
	v_mfma_f32_16x16x32_bf16 v[44:47], v[148:151], v[172:175], v[44:47]
	v_mfma_f32_16x16x32_bf16 v[40:43], v[156:159], v[172:175], v[40:43]
	v_mfma_f32_16x16x32_bf16 v[28:31], v[148:151], v[180:183], v[28:31]
	v_mfma_f32_16x16x32_bf16 v[24:27], v[156:159], v[180:183], v[24:27]
	v_mfma_f32_16x16x32_bf16 v[12:15], v[148:151], v[188:191], v[12:15]
	v_mfma_f32_16x16x32_bf16 v[8:11], v[156:159], v[188:191], v[8:11]
	s_barrier
	s_setprio 0
	s_add_u32 s8, s8, 0x200080
	s_addc_u32 s9, s9, 0
	s_mov_b32 m0, s47
	s_nop 0
	global_load_lds_dwordx4 v202, s[8:9]
	s_mov_b32 m0, s48
	s_nop 0
	global_load_lds_dwordx4 v116, s[8:9]
	s_waitcnt vmcnt(6)
	s_setprio 1
	s_barrier
	v_mfma_f32_16x16x32_bf16 v[52:55], v[192:195], v[160:163], v[52:55]
	v_mfma_f32_16x16x32_bf16 v[48:51], v[204:207], v[160:163], v[48:51]
	v_mfma_f32_16x16x32_bf16 v[36:39], v[192:195], v[168:171], v[36:39]
	v_mfma_f32_16x16x32_bf16 v[32:35], v[204:207], v[168:171], v[32:35]
	v_mfma_f32_16x16x32_bf16 v[20:23], v[192:195], v[176:179], v[20:23]
	v_mfma_f32_16x16x32_bf16 v[16:19], v[204:207], v[176:179], v[16:19]
	v_mfma_f32_16x16x32_bf16 v[4:7], v[192:195], v[184:187], v[4:7]
	v_mfma_f32_16x16x32_bf16 v[0:3], v[204:207], v[184:187], v[0:3]
	v_mfma_f32_16x16x32_bf16 v[52:55], v[196:199], v[164:167], v[52:55]
	v_mfma_f32_16x16x32_bf16 v[48:51], v[208:211], v[164:167], v[48:51]
	v_mfma_f32_16x16x32_bf16 v[36:39], v[196:199], v[172:175], v[36:39]
	v_mfma_f32_16x16x32_bf16 v[32:35], v[208:211], v[172:175], v[32:35]
	v_mfma_f32_16x16x32_bf16 v[20:23], v[196:199], v[180:183], v[20:23]
	v_mfma_f32_16x16x32_bf16 v[16:19], v[208:211], v[180:183], v[16:19]
	v_mfma_f32_16x16x32_bf16 v[4:7], v[196:199], v[188:191], v[4:7]
	v_mfma_f32_16x16x32_bf16 v[0:3], v[208:211], v[188:191], v[0:3]
	s_setprio 0
	s_add_i32 s34, s34, 2
	s_add_u32 s6, s6, 0x100
	s_addc_u32 s7, s7, 0
	s_cmpk_lt_u32 s34, 0x7e
	s_cbranch_scc1 .Lrot_12
	s_barrier
	s_waitcnt vmcnt(0)
	s_cmpk_gt_u32 s18, 0xff
	s_cbranch_scc1 .LBB0_1325
	s_barrier
